# norm phases: rows interleaved across waves (each wave takes rows j+256t of its batch) instead of 16 consecutive rows per wave
# baseline (speedup 1.0000x reference)
.LBB0_94:
	s_cmp_gt_i32 s44, 1
	s_cselect_b64 s[2:3], -1, 0
	s_cmp_lt_i32 s45, 2
	s_cselect_b64 s[4:5], -1, 0
	s_or_b64 s[2:3], s[2:3], s[4:5]
	s_and_b64 vcc, exec, s[2:3]
	s_cbranch_vccnz .LBB0_295
	s_lshl_b32 s96, s22, 3
	s_lshr_b32 s97, s70, 6
	s_add_u32 s96, s96, s97
	s_lshr_b32 s97, s96, 8
	s_lshl_b32 s97, s97, 12
	s_and_b32 s99, s96, 0xff
	s_or_b32 s97, s97, s99
	s_cmpk_ge_u32 s97, 0x8000
	s_cbranch_scc1 .Lnp1_done
	s_load_dwordx2 s[88:89], s[0:1], 0x0
	s_load_dwordx2 s[90:91], s[0:1], 0x18
	s_load_dwordx2 s[92:93], s[0:1], 0x140
	s_load_dwordx2 s[94:95], s[0:1], 0x158
	v_mbcnt_hi_u32_b32 v0, -1, v210
	v_lshlrev_b32_e32 v1, 4, v0
	s_waitcnt lgkmcnt(0)
	s_add_u32 s90, s90, 0
	s_addc_u32 s91, s91, 0
	global_load_dwordx4 v[112:115], v1, s[90:91] nt
	global_load_dwordx4 v[116:119], v1, s[90:91] offset:1024 nt
	global_load_dwordx4 v[120:123], v1, s[90:91] offset:2048 nt
	global_load_dwordx4 v[124:127], v1, s[90:91] offset:3072 nt
	s_lshr_b32 s98, s97, 12
	s_add_u32 s98, s98, 0
	s_mul_i32 s98, s98, 0x3000
	s_add_u32 s92, s92, s98
	s_addc_u32 s93, s93, 0
	global_load_dwordx4 v[144:147], v1, s[92:93] nt
	global_load_dwordx4 v[148:151], v1, s[92:93] offset:1024 nt
	global_load_dwordx4 v[152:155], v1, s[92:93] offset:2048 nt
	global_load_dwordx4 v[156:159], v1, s[92:93] offset:3072 nt
	s_add_u32 s92, s92, 0x1000
	s_addc_u32 s93, s93, 0
	global_load_dwordx4 v[128:131], v1, s[92:93] nt
	global_load_dwordx4 v[132:135], v1, s[92:93] offset:1024 nt
	global_load_dwordx4 v[136:139], v1, s[92:93] offset:2048 nt
	global_load_dwordx4 v[140:143], v1, s[92:93] offset:3072 nt
	s_load_dwordx2 s[90:91], s[0:1], 0x210
	s_load_dwordx2 s[92:93], s[0:1], 0x218
	s_waitcnt vmcnt(0) lgkmcnt(0)
	v_pk_add_f32 v[128:129], v[128:129], 1.0 op_sel_hi:[1,0]
	v_pk_add_f32 v[130:131], v[130:131], 1.0 op_sel_hi:[1,0]
	v_pk_add_f32 v[132:133], v[132:133], 1.0 op_sel_hi:[1,0]
	v_pk_add_f32 v[134:135], v[134:135], 1.0 op_sel_hi:[1,0]
	v_pk_add_f32 v[136:137], v[136:137], 1.0 op_sel_hi:[1,0]
	v_pk_add_f32 v[138:139], v[138:139], 1.0 op_sel_hi:[1,0]
	v_pk_add_f32 v[140:141], v[140:141], 1.0 op_sel_hi:[1,0]
	v_pk_add_f32 v[142:143], v[142:143], 1.0 op_sel_hi:[1,0]
	s_add_u32 s98, s97, 0
	s_lshl_b32 s98, s98, 12
	v_add_u32_e32 v3, s98, v1
	global_load_dwordx4 v[16:19], v3, s[88:89] nt
	global_load_dwordx4 v[20:23], v3, s[88:89] offset:1024 nt
	global_load_dwordx4 v[24:27], v3, s[88:89] offset:2048 nt
	global_load_dwordx4 v[28:31], v3, s[88:89] offset:3072 nt
	s_add_u32 s98, s97, 256
	s_lshl_b32 s98, s98, 12
	v_add_u32_e32 v3, s98, v1
	global_load_dwordx4 v[32:35], v3, s[88:89] nt
	global_load_dwordx4 v[36:39], v3, s[88:89] offset:1024 nt
	global_load_dwordx4 v[40:43], v3, s[88:89] offset:2048 nt
	global_load_dwordx4 v[44:47], v3, s[88:89] offset:3072 nt
	s_add_u32 s98, s97, 512
	s_lshl_b32 s98, s98, 12
	v_add_u32_e32 v3, s98, v1
	global_load_dwordx4 v[48:51], v3, s[88:89] nt
	global_load_dwordx4 v[52:55], v3, s[88:89] offset:1024 nt
	global_load_dwordx4 v[56:59], v3, s[88:89] offset:2048 nt
	global_load_dwordx4 v[60:63], v3, s[88:89] offset:3072 nt
	s_add_u32 s98, s97, 768
	s_lshl_b32 s98, s98, 12
	v_add_u32_e32 v3, s98, v1
	global_load_dwordx4 v[64:67], v3, s[88:89] nt
	global_load_dwordx4 v[68:71], v3, s[88:89] offset:1024 nt
	global_load_dwordx4 v[72:75], v3, s[88:89] offset:2048 nt
	global_load_dwordx4 v[76:79], v3, s[88:89] offset:3072 nt
	s_add_u32 s98, s97, 1024
	s_lshl_b32 s98, s98, 12
	v_add_u32_e32 v3, s98, v1
	global_load_dwordx4 v[80:83], v3, s[88:89] nt
	global_load_dwordx4 v[84:87], v3, s[88:89] offset:1024 nt
	global_load_dwordx4 v[88:91], v3, s[88:89] offset:2048 nt
	global_load_dwordx4 v[92:95], v3, s[88:89] offset:3072 nt
	s_add_u32 s98, s97, 1280
	s_lshl_b32 s98, s98, 12
	v_add_u32_e32 v3, s98, v1
	global_load_dwordx4 v[96:99], v3, s[88:89] nt
	global_load_dwordx4 v[100:103], v3, s[88:89] offset:1024 nt
	global_load_dwordx4 v[104:107], v3, s[88:89] offset:2048 nt
	global_load_dwordx4 v[108:111], v3, s[88:89] offset:3072 nt
	s_waitcnt vmcnt(20)
	v_mul_f32_e32 v4, v16, v16
	v_fma_f32 v4, v17, v17, v4
	v_fma_f32 v4, v18, v18, v4
	v_fma_f32 v4, v19, v19, v4
	v_fma_f32 v4, v20, v20, v4
	v_fma_f32 v4, v21, v21, v4
	v_fma_f32 v4, v22, v22, v4
	v_fma_f32 v4, v23, v23, v4
	v_fma_f32 v4, v24, v24, v4
	v_fma_f32 v4, v25, v25, v4
	v_fma_f32 v4, v26, v26, v4
	v_fma_f32 v4, v27, v27, v4
	v_fma_f32 v4, v28, v28, v4
	v_fma_f32 v4, v29, v29, v4
	v_fma_f32 v4, v30, v30, v4
	v_fma_f32 v4, v31, v31, v4
	s_nop 1
	v_add_f32_dpp v5, v4, v4 quad_perm:[1,0,3,2] row_mask:0xf bank_mask:0xf
	s_nop 1
	v_add_f32_dpp v4, v5, v5 quad_perm:[2,3,0,1] row_mask:0xf bank_mask:0xf
	s_nop 1
	v_add_f32_dpp v5, v4, v4 row_half_mirror row_mask:0xf bank_mask:0xf
	s_nop 1
	v_add_f32_dpp v4, v5, v5 row_mirror row_mask:0xf bank_mask:0xf
	s_nop 1
	v_readlane_b32 s98, v4, 0
	v_readlane_b32 s99, v4, 16
	s_nop 3
	v_mov_b32_e32 v5, s98
	v_add_f32_e32 v5, s99, v5
	v_readlane_b32 s98, v4, 32
	v_readlane_b32 s99, v4, 48
	s_nop 3
	v_add_f32_e32 v5, s98, v5
	v_add_f32_e32 v5, s99, v5
	v_mul_f32_e32 v5, 0x3a800000, v5
	v_add_f32_e32 v5, 0x358637bd, v5
	v_rsq_f32_e32 v6, v5
	s_nop 0
	s_add_u32 s98, s97, 0
	v_pk_mul_f32 v[16:17], v[16:17], v[6:7] op_sel_hi:[1,0]
	v_pk_mul_f32 v[18:19], v[18:19], v[6:7] op_sel_hi:[1,0]
	v_pk_mul_f32 v[20:21], v[20:21], v[6:7] op_sel_hi:[1,0]
	v_pk_mul_f32 v[22:23], v[22:23], v[6:7] op_sel_hi:[1,0]
	v_pk_mul_f32 v[24:25], v[24:25], v[6:7] op_sel_hi:[1,0]
	v_pk_mul_f32 v[26:27], v[26:27], v[6:7] op_sel_hi:[1,0]
	v_pk_mul_f32 v[28:29], v[28:29], v[6:7] op_sel_hi:[1,0]
	v_pk_mul_f32 v[30:31], v[30:31], v[6:7] op_sel_hi:[1,0]
	v_pk_mul_f32 v[16:17], v[16:17], v[112:113]
	v_pk_mul_f32 v[18:19], v[18:19], v[114:115]
	v_pk_mul_f32 v[20:21], v[20:21], v[116:117]
	v_pk_mul_f32 v[22:23], v[22:23], v[118:119]
	v_pk_mul_f32 v[24:25], v[24:25], v[120:121]
	v_pk_mul_f32 v[26:27], v[26:27], v[122:123]
	v_pk_mul_f32 v[28:29], v[28:29], v[124:125]
	v_pk_mul_f32 v[30:31], v[30:31], v[126:127]
	v_pk_fma_f32 v[16:17], v[16:17], v[128:129], v[144:145]
	v_pk_fma_f32 v[18:19], v[18:19], v[130:131], v[146:147]
	v_pk_fma_f32 v[20:21], v[20:21], v[132:133], v[148:149]
	v_pk_fma_f32 v[22:23], v[22:23], v[134:135], v[150:151]
	v_pk_fma_f32 v[24:25], v[24:25], v[136:137], v[152:153]
	v_pk_fma_f32 v[26:27], v[26:27], v[138:139], v[154:155]
	v_pk_fma_f32 v[28:29], v[28:29], v[140:141], v[156:157]
	v_pk_fma_f32 v[30:31], v[30:31], v[142:143], v[158:159]
	v_cvt_pk_bf16_f32 v16, v16, v17
	v_cvt_pk_bf16_f32 v17, v18, v19
	v_cvt_pk_bf16_f32 v18, v20, v21
	v_cvt_pk_bf16_f32 v19, v22, v23
	v_cvt_pk_bf16_f32 v20, v24, v25
	v_cvt_pk_bf16_f32 v21, v26, v27
	v_cvt_pk_bf16_f32 v22, v28, v29
	v_cvt_pk_bf16_f32 v23, v30, v31
	s_lshl_b32 s99, s98, 11
	v_lshl_add_u32 v8, v0, 3, s99
	global_store_dwordx2 v8, v[16:17], s[94:95]
	global_store_dwordx2 v8, v[18:19], s[94:95] offset:512
	global_store_dwordx2 v8, v[20:21], s[94:95] offset:1024
	global_store_dwordx2 v8, v[22:23], s[94:95] offset:1536
	s_lshl_b32 s99, s98, 2
	v_mov_b32_e32 v9, s99
	v_mov_b32_e32 v10, 0
	v_cmp_eq_u32_e32 vcc, 0, v0
	s_and_saveexec_b64 s[98:99], vcc
	global_store_dword v9, v10, s[90:91]
	global_store_dword v9, v10, s[92:93]
	s_or_b64 exec, exec, s[98:99]
	s_add_u32 s98, s97, 1536
	s_lshl_b32 s98, s98, 12
	v_add_u32_e32 v3, s98, v1
	global_load_dwordx4 v[16:19], v3, s[88:89] nt
	global_load_dwordx4 v[20:23], v3, s[88:89] offset:1024 nt
	global_load_dwordx4 v[24:27], v3, s[88:89] offset:2048 nt
	global_load_dwordx4 v[28:31], v3, s[88:89] offset:3072 nt
	s_waitcnt vmcnt(26)
	v_mul_f32_e32 v4, v32, v32
	v_fma_f32 v4, v33, v33, v4
	v_fma_f32 v4, v34, v34, v4
	v_fma_f32 v4, v35, v35, v4
	v_fma_f32 v4, v36, v36, v4
	v_fma_f32 v4, v37, v37, v4
	v_fma_f32 v4, v38, v38, v4
	v_fma_f32 v4, v39, v39, v4
	v_fma_f32 v4, v40, v40, v4
	v_fma_f32 v4, v41, v41, v4
	v_fma_f32 v4, v42, v42, v4
	v_fma_f32 v4, v43, v43, v4
	v_fma_f32 v4, v44, v44, v4
	v_fma_f32 v4, v45, v45, v4
	v_fma_f32 v4, v46, v46, v4
	v_fma_f32 v4, v47, v47, v4
	s_nop 1
	v_add_f32_dpp v5, v4, v4 quad_perm:[1,0,3,2] row_mask:0xf bank_mask:0xf
	s_nop 1
	v_add_f32_dpp v4, v5, v5 quad_perm:[2,3,0,1] row_mask:0xf bank_mask:0xf
	s_nop 1
	v_add_f32_dpp v5, v4, v4 row_half_mirror row_mask:0xf bank_mask:0xf
	s_nop 1
	v_add_f32_dpp v4, v5, v5 row_mirror row_mask:0xf bank_mask:0xf
	s_nop 1
	v_readlane_b32 s98, v4, 0
	v_readlane_b32 s99, v4, 16
	s_nop 3
	v_mov_b32_e32 v5, s98
	v_add_f32_e32 v5, s99, v5
	v_readlane_b32 s98, v4, 32
	v_readlane_b32 s99, v4, 48
	s_nop 3
	v_add_f32_e32 v5, s98, v5
	v_add_f32_e32 v5, s99, v5
	v_mul_f32_e32 v5, 0x3a800000, v5
	v_add_f32_e32 v5, 0x358637bd, v5
	v_rsq_f32_e32 v6, v5
	s_nop 0
	s_add_u32 s98, s97, 256
	v_pk_mul_f32 v[32:33], v[32:33], v[6:7] op_sel_hi:[1,0]
	v_pk_mul_f32 v[34:35], v[34:35], v[6:7] op_sel_hi:[1,0]
	v_pk_mul_f32 v[36:37], v[36:37], v[6:7] op_sel_hi:[1,0]
	v_pk_mul_f32 v[38:39], v[38:39], v[6:7] op_sel_hi:[1,0]
	v_pk_mul_f32 v[40:41], v[40:41], v[6:7] op_sel_hi:[1,0]
	v_pk_mul_f32 v[42:43], v[42:43], v[6:7] op_sel_hi:[1,0]
	v_pk_mul_f32 v[44:45], v[44:45], v[6:7] op_sel_hi:[1,0]
	v_pk_mul_f32 v[46:47], v[46:47], v[6:7] op_sel_hi:[1,0]
	v_pk_mul_f32 v[32:33], v[32:33], v[112:113]
	v_pk_mul_f32 v[34:35], v[34:35], v[114:115]
	v_pk_mul_f32 v[36:37], v[36:37], v[116:117]
	v_pk_mul_f32 v[38:39], v[38:39], v[118:119]
	v_pk_mul_f32 v[40:41], v[40:41], v[120:121]
	v_pk_mul_f32 v[42:43], v[42:43], v[122:123]
	v_pk_mul_f32 v[44:45], v[44:45], v[124:125]
	v_pk_mul_f32 v[46:47], v[46:47], v[126:127]
	v_pk_fma_f32 v[32:33], v[32:33], v[128:129], v[144:145]
	v_pk_fma_f32 v[34:35], v[34:35], v[130:131], v[146:147]
	v_pk_fma_f32 v[36:37], v[36:37], v[132:133], v[148:149]
	v_pk_fma_f32 v[38:39], v[38:39], v[134:135], v[150:151]
	v_pk_fma_f32 v[40:41], v[40:41], v[136:137], v[152:153]
	v_pk_fma_f32 v[42:43], v[42:43], v[138:139], v[154:155]
	v_pk_fma_f32 v[44:45], v[44:45], v[140:141], v[156:157]
	v_pk_fma_f32 v[46:47], v[46:47], v[142:143], v[158:159]
	v_cvt_pk_bf16_f32 v32, v32, v33
	v_cvt_pk_bf16_f32 v33, v34, v35
	v_cvt_pk_bf16_f32 v34, v36, v37
	v_cvt_pk_bf16_f32 v35, v38, v39
	v_cvt_pk_bf16_f32 v36, v40, v41
	v_cvt_pk_bf16_f32 v37, v42, v43
	v_cvt_pk_bf16_f32 v38, v44, v45
	v_cvt_pk_bf16_f32 v39, v46, v47
	s_lshl_b32 s99, s98, 11
	v_lshl_add_u32 v8, v0, 3, s99
	global_store_dwordx2 v8, v[32:33], s[94:95]
	global_store_dwordx2 v8, v[34:35], s[94:95] offset:512
	global_store_dwordx2 v8, v[36:37], s[94:95] offset:1024
	global_store_dwordx2 v8, v[38:39], s[94:95] offset:1536
	s_lshl_b32 s99, s98, 2
	v_mov_b32_e32 v9, s99
	v_mov_b32_e32 v10, 0
	v_cmp_eq_u32_e32 vcc, 0, v0
	s_and_saveexec_b64 s[98:99], vcc
	global_store_dword v9, v10, s[90:91]
	global_store_dword v9, v10, s[92:93]
	s_or_b64 exec, exec, s[98:99]
	s_add_u32 s98, s97, 1792
	s_lshl_b32 s98, s98, 12
	v_add_u32_e32 v3, s98, v1
	global_load_dwordx4 v[32:35], v3, s[88:89] nt
	global_load_dwordx4 v[36:39], v3, s[88:89] offset:1024 nt
	global_load_dwordx4 v[40:43], v3, s[88:89] offset:2048 nt
	global_load_dwordx4 v[44:47], v3, s[88:89] offset:3072 nt
	s_waitcnt vmcnt(32)
	v_mul_f32_e32 v4, v48, v48
	v_fma_f32 v4, v49, v49, v4
	v_fma_f32 v4, v50, v50, v4
	v_fma_f32 v4, v51, v51, v4
	v_fma_f32 v4, v52, v52, v4
	v_fma_f32 v4, v53, v53, v4
	v_fma_f32 v4, v54, v54, v4
	v_fma_f32 v4, v55, v55, v4
	v_fma_f32 v4, v56, v56, v4
	v_fma_f32 v4, v57, v57, v4
	v_fma_f32 v4, v58, v58, v4
	v_fma_f32 v4, v59, v59, v4
	v_fma_f32 v4, v60, v60, v4
	v_fma_f32 v4, v61, v61, v4
	v_fma_f32 v4, v62, v62, v4
	v_fma_f32 v4, v63, v63, v4
	s_nop 1
	v_add_f32_dpp v5, v4, v4 quad_perm:[1,0,3,2] row_mask:0xf bank_mask:0xf
	s_nop 1
	v_add_f32_dpp v4, v5, v5 quad_perm:[2,3,0,1] row_mask:0xf bank_mask:0xf
	s_nop 1
	v_add_f32_dpp v5, v4, v4 row_half_mirror row_mask:0xf bank_mask:0xf
	s_nop 1
	v_add_f32_dpp v4, v5, v5 row_mirror row_mask:0xf bank_mask:0xf
	s_nop 1
	v_readlane_b32 s98, v4, 0
	v_readlane_b32 s99, v4, 16
	s_nop 3
	v_mov_b32_e32 v5, s98
	v_add_f32_e32 v5, s99, v5
	v_readlane_b32 s98, v4, 32
	v_readlane_b32 s99, v4, 48
	s_nop 3
	v_add_f32_e32 v5, s98, v5
	v_add_f32_e32 v5, s99, v5
	v_mul_f32_e32 v5, 0x3a800000, v5
	v_add_f32_e32 v5, 0x358637bd, v5
	v_rsq_f32_e32 v6, v5
	s_nop 0
	s_add_u32 s98, s97, 512
	v_pk_mul_f32 v[48:49], v[48:49], v[6:7] op_sel_hi:[1,0]
	v_pk_mul_f32 v[50:51], v[50:51], v[6:7] op_sel_hi:[1,0]
	v_pk_mul_f32 v[52:53], v[52:53], v[6:7] op_sel_hi:[1,0]
	v_pk_mul_f32 v[54:55], v[54:55], v[6:7] op_sel_hi:[1,0]
	v_pk_mul_f32 v[56:57], v[56:57], v[6:7] op_sel_hi:[1,0]
	v_pk_mul_f32 v[58:59], v[58:59], v[6:7] op_sel_hi:[1,0]
	v_pk_mul_f32 v[60:61], v[60:61], v[6:7] op_sel_hi:[1,0]
	v_pk_mul_f32 v[62:63], v[62:63], v[6:7] op_sel_hi:[1,0]
	v_pk_mul_f32 v[48:49], v[48:49], v[112:113]
	v_pk_mul_f32 v[50:51], v[50:51], v[114:115]
	v_pk_mul_f32 v[52:53], v[52:53], v[116:117]
	v_pk_mul_f32 v[54:55], v[54:55], v[118:119]
	v_pk_mul_f32 v[56:57], v[56:57], v[120:121]
	v_pk_mul_f32 v[58:59], v[58:59], v[122:123]
	v_pk_mul_f32 v[60:61], v[60:61], v[124:125]
	v_pk_mul_f32 v[62:63], v[62:63], v[126:127]
	v_pk_fma_f32 v[48:49], v[48:49], v[128:129], v[144:145]
	v_pk_fma_f32 v[50:51], v[50:51], v[130:131], v[146:147]
	v_pk_fma_f32 v[52:53], v[52:53], v[132:133], v[148:149]
	v_pk_fma_f32 v[54:55], v[54:55], v[134:135], v[150:151]
	v_pk_fma_f32 v[56:57], v[56:57], v[136:137], v[152:153]
	v_pk_fma_f32 v[58:59], v[58:59], v[138:139], v[154:155]
	v_pk_fma_f32 v[60:61], v[60:61], v[140:141], v[156:157]
	v_pk_fma_f32 v[62:63], v[62:63], v[142:143], v[158:159]
	v_cvt_pk_bf16_f32 v48, v48, v49
	v_cvt_pk_bf16_f32 v49, v50, v51
	v_cvt_pk_bf16_f32 v50, v52, v53
	v_cvt_pk_bf16_f32 v51, v54, v55
	v_cvt_pk_bf16_f32 v52, v56, v57
	v_cvt_pk_bf16_f32 v53, v58, v59
	v_cvt_pk_bf16_f32 v54, v60, v61
	v_cvt_pk_bf16_f32 v55, v62, v63
	s_lshl_b32 s99, s98, 11
	v_lshl_add_u32 v8, v0, 3, s99
	global_store_dwordx2 v8, v[48:49], s[94:95]
	global_store_dwordx2 v8, v[50:51], s[94:95] offset:512
	global_store_dwordx2 v8, v[52:53], s[94:95] offset:1024
	global_store_dwordx2 v8, v[54:55], s[94:95] offset:1536
	s_lshl_b32 s99, s98, 2
	v_mov_b32_e32 v9, s99
	v_mov_b32_e32 v10, 0
	v_cmp_eq_u32_e32 vcc, 0, v0
	s_and_saveexec_b64 s[98:99], vcc
	global_store_dword v9, v10, s[90:91]
	global_store_dword v9, v10, s[92:93]
	s_or_b64 exec, exec, s[98:99]
	s_add_u32 s98, s97, 2048
	s_lshl_b32 s98, s98, 12
	v_add_u32_e32 v3, s98, v1
	global_load_dwordx4 v[48:51], v3, s[88:89] nt
	global_load_dwordx4 v[52:55], v3, s[88:89] offset:1024 nt
	global_load_dwordx4 v[56:59], v3, s[88:89] offset:2048 nt
	global_load_dwordx4 v[60:63], v3, s[88:89] offset:3072 nt
	s_waitcnt vmcnt(38)
	v_mul_f32_e32 v4, v64, v64
	v_fma_f32 v4, v65, v65, v4
	v_fma_f32 v4, v66, v66, v4
	v_fma_f32 v4, v67, v67, v4
	v_fma_f32 v4, v68, v68, v4
	v_fma_f32 v4, v69, v69, v4
	v_fma_f32 v4, v70, v70, v4
	v_fma_f32 v4, v71, v71, v4
	v_fma_f32 v4, v72, v72, v4
	v_fma_f32 v4, v73, v73, v4
	v_fma_f32 v4, v74, v74, v4
	v_fma_f32 v4, v75, v75, v4
	v_fma_f32 v4, v76, v76, v4
	v_fma_f32 v4, v77, v77, v4
	v_fma_f32 v4, v78, v78, v4
	v_fma_f32 v4, v79, v79, v4
	s_nop 1
	v_add_f32_dpp v5, v4, v4 quad_perm:[1,0,3,2] row_mask:0xf bank_mask:0xf
	s_nop 1
	v_add_f32_dpp v4, v5, v5 quad_perm:[2,3,0,1] row_mask:0xf bank_mask:0xf
	s_nop 1
	v_add_f32_dpp v5, v4, v4 row_half_mirror row_mask:0xf bank_mask:0xf
	s_nop 1
	v_add_f32_dpp v4, v5, v5 row_mirror row_mask:0xf bank_mask:0xf
	s_nop 1
	v_readlane_b32 s98, v4, 0
	v_readlane_b32 s99, v4, 16
	s_nop 3
	v_mov_b32_e32 v5, s98
	v_add_f32_e32 v5, s99, v5
	v_readlane_b32 s98, v4, 32
	v_readlane_b32 s99, v4, 48
	s_nop 3
	v_add_f32_e32 v5, s98, v5
	v_add_f32_e32 v5, s99, v5
	v_mul_f32_e32 v5, 0x3a800000, v5
	v_add_f32_e32 v5, 0x358637bd, v5
	v_rsq_f32_e32 v6, v5
	s_nop 0
	s_add_u32 s98, s97, 768
	v_pk_mul_f32 v[64:65], v[64:65], v[6:7] op_sel_hi:[1,0]
	v_pk_mul_f32 v[66:67], v[66:67], v[6:7] op_sel_hi:[1,0]
	v_pk_mul_f32 v[68:69], v[68:69], v[6:7] op_sel_hi:[1,0]
	v_pk_mul_f32 v[70:71], v[70:71], v[6:7] op_sel_hi:[1,0]
	v_pk_mul_f32 v[72:73], v[72:73], v[6:7] op_sel_hi:[1,0]
	v_pk_mul_f32 v[74:75], v[74:75], v[6:7] op_sel_hi:[1,0]
	v_pk_mul_f32 v[76:77], v[76:77], v[6:7] op_sel_hi:[1,0]
	v_pk_mul_f32 v[78:79], v[78:79], v[6:7] op_sel_hi:[1,0]
	v_pk_mul_f32 v[64:65], v[64:65], v[112:113]
	v_pk_mul_f32 v[66:67], v[66:67], v[114:115]
	v_pk_mul_f32 v[68:69], v[68:69], v[116:117]
	v_pk_mul_f32 v[70:71], v[70:71], v[118:119]
	v_pk_mul_f32 v[72:73], v[72:73], v[120:121]
	v_pk_mul_f32 v[74:75], v[74:75], v[122:123]
	v_pk_mul_f32 v[76:77], v[76:77], v[124:125]
	v_pk_mul_f32 v[78:79], v[78:79], v[126:127]
	v_pk_fma_f32 v[64:65], v[64:65], v[128:129], v[144:145]
	v_pk_fma_f32 v[66:67], v[66:67], v[130:131], v[146:147]
	v_pk_fma_f32 v[68:69], v[68:69], v[132:133], v[148:149]
	v_pk_fma_f32 v[70:71], v[70:71], v[134:135], v[150:151]
	v_pk_fma_f32 v[72:73], v[72:73], v[136:137], v[152:153]
	v_pk_fma_f32 v[74:75], v[74:75], v[138:139], v[154:155]
	v_pk_fma_f32 v[76:77], v[76:77], v[140:141], v[156:157]
	v_pk_fma_f32 v[78:79], v[78:79], v[142:143], v[158:159]
	v_cvt_pk_bf16_f32 v64, v64, v65
	v_cvt_pk_bf16_f32 v65, v66, v67
	v_cvt_pk_bf16_f32 v66, v68, v69
	v_cvt_pk_bf16_f32 v67, v70, v71
	v_cvt_pk_bf16_f32 v68, v72, v73
	v_cvt_pk_bf16_f32 v69, v74, v75
	v_cvt_pk_bf16_f32 v70, v76, v77
	v_cvt_pk_bf16_f32 v71, v78, v79
	s_lshl_b32 s99, s98, 11
	v_lshl_add_u32 v8, v0, 3, s99
	global_store_dwordx2 v8, v[64:65], s[94:95]
	global_store_dwordx2 v8, v[66:67], s[94:95] offset:512
	global_store_dwordx2 v8, v[68:69], s[94:95] offset:1024
	global_store_dwordx2 v8, v[70:71], s[94:95] offset:1536
	s_lshl_b32 s99, s98, 2
	v_mov_b32_e32 v9, s99
	v_mov_b32_e32 v10, 0
	v_cmp_eq_u32_e32 vcc, 0, v0
	s_and_saveexec_b64 s[98:99], vcc
	global_store_dword v9, v10, s[90:91]
	global_store_dword v9, v10, s[92:93]
	s_or_b64 exec, exec, s[98:99]
	s_add_u32 s98, s97, 2304
	s_lshl_b32 s98, s98, 12
	v_add_u32_e32 v3, s98, v1
	global_load_dwordx4 v[64:67], v3, s[88:89] nt
	global_load_dwordx4 v[68:71], v3, s[88:89] offset:1024 nt
	global_load_dwordx4 v[72:75], v3, s[88:89] offset:2048 nt
	global_load_dwordx4 v[76:79], v3, s[88:89] offset:3072 nt
	s_waitcnt vmcnt(44)
	v_mul_f32_e32 v4, v80, v80
	v_fma_f32 v4, v81, v81, v4
	v_fma_f32 v4, v82, v82, v4
	v_fma_f32 v4, v83, v83, v4
	v_fma_f32 v4, v84, v84, v4
	v_fma_f32 v4, v85, v85, v4
	v_fma_f32 v4, v86, v86, v4
	v_fma_f32 v4, v87, v87, v4
	v_fma_f32 v4, v88, v88, v4
	v_fma_f32 v4, v89, v89, v4
	v_fma_f32 v4, v90, v90, v4
	v_fma_f32 v4, v91, v91, v4
	v_fma_f32 v4, v92, v92, v4
	v_fma_f32 v4, v93, v93, v4
	v_fma_f32 v4, v94, v94, v4
	v_fma_f32 v4, v95, v95, v4
	s_nop 1
	v_add_f32_dpp v5, v4, v4 quad_perm:[1,0,3,2] row_mask:0xf bank_mask:0xf
	s_nop 1
	v_add_f32_dpp v4, v5, v5 quad_perm:[2,3,0,1] row_mask:0xf bank_mask:0xf
	s_nop 1
	v_add_f32_dpp v5, v4, v4 row_half_mirror row_mask:0xf bank_mask:0xf
	s_nop 1
	v_add_f32_dpp v4, v5, v5 row_mirror row_mask:0xf bank_mask:0xf
	s_nop 1
	v_readlane_b32 s98, v4, 0
	v_readlane_b32 s99, v4, 16
	s_nop 3
	v_mov_b32_e32 v5, s98
	v_add_f32_e32 v5, s99, v5
	v_readlane_b32 s98, v4, 32
	v_readlane_b32 s99, v4, 48
	s_nop 3
	v_add_f32_e32 v5, s98, v5
	v_add_f32_e32 v5, s99, v5
	v_mul_f32_e32 v5, 0x3a800000, v5
	v_add_f32_e32 v5, 0x358637bd, v5
	v_rsq_f32_e32 v6, v5
	s_nop 0
	s_add_u32 s98, s97, 1024
	v_pk_mul_f32 v[80:81], v[80:81], v[6:7] op_sel_hi:[1,0]
	v_pk_mul_f32 v[82:83], v[82:83], v[6:7] op_sel_hi:[1,0]
	v_pk_mul_f32 v[84:85], v[84:85], v[6:7] op_sel_hi:[1,0]
	v_pk_mul_f32 v[86:87], v[86:87], v[6:7] op_sel_hi:[1,0]
	v_pk_mul_f32 v[88:89], v[88:89], v[6:7] op_sel_hi:[1,0]
	v_pk_mul_f32 v[90:91], v[90:91], v[6:7] op_sel_hi:[1,0]
	v_pk_mul_f32 v[92:93], v[92:93], v[6:7] op_sel_hi:[1,0]
	v_pk_mul_f32 v[94:95], v[94:95], v[6:7] op_sel_hi:[1,0]
	v_pk_mul_f32 v[80:81], v[80:81], v[112:113]
	v_pk_mul_f32 v[82:83], v[82:83], v[114:115]
	v_pk_mul_f32 v[84:85], v[84:85], v[116:117]
	v_pk_mul_f32 v[86:87], v[86:87], v[118:119]
	v_pk_mul_f32 v[88:89], v[88:89], v[120:121]
	v_pk_mul_f32 v[90:91], v[90:91], v[122:123]
	v_pk_mul_f32 v[92:93], v[92:93], v[124:125]
	v_pk_mul_f32 v[94:95], v[94:95], v[126:127]
	v_pk_fma_f32 v[80:81], v[80:81], v[128:129], v[144:145]
	v_pk_fma_f32 v[82:83], v[82:83], v[130:131], v[146:147]
	v_pk_fma_f32 v[84:85], v[84:85], v[132:133], v[148:149]
	v_pk_fma_f32 v[86:87], v[86:87], v[134:135], v[150:151]
	v_pk_fma_f32 v[88:89], v[88:89], v[136:137], v[152:153]
	v_pk_fma_f32 v[90:91], v[90:91], v[138:139], v[154:155]
	v_pk_fma_f32 v[92:93], v[92:93], v[140:141], v[156:157]
	v_pk_fma_f32 v[94:95], v[94:95], v[142:143], v[158:159]
	v_cvt_pk_bf16_f32 v80, v80, v81
	v_cvt_pk_bf16_f32 v81, v82, v83
	v_cvt_pk_bf16_f32 v82, v84, v85
	v_cvt_pk_bf16_f32 v83, v86, v87
	v_cvt_pk_bf16_f32 v84, v88, v89
	v_cvt_pk_bf16_f32 v85, v90, v91
	v_cvt_pk_bf16_f32 v86, v92, v93
	v_cvt_pk_bf16_f32 v87, v94, v95
	s_lshl_b32 s99, s98, 11
	v_lshl_add_u32 v8, v0, 3, s99
	global_store_dwordx2 v8, v[80:81], s[94:95]
	global_store_dwordx2 v8, v[82:83], s[94:95] offset:512
	global_store_dwordx2 v8, v[84:85], s[94:95] offset:1024
	global_store_dwordx2 v8, v[86:87], s[94:95] offset:1536
	s_lshl_b32 s99, s98, 2
	v_mov_b32_e32 v9, s99
	v_mov_b32_e32 v10, 0
	v_cmp_eq_u32_e32 vcc, 0, v0
	s_and_saveexec_b64 s[98:99], vcc
	global_store_dword v9, v10, s[90:91]
	global_store_dword v9, v10, s[92:93]
	s_or_b64 exec, exec, s[98:99]
	s_add_u32 s98, s97, 2560
	s_lshl_b32 s98, s98, 12
	v_add_u32_e32 v3, s98, v1
	global_load_dwordx4 v[80:83], v3, s[88:89] nt
	global_load_dwordx4 v[84:87], v3, s[88:89] offset:1024 nt
	global_load_dwordx4 v[88:91], v3, s[88:89] offset:2048 nt
	global_load_dwordx4 v[92:95], v3, s[88:89] offset:3072 nt
	s_waitcnt vmcnt(50)
	v_mul_f32_e32 v4, v96, v96
	v_fma_f32 v4, v97, v97, v4
	v_fma_f32 v4, v98, v98, v4
	v_fma_f32 v4, v99, v99, v4
	v_fma_f32 v4, v100, v100, v4
	v_fma_f32 v4, v101, v101, v4
	v_fma_f32 v4, v102, v102, v4
	v_fma_f32 v4, v103, v103, v4
	v_fma_f32 v4, v104, v104, v4
	v_fma_f32 v4, v105, v105, v4
	v_fma_f32 v4, v106, v106, v4
	v_fma_f32 v4, v107, v107, v4
	v_fma_f32 v4, v108, v108, v4
	v_fma_f32 v4, v109, v109, v4
	v_fma_f32 v4, v110, v110, v4
	v_fma_f32 v4, v111, v111, v4
	s_nop 1
	v_add_f32_dpp v5, v4, v4 quad_perm:[1,0,3,2] row_mask:0xf bank_mask:0xf
	s_nop 1
	v_add_f32_dpp v4, v5, v5 quad_perm:[2,3,0,1] row_mask:0xf bank_mask:0xf
	s_nop 1
	v_add_f32_dpp v5, v4, v4 row_half_mirror row_mask:0xf bank_mask:0xf
	s_nop 1
	v_add_f32_dpp v4, v5, v5 row_mirror row_mask:0xf bank_mask:0xf
	s_nop 1
	v_readlane_b32 s98, v4, 0
	v_readlane_b32 s99, v4, 16
	s_nop 3
	v_mov_b32_e32 v5, s98
	v_add_f32_e32 v5, s99, v5
	v_readlane_b32 s98, v4, 32
	v_readlane_b32 s99, v4, 48
	s_nop 3
	v_add_f32_e32 v5, s98, v5
	v_add_f32_e32 v5, s99, v5
	v_mul_f32_e32 v5, 0x3a800000, v5
	v_add_f32_e32 v5, 0x358637bd, v5
	v_rsq_f32_e32 v6, v5
	s_nop 0
	s_add_u32 s98, s97, 1280
	v_pk_mul_f32 v[96:97], v[96:97], v[6:7] op_sel_hi:[1,0]
	v_pk_mul_f32 v[98:99], v[98:99], v[6:7] op_sel_hi:[1,0]
	v_pk_mul_f32 v[100:101], v[100:101], v[6:7] op_sel_hi:[1,0]
	v_pk_mul_f32 v[102:103], v[102:103], v[6:7] op_sel_hi:[1,0]
	v_pk_mul_f32 v[104:105], v[104:105], v[6:7] op_sel_hi:[1,0]
	v_pk_mul_f32 v[106:107], v[106:107], v[6:7] op_sel_hi:[1,0]
	v_pk_mul_f32 v[108:109], v[108:109], v[6:7] op_sel_hi:[1,0]
	v_pk_mul_f32 v[110:111], v[110:111], v[6:7] op_sel_hi:[1,0]
	v_pk_mul_f32 v[96:97], v[96:97], v[112:113]
	v_pk_mul_f32 v[98:99], v[98:99], v[114:115]
	v_pk_mul_f32 v[100:101], v[100:101], v[116:117]
	v_pk_mul_f32 v[102:103], v[102:103], v[118:119]
	v_pk_mul_f32 v[104:105], v[104:105], v[120:121]
	v_pk_mul_f32 v[106:107], v[106:107], v[122:123]
	v_pk_mul_f32 v[108:109], v[108:109], v[124:125]
	v_pk_mul_f32 v[110:111], v[110:111], v[126:127]
	v_pk_fma_f32 v[96:97], v[96:97], v[128:129], v[144:145]
	v_pk_fma_f32 v[98:99], v[98:99], v[130:131], v[146:147]
	v_pk_fma_f32 v[100:101], v[100:101], v[132:133], v[148:149]
	v_pk_fma_f32 v[102:103], v[102:103], v[134:135], v[150:151]
	v_pk_fma_f32 v[104:105], v[104:105], v[136:137], v[152:153]
	v_pk_fma_f32 v[106:107], v[106:107], v[138:139], v[154:155]
	v_pk_fma_f32 v[108:109], v[108:109], v[140:141], v[156:157]
	v_pk_fma_f32 v[110:111], v[110:111], v[142:143], v[158:159]
	v_cvt_pk_bf16_f32 v96, v96, v97
	v_cvt_pk_bf16_f32 v97, v98, v99
	v_cvt_pk_bf16_f32 v98, v100, v101
	v_cvt_pk_bf16_f32 v99, v102, v103
	v_cvt_pk_bf16_f32 v100, v104, v105
	v_cvt_pk_bf16_f32 v101, v106, v107
	v_cvt_pk_bf16_f32 v102, v108, v109
	v_cvt_pk_bf16_f32 v103, v110, v111
	s_lshl_b32 s99, s98, 11
	v_lshl_add_u32 v8, v0, 3, s99
	global_store_dwordx2 v8, v[96:97], s[94:95]
	global_store_dwordx2 v8, v[98:99], s[94:95] offset:512
	global_store_dwordx2 v8, v[100:101], s[94:95] offset:1024
	global_store_dwordx2 v8, v[102:103], s[94:95] offset:1536
	s_lshl_b32 s99, s98, 2
	v_mov_b32_e32 v9, s99
	v_mov_b32_e32 v10, 0
	v_cmp_eq_u32_e32 vcc, 0, v0
	s_and_saveexec_b64 s[98:99], vcc
	global_store_dword v9, v10, s[90:91]
	global_store_dword v9, v10, s[92:93]
	s_or_b64 exec, exec, s[98:99]
	s_add_u32 s98, s97, 2816
	s_lshl_b32 s98, s98, 12
	v_add_u32_e32 v3, s98, v1
	global_load_dwordx4 v[96:99], v3, s[88:89] nt
	global_load_dwordx4 v[100:103], v3, s[88:89] offset:1024 nt
	global_load_dwordx4 v[104:107], v3, s[88:89] offset:2048 nt
	global_load_dwordx4 v[108:111], v3, s[88:89] offset:3072 nt
	s_waitcnt vmcnt(50)
	v_mul_f32_e32 v4, v16, v16
	v_fma_f32 v4, v17, v17, v4
	v_fma_f32 v4, v18, v18, v4
	v_fma_f32 v4, v19, v19, v4
	v_fma_f32 v4, v20, v20, v4
	v_fma_f32 v4, v21, v21, v4
	v_fma_f32 v4, v22, v22, v4
	v_fma_f32 v4, v23, v23, v4
	v_fma_f32 v4, v24, v24, v4
	v_fma_f32 v4, v25, v25, v4
	v_fma_f32 v4, v26, v26, v4
	v_fma_f32 v4, v27, v27, v4
	v_fma_f32 v4, v28, v28, v4
	v_fma_f32 v4, v29, v29, v4
	v_fma_f32 v4, v30, v30, v4
	v_fma_f32 v4, v31, v31, v4
	s_nop 1
	v_add_f32_dpp v5, v4, v4 quad_perm:[1,0,3,2] row_mask:0xf bank_mask:0xf
	s_nop 1
	v_add_f32_dpp v4, v5, v5 quad_perm:[2,3,0,1] row_mask:0xf bank_mask:0xf
	s_nop 1
	v_add_f32_dpp v5, v4, v4 row_half_mirror row_mask:0xf bank_mask:0xf
	s_nop 1
	v_add_f32_dpp v4, v5, v5 row_mirror row_mask:0xf bank_mask:0xf
	s_nop 1
	v_readlane_b32 s98, v4, 0
	v_readlane_b32 s99, v4, 16
	s_nop 3
	v_mov_b32_e32 v5, s98
	v_add_f32_e32 v5, s99, v5
	v_readlane_b32 s98, v4, 32
	v_readlane_b32 s99, v4, 48
	s_nop 3
	v_add_f32_e32 v5, s98, v5
	v_add_f32_e32 v5, s99, v5
	v_mul_f32_e32 v5, 0x3a800000, v5
	v_add_f32_e32 v5, 0x358637bd, v5
	v_rsq_f32_e32 v6, v5
	s_nop 0
	s_add_u32 s98, s97, 1536
	v_pk_mul_f32 v[16:17], v[16:17], v[6:7] op_sel_hi:[1,0]
	v_pk_mul_f32 v[18:19], v[18:19], v[6:7] op_sel_hi:[1,0]
	v_pk_mul_f32 v[20:21], v[20:21], v[6:7] op_sel_hi:[1,0]
	v_pk_mul_f32 v[22:23], v[22:23], v[6:7] op_sel_hi:[1,0]
	v_pk_mul_f32 v[24:25], v[24:25], v[6:7] op_sel_hi:[1,0]
	v_pk_mul_f32 v[26:27], v[26:27], v[6:7] op_sel_hi:[1,0]
	v_pk_mul_f32 v[28:29], v[28:29], v[6:7] op_sel_hi:[1,0]
	v_pk_mul_f32 v[30:31], v[30:31], v[6:7] op_sel_hi:[1,0]
	v_pk_mul_f32 v[16:17], v[16:17], v[112:113]
	v_pk_mul_f32 v[18:19], v[18:19], v[114:115]
	v_pk_mul_f32 v[20:21], v[20:21], v[116:117]
	v_pk_mul_f32 v[22:23], v[22:23], v[118:119]
	v_pk_mul_f32 v[24:25], v[24:25], v[120:121]
	v_pk_mul_f32 v[26:27], v[26:27], v[122:123]
	v_pk_mul_f32 v[28:29], v[28:29], v[124:125]
	v_pk_mul_f32 v[30:31], v[30:31], v[126:127]
	v_pk_fma_f32 v[16:17], v[16:17], v[128:129], v[144:145]
	v_pk_fma_f32 v[18:19], v[18:19], v[130:131], v[146:147]
	v_pk_fma_f32 v[20:21], v[20:21], v[132:133], v[148:149]
	v_pk_fma_f32 v[22:23], v[22:23], v[134:135], v[150:151]
	v_pk_fma_f32 v[24:25], v[24:25], v[136:137], v[152:153]
	v_pk_fma_f32 v[26:27], v[26:27], v[138:139], v[154:155]
	v_pk_fma_f32 v[28:29], v[28:29], v[140:141], v[156:157]
	v_pk_fma_f32 v[30:31], v[30:31], v[142:143], v[158:159]
	v_cvt_pk_bf16_f32 v16, v16, v17
	v_cvt_pk_bf16_f32 v17, v18, v19
	v_cvt_pk_bf16_f32 v18, v20, v21
	v_cvt_pk_bf16_f32 v19, v22, v23
	v_cvt_pk_bf16_f32 v20, v24, v25
	v_cvt_pk_bf16_f32 v21, v26, v27
	v_cvt_pk_bf16_f32 v22, v28, v29
	v_cvt_pk_bf16_f32 v23, v30, v31
	s_lshl_b32 s99, s98, 11
	v_lshl_add_u32 v8, v0, 3, s99
	global_store_dwordx2 v8, v[16:17], s[94:95]
	global_store_dwordx2 v8, v[18:19], s[94:95] offset:512
	global_store_dwordx2 v8, v[20:21], s[94:95] offset:1024
	global_store_dwordx2 v8, v[22:23], s[94:95] offset:1536
	s_lshl_b32 s99, s98, 2
	v_mov_b32_e32 v9, s99
	v_mov_b32_e32 v10, 0
	v_cmp_eq_u32_e32 vcc, 0, v0
	s_and_saveexec_b64 s[98:99], vcc
	global_store_dword v9, v10, s[90:91]
	global_store_dword v9, v10, s[92:93]
	s_or_b64 exec, exec, s[98:99]
	s_add_u32 s98, s97, 3072
	s_lshl_b32 s98, s98, 12
	v_add_u32_e32 v3, s98, v1
	global_load_dwordx4 v[16:19], v3, s[88:89] nt
	global_load_dwordx4 v[20:23], v3, s[88:89] offset:1024 nt
	global_load_dwordx4 v[24:27], v3, s[88:89] offset:2048 nt
	global_load_dwordx4 v[28:31], v3, s[88:89] offset:3072 nt
	s_waitcnt vmcnt(50)
	v_mul_f32_e32 v4, v32, v32
	v_fma_f32 v4, v33, v33, v4
	v_fma_f32 v4, v34, v34, v4
	v_fma_f32 v4, v35, v35, v4
	v_fma_f32 v4, v36, v36, v4
	v_fma_f32 v4, v37, v37, v4
	v_fma_f32 v4, v38, v38, v4
	v_fma_f32 v4, v39, v39, v4
	v_fma_f32 v4, v40, v40, v4
	v_fma_f32 v4, v41, v41, v4
	v_fma_f32 v4, v42, v42, v4
	v_fma_f32 v4, v43, v43, v4
	v_fma_f32 v4, v44, v44, v4
	v_fma_f32 v4, v45, v45, v4
	v_fma_f32 v4, v46, v46, v4
	v_fma_f32 v4, v47, v47, v4
	s_nop 1
	v_add_f32_dpp v5, v4, v4 quad_perm:[1,0,3,2] row_mask:0xf bank_mask:0xf
	s_nop 1
	v_add_f32_dpp v4, v5, v5 quad_perm:[2,3,0,1] row_mask:0xf bank_mask:0xf
	s_nop 1
	v_add_f32_dpp v5, v4, v4 row_half_mirror row_mask:0xf bank_mask:0xf
	s_nop 1
	v_add_f32_dpp v4, v5, v5 row_mirror row_mask:0xf bank_mask:0xf
	s_nop 1
	v_readlane_b32 s98, v4, 0
	v_readlane_b32 s99, v4, 16
	s_nop 3
	v_mov_b32_e32 v5, s98
	v_add_f32_e32 v5, s99, v5
	v_readlane_b32 s98, v4, 32
	v_readlane_b32 s99, v4, 48
	s_nop 3
	v_add_f32_e32 v5, s98, v5
	v_add_f32_e32 v5, s99, v5
	v_mul_f32_e32 v5, 0x3a800000, v5
	v_add_f32_e32 v5, 0x358637bd, v5
	v_rsq_f32_e32 v6, v5
	s_nop 0
	s_add_u32 s98, s97, 1792
	v_pk_mul_f32 v[32:33], v[32:33], v[6:7] op_sel_hi:[1,0]
	v_pk_mul_f32 v[34:35], v[34:35], v[6:7] op_sel_hi:[1,0]
	v_pk_mul_f32 v[36:37], v[36:37], v[6:7] op_sel_hi:[1,0]
	v_pk_mul_f32 v[38:39], v[38:39], v[6:7] op_sel_hi:[1,0]
	v_pk_mul_f32 v[40:41], v[40:41], v[6:7] op_sel_hi:[1,0]
	v_pk_mul_f32 v[42:43], v[42:43], v[6:7] op_sel_hi:[1,0]
	v_pk_mul_f32 v[44:45], v[44:45], v[6:7] op_sel_hi:[1,0]
	v_pk_mul_f32 v[46:47], v[46:47], v[6:7] op_sel_hi:[1,0]
	v_pk_mul_f32 v[32:33], v[32:33], v[112:113]
	v_pk_mul_f32 v[34:35], v[34:35], v[114:115]
	v_pk_mul_f32 v[36:37], v[36:37], v[116:117]
	v_pk_mul_f32 v[38:39], v[38:39], v[118:119]
	v_pk_mul_f32 v[40:41], v[40:41], v[120:121]
	v_pk_mul_f32 v[42:43], v[42:43], v[122:123]
	v_pk_mul_f32 v[44:45], v[44:45], v[124:125]
	v_pk_mul_f32 v[46:47], v[46:47], v[126:127]
	v_pk_fma_f32 v[32:33], v[32:33], v[128:129], v[144:145]
	v_pk_fma_f32 v[34:35], v[34:35], v[130:131], v[146:147]
	v_pk_fma_f32 v[36:37], v[36:37], v[132:133], v[148:149]
	v_pk_fma_f32 v[38:39], v[38:39], v[134:135], v[150:151]
	v_pk_fma_f32 v[40:41], v[40:41], v[136:137], v[152:153]
	v_pk_fma_f32 v[42:43], v[42:43], v[138:139], v[154:155]
	v_pk_fma_f32 v[44:45], v[44:45], v[140:141], v[156:157]
	v_pk_fma_f32 v[46:47], v[46:47], v[142:143], v[158:159]
	v_cvt_pk_bf16_f32 v32, v32, v33
	v_cvt_pk_bf16_f32 v33, v34, v35
	v_cvt_pk_bf16_f32 v34, v36, v37
	v_cvt_pk_bf16_f32 v35, v38, v39
	v_cvt_pk_bf16_f32 v36, v40, v41
	v_cvt_pk_bf16_f32 v37, v42, v43
	v_cvt_pk_bf16_f32 v38, v44, v45
	v_cvt_pk_bf16_f32 v39, v46, v47
	s_lshl_b32 s99, s98, 11
	v_lshl_add_u32 v8, v0, 3, s99
	global_store_dwordx2 v8, v[32:33], s[94:95]
	global_store_dwordx2 v8, v[34:35], s[94:95] offset:512
	global_store_dwordx2 v8, v[36:37], s[94:95] offset:1024
	global_store_dwordx2 v8, v[38:39], s[94:95] offset:1536
	s_lshl_b32 s99, s98, 2
	v_mov_b32_e32 v9, s99
	v_mov_b32_e32 v10, 0
	v_cmp_eq_u32_e32 vcc, 0, v0
	s_and_saveexec_b64 s[98:99], vcc
	global_store_dword v9, v10, s[90:91]
	global_store_dword v9, v10, s[92:93]
	s_or_b64 exec, exec, s[98:99]
	s_add_u32 s98, s97, 3328
	s_lshl_b32 s98, s98, 12
	v_add_u32_e32 v3, s98, v1
	global_load_dwordx4 v[32:35], v3, s[88:89] nt
	global_load_dwordx4 v[36:39], v3, s[88:89] offset:1024 nt
	global_load_dwordx4 v[40:43], v3, s[88:89] offset:2048 nt
	global_load_dwordx4 v[44:47], v3, s[88:89] offset:3072 nt
	s_waitcnt vmcnt(50)
	v_mul_f32_e32 v4, v48, v48
	v_fma_f32 v4, v49, v49, v4
	v_fma_f32 v4, v50, v50, v4
	v_fma_f32 v4, v51, v51, v4
	v_fma_f32 v4, v52, v52, v4
	v_fma_f32 v4, v53, v53, v4
	v_fma_f32 v4, v54, v54, v4
	v_fma_f32 v4, v55, v55, v4
	v_fma_f32 v4, v56, v56, v4
	v_fma_f32 v4, v57, v57, v4
	v_fma_f32 v4, v58, v58, v4
	v_fma_f32 v4, v59, v59, v4
	v_fma_f32 v4, v60, v60, v4
	v_fma_f32 v4, v61, v61, v4
	v_fma_f32 v4, v62, v62, v4
	v_fma_f32 v4, v63, v63, v4
	s_nop 1
	v_add_f32_dpp v5, v4, v4 quad_perm:[1,0,3,2] row_mask:0xf bank_mask:0xf
	s_nop 1
	v_add_f32_dpp v4, v5, v5 quad_perm:[2,3,0,1] row_mask:0xf bank_mask:0xf
	s_nop 1
	v_add_f32_dpp v5, v4, v4 row_half_mirror row_mask:0xf bank_mask:0xf
	s_nop 1
	v_add_f32_dpp v4, v5, v5 row_mirror row_mask:0xf bank_mask:0xf
	s_nop 1
	v_readlane_b32 s98, v4, 0
	v_readlane_b32 s99, v4, 16
	s_nop 3
	v_mov_b32_e32 v5, s98
	v_add_f32_e32 v5, s99, v5
	v_readlane_b32 s98, v4, 32
	v_readlane_b32 s99, v4, 48
	s_nop 3
	v_add_f32_e32 v5, s98, v5
	v_add_f32_e32 v5, s99, v5
	v_mul_f32_e32 v5, 0x3a800000, v5
	v_add_f32_e32 v5, 0x358637bd, v5
	v_rsq_f32_e32 v6, v5
	s_nop 0
	s_add_u32 s98, s97, 2048
	v_pk_mul_f32 v[48:49], v[48:49], v[6:7] op_sel_hi:[1,0]
	v_pk_mul_f32 v[50:51], v[50:51], v[6:7] op_sel_hi:[1,0]
	v_pk_mul_f32 v[52:53], v[52:53], v[6:7] op_sel_hi:[1,0]
	v_pk_mul_f32 v[54:55], v[54:55], v[6:7] op_sel_hi:[1,0]
	v_pk_mul_f32 v[56:57], v[56:57], v[6:7] op_sel_hi:[1,0]
	v_pk_mul_f32 v[58:59], v[58:59], v[6:7] op_sel_hi:[1,0]
	v_pk_mul_f32 v[60:61], v[60:61], v[6:7] op_sel_hi:[1,0]
	v_pk_mul_f32 v[62:63], v[62:63], v[6:7] op_sel_hi:[1,0]
	v_pk_mul_f32 v[48:49], v[48:49], v[112:113]
	v_pk_mul_f32 v[50:51], v[50:51], v[114:115]
	v_pk_mul_f32 v[52:53], v[52:53], v[116:117]
	v_pk_mul_f32 v[54:55], v[54:55], v[118:119]
	v_pk_mul_f32 v[56:57], v[56:57], v[120:121]
	v_pk_mul_f32 v[58:59], v[58:59], v[122:123]
	v_pk_mul_f32 v[60:61], v[60:61], v[124:125]
	v_pk_mul_f32 v[62:63], v[62:63], v[126:127]
	v_pk_fma_f32 v[48:49], v[48:49], v[128:129], v[144:145]
	v_pk_fma_f32 v[50:51], v[50:51], v[130:131], v[146:147]
	v_pk_fma_f32 v[52:53], v[52:53], v[132:133], v[148:149]
	v_pk_fma_f32 v[54:55], v[54:55], v[134:135], v[150:151]
	v_pk_fma_f32 v[56:57], v[56:57], v[136:137], v[152:153]
	v_pk_fma_f32 v[58:59], v[58:59], v[138:139], v[154:155]
	v_pk_fma_f32 v[60:61], v[60:61], v[140:141], v[156:157]
	v_pk_fma_f32 v[62:63], v[62:63], v[142:143], v[158:159]
	v_cvt_pk_bf16_f32 v48, v48, v49
	v_cvt_pk_bf16_f32 v49, v50, v51
	v_cvt_pk_bf16_f32 v50, v52, v53
	v_cvt_pk_bf16_f32 v51, v54, v55
	v_cvt_pk_bf16_f32 v52, v56, v57
	v_cvt_pk_bf16_f32 v53, v58, v59
	v_cvt_pk_bf16_f32 v54, v60, v61
	v_cvt_pk_bf16_f32 v55, v62, v63
	s_lshl_b32 s99, s98, 11
	v_lshl_add_u32 v8, v0, 3, s99
	global_store_dwordx2 v8, v[48:49], s[94:95]
	global_store_dwordx2 v8, v[50:51], s[94:95] offset:512
	global_store_dwordx2 v8, v[52:53], s[94:95] offset:1024
	global_store_dwordx2 v8, v[54:55], s[94:95] offset:1536
	s_lshl_b32 s99, s98, 2
	v_mov_b32_e32 v9, s99
	v_mov_b32_e32 v10, 0
	v_cmp_eq_u32_e32 vcc, 0, v0
	s_and_saveexec_b64 s[98:99], vcc
	global_store_dword v9, v10, s[90:91]
	global_store_dword v9, v10, s[92:93]
	s_or_b64 exec, exec, s[98:99]
	s_add_u32 s98, s97, 3584
	s_lshl_b32 s98, s98, 12
	v_add_u32_e32 v3, s98, v1
	global_load_dwordx4 v[48:51], v3, s[88:89] nt
	global_load_dwordx4 v[52:55], v3, s[88:89] offset:1024 nt
	global_load_dwordx4 v[56:59], v3, s[88:89] offset:2048 nt
	global_load_dwordx4 v[60:63], v3, s[88:89] offset:3072 nt
	s_waitcnt vmcnt(50)
	v_mul_f32_e32 v4, v64, v64
	v_fma_f32 v4, v65, v65, v4
	v_fma_f32 v4, v66, v66, v4
	v_fma_f32 v4, v67, v67, v4
	v_fma_f32 v4, v68, v68, v4
	v_fma_f32 v4, v69, v69, v4
	v_fma_f32 v4, v70, v70, v4
	v_fma_f32 v4, v71, v71, v4
	v_fma_f32 v4, v72, v72, v4
	v_fma_f32 v4, v73, v73, v4
	v_fma_f32 v4, v74, v74, v4
	v_fma_f32 v4, v75, v75, v4
	v_fma_f32 v4, v76, v76, v4
	v_fma_f32 v4, v77, v77, v4
	v_fma_f32 v4, v78, v78, v4
	v_fma_f32 v4, v79, v79, v4
	s_nop 1
	v_add_f32_dpp v5, v4, v4 quad_perm:[1,0,3,2] row_mask:0xf bank_mask:0xf
	s_nop 1
	v_add_f32_dpp v4, v5, v5 quad_perm:[2,3,0,1] row_mask:0xf bank_mask:0xf
	s_nop 1
	v_add_f32_dpp v5, v4, v4 row_half_mirror row_mask:0xf bank_mask:0xf
	s_nop 1
	v_add_f32_dpp v4, v5, v5 row_mirror row_mask:0xf bank_mask:0xf
	s_nop 1
	v_readlane_b32 s98, v4, 0
	v_readlane_b32 s99, v4, 16
	s_nop 3
	v_mov_b32_e32 v5, s98
	v_add_f32_e32 v5, s99, v5
	v_readlane_b32 s98, v4, 32
	v_readlane_b32 s99, v4, 48
	s_nop 3
	v_add_f32_e32 v5, s98, v5
	v_add_f32_e32 v5, s99, v5
	v_mul_f32_e32 v5, 0x3a800000, v5
	v_add_f32_e32 v5, 0x358637bd, v5
	v_rsq_f32_e32 v6, v5
	s_nop 0
	s_add_u32 s98, s97, 2304
	v_pk_mul_f32 v[64:65], v[64:65], v[6:7] op_sel_hi:[1,0]
	v_pk_mul_f32 v[66:67], v[66:67], v[6:7] op_sel_hi:[1,0]
	v_pk_mul_f32 v[68:69], v[68:69], v[6:7] op_sel_hi:[1,0]
	v_pk_mul_f32 v[70:71], v[70:71], v[6:7] op_sel_hi:[1,0]
	v_pk_mul_f32 v[72:73], v[72:73], v[6:7] op_sel_hi:[1,0]
	v_pk_mul_f32 v[74:75], v[74:75], v[6:7] op_sel_hi:[1,0]
	v_pk_mul_f32 v[76:77], v[76:77], v[6:7] op_sel_hi:[1,0]
	v_pk_mul_f32 v[78:79], v[78:79], v[6:7] op_sel_hi:[1,0]
	v_pk_mul_f32 v[64:65], v[64:65], v[112:113]
	v_pk_mul_f32 v[66:67], v[66:67], v[114:115]
	v_pk_mul_f32 v[68:69], v[68:69], v[116:117]
	v_pk_mul_f32 v[70:71], v[70:71], v[118:119]
	v_pk_mul_f32 v[72:73], v[72:73], v[120:121]
	v_pk_mul_f32 v[74:75], v[74:75], v[122:123]
	v_pk_mul_f32 v[76:77], v[76:77], v[124:125]
	v_pk_mul_f32 v[78:79], v[78:79], v[126:127]
	v_pk_fma_f32 v[64:65], v[64:65], v[128:129], v[144:145]
	v_pk_fma_f32 v[66:67], v[66:67], v[130:131], v[146:147]
	v_pk_fma_f32 v[68:69], v[68:69], v[132:133], v[148:149]
	v_pk_fma_f32 v[70:71], v[70:71], v[134:135], v[150:151]
	v_pk_fma_f32 v[72:73], v[72:73], v[136:137], v[152:153]
	v_pk_fma_f32 v[74:75], v[74:75], v[138:139], v[154:155]
	v_pk_fma_f32 v[76:77], v[76:77], v[140:141], v[156:157]
	v_pk_fma_f32 v[78:79], v[78:79], v[142:143], v[158:159]
	v_cvt_pk_bf16_f32 v64, v64, v65
	v_cvt_pk_bf16_f32 v65, v66, v67
	v_cvt_pk_bf16_f32 v66, v68, v69
	v_cvt_pk_bf16_f32 v67, v70, v71
	v_cvt_pk_bf16_f32 v68, v72, v73
	v_cvt_pk_bf16_f32 v69, v74, v75
	v_cvt_pk_bf16_f32 v70, v76, v77
	v_cvt_pk_bf16_f32 v71, v78, v79
	s_lshl_b32 s99, s98, 11
	v_lshl_add_u32 v8, v0, 3, s99
	global_store_dwordx2 v8, v[64:65], s[94:95]
	global_store_dwordx2 v8, v[66:67], s[94:95] offset:512
	global_store_dwordx2 v8, v[68:69], s[94:95] offset:1024
	global_store_dwordx2 v8, v[70:71], s[94:95] offset:1536
	s_lshl_b32 s99, s98, 2
	v_mov_b32_e32 v9, s99
	v_mov_b32_e32 v10, 0
	v_cmp_eq_u32_e32 vcc, 0, v0
	s_and_saveexec_b64 s[98:99], vcc
	global_store_dword v9, v10, s[90:91]
	global_store_dword v9, v10, s[92:93]
	s_or_b64 exec, exec, s[98:99]
	s_add_u32 s98, s97, 3840
	s_lshl_b32 s98, s98, 12
	v_add_u32_e32 v3, s98, v1
	global_load_dwordx4 v[64:67], v3, s[88:89] nt
	global_load_dwordx4 v[68:71], v3, s[88:89] offset:1024 nt
	global_load_dwordx4 v[72:75], v3, s[88:89] offset:2048 nt
	global_load_dwordx4 v[76:79], v3, s[88:89] offset:3072 nt
	s_waitcnt vmcnt(50)
	v_mul_f32_e32 v4, v80, v80
	v_fma_f32 v4, v81, v81, v4
	v_fma_f32 v4, v82, v82, v4
	v_fma_f32 v4, v83, v83, v4
	v_fma_f32 v4, v84, v84, v4
	v_fma_f32 v4, v85, v85, v4
	v_fma_f32 v4, v86, v86, v4
	v_fma_f32 v4, v87, v87, v4
	v_fma_f32 v4, v88, v88, v4
	v_fma_f32 v4, v89, v89, v4
	v_fma_f32 v4, v90, v90, v4
	v_fma_f32 v4, v91, v91, v4
	v_fma_f32 v4, v92, v92, v4
	v_fma_f32 v4, v93, v93, v4
	v_fma_f32 v4, v94, v94, v4
	v_fma_f32 v4, v95, v95, v4
	s_nop 1
	v_add_f32_dpp v5, v4, v4 quad_perm:[1,0,3,2] row_mask:0xf bank_mask:0xf
	s_nop 1
	v_add_f32_dpp v4, v5, v5 quad_perm:[2,3,0,1] row_mask:0xf bank_mask:0xf
	s_nop 1
	v_add_f32_dpp v5, v4, v4 row_half_mirror row_mask:0xf bank_mask:0xf
	s_nop 1
	v_add_f32_dpp v4, v5, v5 row_mirror row_mask:0xf bank_mask:0xf
	s_nop 1
	v_readlane_b32 s98, v4, 0
	v_readlane_b32 s99, v4, 16
	s_nop 3
	v_mov_b32_e32 v5, s98
	v_add_f32_e32 v5, s99, v5
	v_readlane_b32 s98, v4, 32
	v_readlane_b32 s99, v4, 48
	s_nop 3
	v_add_f32_e32 v5, s98, v5
	v_add_f32_e32 v5, s99, v5
	v_mul_f32_e32 v5, 0x3a800000, v5
	v_add_f32_e32 v5, 0x358637bd, v5
	v_rsq_f32_e32 v6, v5
	s_nop 0
	s_add_u32 s98, s97, 2560
	v_pk_mul_f32 v[80:81], v[80:81], v[6:7] op_sel_hi:[1,0]
	v_pk_mul_f32 v[82:83], v[82:83], v[6:7] op_sel_hi:[1,0]
	v_pk_mul_f32 v[84:85], v[84:85], v[6:7] op_sel_hi:[1,0]
	v_pk_mul_f32 v[86:87], v[86:87], v[6:7] op_sel_hi:[1,0]
	v_pk_mul_f32 v[88:89], v[88:89], v[6:7] op_sel_hi:[1,0]
	v_pk_mul_f32 v[90:91], v[90:91], v[6:7] op_sel_hi:[1,0]
	v_pk_mul_f32 v[92:93], v[92:93], v[6:7] op_sel_hi:[1,0]
	v_pk_mul_f32 v[94:95], v[94:95], v[6:7] op_sel_hi:[1,0]
	v_pk_mul_f32 v[80:81], v[80:81], v[112:113]
	v_pk_mul_f32 v[82:83], v[82:83], v[114:115]
	v_pk_mul_f32 v[84:85], v[84:85], v[116:117]
	v_pk_mul_f32 v[86:87], v[86:87], v[118:119]
	v_pk_mul_f32 v[88:89], v[88:89], v[120:121]
	v_pk_mul_f32 v[90:91], v[90:91], v[122:123]
	v_pk_mul_f32 v[92:93], v[92:93], v[124:125]
	v_pk_mul_f32 v[94:95], v[94:95], v[126:127]
	v_pk_fma_f32 v[80:81], v[80:81], v[128:129], v[144:145]
	v_pk_fma_f32 v[82:83], v[82:83], v[130:131], v[146:147]
	v_pk_fma_f32 v[84:85], v[84:85], v[132:133], v[148:149]
	v_pk_fma_f32 v[86:87], v[86:87], v[134:135], v[150:151]
	v_pk_fma_f32 v[88:89], v[88:89], v[136:137], v[152:153]
	v_pk_fma_f32 v[90:91], v[90:91], v[138:139], v[154:155]
	v_pk_fma_f32 v[92:93], v[92:93], v[140:141], v[156:157]
	v_pk_fma_f32 v[94:95], v[94:95], v[142:143], v[158:159]
	v_cvt_pk_bf16_f32 v80, v80, v81
	v_cvt_pk_bf16_f32 v81, v82, v83
	v_cvt_pk_bf16_f32 v82, v84, v85
	v_cvt_pk_bf16_f32 v83, v86, v87
	v_cvt_pk_bf16_f32 v84, v88, v89
	v_cvt_pk_bf16_f32 v85, v90, v91
	v_cvt_pk_bf16_f32 v86, v92, v93
	v_cvt_pk_bf16_f32 v87, v94, v95
	s_lshl_b32 s99, s98, 11
	v_lshl_add_u32 v8, v0, 3, s99
	global_store_dwordx2 v8, v[80:81], s[94:95]
	global_store_dwordx2 v8, v[82:83], s[94:95] offset:512
	global_store_dwordx2 v8, v[84:85], s[94:95] offset:1024
	global_store_dwordx2 v8, v[86:87], s[94:95] offset:1536
	s_lshl_b32 s99, s98, 2
	v_mov_b32_e32 v9, s99
	v_mov_b32_e32 v10, 0
	v_cmp_eq_u32_e32 vcc, 0, v0
	s_and_saveexec_b64 s[98:99], vcc
	global_store_dword v9, v10, s[90:91]
	global_store_dword v9, v10, s[92:93]
	s_or_b64 exec, exec, s[98:99]
	s_waitcnt vmcnt(46)
	v_mul_f32_e32 v4, v96, v96
	v_fma_f32 v4, v97, v97, v4
	v_fma_f32 v4, v98, v98, v4
	v_fma_f32 v4, v99, v99, v4
	v_fma_f32 v4, v100, v100, v4
	v_fma_f32 v4, v101, v101, v4
	v_fma_f32 v4, v102, v102, v4
	v_fma_f32 v4, v103, v103, v4
	v_fma_f32 v4, v104, v104, v4
	v_fma_f32 v4, v105, v105, v4
	v_fma_f32 v4, v106, v106, v4
	v_fma_f32 v4, v107, v107, v4
	v_fma_f32 v4, v108, v108, v4
	v_fma_f32 v4, v109, v109, v4
	v_fma_f32 v4, v110, v110, v4
	v_fma_f32 v4, v111, v111, v4
	s_nop 1
	v_add_f32_dpp v5, v4, v4 quad_perm:[1,0,3,2] row_mask:0xf bank_mask:0xf
	s_nop 1
	v_add_f32_dpp v4, v5, v5 quad_perm:[2,3,0,1] row_mask:0xf bank_mask:0xf
	s_nop 1
	v_add_f32_dpp v5, v4, v4 row_half_mirror row_mask:0xf bank_mask:0xf
	s_nop 1
	v_add_f32_dpp v4, v5, v5 row_mirror row_mask:0xf bank_mask:0xf
	s_nop 1
	v_readlane_b32 s98, v4, 0
	v_readlane_b32 s99, v4, 16
	s_nop 3
	v_mov_b32_e32 v5, s98
	v_add_f32_e32 v5, s99, v5
	v_readlane_b32 s98, v4, 32
	v_readlane_b32 s99, v4, 48
	s_nop 3
	v_add_f32_e32 v5, s98, v5
	v_add_f32_e32 v5, s99, v5
	v_mul_f32_e32 v5, 0x3a800000, v5
	v_add_f32_e32 v5, 0x358637bd, v5
	v_rsq_f32_e32 v6, v5
	s_nop 0
	s_add_u32 s98, s97, 2816
	v_pk_mul_f32 v[96:97], v[96:97], v[6:7] op_sel_hi:[1,0]
	v_pk_mul_f32 v[98:99], v[98:99], v[6:7] op_sel_hi:[1,0]
	v_pk_mul_f32 v[100:101], v[100:101], v[6:7] op_sel_hi:[1,0]
	v_pk_mul_f32 v[102:103], v[102:103], v[6:7] op_sel_hi:[1,0]
	v_pk_mul_f32 v[104:105], v[104:105], v[6:7] op_sel_hi:[1,0]
	v_pk_mul_f32 v[106:107], v[106:107], v[6:7] op_sel_hi:[1,0]
	v_pk_mul_f32 v[108:109], v[108:109], v[6:7] op_sel_hi:[1,0]
	v_pk_mul_f32 v[110:111], v[110:111], v[6:7] op_sel_hi:[1,0]
	v_pk_mul_f32 v[96:97], v[96:97], v[112:113]
	v_pk_mul_f32 v[98:99], v[98:99], v[114:115]
	v_pk_mul_f32 v[100:101], v[100:101], v[116:117]
	v_pk_mul_f32 v[102:103], v[102:103], v[118:119]
	v_pk_mul_f32 v[104:105], v[104:105], v[120:121]
	v_pk_mul_f32 v[106:107], v[106:107], v[122:123]
	v_pk_mul_f32 v[108:109], v[108:109], v[124:125]
	v_pk_mul_f32 v[110:111], v[110:111], v[126:127]
	v_pk_fma_f32 v[96:97], v[96:97], v[128:129], v[144:145]
	v_pk_fma_f32 v[98:99], v[98:99], v[130:131], v[146:147]
	v_pk_fma_f32 v[100:101], v[100:101], v[132:133], v[148:149]
	v_pk_fma_f32 v[102:103], v[102:103], v[134:135], v[150:151]
	v_pk_fma_f32 v[104:105], v[104:105], v[136:137], v[152:153]
	v_pk_fma_f32 v[106:107], v[106:107], v[138:139], v[154:155]
	v_pk_fma_f32 v[108:109], v[108:109], v[140:141], v[156:157]
	v_pk_fma_f32 v[110:111], v[110:111], v[142:143], v[158:159]
	v_cvt_pk_bf16_f32 v96, v96, v97
	v_cvt_pk_bf16_f32 v97, v98, v99
	v_cvt_pk_bf16_f32 v98, v100, v101
	v_cvt_pk_bf16_f32 v99, v102, v103
	v_cvt_pk_bf16_f32 v100, v104, v105
	v_cvt_pk_bf16_f32 v101, v106, v107
	v_cvt_pk_bf16_f32 v102, v108, v109
	v_cvt_pk_bf16_f32 v103, v110, v111
	s_lshl_b32 s99, s98, 11
	v_lshl_add_u32 v8, v0, 3, s99
	global_store_dwordx2 v8, v[96:97], s[94:95]
	global_store_dwordx2 v8, v[98:99], s[94:95] offset:512
	global_store_dwordx2 v8, v[100:101], s[94:95] offset:1024
	global_store_dwordx2 v8, v[102:103], s[94:95] offset:1536
	s_lshl_b32 s99, s98, 2
	v_mov_b32_e32 v9, s99
	v_mov_b32_e32 v10, 0
	v_cmp_eq_u32_e32 vcc, 0, v0
	s_and_saveexec_b64 s[98:99], vcc
	global_store_dword v9, v10, s[90:91]
	global_store_dword v9, v10, s[92:93]
	s_or_b64 exec, exec, s[98:99]
	s_waitcnt vmcnt(42)
	v_mul_f32_e32 v4, v16, v16
	v_fma_f32 v4, v17, v17, v4
	v_fma_f32 v4, v18, v18, v4
	v_fma_f32 v4, v19, v19, v4
	v_fma_f32 v4, v20, v20, v4
	v_fma_f32 v4, v21, v21, v4
	v_fma_f32 v4, v22, v22, v4
	v_fma_f32 v4, v23, v23, v4
	v_fma_f32 v4, v24, v24, v4
	v_fma_f32 v4, v25, v25, v4
	v_fma_f32 v4, v26, v26, v4
	v_fma_f32 v4, v27, v27, v4
	v_fma_f32 v4, v28, v28, v4
	v_fma_f32 v4, v29, v29, v4
	v_fma_f32 v4, v30, v30, v4
	v_fma_f32 v4, v31, v31, v4
	s_nop 1
	v_add_f32_dpp v5, v4, v4 quad_perm:[1,0,3,2] row_mask:0xf bank_mask:0xf
	s_nop 1
	v_add_f32_dpp v4, v5, v5 quad_perm:[2,3,0,1] row_mask:0xf bank_mask:0xf
	s_nop 1
	v_add_f32_dpp v5, v4, v4 row_half_mirror row_mask:0xf bank_mask:0xf
	s_nop 1
	v_add_f32_dpp v4, v5, v5 row_mirror row_mask:0xf bank_mask:0xf
	s_nop 1
	v_readlane_b32 s98, v4, 0
	v_readlane_b32 s99, v4, 16
	s_nop 3
	v_mov_b32_e32 v5, s98
	v_add_f32_e32 v5, s99, v5
	v_readlane_b32 s98, v4, 32
	v_readlane_b32 s99, v4, 48
	s_nop 3
	v_add_f32_e32 v5, s98, v5
	v_add_f32_e32 v5, s99, v5
	v_mul_f32_e32 v5, 0x3a800000, v5
	v_add_f32_e32 v5, 0x358637bd, v5
	v_rsq_f32_e32 v6, v5
	s_nop 0
	s_add_u32 s98, s97, 3072
	v_pk_mul_f32 v[16:17], v[16:17], v[6:7] op_sel_hi:[1,0]
	v_pk_mul_f32 v[18:19], v[18:19], v[6:7] op_sel_hi:[1,0]
	v_pk_mul_f32 v[20:21], v[20:21], v[6:7] op_sel_hi:[1,0]
	v_pk_mul_f32 v[22:23], v[22:23], v[6:7] op_sel_hi:[1,0]
	v_pk_mul_f32 v[24:25], v[24:25], v[6:7] op_sel_hi:[1,0]
	v_pk_mul_f32 v[26:27], v[26:27], v[6:7] op_sel_hi:[1,0]
	v_pk_mul_f32 v[28:29], v[28:29], v[6:7] op_sel_hi:[1,0]
	v_pk_mul_f32 v[30:31], v[30:31], v[6:7] op_sel_hi:[1,0]
	v_pk_mul_f32 v[16:17], v[16:17], v[112:113]
	v_pk_mul_f32 v[18:19], v[18:19], v[114:115]
	v_pk_mul_f32 v[20:21], v[20:21], v[116:117]
	v_pk_mul_f32 v[22:23], v[22:23], v[118:119]
	v_pk_mul_f32 v[24:25], v[24:25], v[120:121]
	v_pk_mul_f32 v[26:27], v[26:27], v[122:123]
	v_pk_mul_f32 v[28:29], v[28:29], v[124:125]
	v_pk_mul_f32 v[30:31], v[30:31], v[126:127]
	v_pk_fma_f32 v[16:17], v[16:17], v[128:129], v[144:145]
	v_pk_fma_f32 v[18:19], v[18:19], v[130:131], v[146:147]
	v_pk_fma_f32 v[20:21], v[20:21], v[132:133], v[148:149]
	v_pk_fma_f32 v[22:23], v[22:23], v[134:135], v[150:151]
	v_pk_fma_f32 v[24:25], v[24:25], v[136:137], v[152:153]
	v_pk_fma_f32 v[26:27], v[26:27], v[138:139], v[154:155]
	v_pk_fma_f32 v[28:29], v[28:29], v[140:141], v[156:157]
	v_pk_fma_f32 v[30:31], v[30:31], v[142:143], v[158:159]
	v_cvt_pk_bf16_f32 v16, v16, v17
	v_cvt_pk_bf16_f32 v17, v18, v19
	v_cvt_pk_bf16_f32 v18, v20, v21
	v_cvt_pk_bf16_f32 v19, v22, v23
	v_cvt_pk_bf16_f32 v20, v24, v25
	v_cvt_pk_bf16_f32 v21, v26, v27
	v_cvt_pk_bf16_f32 v22, v28, v29
	v_cvt_pk_bf16_f32 v23, v30, v31
	s_lshl_b32 s99, s98, 11
	v_lshl_add_u32 v8, v0, 3, s99
	global_store_dwordx2 v8, v[16:17], s[94:95]
	global_store_dwordx2 v8, v[18:19], s[94:95] offset:512
	global_store_dwordx2 v8, v[20:21], s[94:95] offset:1024
	global_store_dwordx2 v8, v[22:23], s[94:95] offset:1536
	s_lshl_b32 s99, s98, 2
	v_mov_b32_e32 v9, s99
	v_mov_b32_e32 v10, 0
	v_cmp_eq_u32_e32 vcc, 0, v0
	s_and_saveexec_b64 s[98:99], vcc
	global_store_dword v9, v10, s[90:91]
	global_store_dword v9, v10, s[92:93]
	s_or_b64 exec, exec, s[98:99]
	s_waitcnt vmcnt(38)
	v_mul_f32_e32 v4, v32, v32
	v_fma_f32 v4, v33, v33, v4
	v_fma_f32 v4, v34, v34, v4
	v_fma_f32 v4, v35, v35, v4
	v_fma_f32 v4, v36, v36, v4
	v_fma_f32 v4, v37, v37, v4
	v_fma_f32 v4, v38, v38, v4
	v_fma_f32 v4, v39, v39, v4
	v_fma_f32 v4, v40, v40, v4
	v_fma_f32 v4, v41, v41, v4
	v_fma_f32 v4, v42, v42, v4
	v_fma_f32 v4, v43, v43, v4
	v_fma_f32 v4, v44, v44, v4
	v_fma_f32 v4, v45, v45, v4
	v_fma_f32 v4, v46, v46, v4
	v_fma_f32 v4, v47, v47, v4
	s_nop 1
	v_add_f32_dpp v5, v4, v4 quad_perm:[1,0,3,2] row_mask:0xf bank_mask:0xf
	s_nop 1
	v_add_f32_dpp v4, v5, v5 quad_perm:[2,3,0,1] row_mask:0xf bank_mask:0xf
	s_nop 1
	v_add_f32_dpp v5, v4, v4 row_half_mirror row_mask:0xf bank_mask:0xf
	s_nop 1
	v_add_f32_dpp v4, v5, v5 row_mirror row_mask:0xf bank_mask:0xf
	s_nop 1
	v_readlane_b32 s98, v4, 0
	v_readlane_b32 s99, v4, 16
	s_nop 3
	v_mov_b32_e32 v5, s98
	v_add_f32_e32 v5, s99, v5
	v_readlane_b32 s98, v4, 32
	v_readlane_b32 s99, v4, 48
	s_nop 3
	v_add_f32_e32 v5, s98, v5
	v_add_f32_e32 v5, s99, v5
	v_mul_f32_e32 v5, 0x3a800000, v5
	v_add_f32_e32 v5, 0x358637bd, v5
	v_rsq_f32_e32 v6, v5
	s_nop 0
	s_add_u32 s98, s97, 3328
	v_pk_mul_f32 v[32:33], v[32:33], v[6:7] op_sel_hi:[1,0]
	v_pk_mul_f32 v[34:35], v[34:35], v[6:7] op_sel_hi:[1,0]
	v_pk_mul_f32 v[36:37], v[36:37], v[6:7] op_sel_hi:[1,0]
	v_pk_mul_f32 v[38:39], v[38:39], v[6:7] op_sel_hi:[1,0]
	v_pk_mul_f32 v[40:41], v[40:41], v[6:7] op_sel_hi:[1,0]
	v_pk_mul_f32 v[42:43], v[42:43], v[6:7] op_sel_hi:[1,0]
	v_pk_mul_f32 v[44:45], v[44:45], v[6:7] op_sel_hi:[1,0]
	v_pk_mul_f32 v[46:47], v[46:47], v[6:7] op_sel_hi:[1,0]
	v_pk_mul_f32 v[32:33], v[32:33], v[112:113]
	v_pk_mul_f32 v[34:35], v[34:35], v[114:115]
	v_pk_mul_f32 v[36:37], v[36:37], v[116:117]
	v_pk_mul_f32 v[38:39], v[38:39], v[118:119]
	v_pk_mul_f32 v[40:41], v[40:41], v[120:121]
	v_pk_mul_f32 v[42:43], v[42:43], v[122:123]
	v_pk_mul_f32 v[44:45], v[44:45], v[124:125]
	v_pk_mul_f32 v[46:47], v[46:47], v[126:127]
	v_pk_fma_f32 v[32:33], v[32:33], v[128:129], v[144:145]
	v_pk_fma_f32 v[34:35], v[34:35], v[130:131], v[146:147]
	v_pk_fma_f32 v[36:37], v[36:37], v[132:133], v[148:149]
	v_pk_fma_f32 v[38:39], v[38:39], v[134:135], v[150:151]
	v_pk_fma_f32 v[40:41], v[40:41], v[136:137], v[152:153]
	v_pk_fma_f32 v[42:43], v[42:43], v[138:139], v[154:155]
	v_pk_fma_f32 v[44:45], v[44:45], v[140:141], v[156:157]
	v_pk_fma_f32 v[46:47], v[46:47], v[142:143], v[158:159]
	v_cvt_pk_bf16_f32 v32, v32, v33
	v_cvt_pk_bf16_f32 v33, v34, v35
	v_cvt_pk_bf16_f32 v34, v36, v37
	v_cvt_pk_bf16_f32 v35, v38, v39
	v_cvt_pk_bf16_f32 v36, v40, v41
	v_cvt_pk_bf16_f32 v37, v42, v43
	v_cvt_pk_bf16_f32 v38, v44, v45
	v_cvt_pk_bf16_f32 v39, v46, v47
	s_lshl_b32 s99, s98, 11
	v_lshl_add_u32 v8, v0, 3, s99
	global_store_dwordx2 v8, v[32:33], s[94:95]
	global_store_dwordx2 v8, v[34:35], s[94:95] offset:512
	global_store_dwordx2 v8, v[36:37], s[94:95] offset:1024
	global_store_dwordx2 v8, v[38:39], s[94:95] offset:1536
	s_lshl_b32 s99, s98, 2
	v_mov_b32_e32 v9, s99
	v_mov_b32_e32 v10, 0
	v_cmp_eq_u32_e32 vcc, 0, v0
	s_and_saveexec_b64 s[98:99], vcc
	global_store_dword v9, v10, s[90:91]
	global_store_dword v9, v10, s[92:93]
	s_or_b64 exec, exec, s[98:99]
	s_waitcnt vmcnt(34)
	v_mul_f32_e32 v4, v48, v48
	v_fma_f32 v4, v49, v49, v4
	v_fma_f32 v4, v50, v50, v4
	v_fma_f32 v4, v51, v51, v4
	v_fma_f32 v4, v52, v52, v4
	v_fma_f32 v4, v53, v53, v4
	v_fma_f32 v4, v54, v54, v4
	v_fma_f32 v4, v55, v55, v4
	v_fma_f32 v4, v56, v56, v4
	v_fma_f32 v4, v57, v57, v4
	v_fma_f32 v4, v58, v58, v4
	v_fma_f32 v4, v59, v59, v4
	v_fma_f32 v4, v60, v60, v4
	v_fma_f32 v4, v61, v61, v4
	v_fma_f32 v4, v62, v62, v4
	v_fma_f32 v4, v63, v63, v4
	s_nop 1
	v_add_f32_dpp v5, v4, v4 quad_perm:[1,0,3,2] row_mask:0xf bank_mask:0xf
	s_nop 1
	v_add_f32_dpp v4, v5, v5 quad_perm:[2,3,0,1] row_mask:0xf bank_mask:0xf
	s_nop 1
	v_add_f32_dpp v5, v4, v4 row_half_mirror row_mask:0xf bank_mask:0xf
	s_nop 1
	v_add_f32_dpp v4, v5, v5 row_mirror row_mask:0xf bank_mask:0xf
	s_nop 1
	v_readlane_b32 s98, v4, 0
	v_readlane_b32 s99, v4, 16
	s_nop 3
	v_mov_b32_e32 v5, s98
	v_add_f32_e32 v5, s99, v5
	v_readlane_b32 s98, v4, 32
	v_readlane_b32 s99, v4, 48
	s_nop 3
	v_add_f32_e32 v5, s98, v5
	v_add_f32_e32 v5, s99, v5
	v_mul_f32_e32 v5, 0x3a800000, v5
	v_add_f32_e32 v5, 0x358637bd, v5
	v_rsq_f32_e32 v6, v5
	s_nop 0
	s_add_u32 s98, s97, 3584
	v_pk_mul_f32 v[48:49], v[48:49], v[6:7] op_sel_hi:[1,0]
	v_pk_mul_f32 v[50:51], v[50:51], v[6:7] op_sel_hi:[1,0]
	v_pk_mul_f32 v[52:53], v[52:53], v[6:7] op_sel_hi:[1,0]
	v_pk_mul_f32 v[54:55], v[54:55], v[6:7] op_sel_hi:[1,0]
	v_pk_mul_f32 v[56:57], v[56:57], v[6:7] op_sel_hi:[1,0]
	v_pk_mul_f32 v[58:59], v[58:59], v[6:7] op_sel_hi:[1,0]
	v_pk_mul_f32 v[60:61], v[60:61], v[6:7] op_sel_hi:[1,0]
	v_pk_mul_f32 v[62:63], v[62:63], v[6:7] op_sel_hi:[1,0]
	v_pk_mul_f32 v[48:49], v[48:49], v[112:113]
	v_pk_mul_f32 v[50:51], v[50:51], v[114:115]
	v_pk_mul_f32 v[52:53], v[52:53], v[116:117]
	v_pk_mul_f32 v[54:55], v[54:55], v[118:119]
	v_pk_mul_f32 v[56:57], v[56:57], v[120:121]
	v_pk_mul_f32 v[58:59], v[58:59], v[122:123]
	v_pk_mul_f32 v[60:61], v[60:61], v[124:125]
	v_pk_mul_f32 v[62:63], v[62:63], v[126:127]
	v_pk_fma_f32 v[48:49], v[48:49], v[128:129], v[144:145]
	v_pk_fma_f32 v[50:51], v[50:51], v[130:131], v[146:147]
	v_pk_fma_f32 v[52:53], v[52:53], v[132:133], v[148:149]
	v_pk_fma_f32 v[54:55], v[54:55], v[134:135], v[150:151]
	v_pk_fma_f32 v[56:57], v[56:57], v[136:137], v[152:153]
	v_pk_fma_f32 v[58:59], v[58:59], v[138:139], v[154:155]
	v_pk_fma_f32 v[60:61], v[60:61], v[140:141], v[156:157]
	v_pk_fma_f32 v[62:63], v[62:63], v[142:143], v[158:159]
	v_cvt_pk_bf16_f32 v48, v48, v49
	v_cvt_pk_bf16_f32 v49, v50, v51
	v_cvt_pk_bf16_f32 v50, v52, v53
	v_cvt_pk_bf16_f32 v51, v54, v55
	v_cvt_pk_bf16_f32 v52, v56, v57
	v_cvt_pk_bf16_f32 v53, v58, v59
	v_cvt_pk_bf16_f32 v54, v60, v61
	v_cvt_pk_bf16_f32 v55, v62, v63
	s_lshl_b32 s99, s98, 11
	v_lshl_add_u32 v8, v0, 3, s99
	global_store_dwordx2 v8, v[48:49], s[94:95]
	global_store_dwordx2 v8, v[50:51], s[94:95] offset:512
	global_store_dwordx2 v8, v[52:53], s[94:95] offset:1024
	global_store_dwordx2 v8, v[54:55], s[94:95] offset:1536
	s_lshl_b32 s99, s98, 2
	v_mov_b32_e32 v9, s99
	v_mov_b32_e32 v10, 0
	v_cmp_eq_u32_e32 vcc, 0, v0
	s_and_saveexec_b64 s[98:99], vcc
	global_store_dword v9, v10, s[90:91]
	global_store_dword v9, v10, s[92:93]
	s_or_b64 exec, exec, s[98:99]
	s_waitcnt vmcnt(30)
	v_mul_f32_e32 v4, v64, v64
	v_fma_f32 v4, v65, v65, v4
	v_fma_f32 v4, v66, v66, v4
	v_fma_f32 v4, v67, v67, v4
	v_fma_f32 v4, v68, v68, v4
	v_fma_f32 v4, v69, v69, v4
	v_fma_f32 v4, v70, v70, v4
	v_fma_f32 v4, v71, v71, v4
	v_fma_f32 v4, v72, v72, v4
	v_fma_f32 v4, v73, v73, v4
	v_fma_f32 v4, v74, v74, v4
	v_fma_f32 v4, v75, v75, v4
	v_fma_f32 v4, v76, v76, v4
	v_fma_f32 v4, v77, v77, v4
	v_fma_f32 v4, v78, v78, v4
	v_fma_f32 v4, v79, v79, v4
	s_nop 1
	v_add_f32_dpp v5, v4, v4 quad_perm:[1,0,3,2] row_mask:0xf bank_mask:0xf
	s_nop 1
	v_add_f32_dpp v4, v5, v5 quad_perm:[2,3,0,1] row_mask:0xf bank_mask:0xf
	s_nop 1
	v_add_f32_dpp v5, v4, v4 row_half_mirror row_mask:0xf bank_mask:0xf
	s_nop 1
	v_add_f32_dpp v4, v5, v5 row_mirror row_mask:0xf bank_mask:0xf
	s_nop 1
	v_readlane_b32 s98, v4, 0
	v_readlane_b32 s99, v4, 16
	s_nop 3
	v_mov_b32_e32 v5, s98
	v_add_f32_e32 v5, s99, v5
	v_readlane_b32 s98, v4, 32
	v_readlane_b32 s99, v4, 48
	s_nop 3
	v_add_f32_e32 v5, s98, v5
	v_add_f32_e32 v5, s99, v5
	v_mul_f32_e32 v5, 0x3a800000, v5
	v_add_f32_e32 v5, 0x358637bd, v5
	v_rsq_f32_e32 v6, v5
	s_nop 0
	s_add_u32 s98, s97, 3840
	v_pk_mul_f32 v[64:65], v[64:65], v[6:7] op_sel_hi:[1,0]
	v_pk_mul_f32 v[66:67], v[66:67], v[6:7] op_sel_hi:[1,0]
	v_pk_mul_f32 v[68:69], v[68:69], v[6:7] op_sel_hi:[1,0]
	v_pk_mul_f32 v[70:71], v[70:71], v[6:7] op_sel_hi:[1,0]
	v_pk_mul_f32 v[72:73], v[72:73], v[6:7] op_sel_hi:[1,0]
	v_pk_mul_f32 v[74:75], v[74:75], v[6:7] op_sel_hi:[1,0]
	v_pk_mul_f32 v[76:77], v[76:77], v[6:7] op_sel_hi:[1,0]
	v_pk_mul_f32 v[78:79], v[78:79], v[6:7] op_sel_hi:[1,0]
	v_pk_mul_f32 v[64:65], v[64:65], v[112:113]
	v_pk_mul_f32 v[66:67], v[66:67], v[114:115]
	v_pk_mul_f32 v[68:69], v[68:69], v[116:117]
	v_pk_mul_f32 v[70:71], v[70:71], v[118:119]
	v_pk_mul_f32 v[72:73], v[72:73], v[120:121]
	v_pk_mul_f32 v[74:75], v[74:75], v[122:123]
	v_pk_mul_f32 v[76:77], v[76:77], v[124:125]
	v_pk_mul_f32 v[78:79], v[78:79], v[126:127]
	v_pk_fma_f32 v[64:65], v[64:65], v[128:129], v[144:145]
	v_pk_fma_f32 v[66:67], v[66:67], v[130:131], v[146:147]
	v_pk_fma_f32 v[68:69], v[68:69], v[132:133], v[148:149]
	v_pk_fma_f32 v[70:71], v[70:71], v[134:135], v[150:151]
	v_pk_fma_f32 v[72:73], v[72:73], v[136:137], v[152:153]
	v_pk_fma_f32 v[74:75], v[74:75], v[138:139], v[154:155]
	v_pk_fma_f32 v[76:77], v[76:77], v[140:141], v[156:157]
	v_pk_fma_f32 v[78:79], v[78:79], v[142:143], v[158:159]
	v_cvt_pk_bf16_f32 v64, v64, v65
	v_cvt_pk_bf16_f32 v65, v66, v67
	v_cvt_pk_bf16_f32 v66, v68, v69
	v_cvt_pk_bf16_f32 v67, v70, v71
	v_cvt_pk_bf16_f32 v68, v72, v73
	v_cvt_pk_bf16_f32 v69, v74, v75
	v_cvt_pk_bf16_f32 v70, v76, v77
	v_cvt_pk_bf16_f32 v71, v78, v79
	s_lshl_b32 s99, s98, 11
	v_lshl_add_u32 v8, v0, 3, s99
	global_store_dwordx2 v8, v[64:65], s[94:95]
	global_store_dwordx2 v8, v[66:67], s[94:95] offset:512
	global_store_dwordx2 v8, v[68:69], s[94:95] offset:1024
	global_store_dwordx2 v8, v[70:71], s[94:95] offset:1536
	s_lshl_b32 s99, s98, 2
	v_mov_b32_e32 v9, s99
	v_mov_b32_e32 v10, 0
	v_cmp_eq_u32_e32 vcc, 0, v0
	s_and_saveexec_b64 s[98:99], vcc
	global_store_dword v9, v10, s[90:91]
	global_store_dword v9, v10, s[92:93]
	s_or_b64 exec, exec, s[98:99]
	s_waitcnt vmcnt(0)

.LBB0_1397:
	s_cmp_gt_i32 s44, 6
	s_waitcnt lgkmcnt(0)
	s_cselect_b64 s[2:3], -1, 0
	s_cmp_lt_i32 s45, 7
	s_cselect_b64 s[4:5], -1, 0
	s_or_b64 s[2:3], s[2:3], s[4:5]
	s_and_b64 vcc, exec, s[2:3]
	s_cbranch_vccnz .LBB0_1457
	s_lshl_b32 s96, s22, 3
	s_lshr_b32 s97, s70, 6
	s_add_u32 s96, s96, s97
	s_lshr_b32 s97, s96, 8
	s_lshl_b32 s97, s97, 12
	s_and_b32 s99, s96, 0xff
	s_or_b32 s97, s97, s99
	s_cmpk_ge_u32 s97, 0x8000
	s_cbranch_scc1 .Lnp6_done
	s_load_dwordx2 s[88:89], s[0:1], 0xb8
	s_load_dwordx2 s[90:91], s[0:1], 0x18
	s_load_dwordx2 s[92:93], s[0:1], 0x140
	s_load_dwordx2 s[94:95], s[0:1], 0x158
	v_mbcnt_hi_u32_b32 v0, -1, v210
	v_lshlrev_b32_e32 v1, 4, v0
	s_waitcnt lgkmcnt(0)
	s_add_u32 s90, s90, 4096
	s_addc_u32 s91, s91, 0
	global_load_dwordx4 v[112:115], v1, s[90:91] nt
	global_load_dwordx4 v[116:119], v1, s[90:91] offset:1024 nt
	global_load_dwordx4 v[120:123], v1, s[90:91] offset:2048 nt
	global_load_dwordx4 v[124:127], v1, s[90:91] offset:3072 nt
	s_lshr_b32 s98, s97, 12
	s_add_u32 s98, s98, 8
	s_mul_i32 s98, s98, 0x3000
	s_add_u32 s92, s92, s98
	s_addc_u32 s93, s93, 0
	global_load_dwordx4 v[144:147], v1, s[92:93] nt
	global_load_dwordx4 v[148:151], v1, s[92:93] offset:1024 nt
	global_load_dwordx4 v[152:155], v1, s[92:93] offset:2048 nt
	global_load_dwordx4 v[156:159], v1, s[92:93] offset:3072 nt
	s_add_u32 s92, s92, 0x1000
	s_addc_u32 s93, s93, 0
	global_load_dwordx4 v[128:131], v1, s[92:93] nt
	global_load_dwordx4 v[132:135], v1, s[92:93] offset:1024 nt
	global_load_dwordx4 v[136:139], v1, s[92:93] offset:2048 nt
	global_load_dwordx4 v[140:143], v1, s[92:93] offset:3072 nt
	s_load_dwordx2 s[90:91], s[0:1], 0x210
	s_load_dwordx2 s[92:93], s[0:1], 0x218
	s_waitcnt vmcnt(0) lgkmcnt(0)
	v_pk_add_f32 v[128:129], v[128:129], 1.0 op_sel_hi:[1,0]
	v_pk_add_f32 v[130:131], v[130:131], 1.0 op_sel_hi:[1,0]
	v_pk_add_f32 v[132:133], v[132:133], 1.0 op_sel_hi:[1,0]
	v_pk_add_f32 v[134:135], v[134:135], 1.0 op_sel_hi:[1,0]
	v_pk_add_f32 v[136:137], v[136:137], 1.0 op_sel_hi:[1,0]
	v_pk_add_f32 v[138:139], v[138:139], 1.0 op_sel_hi:[1,0]
	v_pk_add_f32 v[140:141], v[140:141], 1.0 op_sel_hi:[1,0]
	v_pk_add_f32 v[142:143], v[142:143], 1.0 op_sel_hi:[1,0]
	s_add_u32 s98, s97, 0
	s_lshl_b32 s98, s98, 12
	v_add_u32_e32 v3, s98, v1
	global_load_dwordx4 v[16:19], v3, s[88:89] nt
	global_load_dwordx4 v[20:23], v3, s[88:89] offset:1024 nt
	global_load_dwordx4 v[24:27], v3, s[88:89] offset:2048 nt
	global_load_dwordx4 v[28:31], v3, s[88:89] offset:3072 nt
	s_add_u32 s98, s97, 256
	s_lshl_b32 s98, s98, 12
	v_add_u32_e32 v3, s98, v1
	global_load_dwordx4 v[32:35], v3, s[88:89] nt
	global_load_dwordx4 v[36:39], v3, s[88:89] offset:1024 nt
	global_load_dwordx4 v[40:43], v3, s[88:89] offset:2048 nt
	global_load_dwordx4 v[44:47], v3, s[88:89] offset:3072 nt
	s_add_u32 s98, s97, 512
	s_lshl_b32 s98, s98, 12
	v_add_u32_e32 v3, s98, v1
	global_load_dwordx4 v[48:51], v3, s[88:89] nt
	global_load_dwordx4 v[52:55], v3, s[88:89] offset:1024 nt
	global_load_dwordx4 v[56:59], v3, s[88:89] offset:2048 nt
	global_load_dwordx4 v[60:63], v3, s[88:89] offset:3072 nt
	s_add_u32 s98, s97, 768
	s_lshl_b32 s98, s98, 12
	v_add_u32_e32 v3, s98, v1
	global_load_dwordx4 v[64:67], v3, s[88:89] nt
	global_load_dwordx4 v[68:71], v3, s[88:89] offset:1024 nt
	global_load_dwordx4 v[72:75], v3, s[88:89] offset:2048 nt
	global_load_dwordx4 v[76:79], v3, s[88:89] offset:3072 nt
	s_add_u32 s98, s97, 1024
	s_lshl_b32 s98, s98, 12
	v_add_u32_e32 v3, s98, v1
	global_load_dwordx4 v[80:83], v3, s[88:89] nt
	global_load_dwordx4 v[84:87], v3, s[88:89] offset:1024 nt
	global_load_dwordx4 v[88:91], v3, s[88:89] offset:2048 nt
	global_load_dwordx4 v[92:95], v3, s[88:89] offset:3072 nt
	s_add_u32 s98, s97, 1280
	s_lshl_b32 s98, s98, 12
	v_add_u32_e32 v3, s98, v1
	global_load_dwordx4 v[96:99], v3, s[88:89] nt
	global_load_dwordx4 v[100:103], v3, s[88:89] offset:1024 nt
	global_load_dwordx4 v[104:107], v3, s[88:89] offset:2048 nt
	global_load_dwordx4 v[108:111], v3, s[88:89] offset:3072 nt
	s_waitcnt vmcnt(20)
	v_mul_f32_e32 v4, v16, v16
	v_fma_f32 v4, v17, v17, v4
	v_fma_f32 v4, v18, v18, v4
	v_fma_f32 v4, v19, v19, v4
	v_fma_f32 v4, v20, v20, v4
	v_fma_f32 v4, v21, v21, v4
	v_fma_f32 v4, v22, v22, v4
	v_fma_f32 v4, v23, v23, v4
	v_fma_f32 v4, v24, v24, v4
	v_fma_f32 v4, v25, v25, v4
	v_fma_f32 v4, v26, v26, v4
	v_fma_f32 v4, v27, v27, v4
	v_fma_f32 v4, v28, v28, v4
	v_fma_f32 v4, v29, v29, v4
	v_fma_f32 v4, v30, v30, v4
	v_fma_f32 v4, v31, v31, v4
	s_nop 1
	v_add_f32_dpp v5, v4, v4 quad_perm:[1,0,3,2] row_mask:0xf bank_mask:0xf
	s_nop 1
	v_add_f32_dpp v4, v5, v5 quad_perm:[2,3,0,1] row_mask:0xf bank_mask:0xf
	s_nop 1
	v_add_f32_dpp v5, v4, v4 row_half_mirror row_mask:0xf bank_mask:0xf
	s_nop 1
	v_add_f32_dpp v4, v5, v5 row_mirror row_mask:0xf bank_mask:0xf
	s_nop 1
	v_readlane_b32 s98, v4, 0
	v_readlane_b32 s99, v4, 16
	s_nop 3
	v_mov_b32_e32 v5, s98
	v_add_f32_e32 v5, s99, v5
	v_readlane_b32 s98, v4, 32
	v_readlane_b32 s99, v4, 48
	s_nop 3
	v_add_f32_e32 v5, s98, v5
	v_add_f32_e32 v5, s99, v5
	v_mul_f32_e32 v5, 0x3a800000, v5
	v_add_f32_e32 v5, 0x358637bd, v5
	v_rsq_f32_e32 v6, v5
	s_nop 0
	s_add_u32 s98, s97, 0
	v_pk_mul_f32 v[16:17], v[16:17], v[6:7] op_sel_hi:[1,0]
	v_pk_mul_f32 v[18:19], v[18:19], v[6:7] op_sel_hi:[1,0]
	v_pk_mul_f32 v[20:21], v[20:21], v[6:7] op_sel_hi:[1,0]
	v_pk_mul_f32 v[22:23], v[22:23], v[6:7] op_sel_hi:[1,0]
	v_pk_mul_f32 v[24:25], v[24:25], v[6:7] op_sel_hi:[1,0]
	v_pk_mul_f32 v[26:27], v[26:27], v[6:7] op_sel_hi:[1,0]
	v_pk_mul_f32 v[28:29], v[28:29], v[6:7] op_sel_hi:[1,0]
	v_pk_mul_f32 v[30:31], v[30:31], v[6:7] op_sel_hi:[1,0]
	v_pk_mul_f32 v[16:17], v[16:17], v[112:113]
	v_pk_mul_f32 v[18:19], v[18:19], v[114:115]
	v_pk_mul_f32 v[20:21], v[20:21], v[116:117]
	v_pk_mul_f32 v[22:23], v[22:23], v[118:119]
	v_pk_mul_f32 v[24:25], v[24:25], v[120:121]
	v_pk_mul_f32 v[26:27], v[26:27], v[122:123]
	v_pk_mul_f32 v[28:29], v[28:29], v[124:125]
	v_pk_mul_f32 v[30:31], v[30:31], v[126:127]
	v_pk_fma_f32 v[16:17], v[16:17], v[128:129], v[144:145]
	v_pk_fma_f32 v[18:19], v[18:19], v[130:131], v[146:147]
	v_pk_fma_f32 v[20:21], v[20:21], v[132:133], v[148:149]
	v_pk_fma_f32 v[22:23], v[22:23], v[134:135], v[150:151]
	v_pk_fma_f32 v[24:25], v[24:25], v[136:137], v[152:153]
	v_pk_fma_f32 v[26:27], v[26:27], v[138:139], v[154:155]
	v_pk_fma_f32 v[28:29], v[28:29], v[140:141], v[156:157]
	v_pk_fma_f32 v[30:31], v[30:31], v[142:143], v[158:159]
	v_cvt_pk_bf16_f32 v16, v16, v17
	v_cvt_pk_bf16_f32 v17, v18, v19
	v_cvt_pk_bf16_f32 v18, v20, v21
	v_cvt_pk_bf16_f32 v19, v22, v23
	v_cvt_pk_bf16_f32 v20, v24, v25
	v_cvt_pk_bf16_f32 v21, v26, v27
	v_cvt_pk_bf16_f32 v22, v28, v29
	v_cvt_pk_bf16_f32 v23, v30, v31
	s_lshl_b32 s99, s98, 11
	v_lshl_add_u32 v8, v0, 3, s99
	global_store_dwordx2 v8, v[16:17], s[94:95]
	global_store_dwordx2 v8, v[18:19], s[94:95] offset:512
	global_store_dwordx2 v8, v[20:21], s[94:95] offset:1024
	global_store_dwordx2 v8, v[22:23], s[94:95] offset:1536
	s_lshl_b32 s99, s98, 2
	v_mov_b32_e32 v9, s99
	v_mov_b32_e32 v10, 0
	v_cmp_eq_u32_e32 vcc, 0, v0
	s_and_saveexec_b64 s[98:99], vcc
	global_store_dword v9, v10, s[90:91]
	global_store_dword v9, v10, s[92:93]
	s_or_b64 exec, exec, s[98:99]
	s_add_u32 s98, s97, 1536
	s_lshl_b32 s98, s98, 12
	v_add_u32_e32 v3, s98, v1
	global_load_dwordx4 v[16:19], v3, s[88:89] nt
	global_load_dwordx4 v[20:23], v3, s[88:89] offset:1024 nt
	global_load_dwordx4 v[24:27], v3, s[88:89] offset:2048 nt
	global_load_dwordx4 v[28:31], v3, s[88:89] offset:3072 nt
	s_waitcnt vmcnt(26)
	v_mul_f32_e32 v4, v32, v32
	v_fma_f32 v4, v33, v33, v4
	v_fma_f32 v4, v34, v34, v4
	v_fma_f32 v4, v35, v35, v4
	v_fma_f32 v4, v36, v36, v4
	v_fma_f32 v4, v37, v37, v4
	v_fma_f32 v4, v38, v38, v4
	v_fma_f32 v4, v39, v39, v4
	v_fma_f32 v4, v40, v40, v4
	v_fma_f32 v4, v41, v41, v4
	v_fma_f32 v4, v42, v42, v4
	v_fma_f32 v4, v43, v43, v4
	v_fma_f32 v4, v44, v44, v4
	v_fma_f32 v4, v45, v45, v4
	v_fma_f32 v4, v46, v46, v4
	v_fma_f32 v4, v47, v47, v4
	s_nop 1
	v_add_f32_dpp v5, v4, v4 quad_perm:[1,0,3,2] row_mask:0xf bank_mask:0xf
	s_nop 1
	v_add_f32_dpp v4, v5, v5 quad_perm:[2,3,0,1] row_mask:0xf bank_mask:0xf
	s_nop 1
	v_add_f32_dpp v5, v4, v4 row_half_mirror row_mask:0xf bank_mask:0xf
	s_nop 1
	v_add_f32_dpp v4, v5, v5 row_mirror row_mask:0xf bank_mask:0xf
	s_nop 1
	v_readlane_b32 s98, v4, 0
	v_readlane_b32 s99, v4, 16
	s_nop 3
	v_mov_b32_e32 v5, s98
	v_add_f32_e32 v5, s99, v5
	v_readlane_b32 s98, v4, 32
	v_readlane_b32 s99, v4, 48
	s_nop 3
	v_add_f32_e32 v5, s98, v5
	v_add_f32_e32 v5, s99, v5
	v_mul_f32_e32 v5, 0x3a800000, v5
	v_add_f32_e32 v5, 0x358637bd, v5
	v_rsq_f32_e32 v6, v5
	s_nop 0
	s_add_u32 s98, s97, 256
	v_pk_mul_f32 v[32:33], v[32:33], v[6:7] op_sel_hi:[1,0]
	v_pk_mul_f32 v[34:35], v[34:35], v[6:7] op_sel_hi:[1,0]
	v_pk_mul_f32 v[36:37], v[36:37], v[6:7] op_sel_hi:[1,0]
	v_pk_mul_f32 v[38:39], v[38:39], v[6:7] op_sel_hi:[1,0]
	v_pk_mul_f32 v[40:41], v[40:41], v[6:7] op_sel_hi:[1,0]
	v_pk_mul_f32 v[42:43], v[42:43], v[6:7] op_sel_hi:[1,0]
	v_pk_mul_f32 v[44:45], v[44:45], v[6:7] op_sel_hi:[1,0]
	v_pk_mul_f32 v[46:47], v[46:47], v[6:7] op_sel_hi:[1,0]
	v_pk_mul_f32 v[32:33], v[32:33], v[112:113]
	v_pk_mul_f32 v[34:35], v[34:35], v[114:115]
	v_pk_mul_f32 v[36:37], v[36:37], v[116:117]
	v_pk_mul_f32 v[38:39], v[38:39], v[118:119]
	v_pk_mul_f32 v[40:41], v[40:41], v[120:121]
	v_pk_mul_f32 v[42:43], v[42:43], v[122:123]
	v_pk_mul_f32 v[44:45], v[44:45], v[124:125]
	v_pk_mul_f32 v[46:47], v[46:47], v[126:127]
	v_pk_fma_f32 v[32:33], v[32:33], v[128:129], v[144:145]
	v_pk_fma_f32 v[34:35], v[34:35], v[130:131], v[146:147]
	v_pk_fma_f32 v[36:37], v[36:37], v[132:133], v[148:149]
	v_pk_fma_f32 v[38:39], v[38:39], v[134:135], v[150:151]
	v_pk_fma_f32 v[40:41], v[40:41], v[136:137], v[152:153]
	v_pk_fma_f32 v[42:43], v[42:43], v[138:139], v[154:155]
	v_pk_fma_f32 v[44:45], v[44:45], v[140:141], v[156:157]
	v_pk_fma_f32 v[46:47], v[46:47], v[142:143], v[158:159]
	v_cvt_pk_bf16_f32 v32, v32, v33
	v_cvt_pk_bf16_f32 v33, v34, v35
	v_cvt_pk_bf16_f32 v34, v36, v37
	v_cvt_pk_bf16_f32 v35, v38, v39
	v_cvt_pk_bf16_f32 v36, v40, v41
	v_cvt_pk_bf16_f32 v37, v42, v43
	v_cvt_pk_bf16_f32 v38, v44, v45
	v_cvt_pk_bf16_f32 v39, v46, v47
	s_lshl_b32 s99, s98, 11
	v_lshl_add_u32 v8, v0, 3, s99
	global_store_dwordx2 v8, v[32:33], s[94:95]
	global_store_dwordx2 v8, v[34:35], s[94:95] offset:512
	global_store_dwordx2 v8, v[36:37], s[94:95] offset:1024
	global_store_dwordx2 v8, v[38:39], s[94:95] offset:1536
	s_lshl_b32 s99, s98, 2
	v_mov_b32_e32 v9, s99
	v_mov_b32_e32 v10, 0
	v_cmp_eq_u32_e32 vcc, 0, v0
	s_and_saveexec_b64 s[98:99], vcc
	global_store_dword v9, v10, s[90:91]
	global_store_dword v9, v10, s[92:93]
	s_or_b64 exec, exec, s[98:99]
	s_add_u32 s98, s97, 1792
	s_lshl_b32 s98, s98, 12
	v_add_u32_e32 v3, s98, v1
	global_load_dwordx4 v[32:35], v3, s[88:89] nt
	global_load_dwordx4 v[36:39], v3, s[88:89] offset:1024 nt
	global_load_dwordx4 v[40:43], v3, s[88:89] offset:2048 nt
	global_load_dwordx4 v[44:47], v3, s[88:89] offset:3072 nt
	s_waitcnt vmcnt(32)
	v_mul_f32_e32 v4, v48, v48
	v_fma_f32 v4, v49, v49, v4
	v_fma_f32 v4, v50, v50, v4
	v_fma_f32 v4, v51, v51, v4
	v_fma_f32 v4, v52, v52, v4
	v_fma_f32 v4, v53, v53, v4
	v_fma_f32 v4, v54, v54, v4
	v_fma_f32 v4, v55, v55, v4
	v_fma_f32 v4, v56, v56, v4
	v_fma_f32 v4, v57, v57, v4
	v_fma_f32 v4, v58, v58, v4
	v_fma_f32 v4, v59, v59, v4
	v_fma_f32 v4, v60, v60, v4
	v_fma_f32 v4, v61, v61, v4
	v_fma_f32 v4, v62, v62, v4
	v_fma_f32 v4, v63, v63, v4
	s_nop 1
	v_add_f32_dpp v5, v4, v4 quad_perm:[1,0,3,2] row_mask:0xf bank_mask:0xf
	s_nop 1
	v_add_f32_dpp v4, v5, v5 quad_perm:[2,3,0,1] row_mask:0xf bank_mask:0xf
	s_nop 1
	v_add_f32_dpp v5, v4, v4 row_half_mirror row_mask:0xf bank_mask:0xf
	s_nop 1
	v_add_f32_dpp v4, v5, v5 row_mirror row_mask:0xf bank_mask:0xf
	s_nop 1
	v_readlane_b32 s98, v4, 0
	v_readlane_b32 s99, v4, 16
	s_nop 3
	v_mov_b32_e32 v5, s98
	v_add_f32_e32 v5, s99, v5
	v_readlane_b32 s98, v4, 32
	v_readlane_b32 s99, v4, 48
	s_nop 3
	v_add_f32_e32 v5, s98, v5
	v_add_f32_e32 v5, s99, v5
	v_mul_f32_e32 v5, 0x3a800000, v5
	v_add_f32_e32 v5, 0x358637bd, v5
	v_rsq_f32_e32 v6, v5
	s_nop 0
	s_add_u32 s98, s97, 512
	v_pk_mul_f32 v[48:49], v[48:49], v[6:7] op_sel_hi:[1,0]
	v_pk_mul_f32 v[50:51], v[50:51], v[6:7] op_sel_hi:[1,0]
	v_pk_mul_f32 v[52:53], v[52:53], v[6:7] op_sel_hi:[1,0]
	v_pk_mul_f32 v[54:55], v[54:55], v[6:7] op_sel_hi:[1,0]
	v_pk_mul_f32 v[56:57], v[56:57], v[6:7] op_sel_hi:[1,0]
	v_pk_mul_f32 v[58:59], v[58:59], v[6:7] op_sel_hi:[1,0]
	v_pk_mul_f32 v[60:61], v[60:61], v[6:7] op_sel_hi:[1,0]
	v_pk_mul_f32 v[62:63], v[62:63], v[6:7] op_sel_hi:[1,0]
	v_pk_mul_f32 v[48:49], v[48:49], v[112:113]
	v_pk_mul_f32 v[50:51], v[50:51], v[114:115]
	v_pk_mul_f32 v[52:53], v[52:53], v[116:117]
	v_pk_mul_f32 v[54:55], v[54:55], v[118:119]
	v_pk_mul_f32 v[56:57], v[56:57], v[120:121]
	v_pk_mul_f32 v[58:59], v[58:59], v[122:123]
	v_pk_mul_f32 v[60:61], v[60:61], v[124:125]
	v_pk_mul_f32 v[62:63], v[62:63], v[126:127]
	v_pk_fma_f32 v[48:49], v[48:49], v[128:129], v[144:145]
	v_pk_fma_f32 v[50:51], v[50:51], v[130:131], v[146:147]
	v_pk_fma_f32 v[52:53], v[52:53], v[132:133], v[148:149]
	v_pk_fma_f32 v[54:55], v[54:55], v[134:135], v[150:151]
	v_pk_fma_f32 v[56:57], v[56:57], v[136:137], v[152:153]
	v_pk_fma_f32 v[58:59], v[58:59], v[138:139], v[154:155]
	v_pk_fma_f32 v[60:61], v[60:61], v[140:141], v[156:157]
	v_pk_fma_f32 v[62:63], v[62:63], v[142:143], v[158:159]
	v_cvt_pk_bf16_f32 v48, v48, v49
	v_cvt_pk_bf16_f32 v49, v50, v51
	v_cvt_pk_bf16_f32 v50, v52, v53
	v_cvt_pk_bf16_f32 v51, v54, v55
	v_cvt_pk_bf16_f32 v52, v56, v57
	v_cvt_pk_bf16_f32 v53, v58, v59
	v_cvt_pk_bf16_f32 v54, v60, v61
	v_cvt_pk_bf16_f32 v55, v62, v63
	s_lshl_b32 s99, s98, 11
	v_lshl_add_u32 v8, v0, 3, s99
	global_store_dwordx2 v8, v[48:49], s[94:95]
	global_store_dwordx2 v8, v[50:51], s[94:95] offset:512
	global_store_dwordx2 v8, v[52:53], s[94:95] offset:1024
	global_store_dwordx2 v8, v[54:55], s[94:95] offset:1536
	s_lshl_b32 s99, s98, 2
	v_mov_b32_e32 v9, s99
	v_mov_b32_e32 v10, 0
	v_cmp_eq_u32_e32 vcc, 0, v0
	s_and_saveexec_b64 s[98:99], vcc
	global_store_dword v9, v10, s[90:91]
	global_store_dword v9, v10, s[92:93]
	s_or_b64 exec, exec, s[98:99]
	s_add_u32 s98, s97, 2048
	s_lshl_b32 s98, s98, 12
	v_add_u32_e32 v3, s98, v1
	global_load_dwordx4 v[48:51], v3, s[88:89] nt
	global_load_dwordx4 v[52:55], v3, s[88:89] offset:1024 nt
	global_load_dwordx4 v[56:59], v3, s[88:89] offset:2048 nt
	global_load_dwordx4 v[60:63], v3, s[88:89] offset:3072 nt
	s_waitcnt vmcnt(38)
	v_mul_f32_e32 v4, v64, v64
	v_fma_f32 v4, v65, v65, v4
	v_fma_f32 v4, v66, v66, v4
	v_fma_f32 v4, v67, v67, v4
	v_fma_f32 v4, v68, v68, v4
	v_fma_f32 v4, v69, v69, v4
	v_fma_f32 v4, v70, v70, v4
	v_fma_f32 v4, v71, v71, v4
	v_fma_f32 v4, v72, v72, v4
	v_fma_f32 v4, v73, v73, v4
	v_fma_f32 v4, v74, v74, v4
	v_fma_f32 v4, v75, v75, v4
	v_fma_f32 v4, v76, v76, v4
	v_fma_f32 v4, v77, v77, v4
	v_fma_f32 v4, v78, v78, v4
	v_fma_f32 v4, v79, v79, v4
	s_nop 1
	v_add_f32_dpp v5, v4, v4 quad_perm:[1,0,3,2] row_mask:0xf bank_mask:0xf
	s_nop 1
	v_add_f32_dpp v4, v5, v5 quad_perm:[2,3,0,1] row_mask:0xf bank_mask:0xf
	s_nop 1
	v_add_f32_dpp v5, v4, v4 row_half_mirror row_mask:0xf bank_mask:0xf
	s_nop 1
	v_add_f32_dpp v4, v5, v5 row_mirror row_mask:0xf bank_mask:0xf
	s_nop 1
	v_readlane_b32 s98, v4, 0
	v_readlane_b32 s99, v4, 16
	s_nop 3
	v_mov_b32_e32 v5, s98
	v_add_f32_e32 v5, s99, v5
	v_readlane_b32 s98, v4, 32
	v_readlane_b32 s99, v4, 48
	s_nop 3
	v_add_f32_e32 v5, s98, v5
	v_add_f32_e32 v5, s99, v5
	v_mul_f32_e32 v5, 0x3a800000, v5
	v_add_f32_e32 v5, 0x358637bd, v5
	v_rsq_f32_e32 v6, v5
	s_nop 0
	s_add_u32 s98, s97, 768
	v_pk_mul_f32 v[64:65], v[64:65], v[6:7] op_sel_hi:[1,0]
	v_pk_mul_f32 v[66:67], v[66:67], v[6:7] op_sel_hi:[1,0]
	v_pk_mul_f32 v[68:69], v[68:69], v[6:7] op_sel_hi:[1,0]
	v_pk_mul_f32 v[70:71], v[70:71], v[6:7] op_sel_hi:[1,0]
	v_pk_mul_f32 v[72:73], v[72:73], v[6:7] op_sel_hi:[1,0]
	v_pk_mul_f32 v[74:75], v[74:75], v[6:7] op_sel_hi:[1,0]
	v_pk_mul_f32 v[76:77], v[76:77], v[6:7] op_sel_hi:[1,0]
	v_pk_mul_f32 v[78:79], v[78:79], v[6:7] op_sel_hi:[1,0]
	v_pk_mul_f32 v[64:65], v[64:65], v[112:113]
	v_pk_mul_f32 v[66:67], v[66:67], v[114:115]
	v_pk_mul_f32 v[68:69], v[68:69], v[116:117]
	v_pk_mul_f32 v[70:71], v[70:71], v[118:119]
	v_pk_mul_f32 v[72:73], v[72:73], v[120:121]
	v_pk_mul_f32 v[74:75], v[74:75], v[122:123]
	v_pk_mul_f32 v[76:77], v[76:77], v[124:125]
	v_pk_mul_f32 v[78:79], v[78:79], v[126:127]
	v_pk_fma_f32 v[64:65], v[64:65], v[128:129], v[144:145]
	v_pk_fma_f32 v[66:67], v[66:67], v[130:131], v[146:147]
	v_pk_fma_f32 v[68:69], v[68:69], v[132:133], v[148:149]
	v_pk_fma_f32 v[70:71], v[70:71], v[134:135], v[150:151]
	v_pk_fma_f32 v[72:73], v[72:73], v[136:137], v[152:153]
	v_pk_fma_f32 v[74:75], v[74:75], v[138:139], v[154:155]
	v_pk_fma_f32 v[76:77], v[76:77], v[140:141], v[156:157]
	v_pk_fma_f32 v[78:79], v[78:79], v[142:143], v[158:159]
	v_cvt_pk_bf16_f32 v64, v64, v65
	v_cvt_pk_bf16_f32 v65, v66, v67
	v_cvt_pk_bf16_f32 v66, v68, v69
	v_cvt_pk_bf16_f32 v67, v70, v71
	v_cvt_pk_bf16_f32 v68, v72, v73
	v_cvt_pk_bf16_f32 v69, v74, v75
	v_cvt_pk_bf16_f32 v70, v76, v77
	v_cvt_pk_bf16_f32 v71, v78, v79
	s_lshl_b32 s99, s98, 11
	v_lshl_add_u32 v8, v0, 3, s99
	global_store_dwordx2 v8, v[64:65], s[94:95]
	global_store_dwordx2 v8, v[66:67], s[94:95] offset:512
	global_store_dwordx2 v8, v[68:69], s[94:95] offset:1024
	global_store_dwordx2 v8, v[70:71], s[94:95] offset:1536
	s_lshl_b32 s99, s98, 2
	v_mov_b32_e32 v9, s99
	v_mov_b32_e32 v10, 0
	v_cmp_eq_u32_e32 vcc, 0, v0
	s_and_saveexec_b64 s[98:99], vcc
	global_store_dword v9, v10, s[90:91]
	global_store_dword v9, v10, s[92:93]
	s_or_b64 exec, exec, s[98:99]
	s_add_u32 s98, s97, 2304
	s_lshl_b32 s98, s98, 12
	v_add_u32_e32 v3, s98, v1
	global_load_dwordx4 v[64:67], v3, s[88:89] nt
	global_load_dwordx4 v[68:71], v3, s[88:89] offset:1024 nt
	global_load_dwordx4 v[72:75], v3, s[88:89] offset:2048 nt
	global_load_dwordx4 v[76:79], v3, s[88:89] offset:3072 nt
	s_waitcnt vmcnt(44)
	v_mul_f32_e32 v4, v80, v80
	v_fma_f32 v4, v81, v81, v4
	v_fma_f32 v4, v82, v82, v4
	v_fma_f32 v4, v83, v83, v4
	v_fma_f32 v4, v84, v84, v4
	v_fma_f32 v4, v85, v85, v4
	v_fma_f32 v4, v86, v86, v4
	v_fma_f32 v4, v87, v87, v4
	v_fma_f32 v4, v88, v88, v4
	v_fma_f32 v4, v89, v89, v4
	v_fma_f32 v4, v90, v90, v4
	v_fma_f32 v4, v91, v91, v4
	v_fma_f32 v4, v92, v92, v4
	v_fma_f32 v4, v93, v93, v4
	v_fma_f32 v4, v94, v94, v4
	v_fma_f32 v4, v95, v95, v4
	s_nop 1
	v_add_f32_dpp v5, v4, v4 quad_perm:[1,0,3,2] row_mask:0xf bank_mask:0xf
	s_nop 1
	v_add_f32_dpp v4, v5, v5 quad_perm:[2,3,0,1] row_mask:0xf bank_mask:0xf
	s_nop 1
	v_add_f32_dpp v5, v4, v4 row_half_mirror row_mask:0xf bank_mask:0xf
	s_nop 1
	v_add_f32_dpp v4, v5, v5 row_mirror row_mask:0xf bank_mask:0xf
	s_nop 1
	v_readlane_b32 s98, v4, 0
	v_readlane_b32 s99, v4, 16
	s_nop 3
	v_mov_b32_e32 v5, s98
	v_add_f32_e32 v5, s99, v5
	v_readlane_b32 s98, v4, 32
	v_readlane_b32 s99, v4, 48
	s_nop 3
	v_add_f32_e32 v5, s98, v5
	v_add_f32_e32 v5, s99, v5
	v_mul_f32_e32 v5, 0x3a800000, v5
	v_add_f32_e32 v5, 0x358637bd, v5
	v_rsq_f32_e32 v6, v5
	s_nop 0
	s_add_u32 s98, s97, 1024
	v_pk_mul_f32 v[80:81], v[80:81], v[6:7] op_sel_hi:[1,0]
	v_pk_mul_f32 v[82:83], v[82:83], v[6:7] op_sel_hi:[1,0]
	v_pk_mul_f32 v[84:85], v[84:85], v[6:7] op_sel_hi:[1,0]
	v_pk_mul_f32 v[86:87], v[86:87], v[6:7] op_sel_hi:[1,0]
	v_pk_mul_f32 v[88:89], v[88:89], v[6:7] op_sel_hi:[1,0]
	v_pk_mul_f32 v[90:91], v[90:91], v[6:7] op_sel_hi:[1,0]
	v_pk_mul_f32 v[92:93], v[92:93], v[6:7] op_sel_hi:[1,0]
	v_pk_mul_f32 v[94:95], v[94:95], v[6:7] op_sel_hi:[1,0]
	v_pk_mul_f32 v[80:81], v[80:81], v[112:113]
	v_pk_mul_f32 v[82:83], v[82:83], v[114:115]
	v_pk_mul_f32 v[84:85], v[84:85], v[116:117]
	v_pk_mul_f32 v[86:87], v[86:87], v[118:119]
	v_pk_mul_f32 v[88:89], v[88:89], v[120:121]
	v_pk_mul_f32 v[90:91], v[90:91], v[122:123]
	v_pk_mul_f32 v[92:93], v[92:93], v[124:125]
	v_pk_mul_f32 v[94:95], v[94:95], v[126:127]
	v_pk_fma_f32 v[80:81], v[80:81], v[128:129], v[144:145]
	v_pk_fma_f32 v[82:83], v[82:83], v[130:131], v[146:147]
	v_pk_fma_f32 v[84:85], v[84:85], v[132:133], v[148:149]
	v_pk_fma_f32 v[86:87], v[86:87], v[134:135], v[150:151]
	v_pk_fma_f32 v[88:89], v[88:89], v[136:137], v[152:153]
	v_pk_fma_f32 v[90:91], v[90:91], v[138:139], v[154:155]
	v_pk_fma_f32 v[92:93], v[92:93], v[140:141], v[156:157]
	v_pk_fma_f32 v[94:95], v[94:95], v[142:143], v[158:159]
	v_cvt_pk_bf16_f32 v80, v80, v81
	v_cvt_pk_bf16_f32 v81, v82, v83
	v_cvt_pk_bf16_f32 v82, v84, v85
	v_cvt_pk_bf16_f32 v83, v86, v87
	v_cvt_pk_bf16_f32 v84, v88, v89
	v_cvt_pk_bf16_f32 v85, v90, v91
	v_cvt_pk_bf16_f32 v86, v92, v93
	v_cvt_pk_bf16_f32 v87, v94, v95
	s_lshl_b32 s99, s98, 11
	v_lshl_add_u32 v8, v0, 3, s99
	global_store_dwordx2 v8, v[80:81], s[94:95]
	global_store_dwordx2 v8, v[82:83], s[94:95] offset:512
	global_store_dwordx2 v8, v[84:85], s[94:95] offset:1024
	global_store_dwordx2 v8, v[86:87], s[94:95] offset:1536
	s_lshl_b32 s99, s98, 2
	v_mov_b32_e32 v9, s99
	v_mov_b32_e32 v10, 0
	v_cmp_eq_u32_e32 vcc, 0, v0
	s_and_saveexec_b64 s[98:99], vcc
	global_store_dword v9, v10, s[90:91]
	global_store_dword v9, v10, s[92:93]
	s_or_b64 exec, exec, s[98:99]
	s_add_u32 s98, s97, 2560
	s_lshl_b32 s98, s98, 12
	v_add_u32_e32 v3, s98, v1
	global_load_dwordx4 v[80:83], v3, s[88:89] nt
	global_load_dwordx4 v[84:87], v3, s[88:89] offset:1024 nt
	global_load_dwordx4 v[88:91], v3, s[88:89] offset:2048 nt
	global_load_dwordx4 v[92:95], v3, s[88:89] offset:3072 nt
	s_waitcnt vmcnt(50)
	v_mul_f32_e32 v4, v96, v96
	v_fma_f32 v4, v97, v97, v4
	v_fma_f32 v4, v98, v98, v4
	v_fma_f32 v4, v99, v99, v4
	v_fma_f32 v4, v100, v100, v4
	v_fma_f32 v4, v101, v101, v4
	v_fma_f32 v4, v102, v102, v4
	v_fma_f32 v4, v103, v103, v4
	v_fma_f32 v4, v104, v104, v4
	v_fma_f32 v4, v105, v105, v4
	v_fma_f32 v4, v106, v106, v4
	v_fma_f32 v4, v107, v107, v4
	v_fma_f32 v4, v108, v108, v4
	v_fma_f32 v4, v109, v109, v4
	v_fma_f32 v4, v110, v110, v4
	v_fma_f32 v4, v111, v111, v4
	s_nop 1
	v_add_f32_dpp v5, v4, v4 quad_perm:[1,0,3,2] row_mask:0xf bank_mask:0xf
	s_nop 1
	v_add_f32_dpp v4, v5, v5 quad_perm:[2,3,0,1] row_mask:0xf bank_mask:0xf
	s_nop 1
	v_add_f32_dpp v5, v4, v4 row_half_mirror row_mask:0xf bank_mask:0xf
	s_nop 1
	v_add_f32_dpp v4, v5, v5 row_mirror row_mask:0xf bank_mask:0xf
	s_nop 1
	v_readlane_b32 s98, v4, 0
	v_readlane_b32 s99, v4, 16
	s_nop 3
	v_mov_b32_e32 v5, s98
	v_add_f32_e32 v5, s99, v5
	v_readlane_b32 s98, v4, 32
	v_readlane_b32 s99, v4, 48
	s_nop 3
	v_add_f32_e32 v5, s98, v5
	v_add_f32_e32 v5, s99, v5
	v_mul_f32_e32 v5, 0x3a800000, v5
	v_add_f32_e32 v5, 0x358637bd, v5
	v_rsq_f32_e32 v6, v5
	s_nop 0
	s_add_u32 s98, s97, 1280
	v_pk_mul_f32 v[96:97], v[96:97], v[6:7] op_sel_hi:[1,0]
	v_pk_mul_f32 v[98:99], v[98:99], v[6:7] op_sel_hi:[1,0]
	v_pk_mul_f32 v[100:101], v[100:101], v[6:7] op_sel_hi:[1,0]
	v_pk_mul_f32 v[102:103], v[102:103], v[6:7] op_sel_hi:[1,0]
	v_pk_mul_f32 v[104:105], v[104:105], v[6:7] op_sel_hi:[1,0]
	v_pk_mul_f32 v[106:107], v[106:107], v[6:7] op_sel_hi:[1,0]
	v_pk_mul_f32 v[108:109], v[108:109], v[6:7] op_sel_hi:[1,0]
	v_pk_mul_f32 v[110:111], v[110:111], v[6:7] op_sel_hi:[1,0]
	v_pk_mul_f32 v[96:97], v[96:97], v[112:113]
	v_pk_mul_f32 v[98:99], v[98:99], v[114:115]
	v_pk_mul_f32 v[100:101], v[100:101], v[116:117]
	v_pk_mul_f32 v[102:103], v[102:103], v[118:119]
	v_pk_mul_f32 v[104:105], v[104:105], v[120:121]
	v_pk_mul_f32 v[106:107], v[106:107], v[122:123]
	v_pk_mul_f32 v[108:109], v[108:109], v[124:125]
	v_pk_mul_f32 v[110:111], v[110:111], v[126:127]
	v_pk_fma_f32 v[96:97], v[96:97], v[128:129], v[144:145]
	v_pk_fma_f32 v[98:99], v[98:99], v[130:131], v[146:147]
	v_pk_fma_f32 v[100:101], v[100:101], v[132:133], v[148:149]
	v_pk_fma_f32 v[102:103], v[102:103], v[134:135], v[150:151]
	v_pk_fma_f32 v[104:105], v[104:105], v[136:137], v[152:153]
	v_pk_fma_f32 v[106:107], v[106:107], v[138:139], v[154:155]
	v_pk_fma_f32 v[108:109], v[108:109], v[140:141], v[156:157]
	v_pk_fma_f32 v[110:111], v[110:111], v[142:143], v[158:159]
	v_cvt_pk_bf16_f32 v96, v96, v97
	v_cvt_pk_bf16_f32 v97, v98, v99
	v_cvt_pk_bf16_f32 v98, v100, v101
	v_cvt_pk_bf16_f32 v99, v102, v103
	v_cvt_pk_bf16_f32 v100, v104, v105
	v_cvt_pk_bf16_f32 v101, v106, v107
	v_cvt_pk_bf16_f32 v102, v108, v109
	v_cvt_pk_bf16_f32 v103, v110, v111
	s_lshl_b32 s99, s98, 11
	v_lshl_add_u32 v8, v0, 3, s99
	global_store_dwordx2 v8, v[96:97], s[94:95]
	global_store_dwordx2 v8, v[98:99], s[94:95] offset:512
	global_store_dwordx2 v8, v[100:101], s[94:95] offset:1024
	global_store_dwordx2 v8, v[102:103], s[94:95] offset:1536
	s_lshl_b32 s99, s98, 2
	v_mov_b32_e32 v9, s99
	v_mov_b32_e32 v10, 0
	v_cmp_eq_u32_e32 vcc, 0, v0
	s_and_saveexec_b64 s[98:99], vcc
	global_store_dword v9, v10, s[90:91]
	global_store_dword v9, v10, s[92:93]
	s_or_b64 exec, exec, s[98:99]
	s_add_u32 s98, s97, 2816
	s_lshl_b32 s98, s98, 12
	v_add_u32_e32 v3, s98, v1
	global_load_dwordx4 v[96:99], v3, s[88:89] nt
	global_load_dwordx4 v[100:103], v3, s[88:89] offset:1024 nt
	global_load_dwordx4 v[104:107], v3, s[88:89] offset:2048 nt
	global_load_dwordx4 v[108:111], v3, s[88:89] offset:3072 nt
	s_waitcnt vmcnt(50)
	v_mul_f32_e32 v4, v16, v16
	v_fma_f32 v4, v17, v17, v4
	v_fma_f32 v4, v18, v18, v4
	v_fma_f32 v4, v19, v19, v4
	v_fma_f32 v4, v20, v20, v4
	v_fma_f32 v4, v21, v21, v4
	v_fma_f32 v4, v22, v22, v4
	v_fma_f32 v4, v23, v23, v4
	v_fma_f32 v4, v24, v24, v4
	v_fma_f32 v4, v25, v25, v4
	v_fma_f32 v4, v26, v26, v4
	v_fma_f32 v4, v27, v27, v4
	v_fma_f32 v4, v28, v28, v4
	v_fma_f32 v4, v29, v29, v4
	v_fma_f32 v4, v30, v30, v4
	v_fma_f32 v4, v31, v31, v4
	s_nop 1
	v_add_f32_dpp v5, v4, v4 quad_perm:[1,0,3,2] row_mask:0xf bank_mask:0xf
	s_nop 1
	v_add_f32_dpp v4, v5, v5 quad_perm:[2,3,0,1] row_mask:0xf bank_mask:0xf
	s_nop 1
	v_add_f32_dpp v5, v4, v4 row_half_mirror row_mask:0xf bank_mask:0xf
	s_nop 1
	v_add_f32_dpp v4, v5, v5 row_mirror row_mask:0xf bank_mask:0xf
	s_nop 1
	v_readlane_b32 s98, v4, 0
	v_readlane_b32 s99, v4, 16
	s_nop 3
	v_mov_b32_e32 v5, s98
	v_add_f32_e32 v5, s99, v5
	v_readlane_b32 s98, v4, 32
	v_readlane_b32 s99, v4, 48
	s_nop 3
	v_add_f32_e32 v5, s98, v5
	v_add_f32_e32 v5, s99, v5
	v_mul_f32_e32 v5, 0x3a800000, v5
	v_add_f32_e32 v5, 0x358637bd, v5
	v_rsq_f32_e32 v6, v5
	s_nop 0
	s_add_u32 s98, s97, 1536
	v_pk_mul_f32 v[16:17], v[16:17], v[6:7] op_sel_hi:[1,0]
	v_pk_mul_f32 v[18:19], v[18:19], v[6:7] op_sel_hi:[1,0]
	v_pk_mul_f32 v[20:21], v[20:21], v[6:7] op_sel_hi:[1,0]
	v_pk_mul_f32 v[22:23], v[22:23], v[6:7] op_sel_hi:[1,0]
	v_pk_mul_f32 v[24:25], v[24:25], v[6:7] op_sel_hi:[1,0]
	v_pk_mul_f32 v[26:27], v[26:27], v[6:7] op_sel_hi:[1,0]
	v_pk_mul_f32 v[28:29], v[28:29], v[6:7] op_sel_hi:[1,0]
	v_pk_mul_f32 v[30:31], v[30:31], v[6:7] op_sel_hi:[1,0]
	v_pk_mul_f32 v[16:17], v[16:17], v[112:113]
	v_pk_mul_f32 v[18:19], v[18:19], v[114:115]
	v_pk_mul_f32 v[20:21], v[20:21], v[116:117]
	v_pk_mul_f32 v[22:23], v[22:23], v[118:119]
	v_pk_mul_f32 v[24:25], v[24:25], v[120:121]
	v_pk_mul_f32 v[26:27], v[26:27], v[122:123]
	v_pk_mul_f32 v[28:29], v[28:29], v[124:125]
	v_pk_mul_f32 v[30:31], v[30:31], v[126:127]
	v_pk_fma_f32 v[16:17], v[16:17], v[128:129], v[144:145]
	v_pk_fma_f32 v[18:19], v[18:19], v[130:131], v[146:147]
	v_pk_fma_f32 v[20:21], v[20:21], v[132:133], v[148:149]
	v_pk_fma_f32 v[22:23], v[22:23], v[134:135], v[150:151]
	v_pk_fma_f32 v[24:25], v[24:25], v[136:137], v[152:153]
	v_pk_fma_f32 v[26:27], v[26:27], v[138:139], v[154:155]
	v_pk_fma_f32 v[28:29], v[28:29], v[140:141], v[156:157]
	v_pk_fma_f32 v[30:31], v[30:31], v[142:143], v[158:159]
	v_cvt_pk_bf16_f32 v16, v16, v17
	v_cvt_pk_bf16_f32 v17, v18, v19
	v_cvt_pk_bf16_f32 v18, v20, v21
	v_cvt_pk_bf16_f32 v19, v22, v23
	v_cvt_pk_bf16_f32 v20, v24, v25
	v_cvt_pk_bf16_f32 v21, v26, v27
	v_cvt_pk_bf16_f32 v22, v28, v29
	v_cvt_pk_bf16_f32 v23, v30, v31
	s_lshl_b32 s99, s98, 11
	v_lshl_add_u32 v8, v0, 3, s99
	global_store_dwordx2 v8, v[16:17], s[94:95]
	global_store_dwordx2 v8, v[18:19], s[94:95] offset:512
	global_store_dwordx2 v8, v[20:21], s[94:95] offset:1024
	global_store_dwordx2 v8, v[22:23], s[94:95] offset:1536
	s_lshl_b32 s99, s98, 2
	v_mov_b32_e32 v9, s99
	v_mov_b32_e32 v10, 0
	v_cmp_eq_u32_e32 vcc, 0, v0
	s_and_saveexec_b64 s[98:99], vcc
	global_store_dword v9, v10, s[90:91]
	global_store_dword v9, v10, s[92:93]
	s_or_b64 exec, exec, s[98:99]
	s_add_u32 s98, s97, 3072
	s_lshl_b32 s98, s98, 12
	v_add_u32_e32 v3, s98, v1
	global_load_dwordx4 v[16:19], v3, s[88:89] nt
	global_load_dwordx4 v[20:23], v3, s[88:89] offset:1024 nt
	global_load_dwordx4 v[24:27], v3, s[88:89] offset:2048 nt
	global_load_dwordx4 v[28:31], v3, s[88:89] offset:3072 nt
	s_waitcnt vmcnt(50)
	v_mul_f32_e32 v4, v32, v32
	v_fma_f32 v4, v33, v33, v4
	v_fma_f32 v4, v34, v34, v4
	v_fma_f32 v4, v35, v35, v4
	v_fma_f32 v4, v36, v36, v4
	v_fma_f32 v4, v37, v37, v4
	v_fma_f32 v4, v38, v38, v4
	v_fma_f32 v4, v39, v39, v4
	v_fma_f32 v4, v40, v40, v4
	v_fma_f32 v4, v41, v41, v4
	v_fma_f32 v4, v42, v42, v4
	v_fma_f32 v4, v43, v43, v4
	v_fma_f32 v4, v44, v44, v4
	v_fma_f32 v4, v45, v45, v4
	v_fma_f32 v4, v46, v46, v4
	v_fma_f32 v4, v47, v47, v4
	s_nop 1
	v_add_f32_dpp v5, v4, v4 quad_perm:[1,0,3,2] row_mask:0xf bank_mask:0xf
	s_nop 1
	v_add_f32_dpp v4, v5, v5 quad_perm:[2,3,0,1] row_mask:0xf bank_mask:0xf
	s_nop 1
	v_add_f32_dpp v5, v4, v4 row_half_mirror row_mask:0xf bank_mask:0xf
	s_nop 1
	v_add_f32_dpp v4, v5, v5 row_mirror row_mask:0xf bank_mask:0xf
	s_nop 1
	v_readlane_b32 s98, v4, 0
	v_readlane_b32 s99, v4, 16
	s_nop 3
	v_mov_b32_e32 v5, s98
	v_add_f32_e32 v5, s99, v5
	v_readlane_b32 s98, v4, 32
	v_readlane_b32 s99, v4, 48
	s_nop 3
	v_add_f32_e32 v5, s98, v5
	v_add_f32_e32 v5, s99, v5
	v_mul_f32_e32 v5, 0x3a800000, v5
	v_add_f32_e32 v5, 0x358637bd, v5
	v_rsq_f32_e32 v6, v5
	s_nop 0
	s_add_u32 s98, s97, 1792
	v_pk_mul_f32 v[32:33], v[32:33], v[6:7] op_sel_hi:[1,0]
	v_pk_mul_f32 v[34:35], v[34:35], v[6:7] op_sel_hi:[1,0]
	v_pk_mul_f32 v[36:37], v[36:37], v[6:7] op_sel_hi:[1,0]
	v_pk_mul_f32 v[38:39], v[38:39], v[6:7] op_sel_hi:[1,0]
	v_pk_mul_f32 v[40:41], v[40:41], v[6:7] op_sel_hi:[1,0]
	v_pk_mul_f32 v[42:43], v[42:43], v[6:7] op_sel_hi:[1,0]
	v_pk_mul_f32 v[44:45], v[44:45], v[6:7] op_sel_hi:[1,0]
	v_pk_mul_f32 v[46:47], v[46:47], v[6:7] op_sel_hi:[1,0]
	v_pk_mul_f32 v[32:33], v[32:33], v[112:113]
	v_pk_mul_f32 v[34:35], v[34:35], v[114:115]
	v_pk_mul_f32 v[36:37], v[36:37], v[116:117]
	v_pk_mul_f32 v[38:39], v[38:39], v[118:119]
	v_pk_mul_f32 v[40:41], v[40:41], v[120:121]
	v_pk_mul_f32 v[42:43], v[42:43], v[122:123]
	v_pk_mul_f32 v[44:45], v[44:45], v[124:125]
	v_pk_mul_f32 v[46:47], v[46:47], v[126:127]
	v_pk_fma_f32 v[32:33], v[32:33], v[128:129], v[144:145]
	v_pk_fma_f32 v[34:35], v[34:35], v[130:131], v[146:147]
	v_pk_fma_f32 v[36:37], v[36:37], v[132:133], v[148:149]
	v_pk_fma_f32 v[38:39], v[38:39], v[134:135], v[150:151]
	v_pk_fma_f32 v[40:41], v[40:41], v[136:137], v[152:153]
	v_pk_fma_f32 v[42:43], v[42:43], v[138:139], v[154:155]
	v_pk_fma_f32 v[44:45], v[44:45], v[140:141], v[156:157]
	v_pk_fma_f32 v[46:47], v[46:47], v[142:143], v[158:159]
	v_cvt_pk_bf16_f32 v32, v32, v33
	v_cvt_pk_bf16_f32 v33, v34, v35
	v_cvt_pk_bf16_f32 v34, v36, v37
	v_cvt_pk_bf16_f32 v35, v38, v39
	v_cvt_pk_bf16_f32 v36, v40, v41
	v_cvt_pk_bf16_f32 v37, v42, v43
	v_cvt_pk_bf16_f32 v38, v44, v45
	v_cvt_pk_bf16_f32 v39, v46, v47
	s_lshl_b32 s99, s98, 11
	v_lshl_add_u32 v8, v0, 3, s99
	global_store_dwordx2 v8, v[32:33], s[94:95]
	global_store_dwordx2 v8, v[34:35], s[94:95] offset:512
	global_store_dwordx2 v8, v[36:37], s[94:95] offset:1024
	global_store_dwordx2 v8, v[38:39], s[94:95] offset:1536
	s_lshl_b32 s99, s98, 2
	v_mov_b32_e32 v9, s99
	v_mov_b32_e32 v10, 0
	v_cmp_eq_u32_e32 vcc, 0, v0
	s_and_saveexec_b64 s[98:99], vcc
	global_store_dword v9, v10, s[90:91]
	global_store_dword v9, v10, s[92:93]
	s_or_b64 exec, exec, s[98:99]
	s_add_u32 s98, s97, 3328
	s_lshl_b32 s98, s98, 12
	v_add_u32_e32 v3, s98, v1
	global_load_dwordx4 v[32:35], v3, s[88:89] nt
	global_load_dwordx4 v[36:39], v3, s[88:89] offset:1024 nt
	global_load_dwordx4 v[40:43], v3, s[88:89] offset:2048 nt
	global_load_dwordx4 v[44:47], v3, s[88:89] offset:3072 nt
	s_waitcnt vmcnt(50)
	v_mul_f32_e32 v4, v48, v48
	v_fma_f32 v4, v49, v49, v4
	v_fma_f32 v4, v50, v50, v4
	v_fma_f32 v4, v51, v51, v4
	v_fma_f32 v4, v52, v52, v4
	v_fma_f32 v4, v53, v53, v4
	v_fma_f32 v4, v54, v54, v4
	v_fma_f32 v4, v55, v55, v4
	v_fma_f32 v4, v56, v56, v4
	v_fma_f32 v4, v57, v57, v4
	v_fma_f32 v4, v58, v58, v4
	v_fma_f32 v4, v59, v59, v4
	v_fma_f32 v4, v60, v60, v4
	v_fma_f32 v4, v61, v61, v4
	v_fma_f32 v4, v62, v62, v4
	v_fma_f32 v4, v63, v63, v4
	s_nop 1
	v_add_f32_dpp v5, v4, v4 quad_perm:[1,0,3,2] row_mask:0xf bank_mask:0xf
	s_nop 1
	v_add_f32_dpp v4, v5, v5 quad_perm:[2,3,0,1] row_mask:0xf bank_mask:0xf
	s_nop 1
	v_add_f32_dpp v5, v4, v4 row_half_mirror row_mask:0xf bank_mask:0xf
	s_nop 1
	v_add_f32_dpp v4, v5, v5 row_mirror row_mask:0xf bank_mask:0xf
	s_nop 1
	v_readlane_b32 s98, v4, 0
	v_readlane_b32 s99, v4, 16
	s_nop 3
	v_mov_b32_e32 v5, s98
	v_add_f32_e32 v5, s99, v5
	v_readlane_b32 s98, v4, 32
	v_readlane_b32 s99, v4, 48
	s_nop 3
	v_add_f32_e32 v5, s98, v5
	v_add_f32_e32 v5, s99, v5
	v_mul_f32_e32 v5, 0x3a800000, v5
	v_add_f32_e32 v5, 0x358637bd, v5
	v_rsq_f32_e32 v6, v5
	s_nop 0
	s_add_u32 s98, s97, 2048
	v_pk_mul_f32 v[48:49], v[48:49], v[6:7] op_sel_hi:[1,0]
	v_pk_mul_f32 v[50:51], v[50:51], v[6:7] op_sel_hi:[1,0]
	v_pk_mul_f32 v[52:53], v[52:53], v[6:7] op_sel_hi:[1,0]
	v_pk_mul_f32 v[54:55], v[54:55], v[6:7] op_sel_hi:[1,0]
	v_pk_mul_f32 v[56:57], v[56:57], v[6:7] op_sel_hi:[1,0]
	v_pk_mul_f32 v[58:59], v[58:59], v[6:7] op_sel_hi:[1,0]
	v_pk_mul_f32 v[60:61], v[60:61], v[6:7] op_sel_hi:[1,0]
	v_pk_mul_f32 v[62:63], v[62:63], v[6:7] op_sel_hi:[1,0]
	v_pk_mul_f32 v[48:49], v[48:49], v[112:113]
	v_pk_mul_f32 v[50:51], v[50:51], v[114:115]
	v_pk_mul_f32 v[52:53], v[52:53], v[116:117]
	v_pk_mul_f32 v[54:55], v[54:55], v[118:119]
	v_pk_mul_f32 v[56:57], v[56:57], v[120:121]
	v_pk_mul_f32 v[58:59], v[58:59], v[122:123]
	v_pk_mul_f32 v[60:61], v[60:61], v[124:125]
	v_pk_mul_f32 v[62:63], v[62:63], v[126:127]
	v_pk_fma_f32 v[48:49], v[48:49], v[128:129], v[144:145]
	v_pk_fma_f32 v[50:51], v[50:51], v[130:131], v[146:147]
	v_pk_fma_f32 v[52:53], v[52:53], v[132:133], v[148:149]
	v_pk_fma_f32 v[54:55], v[54:55], v[134:135], v[150:151]
	v_pk_fma_f32 v[56:57], v[56:57], v[136:137], v[152:153]
	v_pk_fma_f32 v[58:59], v[58:59], v[138:139], v[154:155]
	v_pk_fma_f32 v[60:61], v[60:61], v[140:141], v[156:157]
	v_pk_fma_f32 v[62:63], v[62:63], v[142:143], v[158:159]
	v_cvt_pk_bf16_f32 v48, v48, v49
	v_cvt_pk_bf16_f32 v49, v50, v51
	v_cvt_pk_bf16_f32 v50, v52, v53
	v_cvt_pk_bf16_f32 v51, v54, v55
	v_cvt_pk_bf16_f32 v52, v56, v57
	v_cvt_pk_bf16_f32 v53, v58, v59
	v_cvt_pk_bf16_f32 v54, v60, v61
	v_cvt_pk_bf16_f32 v55, v62, v63
	s_lshl_b32 s99, s98, 11
	v_lshl_add_u32 v8, v0, 3, s99
	global_store_dwordx2 v8, v[48:49], s[94:95]
	global_store_dwordx2 v8, v[50:51], s[94:95] offset:512
	global_store_dwordx2 v8, v[52:53], s[94:95] offset:1024
	global_store_dwordx2 v8, v[54:55], s[94:95] offset:1536
	s_lshl_b32 s99, s98, 2
	v_mov_b32_e32 v9, s99
	v_mov_b32_e32 v10, 0
	v_cmp_eq_u32_e32 vcc, 0, v0
	s_and_saveexec_b64 s[98:99], vcc
	global_store_dword v9, v10, s[90:91]
	global_store_dword v9, v10, s[92:93]
	s_or_b64 exec, exec, s[98:99]
	s_add_u32 s98, s97, 3584
	s_lshl_b32 s98, s98, 12
	v_add_u32_e32 v3, s98, v1
	global_load_dwordx4 v[48:51], v3, s[88:89] nt
	global_load_dwordx4 v[52:55], v3, s[88:89] offset:1024 nt
	global_load_dwordx4 v[56:59], v3, s[88:89] offset:2048 nt
	global_load_dwordx4 v[60:63], v3, s[88:89] offset:3072 nt
	s_waitcnt vmcnt(50)
	v_mul_f32_e32 v4, v64, v64
	v_fma_f32 v4, v65, v65, v4
	v_fma_f32 v4, v66, v66, v4
	v_fma_f32 v4, v67, v67, v4
	v_fma_f32 v4, v68, v68, v4
	v_fma_f32 v4, v69, v69, v4
	v_fma_f32 v4, v70, v70, v4
	v_fma_f32 v4, v71, v71, v4
	v_fma_f32 v4, v72, v72, v4
	v_fma_f32 v4, v73, v73, v4
	v_fma_f32 v4, v74, v74, v4
	v_fma_f32 v4, v75, v75, v4
	v_fma_f32 v4, v76, v76, v4
	v_fma_f32 v4, v77, v77, v4
	v_fma_f32 v4, v78, v78, v4
	v_fma_f32 v4, v79, v79, v4
	s_nop 1
	v_add_f32_dpp v5, v4, v4 quad_perm:[1,0,3,2] row_mask:0xf bank_mask:0xf
	s_nop 1
	v_add_f32_dpp v4, v5, v5 quad_perm:[2,3,0,1] row_mask:0xf bank_mask:0xf
	s_nop 1
	v_add_f32_dpp v5, v4, v4 row_half_mirror row_mask:0xf bank_mask:0xf
	s_nop 1
	v_add_f32_dpp v4, v5, v5 row_mirror row_mask:0xf bank_mask:0xf
	s_nop 1
	v_readlane_b32 s98, v4, 0
	v_readlane_b32 s99, v4, 16
	s_nop 3
	v_mov_b32_e32 v5, s98
	v_add_f32_e32 v5, s99, v5
	v_readlane_b32 s98, v4, 32
	v_readlane_b32 s99, v4, 48
	s_nop 3
	v_add_f32_e32 v5, s98, v5
	v_add_f32_e32 v5, s99, v5
	v_mul_f32_e32 v5, 0x3a800000, v5
	v_add_f32_e32 v5, 0x358637bd, v5
	v_rsq_f32_e32 v6, v5
	s_nop 0
	s_add_u32 s98, s97, 2304
	v_pk_mul_f32 v[64:65], v[64:65], v[6:7] op_sel_hi:[1,0]
	v_pk_mul_f32 v[66:67], v[66:67], v[6:7] op_sel_hi:[1,0]
	v_pk_mul_f32 v[68:69], v[68:69], v[6:7] op_sel_hi:[1,0]
	v_pk_mul_f32 v[70:71], v[70:71], v[6:7] op_sel_hi:[1,0]
	v_pk_mul_f32 v[72:73], v[72:73], v[6:7] op_sel_hi:[1,0]
	v_pk_mul_f32 v[74:75], v[74:75], v[6:7] op_sel_hi:[1,0]
	v_pk_mul_f32 v[76:77], v[76:77], v[6:7] op_sel_hi:[1,0]
	v_pk_mul_f32 v[78:79], v[78:79], v[6:7] op_sel_hi:[1,0]
	v_pk_mul_f32 v[64:65], v[64:65], v[112:113]
	v_pk_mul_f32 v[66:67], v[66:67], v[114:115]
	v_pk_mul_f32 v[68:69], v[68:69], v[116:117]
	v_pk_mul_f32 v[70:71], v[70:71], v[118:119]
	v_pk_mul_f32 v[72:73], v[72:73], v[120:121]
	v_pk_mul_f32 v[74:75], v[74:75], v[122:123]
	v_pk_mul_f32 v[76:77], v[76:77], v[124:125]
	v_pk_mul_f32 v[78:79], v[78:79], v[126:127]
	v_pk_fma_f32 v[64:65], v[64:65], v[128:129], v[144:145]
	v_pk_fma_f32 v[66:67], v[66:67], v[130:131], v[146:147]
	v_pk_fma_f32 v[68:69], v[68:69], v[132:133], v[148:149]
	v_pk_fma_f32 v[70:71], v[70:71], v[134:135], v[150:151]
	v_pk_fma_f32 v[72:73], v[72:73], v[136:137], v[152:153]
	v_pk_fma_f32 v[74:75], v[74:75], v[138:139], v[154:155]
	v_pk_fma_f32 v[76:77], v[76:77], v[140:141], v[156:157]
	v_pk_fma_f32 v[78:79], v[78:79], v[142:143], v[158:159]
	v_cvt_pk_bf16_f32 v64, v64, v65
	v_cvt_pk_bf16_f32 v65, v66, v67
	v_cvt_pk_bf16_f32 v66, v68, v69
	v_cvt_pk_bf16_f32 v67, v70, v71
	v_cvt_pk_bf16_f32 v68, v72, v73
	v_cvt_pk_bf16_f32 v69, v74, v75
	v_cvt_pk_bf16_f32 v70, v76, v77
	v_cvt_pk_bf16_f32 v71, v78, v79
	s_lshl_b32 s99, s98, 11
	v_lshl_add_u32 v8, v0, 3, s99
	global_store_dwordx2 v8, v[64:65], s[94:95]
	global_store_dwordx2 v8, v[66:67], s[94:95] offset:512
	global_store_dwordx2 v8, v[68:69], s[94:95] offset:1024
	global_store_dwordx2 v8, v[70:71], s[94:95] offset:1536
	s_lshl_b32 s99, s98, 2
	v_mov_b32_e32 v9, s99
	v_mov_b32_e32 v10, 0
	v_cmp_eq_u32_e32 vcc, 0, v0
	s_and_saveexec_b64 s[98:99], vcc
	global_store_dword v9, v10, s[90:91]
	global_store_dword v9, v10, s[92:93]
	s_or_b64 exec, exec, s[98:99]
	s_add_u32 s98, s97, 3840
	s_lshl_b32 s98, s98, 12
	v_add_u32_e32 v3, s98, v1
	global_load_dwordx4 v[64:67], v3, s[88:89] nt
	global_load_dwordx4 v[68:71], v3, s[88:89] offset:1024 nt
	global_load_dwordx4 v[72:75], v3, s[88:89] offset:2048 nt
	global_load_dwordx4 v[76:79], v3, s[88:89] offset:3072 nt
	s_waitcnt vmcnt(50)
	v_mul_f32_e32 v4, v80, v80
	v_fma_f32 v4, v81, v81, v4
	v_fma_f32 v4, v82, v82, v4
	v_fma_f32 v4, v83, v83, v4
	v_fma_f32 v4, v84, v84, v4
	v_fma_f32 v4, v85, v85, v4
	v_fma_f32 v4, v86, v86, v4
	v_fma_f32 v4, v87, v87, v4
	v_fma_f32 v4, v88, v88, v4
	v_fma_f32 v4, v89, v89, v4
	v_fma_f32 v4, v90, v90, v4
	v_fma_f32 v4, v91, v91, v4
	v_fma_f32 v4, v92, v92, v4
	v_fma_f32 v4, v93, v93, v4
	v_fma_f32 v4, v94, v94, v4
	v_fma_f32 v4, v95, v95, v4
	s_nop 1
	v_add_f32_dpp v5, v4, v4 quad_perm:[1,0,3,2] row_mask:0xf bank_mask:0xf
	s_nop 1
	v_add_f32_dpp v4, v5, v5 quad_perm:[2,3,0,1] row_mask:0xf bank_mask:0xf
	s_nop 1
	v_add_f32_dpp v5, v4, v4 row_half_mirror row_mask:0xf bank_mask:0xf
	s_nop 1
	v_add_f32_dpp v4, v5, v5 row_mirror row_mask:0xf bank_mask:0xf
	s_nop 1
	v_readlane_b32 s98, v4, 0
	v_readlane_b32 s99, v4, 16
	s_nop 3
	v_mov_b32_e32 v5, s98
	v_add_f32_e32 v5, s99, v5
	v_readlane_b32 s98, v4, 32
	v_readlane_b32 s99, v4, 48
	s_nop 3
	v_add_f32_e32 v5, s98, v5
	v_add_f32_e32 v5, s99, v5
	v_mul_f32_e32 v5, 0x3a800000, v5
	v_add_f32_e32 v5, 0x358637bd, v5
	v_rsq_f32_e32 v6, v5
	s_nop 0
	s_add_u32 s98, s97, 2560
	v_pk_mul_f32 v[80:81], v[80:81], v[6:7] op_sel_hi:[1,0]
	v_pk_mul_f32 v[82:83], v[82:83], v[6:7] op_sel_hi:[1,0]
	v_pk_mul_f32 v[84:85], v[84:85], v[6:7] op_sel_hi:[1,0]
	v_pk_mul_f32 v[86:87], v[86:87], v[6:7] op_sel_hi:[1,0]
	v_pk_mul_f32 v[88:89], v[88:89], v[6:7] op_sel_hi:[1,0]
	v_pk_mul_f32 v[90:91], v[90:91], v[6:7] op_sel_hi:[1,0]
	v_pk_mul_f32 v[92:93], v[92:93], v[6:7] op_sel_hi:[1,0]
	v_pk_mul_f32 v[94:95], v[94:95], v[6:7] op_sel_hi:[1,0]
	v_pk_mul_f32 v[80:81], v[80:81], v[112:113]
	v_pk_mul_f32 v[82:83], v[82:83], v[114:115]
	v_pk_mul_f32 v[84:85], v[84:85], v[116:117]
	v_pk_mul_f32 v[86:87], v[86:87], v[118:119]
	v_pk_mul_f32 v[88:89], v[88:89], v[120:121]
	v_pk_mul_f32 v[90:91], v[90:91], v[122:123]
	v_pk_mul_f32 v[92:93], v[92:93], v[124:125]
	v_pk_mul_f32 v[94:95], v[94:95], v[126:127]
	v_pk_fma_f32 v[80:81], v[80:81], v[128:129], v[144:145]
	v_pk_fma_f32 v[82:83], v[82:83], v[130:131], v[146:147]
	v_pk_fma_f32 v[84:85], v[84:85], v[132:133], v[148:149]
	v_pk_fma_f32 v[86:87], v[86:87], v[134:135], v[150:151]
	v_pk_fma_f32 v[88:89], v[88:89], v[136:137], v[152:153]
	v_pk_fma_f32 v[90:91], v[90:91], v[138:139], v[154:155]
	v_pk_fma_f32 v[92:93], v[92:93], v[140:141], v[156:157]
	v_pk_fma_f32 v[94:95], v[94:95], v[142:143], v[158:159]
	v_cvt_pk_bf16_f32 v80, v80, v81
	v_cvt_pk_bf16_f32 v81, v82, v83
	v_cvt_pk_bf16_f32 v82, v84, v85
	v_cvt_pk_bf16_f32 v83, v86, v87
	v_cvt_pk_bf16_f32 v84, v88, v89
	v_cvt_pk_bf16_f32 v85, v90, v91
	v_cvt_pk_bf16_f32 v86, v92, v93
	v_cvt_pk_bf16_f32 v87, v94, v95
	s_lshl_b32 s99, s98, 11
	v_lshl_add_u32 v8, v0, 3, s99
	global_store_dwordx2 v8, v[80:81], s[94:95]
	global_store_dwordx2 v8, v[82:83], s[94:95] offset:512
	global_store_dwordx2 v8, v[84:85], s[94:95] offset:1024
	global_store_dwordx2 v8, v[86:87], s[94:95] offset:1536
	s_lshl_b32 s99, s98, 2
	v_mov_b32_e32 v9, s99
	v_mov_b32_e32 v10, 0
	v_cmp_eq_u32_e32 vcc, 0, v0
	s_and_saveexec_b64 s[98:99], vcc
	global_store_dword v9, v10, s[90:91]
	global_store_dword v9, v10, s[92:93]
	s_or_b64 exec, exec, s[98:99]
	s_waitcnt vmcnt(46)
	v_mul_f32_e32 v4, v96, v96
	v_fma_f32 v4, v97, v97, v4
	v_fma_f32 v4, v98, v98, v4
	v_fma_f32 v4, v99, v99, v4
	v_fma_f32 v4, v100, v100, v4
	v_fma_f32 v4, v101, v101, v4
	v_fma_f32 v4, v102, v102, v4
	v_fma_f32 v4, v103, v103, v4
	v_fma_f32 v4, v104, v104, v4
	v_fma_f32 v4, v105, v105, v4
	v_fma_f32 v4, v106, v106, v4
	v_fma_f32 v4, v107, v107, v4
	v_fma_f32 v4, v108, v108, v4
	v_fma_f32 v4, v109, v109, v4
	v_fma_f32 v4, v110, v110, v4
	v_fma_f32 v4, v111, v111, v4
	s_nop 1
	v_add_f32_dpp v5, v4, v4 quad_perm:[1,0,3,2] row_mask:0xf bank_mask:0xf
	s_nop 1
	v_add_f32_dpp v4, v5, v5 quad_perm:[2,3,0,1] row_mask:0xf bank_mask:0xf
	s_nop 1
	v_add_f32_dpp v5, v4, v4 row_half_mirror row_mask:0xf bank_mask:0xf
	s_nop 1
	v_add_f32_dpp v4, v5, v5 row_mirror row_mask:0xf bank_mask:0xf
	s_nop 1
	v_readlane_b32 s98, v4, 0
	v_readlane_b32 s99, v4, 16
	s_nop 3
	v_mov_b32_e32 v5, s98
	v_add_f32_e32 v5, s99, v5
	v_readlane_b32 s98, v4, 32
	v_readlane_b32 s99, v4, 48
	s_nop 3
	v_add_f32_e32 v5, s98, v5
	v_add_f32_e32 v5, s99, v5
	v_mul_f32_e32 v5, 0x3a800000, v5
	v_add_f32_e32 v5, 0x358637bd, v5
	v_rsq_f32_e32 v6, v5
	s_nop 0
	s_add_u32 s98, s97, 2816
	v_pk_mul_f32 v[96:97], v[96:97], v[6:7] op_sel_hi:[1,0]
	v_pk_mul_f32 v[98:99], v[98:99], v[6:7] op_sel_hi:[1,0]
	v_pk_mul_f32 v[100:101], v[100:101], v[6:7] op_sel_hi:[1,0]
	v_pk_mul_f32 v[102:103], v[102:103], v[6:7] op_sel_hi:[1,0]
	v_pk_mul_f32 v[104:105], v[104:105], v[6:7] op_sel_hi:[1,0]
	v_pk_mul_f32 v[106:107], v[106:107], v[6:7] op_sel_hi:[1,0]
	v_pk_mul_f32 v[108:109], v[108:109], v[6:7] op_sel_hi:[1,0]
	v_pk_mul_f32 v[110:111], v[110:111], v[6:7] op_sel_hi:[1,0]
	v_pk_mul_f32 v[96:97], v[96:97], v[112:113]
	v_pk_mul_f32 v[98:99], v[98:99], v[114:115]
	v_pk_mul_f32 v[100:101], v[100:101], v[116:117]
	v_pk_mul_f32 v[102:103], v[102:103], v[118:119]
	v_pk_mul_f32 v[104:105], v[104:105], v[120:121]
	v_pk_mul_f32 v[106:107], v[106:107], v[122:123]
	v_pk_mul_f32 v[108:109], v[108:109], v[124:125]
	v_pk_mul_f32 v[110:111], v[110:111], v[126:127]
	v_pk_fma_f32 v[96:97], v[96:97], v[128:129], v[144:145]
	v_pk_fma_f32 v[98:99], v[98:99], v[130:131], v[146:147]
	v_pk_fma_f32 v[100:101], v[100:101], v[132:133], v[148:149]
	v_pk_fma_f32 v[102:103], v[102:103], v[134:135], v[150:151]
	v_pk_fma_f32 v[104:105], v[104:105], v[136:137], v[152:153]
	v_pk_fma_f32 v[106:107], v[106:107], v[138:139], v[154:155]
	v_pk_fma_f32 v[108:109], v[108:109], v[140:141], v[156:157]
	v_pk_fma_f32 v[110:111], v[110:111], v[142:143], v[158:159]
	v_cvt_pk_bf16_f32 v96, v96, v97
	v_cvt_pk_bf16_f32 v97, v98, v99
	v_cvt_pk_bf16_f32 v98, v100, v101
	v_cvt_pk_bf16_f32 v99, v102, v103
	v_cvt_pk_bf16_f32 v100, v104, v105
	v_cvt_pk_bf16_f32 v101, v106, v107
	v_cvt_pk_bf16_f32 v102, v108, v109
	v_cvt_pk_bf16_f32 v103, v110, v111
	s_lshl_b32 s99, s98, 11
	v_lshl_add_u32 v8, v0, 3, s99
	global_store_dwordx2 v8, v[96:97], s[94:95]
	global_store_dwordx2 v8, v[98:99], s[94:95] offset:512
	global_store_dwordx2 v8, v[100:101], s[94:95] offset:1024
	global_store_dwordx2 v8, v[102:103], s[94:95] offset:1536
	s_lshl_b32 s99, s98, 2
	v_mov_b32_e32 v9, s99
	v_mov_b32_e32 v10, 0
	v_cmp_eq_u32_e32 vcc, 0, v0
	s_and_saveexec_b64 s[98:99], vcc
	global_store_dword v9, v10, s[90:91]
	global_store_dword v9, v10, s[92:93]
	s_or_b64 exec, exec, s[98:99]
	s_waitcnt vmcnt(42)
	v_mul_f32_e32 v4, v16, v16
	v_fma_f32 v4, v17, v17, v4
	v_fma_f32 v4, v18, v18, v4
	v_fma_f32 v4, v19, v19, v4
	v_fma_f32 v4, v20, v20, v4
	v_fma_f32 v4, v21, v21, v4
	v_fma_f32 v4, v22, v22, v4
	v_fma_f32 v4, v23, v23, v4
	v_fma_f32 v4, v24, v24, v4
	v_fma_f32 v4, v25, v25, v4
	v_fma_f32 v4, v26, v26, v4
	v_fma_f32 v4, v27, v27, v4
	v_fma_f32 v4, v28, v28, v4
	v_fma_f32 v4, v29, v29, v4
	v_fma_f32 v4, v30, v30, v4
	v_fma_f32 v4, v31, v31, v4
	s_nop 1
	v_add_f32_dpp v5, v4, v4 quad_perm:[1,0,3,2] row_mask:0xf bank_mask:0xf
	s_nop 1
	v_add_f32_dpp v4, v5, v5 quad_perm:[2,3,0,1] row_mask:0xf bank_mask:0xf
	s_nop 1
	v_add_f32_dpp v5, v4, v4 row_half_mirror row_mask:0xf bank_mask:0xf
	s_nop 1
	v_add_f32_dpp v4, v5, v5 row_mirror row_mask:0xf bank_mask:0xf
	s_nop 1
	v_readlane_b32 s98, v4, 0
	v_readlane_b32 s99, v4, 16
	s_nop 3
	v_mov_b32_e32 v5, s98
	v_add_f32_e32 v5, s99, v5
	v_readlane_b32 s98, v4, 32
	v_readlane_b32 s99, v4, 48
	s_nop 3
	v_add_f32_e32 v5, s98, v5
	v_add_f32_e32 v5, s99, v5
	v_mul_f32_e32 v5, 0x3a800000, v5
	v_add_f32_e32 v5, 0x358637bd, v5
	v_rsq_f32_e32 v6, v5
	s_nop 0
	s_add_u32 s98, s97, 3072
	v_pk_mul_f32 v[16:17], v[16:17], v[6:7] op_sel_hi:[1,0]
	v_pk_mul_f32 v[18:19], v[18:19], v[6:7] op_sel_hi:[1,0]
	v_pk_mul_f32 v[20:21], v[20:21], v[6:7] op_sel_hi:[1,0]
	v_pk_mul_f32 v[22:23], v[22:23], v[6:7] op_sel_hi:[1,0]
	v_pk_mul_f32 v[24:25], v[24:25], v[6:7] op_sel_hi:[1,0]
	v_pk_mul_f32 v[26:27], v[26:27], v[6:7] op_sel_hi:[1,0]
	v_pk_mul_f32 v[28:29], v[28:29], v[6:7] op_sel_hi:[1,0]
	v_pk_mul_f32 v[30:31], v[30:31], v[6:7] op_sel_hi:[1,0]
	v_pk_mul_f32 v[16:17], v[16:17], v[112:113]
	v_pk_mul_f32 v[18:19], v[18:19], v[114:115]
	v_pk_mul_f32 v[20:21], v[20:21], v[116:117]
	v_pk_mul_f32 v[22:23], v[22:23], v[118:119]
	v_pk_mul_f32 v[24:25], v[24:25], v[120:121]
	v_pk_mul_f32 v[26:27], v[26:27], v[122:123]
	v_pk_mul_f32 v[28:29], v[28:29], v[124:125]
	v_pk_mul_f32 v[30:31], v[30:31], v[126:127]
	v_pk_fma_f32 v[16:17], v[16:17], v[128:129], v[144:145]
	v_pk_fma_f32 v[18:19], v[18:19], v[130:131], v[146:147]
	v_pk_fma_f32 v[20:21], v[20:21], v[132:133], v[148:149]
	v_pk_fma_f32 v[22:23], v[22:23], v[134:135], v[150:151]
	v_pk_fma_f32 v[24:25], v[24:25], v[136:137], v[152:153]
	v_pk_fma_f32 v[26:27], v[26:27], v[138:139], v[154:155]
	v_pk_fma_f32 v[28:29], v[28:29], v[140:141], v[156:157]
	v_pk_fma_f32 v[30:31], v[30:31], v[142:143], v[158:159]
	v_cvt_pk_bf16_f32 v16, v16, v17
	v_cvt_pk_bf16_f32 v17, v18, v19
	v_cvt_pk_bf16_f32 v18, v20, v21
	v_cvt_pk_bf16_f32 v19, v22, v23
	v_cvt_pk_bf16_f32 v20, v24, v25
	v_cvt_pk_bf16_f32 v21, v26, v27
	v_cvt_pk_bf16_f32 v22, v28, v29
	v_cvt_pk_bf16_f32 v23, v30, v31
	s_lshl_b32 s99, s98, 11
	v_lshl_add_u32 v8, v0, 3, s99
	global_store_dwordx2 v8, v[16:17], s[94:95]
	global_store_dwordx2 v8, v[18:19], s[94:95] offset:512
	global_store_dwordx2 v8, v[20:21], s[94:95] offset:1024
	global_store_dwordx2 v8, v[22:23], s[94:95] offset:1536
	s_lshl_b32 s99, s98, 2
	v_mov_b32_e32 v9, s99
	v_mov_b32_e32 v10, 0
	v_cmp_eq_u32_e32 vcc, 0, v0
	s_and_saveexec_b64 s[98:99], vcc
	global_store_dword v9, v10, s[90:91]
	global_store_dword v9, v10, s[92:93]
	s_or_b64 exec, exec, s[98:99]
	s_waitcnt vmcnt(38)
	v_mul_f32_e32 v4, v32, v32
	v_fma_f32 v4, v33, v33, v4
	v_fma_f32 v4, v34, v34, v4
	v_fma_f32 v4, v35, v35, v4
	v_fma_f32 v4, v36, v36, v4
	v_fma_f32 v4, v37, v37, v4
	v_fma_f32 v4, v38, v38, v4
	v_fma_f32 v4, v39, v39, v4
	v_fma_f32 v4, v40, v40, v4
	v_fma_f32 v4, v41, v41, v4
	v_fma_f32 v4, v42, v42, v4
	v_fma_f32 v4, v43, v43, v4
	v_fma_f32 v4, v44, v44, v4
	v_fma_f32 v4, v45, v45, v4
	v_fma_f32 v4, v46, v46, v4
	v_fma_f32 v4, v47, v47, v4
	s_nop 1
	v_add_f32_dpp v5, v4, v4 quad_perm:[1,0,3,2] row_mask:0xf bank_mask:0xf
	s_nop 1
	v_add_f32_dpp v4, v5, v5 quad_perm:[2,3,0,1] row_mask:0xf bank_mask:0xf
	s_nop 1
	v_add_f32_dpp v5, v4, v4 row_half_mirror row_mask:0xf bank_mask:0xf
	s_nop 1
	v_add_f32_dpp v4, v5, v5 row_mirror row_mask:0xf bank_mask:0xf
	s_nop 1
	v_readlane_b32 s98, v4, 0
	v_readlane_b32 s99, v4, 16
	s_nop 3
	v_mov_b32_e32 v5, s98
	v_add_f32_e32 v5, s99, v5
	v_readlane_b32 s98, v4, 32
	v_readlane_b32 s99, v4, 48
	s_nop 3
	v_add_f32_e32 v5, s98, v5
	v_add_f32_e32 v5, s99, v5
	v_mul_f32_e32 v5, 0x3a800000, v5
	v_add_f32_e32 v5, 0x358637bd, v5
	v_rsq_f32_e32 v6, v5
	s_nop 0
	s_add_u32 s98, s97, 3328
	v_pk_mul_f32 v[32:33], v[32:33], v[6:7] op_sel_hi:[1,0]
	v_pk_mul_f32 v[34:35], v[34:35], v[6:7] op_sel_hi:[1,0]
	v_pk_mul_f32 v[36:37], v[36:37], v[6:7] op_sel_hi:[1,0]
	v_pk_mul_f32 v[38:39], v[38:39], v[6:7] op_sel_hi:[1,0]
	v_pk_mul_f32 v[40:41], v[40:41], v[6:7] op_sel_hi:[1,0]
	v_pk_mul_f32 v[42:43], v[42:43], v[6:7] op_sel_hi:[1,0]
	v_pk_mul_f32 v[44:45], v[44:45], v[6:7] op_sel_hi:[1,0]
	v_pk_mul_f32 v[46:47], v[46:47], v[6:7] op_sel_hi:[1,0]
	v_pk_mul_f32 v[32:33], v[32:33], v[112:113]
	v_pk_mul_f32 v[34:35], v[34:35], v[114:115]
	v_pk_mul_f32 v[36:37], v[36:37], v[116:117]
	v_pk_mul_f32 v[38:39], v[38:39], v[118:119]
	v_pk_mul_f32 v[40:41], v[40:41], v[120:121]
	v_pk_mul_f32 v[42:43], v[42:43], v[122:123]
	v_pk_mul_f32 v[44:45], v[44:45], v[124:125]
	v_pk_mul_f32 v[46:47], v[46:47], v[126:127]
	v_pk_fma_f32 v[32:33], v[32:33], v[128:129], v[144:145]
	v_pk_fma_f32 v[34:35], v[34:35], v[130:131], v[146:147]
	v_pk_fma_f32 v[36:37], v[36:37], v[132:133], v[148:149]
	v_pk_fma_f32 v[38:39], v[38:39], v[134:135], v[150:151]
	v_pk_fma_f32 v[40:41], v[40:41], v[136:137], v[152:153]
	v_pk_fma_f32 v[42:43], v[42:43], v[138:139], v[154:155]
	v_pk_fma_f32 v[44:45], v[44:45], v[140:141], v[156:157]
	v_pk_fma_f32 v[46:47], v[46:47], v[142:143], v[158:159]
	v_cvt_pk_bf16_f32 v32, v32, v33
	v_cvt_pk_bf16_f32 v33, v34, v35
	v_cvt_pk_bf16_f32 v34, v36, v37
	v_cvt_pk_bf16_f32 v35, v38, v39
	v_cvt_pk_bf16_f32 v36, v40, v41
	v_cvt_pk_bf16_f32 v37, v42, v43
	v_cvt_pk_bf16_f32 v38, v44, v45
	v_cvt_pk_bf16_f32 v39, v46, v47
	s_lshl_b32 s99, s98, 11
	v_lshl_add_u32 v8, v0, 3, s99
	global_store_dwordx2 v8, v[32:33], s[94:95]
	global_store_dwordx2 v8, v[34:35], s[94:95] offset:512
	global_store_dwordx2 v8, v[36:37], s[94:95] offset:1024
	global_store_dwordx2 v8, v[38:39], s[94:95] offset:1536
	s_lshl_b32 s99, s98, 2
	v_mov_b32_e32 v9, s99
	v_mov_b32_e32 v10, 0
	v_cmp_eq_u32_e32 vcc, 0, v0
	s_and_saveexec_b64 s[98:99], vcc
	global_store_dword v9, v10, s[90:91]
	global_store_dword v9, v10, s[92:93]
	s_or_b64 exec, exec, s[98:99]
	s_waitcnt vmcnt(34)
	v_mul_f32_e32 v4, v48, v48
	v_fma_f32 v4, v49, v49, v4
	v_fma_f32 v4, v50, v50, v4
	v_fma_f32 v4, v51, v51, v4
	v_fma_f32 v4, v52, v52, v4
	v_fma_f32 v4, v53, v53, v4
	v_fma_f32 v4, v54, v54, v4
	v_fma_f32 v4, v55, v55, v4
	v_fma_f32 v4, v56, v56, v4
	v_fma_f32 v4, v57, v57, v4
	v_fma_f32 v4, v58, v58, v4
	v_fma_f32 v4, v59, v59, v4
	v_fma_f32 v4, v60, v60, v4
	v_fma_f32 v4, v61, v61, v4
	v_fma_f32 v4, v62, v62, v4
	v_fma_f32 v4, v63, v63, v4
	s_nop 1
	v_add_f32_dpp v5, v4, v4 quad_perm:[1,0,3,2] row_mask:0xf bank_mask:0xf
	s_nop 1
	v_add_f32_dpp v4, v5, v5 quad_perm:[2,3,0,1] row_mask:0xf bank_mask:0xf
	s_nop 1
	v_add_f32_dpp v5, v4, v4 row_half_mirror row_mask:0xf bank_mask:0xf
	s_nop 1
	v_add_f32_dpp v4, v5, v5 row_mirror row_mask:0xf bank_mask:0xf
	s_nop 1
	v_readlane_b32 s98, v4, 0
	v_readlane_b32 s99, v4, 16
	s_nop 3
	v_mov_b32_e32 v5, s98
	v_add_f32_e32 v5, s99, v5
	v_readlane_b32 s98, v4, 32
	v_readlane_b32 s99, v4, 48
	s_nop 3
	v_add_f32_e32 v5, s98, v5
	v_add_f32_e32 v5, s99, v5
	v_mul_f32_e32 v5, 0x3a800000, v5
	v_add_f32_e32 v5, 0x358637bd, v5
	v_rsq_f32_e32 v6, v5
	s_nop 0
	s_add_u32 s98, s97, 3584
	v_pk_mul_f32 v[48:49], v[48:49], v[6:7] op_sel_hi:[1,0]
	v_pk_mul_f32 v[50:51], v[50:51], v[6:7] op_sel_hi:[1,0]
	v_pk_mul_f32 v[52:53], v[52:53], v[6:7] op_sel_hi:[1,0]
	v_pk_mul_f32 v[54:55], v[54:55], v[6:7] op_sel_hi:[1,0]
	v_pk_mul_f32 v[56:57], v[56:57], v[6:7] op_sel_hi:[1,0]
	v_pk_mul_f32 v[58:59], v[58:59], v[6:7] op_sel_hi:[1,0]
	v_pk_mul_f32 v[60:61], v[60:61], v[6:7] op_sel_hi:[1,0]
	v_pk_mul_f32 v[62:63], v[62:63], v[6:7] op_sel_hi:[1,0]
	v_pk_mul_f32 v[48:49], v[48:49], v[112:113]
	v_pk_mul_f32 v[50:51], v[50:51], v[114:115]
	v_pk_mul_f32 v[52:53], v[52:53], v[116:117]
	v_pk_mul_f32 v[54:55], v[54:55], v[118:119]
	v_pk_mul_f32 v[56:57], v[56:57], v[120:121]
	v_pk_mul_f32 v[58:59], v[58:59], v[122:123]
	v_pk_mul_f32 v[60:61], v[60:61], v[124:125]
	v_pk_mul_f32 v[62:63], v[62:63], v[126:127]
	v_pk_fma_f32 v[48:49], v[48:49], v[128:129], v[144:145]
	v_pk_fma_f32 v[50:51], v[50:51], v[130:131], v[146:147]
	v_pk_fma_f32 v[52:53], v[52:53], v[132:133], v[148:149]
	v_pk_fma_f32 v[54:55], v[54:55], v[134:135], v[150:151]
	v_pk_fma_f32 v[56:57], v[56:57], v[136:137], v[152:153]
	v_pk_fma_f32 v[58:59], v[58:59], v[138:139], v[154:155]
	v_pk_fma_f32 v[60:61], v[60:61], v[140:141], v[156:157]
	v_pk_fma_f32 v[62:63], v[62:63], v[142:143], v[158:159]
	v_cvt_pk_bf16_f32 v48, v48, v49
	v_cvt_pk_bf16_f32 v49, v50, v51
	v_cvt_pk_bf16_f32 v50, v52, v53
	v_cvt_pk_bf16_f32 v51, v54, v55
	v_cvt_pk_bf16_f32 v52, v56, v57
	v_cvt_pk_bf16_f32 v53, v58, v59
	v_cvt_pk_bf16_f32 v54, v60, v61
	v_cvt_pk_bf16_f32 v55, v62, v63
	s_lshl_b32 s99, s98, 11
	v_lshl_add_u32 v8, v0, 3, s99
	global_store_dwordx2 v8, v[48:49], s[94:95]
	global_store_dwordx2 v8, v[50:51], s[94:95] offset:512
	global_store_dwordx2 v8, v[52:53], s[94:95] offset:1024
	global_store_dwordx2 v8, v[54:55], s[94:95] offset:1536
	s_lshl_b32 s99, s98, 2
	v_mov_b32_e32 v9, s99
	v_mov_b32_e32 v10, 0
	v_cmp_eq_u32_e32 vcc, 0, v0
	s_and_saveexec_b64 s[98:99], vcc
	global_store_dword v9, v10, s[90:91]
	global_store_dword v9, v10, s[92:93]
	s_or_b64 exec, exec, s[98:99]
	s_waitcnt vmcnt(30)
	v_mul_f32_e32 v4, v64, v64
	v_fma_f32 v4, v65, v65, v4
	v_fma_f32 v4, v66, v66, v4
	v_fma_f32 v4, v67, v67, v4
	v_fma_f32 v4, v68, v68, v4
	v_fma_f32 v4, v69, v69, v4
	v_fma_f32 v4, v70, v70, v4
	v_fma_f32 v4, v71, v71, v4
	v_fma_f32 v4, v72, v72, v4
	v_fma_f32 v4, v73, v73, v4
	v_fma_f32 v4, v74, v74, v4
	v_fma_f32 v4, v75, v75, v4
	v_fma_f32 v4, v76, v76, v4
	v_fma_f32 v4, v77, v77, v4
	v_fma_f32 v4, v78, v78, v4
	v_fma_f32 v4, v79, v79, v4
	s_nop 1
	v_add_f32_dpp v5, v4, v4 quad_perm:[1,0,3,2] row_mask:0xf bank_mask:0xf
	s_nop 1
	v_add_f32_dpp v4, v5, v5 quad_perm:[2,3,0,1] row_mask:0xf bank_mask:0xf
	s_nop 1
	v_add_f32_dpp v5, v4, v4 row_half_mirror row_mask:0xf bank_mask:0xf
	s_nop 1
	v_add_f32_dpp v4, v5, v5 row_mirror row_mask:0xf bank_mask:0xf
	s_nop 1
	v_readlane_b32 s98, v4, 0
	v_readlane_b32 s99, v4, 16
	s_nop 3
	v_mov_b32_e32 v5, s98
	v_add_f32_e32 v5, s99, v5
	v_readlane_b32 s98, v4, 32
	v_readlane_b32 s99, v4, 48
	s_nop 3
	v_add_f32_e32 v5, s98, v5
	v_add_f32_e32 v5, s99, v5
	v_mul_f32_e32 v5, 0x3a800000, v5
	v_add_f32_e32 v5, 0x358637bd, v5
	v_rsq_f32_e32 v6, v5
	s_nop 0
	s_add_u32 s98, s97, 3840
	v_pk_mul_f32 v[64:65], v[64:65], v[6:7] op_sel_hi:[1,0]
	v_pk_mul_f32 v[66:67], v[66:67], v[6:7] op_sel_hi:[1,0]
	v_pk_mul_f32 v[68:69], v[68:69], v[6:7] op_sel_hi:[1,0]
	v_pk_mul_f32 v[70:71], v[70:71], v[6:7] op_sel_hi:[1,0]
	v_pk_mul_f32 v[72:73], v[72:73], v[6:7] op_sel_hi:[1,0]
	v_pk_mul_f32 v[74:75], v[74:75], v[6:7] op_sel_hi:[1,0]
	v_pk_mul_f32 v[76:77], v[76:77], v[6:7] op_sel_hi:[1,0]
	v_pk_mul_f32 v[78:79], v[78:79], v[6:7] op_sel_hi:[1,0]
	v_pk_mul_f32 v[64:65], v[64:65], v[112:113]
	v_pk_mul_f32 v[66:67], v[66:67], v[114:115]
	v_pk_mul_f32 v[68:69], v[68:69], v[116:117]
	v_pk_mul_f32 v[70:71], v[70:71], v[118:119]
	v_pk_mul_f32 v[72:73], v[72:73], v[120:121]
	v_pk_mul_f32 v[74:75], v[74:75], v[122:123]
	v_pk_mul_f32 v[76:77], v[76:77], v[124:125]
	v_pk_mul_f32 v[78:79], v[78:79], v[126:127]
	v_pk_fma_f32 v[64:65], v[64:65], v[128:129], v[144:145]
	v_pk_fma_f32 v[66:67], v[66:67], v[130:131], v[146:147]
	v_pk_fma_f32 v[68:69], v[68:69], v[132:133], v[148:149]
	v_pk_fma_f32 v[70:71], v[70:71], v[134:135], v[150:151]
	v_pk_fma_f32 v[72:73], v[72:73], v[136:137], v[152:153]
	v_pk_fma_f32 v[74:75], v[74:75], v[138:139], v[154:155]
	v_pk_fma_f32 v[76:77], v[76:77], v[140:141], v[156:157]
	v_pk_fma_f32 v[78:79], v[78:79], v[142:143], v[158:159]
	v_cvt_pk_bf16_f32 v64, v64, v65
	v_cvt_pk_bf16_f32 v65, v66, v67
	v_cvt_pk_bf16_f32 v66, v68, v69
	v_cvt_pk_bf16_f32 v67, v70, v71
	v_cvt_pk_bf16_f32 v68, v72, v73
	v_cvt_pk_bf16_f32 v69, v74, v75
	v_cvt_pk_bf16_f32 v70, v76, v77
	v_cvt_pk_bf16_f32 v71, v78, v79
	s_lshl_b32 s99, s98, 11
	v_lshl_add_u32 v8, v0, 3, s99
	global_store_dwordx2 v8, v[64:65], s[94:95]
	global_store_dwordx2 v8, v[66:67], s[94:95] offset:512
	global_store_dwordx2 v8, v[68:69], s[94:95] offset:1024
	global_store_dwordx2 v8, v[70:71], s[94:95] offset:1536
	s_lshl_b32 s99, s98, 2
	v_mov_b32_e32 v9, s99
	v_mov_b32_e32 v10, 0
	v_cmp_eq_u32_e32 vcc, 0, v0
	s_and_saveexec_b64 s[98:99], vcc
	global_store_dword v9, v10, s[90:91]
	global_store_dword v9, v10, s[92:93]
	s_or_b64 exec, exec, s[98:99]
	s_waitcnt vmcnt(0)

.LBB0_2341:
	s_cmp_gt_i32 s44, 10
	s_waitcnt lgkmcnt(0)
	s_cselect_b64 s[2:3], -1, 0
	s_cmp_lt_i32 s45, 11
	s_cselect_b64 s[4:5], -1, 0
	s_or_b64 s[2:3], s[2:3], s[4:5]
	s_and_b64 vcc, exec, s[2:3]
	s_cbranch_vccnz .LBB0_2401
	s_lshl_b32 s96, s22, 3
	s_lshr_b32 s97, s70, 6
	s_add_u32 s96, s96, s97
	s_lshr_b32 s97, s96, 8
	s_lshl_b32 s97, s97, 12
	s_and_b32 s99, s96, 0xff
	s_or_b32 s97, s97, s99
	s_cmpk_ge_u32 s97, 0x8000
	s_cbranch_scc1 .Lnp10_done
	s_load_dwordx2 s[88:89], s[0:1], 0xb8
	s_load_dwordx2 s[90:91], s[0:1], 0x18
	s_load_dwordx2 s[92:93], s[0:1], 0x140
	s_load_dwordx2 s[94:95], s[0:1], 0x158
	v_mbcnt_hi_u32_b32 v0, -1, v210
	v_lshlrev_b32_e32 v1, 4, v0
	s_waitcnt lgkmcnt(0)
	s_add_u32 s90, s90, 8192
	s_addc_u32 s91, s91, 0
	global_load_dwordx4 v[112:115], v1, s[90:91] nt
	global_load_dwordx4 v[116:119], v1, s[90:91] offset:1024 nt
	global_load_dwordx4 v[120:123], v1, s[90:91] offset:2048 nt
	global_load_dwordx4 v[124:127], v1, s[90:91] offset:3072 nt
	s_lshr_b32 s98, s97, 12
	s_add_u32 s98, s98, 16
	s_mul_i32 s98, s98, 0x3000
	s_add_u32 s92, s92, s98
	s_addc_u32 s93, s93, 0
	global_load_dwordx4 v[144:147], v1, s[92:93] nt
	global_load_dwordx4 v[148:151], v1, s[92:93] offset:1024 nt
	global_load_dwordx4 v[152:155], v1, s[92:93] offset:2048 nt
	global_load_dwordx4 v[156:159], v1, s[92:93] offset:3072 nt
	s_add_u32 s92, s92, 0x1000
	s_addc_u32 s93, s93, 0
	global_load_dwordx4 v[128:131], v1, s[92:93] nt
	global_load_dwordx4 v[132:135], v1, s[92:93] offset:1024 nt
	global_load_dwordx4 v[136:139], v1, s[92:93] offset:2048 nt
	global_load_dwordx4 v[140:143], v1, s[92:93] offset:3072 nt
	s_load_dwordx2 s[90:91], s[0:1], 0x210
	s_load_dwordx2 s[92:93], s[0:1], 0x218
	s_waitcnt vmcnt(0) lgkmcnt(0)
	v_pk_add_f32 v[128:129], v[128:129], 1.0 op_sel_hi:[1,0]
	v_pk_add_f32 v[130:131], v[130:131], 1.0 op_sel_hi:[1,0]
	v_pk_add_f32 v[132:133], v[132:133], 1.0 op_sel_hi:[1,0]
	v_pk_add_f32 v[134:135], v[134:135], 1.0 op_sel_hi:[1,0]
	v_pk_add_f32 v[136:137], v[136:137], 1.0 op_sel_hi:[1,0]
	v_pk_add_f32 v[138:139], v[138:139], 1.0 op_sel_hi:[1,0]
	v_pk_add_f32 v[140:141], v[140:141], 1.0 op_sel_hi:[1,0]
	v_pk_add_f32 v[142:143], v[142:143], 1.0 op_sel_hi:[1,0]
	s_add_u32 s98, s97, 0
	s_lshl_b32 s98, s98, 12
	v_add_u32_e32 v3, s98, v1
	global_load_dwordx4 v[16:19], v3, s[88:89] nt
	global_load_dwordx4 v[20:23], v3, s[88:89] offset:1024 nt
	global_load_dwordx4 v[24:27], v3, s[88:89] offset:2048 nt
	global_load_dwordx4 v[28:31], v3, s[88:89] offset:3072 nt
	s_add_u32 s98, s97, 256
	s_lshl_b32 s98, s98, 12
	v_add_u32_e32 v3, s98, v1
	global_load_dwordx4 v[32:35], v3, s[88:89] nt
	global_load_dwordx4 v[36:39], v3, s[88:89] offset:1024 nt
	global_load_dwordx4 v[40:43], v3, s[88:89] offset:2048 nt
	global_load_dwordx4 v[44:47], v3, s[88:89] offset:3072 nt
	s_add_u32 s98, s97, 512
	s_lshl_b32 s98, s98, 12
	v_add_u32_e32 v3, s98, v1
	global_load_dwordx4 v[48:51], v3, s[88:89] nt
	global_load_dwordx4 v[52:55], v3, s[88:89] offset:1024 nt
	global_load_dwordx4 v[56:59], v3, s[88:89] offset:2048 nt
	global_load_dwordx4 v[60:63], v3, s[88:89] offset:3072 nt
	s_add_u32 s98, s97, 768
	s_lshl_b32 s98, s98, 12
	v_add_u32_e32 v3, s98, v1
	global_load_dwordx4 v[64:67], v3, s[88:89] nt
	global_load_dwordx4 v[68:71], v3, s[88:89] offset:1024 nt
	global_load_dwordx4 v[72:75], v3, s[88:89] offset:2048 nt
	global_load_dwordx4 v[76:79], v3, s[88:89] offset:3072 nt
	s_add_u32 s98, s97, 1024
	s_lshl_b32 s98, s98, 12
	v_add_u32_e32 v3, s98, v1
	global_load_dwordx4 v[80:83], v3, s[88:89] nt
	global_load_dwordx4 v[84:87], v3, s[88:89] offset:1024 nt
	global_load_dwordx4 v[88:91], v3, s[88:89] offset:2048 nt
	global_load_dwordx4 v[92:95], v3, s[88:89] offset:3072 nt
	s_add_u32 s98, s97, 1280
	s_lshl_b32 s98, s98, 12
	v_add_u32_e32 v3, s98, v1
	global_load_dwordx4 v[96:99], v3, s[88:89] nt
	global_load_dwordx4 v[100:103], v3, s[88:89] offset:1024 nt
	global_load_dwordx4 v[104:107], v3, s[88:89] offset:2048 nt
	global_load_dwordx4 v[108:111], v3, s[88:89] offset:3072 nt
	s_waitcnt vmcnt(20)
	v_mul_f32_e32 v4, v16, v16
	v_fma_f32 v4, v17, v17, v4
	v_fma_f32 v4, v18, v18, v4
	v_fma_f32 v4, v19, v19, v4
	v_fma_f32 v4, v20, v20, v4
	v_fma_f32 v4, v21, v21, v4
	v_fma_f32 v4, v22, v22, v4
	v_fma_f32 v4, v23, v23, v4
	v_fma_f32 v4, v24, v24, v4
	v_fma_f32 v4, v25, v25, v4
	v_fma_f32 v4, v26, v26, v4
	v_fma_f32 v4, v27, v27, v4
	v_fma_f32 v4, v28, v28, v4
	v_fma_f32 v4, v29, v29, v4
	v_fma_f32 v4, v30, v30, v4
	v_fma_f32 v4, v31, v31, v4
	s_nop 1
	v_add_f32_dpp v5, v4, v4 quad_perm:[1,0,3,2] row_mask:0xf bank_mask:0xf
	s_nop 1
	v_add_f32_dpp v4, v5, v5 quad_perm:[2,3,0,1] row_mask:0xf bank_mask:0xf
	s_nop 1
	v_add_f32_dpp v5, v4, v4 row_half_mirror row_mask:0xf bank_mask:0xf
	s_nop 1
	v_add_f32_dpp v4, v5, v5 row_mirror row_mask:0xf bank_mask:0xf
	s_nop 1
	v_readlane_b32 s98, v4, 0
	v_readlane_b32 s99, v4, 16
	s_nop 3
	v_mov_b32_e32 v5, s98
	v_add_f32_e32 v5, s99, v5
	v_readlane_b32 s98, v4, 32
	v_readlane_b32 s99, v4, 48
	s_nop 3
	v_add_f32_e32 v5, s98, v5
	v_add_f32_e32 v5, s99, v5
	v_mul_f32_e32 v5, 0x3a800000, v5
	v_add_f32_e32 v5, 0x358637bd, v5
	v_rsq_f32_e32 v6, v5
	s_nop 0
	s_add_u32 s98, s97, 0
	v_pk_mul_f32 v[16:17], v[16:17], v[6:7] op_sel_hi:[1,0]
	v_pk_mul_f32 v[18:19], v[18:19], v[6:7] op_sel_hi:[1,0]
	v_pk_mul_f32 v[20:21], v[20:21], v[6:7] op_sel_hi:[1,0]
	v_pk_mul_f32 v[22:23], v[22:23], v[6:7] op_sel_hi:[1,0]
	v_pk_mul_f32 v[24:25], v[24:25], v[6:7] op_sel_hi:[1,0]
	v_pk_mul_f32 v[26:27], v[26:27], v[6:7] op_sel_hi:[1,0]
	v_pk_mul_f32 v[28:29], v[28:29], v[6:7] op_sel_hi:[1,0]
	v_pk_mul_f32 v[30:31], v[30:31], v[6:7] op_sel_hi:[1,0]
	v_pk_mul_f32 v[16:17], v[16:17], v[112:113]
	v_pk_mul_f32 v[18:19], v[18:19], v[114:115]
	v_pk_mul_f32 v[20:21], v[20:21], v[116:117]
	v_pk_mul_f32 v[22:23], v[22:23], v[118:119]
	v_pk_mul_f32 v[24:25], v[24:25], v[120:121]
	v_pk_mul_f32 v[26:27], v[26:27], v[122:123]
	v_pk_mul_f32 v[28:29], v[28:29], v[124:125]
	v_pk_mul_f32 v[30:31], v[30:31], v[126:127]
	v_pk_fma_f32 v[16:17], v[16:17], v[128:129], v[144:145]
	v_pk_fma_f32 v[18:19], v[18:19], v[130:131], v[146:147]
	v_pk_fma_f32 v[20:21], v[20:21], v[132:133], v[148:149]
	v_pk_fma_f32 v[22:23], v[22:23], v[134:135], v[150:151]
	v_pk_fma_f32 v[24:25], v[24:25], v[136:137], v[152:153]
	v_pk_fma_f32 v[26:27], v[26:27], v[138:139], v[154:155]
	v_pk_fma_f32 v[28:29], v[28:29], v[140:141], v[156:157]
	v_pk_fma_f32 v[30:31], v[30:31], v[142:143], v[158:159]
	v_cvt_pk_bf16_f32 v16, v16, v17
	v_cvt_pk_bf16_f32 v17, v18, v19
	v_cvt_pk_bf16_f32 v18, v20, v21
	v_cvt_pk_bf16_f32 v19, v22, v23
	v_cvt_pk_bf16_f32 v20, v24, v25
	v_cvt_pk_bf16_f32 v21, v26, v27
	v_cvt_pk_bf16_f32 v22, v28, v29
	v_cvt_pk_bf16_f32 v23, v30, v31
	s_lshl_b32 s99, s98, 11
	v_lshl_add_u32 v8, v0, 3, s99
	global_store_dwordx2 v8, v[16:17], s[94:95]
	global_store_dwordx2 v8, v[18:19], s[94:95] offset:512
	global_store_dwordx2 v8, v[20:21], s[94:95] offset:1024
	global_store_dwordx2 v8, v[22:23], s[94:95] offset:1536
	s_lshl_b32 s99, s98, 2
	v_mov_b32_e32 v9, s99
	v_mov_b32_e32 v10, 0
	v_cmp_eq_u32_e32 vcc, 0, v0
	s_and_saveexec_b64 s[98:99], vcc
	global_store_dword v9, v10, s[90:91]
	global_store_dword v9, v10, s[92:93]
	s_or_b64 exec, exec, s[98:99]
	s_add_u32 s98, s97, 1536
	s_lshl_b32 s98, s98, 12
	v_add_u32_e32 v3, s98, v1
	global_load_dwordx4 v[16:19], v3, s[88:89] nt
	global_load_dwordx4 v[20:23], v3, s[88:89] offset:1024 nt
	global_load_dwordx4 v[24:27], v3, s[88:89] offset:2048 nt
	global_load_dwordx4 v[28:31], v3, s[88:89] offset:3072 nt
	s_waitcnt vmcnt(26)
	v_mul_f32_e32 v4, v32, v32
	v_fma_f32 v4, v33, v33, v4
	v_fma_f32 v4, v34, v34, v4
	v_fma_f32 v4, v35, v35, v4
	v_fma_f32 v4, v36, v36, v4
	v_fma_f32 v4, v37, v37, v4
	v_fma_f32 v4, v38, v38, v4
	v_fma_f32 v4, v39, v39, v4
	v_fma_f32 v4, v40, v40, v4
	v_fma_f32 v4, v41, v41, v4
	v_fma_f32 v4, v42, v42, v4
	v_fma_f32 v4, v43, v43, v4
	v_fma_f32 v4, v44, v44, v4
	v_fma_f32 v4, v45, v45, v4
	v_fma_f32 v4, v46, v46, v4
	v_fma_f32 v4, v47, v47, v4
	s_nop 1
	v_add_f32_dpp v5, v4, v4 quad_perm:[1,0,3,2] row_mask:0xf bank_mask:0xf
	s_nop 1
	v_add_f32_dpp v4, v5, v5 quad_perm:[2,3,0,1] row_mask:0xf bank_mask:0xf
	s_nop 1
	v_add_f32_dpp v5, v4, v4 row_half_mirror row_mask:0xf bank_mask:0xf
	s_nop 1
	v_add_f32_dpp v4, v5, v5 row_mirror row_mask:0xf bank_mask:0xf
	s_nop 1
	v_readlane_b32 s98, v4, 0
	v_readlane_b32 s99, v4, 16
	s_nop 3
	v_mov_b32_e32 v5, s98
	v_add_f32_e32 v5, s99, v5
	v_readlane_b32 s98, v4, 32
	v_readlane_b32 s99, v4, 48
	s_nop 3
	v_add_f32_e32 v5, s98, v5
	v_add_f32_e32 v5, s99, v5
	v_mul_f32_e32 v5, 0x3a800000, v5
	v_add_f32_e32 v5, 0x358637bd, v5
	v_rsq_f32_e32 v6, v5
	s_nop 0
	s_add_u32 s98, s97, 256
	v_pk_mul_f32 v[32:33], v[32:33], v[6:7] op_sel_hi:[1,0]
	v_pk_mul_f32 v[34:35], v[34:35], v[6:7] op_sel_hi:[1,0]
	v_pk_mul_f32 v[36:37], v[36:37], v[6:7] op_sel_hi:[1,0]
	v_pk_mul_f32 v[38:39], v[38:39], v[6:7] op_sel_hi:[1,0]
	v_pk_mul_f32 v[40:41], v[40:41], v[6:7] op_sel_hi:[1,0]
	v_pk_mul_f32 v[42:43], v[42:43], v[6:7] op_sel_hi:[1,0]
	v_pk_mul_f32 v[44:45], v[44:45], v[6:7] op_sel_hi:[1,0]
	v_pk_mul_f32 v[46:47], v[46:47], v[6:7] op_sel_hi:[1,0]
	v_pk_mul_f32 v[32:33], v[32:33], v[112:113]
	v_pk_mul_f32 v[34:35], v[34:35], v[114:115]
	v_pk_mul_f32 v[36:37], v[36:37], v[116:117]
	v_pk_mul_f32 v[38:39], v[38:39], v[118:119]
	v_pk_mul_f32 v[40:41], v[40:41], v[120:121]
	v_pk_mul_f32 v[42:43], v[42:43], v[122:123]
	v_pk_mul_f32 v[44:45], v[44:45], v[124:125]
	v_pk_mul_f32 v[46:47], v[46:47], v[126:127]
	v_pk_fma_f32 v[32:33], v[32:33], v[128:129], v[144:145]
	v_pk_fma_f32 v[34:35], v[34:35], v[130:131], v[146:147]
	v_pk_fma_f32 v[36:37], v[36:37], v[132:133], v[148:149]
	v_pk_fma_f32 v[38:39], v[38:39], v[134:135], v[150:151]
	v_pk_fma_f32 v[40:41], v[40:41], v[136:137], v[152:153]
	v_pk_fma_f32 v[42:43], v[42:43], v[138:139], v[154:155]
	v_pk_fma_f32 v[44:45], v[44:45], v[140:141], v[156:157]
	v_pk_fma_f32 v[46:47], v[46:47], v[142:143], v[158:159]
	v_cvt_pk_bf16_f32 v32, v32, v33
	v_cvt_pk_bf16_f32 v33, v34, v35
	v_cvt_pk_bf16_f32 v34, v36, v37
	v_cvt_pk_bf16_f32 v35, v38, v39
	v_cvt_pk_bf16_f32 v36, v40, v41
	v_cvt_pk_bf16_f32 v37, v42, v43
	v_cvt_pk_bf16_f32 v38, v44, v45
	v_cvt_pk_bf16_f32 v39, v46, v47
	s_lshl_b32 s99, s98, 11
	v_lshl_add_u32 v8, v0, 3, s99
	global_store_dwordx2 v8, v[32:33], s[94:95]
	global_store_dwordx2 v8, v[34:35], s[94:95] offset:512
	global_store_dwordx2 v8, v[36:37], s[94:95] offset:1024
	global_store_dwordx2 v8, v[38:39], s[94:95] offset:1536
	s_lshl_b32 s99, s98, 2
	v_mov_b32_e32 v9, s99
	v_mov_b32_e32 v10, 0
	v_cmp_eq_u32_e32 vcc, 0, v0
	s_and_saveexec_b64 s[98:99], vcc
	global_store_dword v9, v10, s[90:91]
	global_store_dword v9, v10, s[92:93]
	s_or_b64 exec, exec, s[98:99]
	s_add_u32 s98, s97, 1792
	s_lshl_b32 s98, s98, 12
	v_add_u32_e32 v3, s98, v1
	global_load_dwordx4 v[32:35], v3, s[88:89] nt
	global_load_dwordx4 v[36:39], v3, s[88:89] offset:1024 nt
	global_load_dwordx4 v[40:43], v3, s[88:89] offset:2048 nt
	global_load_dwordx4 v[44:47], v3, s[88:89] offset:3072 nt
	s_waitcnt vmcnt(32)
	v_mul_f32_e32 v4, v48, v48
	v_fma_f32 v4, v49, v49, v4
	v_fma_f32 v4, v50, v50, v4
	v_fma_f32 v4, v51, v51, v4
	v_fma_f32 v4, v52, v52, v4
	v_fma_f32 v4, v53, v53, v4
	v_fma_f32 v4, v54, v54, v4
	v_fma_f32 v4, v55, v55, v4
	v_fma_f32 v4, v56, v56, v4
	v_fma_f32 v4, v57, v57, v4
	v_fma_f32 v4, v58, v58, v4
	v_fma_f32 v4, v59, v59, v4
	v_fma_f32 v4, v60, v60, v4
	v_fma_f32 v4, v61, v61, v4
	v_fma_f32 v4, v62, v62, v4
	v_fma_f32 v4, v63, v63, v4
	s_nop 1
	v_add_f32_dpp v5, v4, v4 quad_perm:[1,0,3,2] row_mask:0xf bank_mask:0xf
	s_nop 1
	v_add_f32_dpp v4, v5, v5 quad_perm:[2,3,0,1] row_mask:0xf bank_mask:0xf
	s_nop 1
	v_add_f32_dpp v5, v4, v4 row_half_mirror row_mask:0xf bank_mask:0xf
	s_nop 1
	v_add_f32_dpp v4, v5, v5 row_mirror row_mask:0xf bank_mask:0xf
	s_nop 1
	v_readlane_b32 s98, v4, 0
	v_readlane_b32 s99, v4, 16
	s_nop 3
	v_mov_b32_e32 v5, s98
	v_add_f32_e32 v5, s99, v5
	v_readlane_b32 s98, v4, 32
	v_readlane_b32 s99, v4, 48
	s_nop 3
	v_add_f32_e32 v5, s98, v5
	v_add_f32_e32 v5, s99, v5
	v_mul_f32_e32 v5, 0x3a800000, v5
	v_add_f32_e32 v5, 0x358637bd, v5
	v_rsq_f32_e32 v6, v5
	s_nop 0
	s_add_u32 s98, s97, 512
	v_pk_mul_f32 v[48:49], v[48:49], v[6:7] op_sel_hi:[1,0]
	v_pk_mul_f32 v[50:51], v[50:51], v[6:7] op_sel_hi:[1,0]
	v_pk_mul_f32 v[52:53], v[52:53], v[6:7] op_sel_hi:[1,0]
	v_pk_mul_f32 v[54:55], v[54:55], v[6:7] op_sel_hi:[1,0]
	v_pk_mul_f32 v[56:57], v[56:57], v[6:7] op_sel_hi:[1,0]
	v_pk_mul_f32 v[58:59], v[58:59], v[6:7] op_sel_hi:[1,0]
	v_pk_mul_f32 v[60:61], v[60:61], v[6:7] op_sel_hi:[1,0]
	v_pk_mul_f32 v[62:63], v[62:63], v[6:7] op_sel_hi:[1,0]
	v_pk_mul_f32 v[48:49], v[48:49], v[112:113]
	v_pk_mul_f32 v[50:51], v[50:51], v[114:115]
	v_pk_mul_f32 v[52:53], v[52:53], v[116:117]
	v_pk_mul_f32 v[54:55], v[54:55], v[118:119]
	v_pk_mul_f32 v[56:57], v[56:57], v[120:121]
	v_pk_mul_f32 v[58:59], v[58:59], v[122:123]
	v_pk_mul_f32 v[60:61], v[60:61], v[124:125]
	v_pk_mul_f32 v[62:63], v[62:63], v[126:127]
	v_pk_fma_f32 v[48:49], v[48:49], v[128:129], v[144:145]
	v_pk_fma_f32 v[50:51], v[50:51], v[130:131], v[146:147]
	v_pk_fma_f32 v[52:53], v[52:53], v[132:133], v[148:149]
	v_pk_fma_f32 v[54:55], v[54:55], v[134:135], v[150:151]
	v_pk_fma_f32 v[56:57], v[56:57], v[136:137], v[152:153]
	v_pk_fma_f32 v[58:59], v[58:59], v[138:139], v[154:155]
	v_pk_fma_f32 v[60:61], v[60:61], v[140:141], v[156:157]
	v_pk_fma_f32 v[62:63], v[62:63], v[142:143], v[158:159]
	v_cvt_pk_bf16_f32 v48, v48, v49
	v_cvt_pk_bf16_f32 v49, v50, v51
	v_cvt_pk_bf16_f32 v50, v52, v53
	v_cvt_pk_bf16_f32 v51, v54, v55
	v_cvt_pk_bf16_f32 v52, v56, v57
	v_cvt_pk_bf16_f32 v53, v58, v59
	v_cvt_pk_bf16_f32 v54, v60, v61
	v_cvt_pk_bf16_f32 v55, v62, v63
	s_lshl_b32 s99, s98, 11
	v_lshl_add_u32 v8, v0, 3, s99
	global_store_dwordx2 v8, v[48:49], s[94:95]
	global_store_dwordx2 v8, v[50:51], s[94:95] offset:512
	global_store_dwordx2 v8, v[52:53], s[94:95] offset:1024
	global_store_dwordx2 v8, v[54:55], s[94:95] offset:1536
	s_lshl_b32 s99, s98, 2
	v_mov_b32_e32 v9, s99
	v_mov_b32_e32 v10, 0
	v_cmp_eq_u32_e32 vcc, 0, v0
	s_and_saveexec_b64 s[98:99], vcc
	global_store_dword v9, v10, s[90:91]
	global_store_dword v9, v10, s[92:93]
	s_or_b64 exec, exec, s[98:99]
	s_add_u32 s98, s97, 2048
	s_lshl_b32 s98, s98, 12
	v_add_u32_e32 v3, s98, v1
	global_load_dwordx4 v[48:51], v3, s[88:89] nt
	global_load_dwordx4 v[52:55], v3, s[88:89] offset:1024 nt
	global_load_dwordx4 v[56:59], v3, s[88:89] offset:2048 nt
	global_load_dwordx4 v[60:63], v3, s[88:89] offset:3072 nt
	s_waitcnt vmcnt(38)
	v_mul_f32_e32 v4, v64, v64
	v_fma_f32 v4, v65, v65, v4
	v_fma_f32 v4, v66, v66, v4
	v_fma_f32 v4, v67, v67, v4
	v_fma_f32 v4, v68, v68, v4
	v_fma_f32 v4, v69, v69, v4
	v_fma_f32 v4, v70, v70, v4
	v_fma_f32 v4, v71, v71, v4
	v_fma_f32 v4, v72, v72, v4
	v_fma_f32 v4, v73, v73, v4
	v_fma_f32 v4, v74, v74, v4
	v_fma_f32 v4, v75, v75, v4
	v_fma_f32 v4, v76, v76, v4
	v_fma_f32 v4, v77, v77, v4
	v_fma_f32 v4, v78, v78, v4
	v_fma_f32 v4, v79, v79, v4
	s_nop 1
	v_add_f32_dpp v5, v4, v4 quad_perm:[1,0,3,2] row_mask:0xf bank_mask:0xf
	s_nop 1
	v_add_f32_dpp v4, v5, v5 quad_perm:[2,3,0,1] row_mask:0xf bank_mask:0xf
	s_nop 1
	v_add_f32_dpp v5, v4, v4 row_half_mirror row_mask:0xf bank_mask:0xf
	s_nop 1
	v_add_f32_dpp v4, v5, v5 row_mirror row_mask:0xf bank_mask:0xf
	s_nop 1
	v_readlane_b32 s98, v4, 0
	v_readlane_b32 s99, v4, 16
	s_nop 3
	v_mov_b32_e32 v5, s98
	v_add_f32_e32 v5, s99, v5
	v_readlane_b32 s98, v4, 32
	v_readlane_b32 s99, v4, 48
	s_nop 3
	v_add_f32_e32 v5, s98, v5
	v_add_f32_e32 v5, s99, v5
	v_mul_f32_e32 v5, 0x3a800000, v5
	v_add_f32_e32 v5, 0x358637bd, v5
	v_rsq_f32_e32 v6, v5
	s_nop 0
	s_add_u32 s98, s97, 768
	v_pk_mul_f32 v[64:65], v[64:65], v[6:7] op_sel_hi:[1,0]
	v_pk_mul_f32 v[66:67], v[66:67], v[6:7] op_sel_hi:[1,0]
	v_pk_mul_f32 v[68:69], v[68:69], v[6:7] op_sel_hi:[1,0]
	v_pk_mul_f32 v[70:71], v[70:71], v[6:7] op_sel_hi:[1,0]
	v_pk_mul_f32 v[72:73], v[72:73], v[6:7] op_sel_hi:[1,0]
	v_pk_mul_f32 v[74:75], v[74:75], v[6:7] op_sel_hi:[1,0]
	v_pk_mul_f32 v[76:77], v[76:77], v[6:7] op_sel_hi:[1,0]
	v_pk_mul_f32 v[78:79], v[78:79], v[6:7] op_sel_hi:[1,0]
	v_pk_mul_f32 v[64:65], v[64:65], v[112:113]
	v_pk_mul_f32 v[66:67], v[66:67], v[114:115]
	v_pk_mul_f32 v[68:69], v[68:69], v[116:117]
	v_pk_mul_f32 v[70:71], v[70:71], v[118:119]
	v_pk_mul_f32 v[72:73], v[72:73], v[120:121]
	v_pk_mul_f32 v[74:75], v[74:75], v[122:123]
	v_pk_mul_f32 v[76:77], v[76:77], v[124:125]
	v_pk_mul_f32 v[78:79], v[78:79], v[126:127]
	v_pk_fma_f32 v[64:65], v[64:65], v[128:129], v[144:145]
	v_pk_fma_f32 v[66:67], v[66:67], v[130:131], v[146:147]
	v_pk_fma_f32 v[68:69], v[68:69], v[132:133], v[148:149]
	v_pk_fma_f32 v[70:71], v[70:71], v[134:135], v[150:151]
	v_pk_fma_f32 v[72:73], v[72:73], v[136:137], v[152:153]
	v_pk_fma_f32 v[74:75], v[74:75], v[138:139], v[154:155]
	v_pk_fma_f32 v[76:77], v[76:77], v[140:141], v[156:157]
	v_pk_fma_f32 v[78:79], v[78:79], v[142:143], v[158:159]
	v_cvt_pk_bf16_f32 v64, v64, v65
	v_cvt_pk_bf16_f32 v65, v66, v67
	v_cvt_pk_bf16_f32 v66, v68, v69
	v_cvt_pk_bf16_f32 v67, v70, v71
	v_cvt_pk_bf16_f32 v68, v72, v73
	v_cvt_pk_bf16_f32 v69, v74, v75
	v_cvt_pk_bf16_f32 v70, v76, v77
	v_cvt_pk_bf16_f32 v71, v78, v79
	s_lshl_b32 s99, s98, 11
	v_lshl_add_u32 v8, v0, 3, s99
	global_store_dwordx2 v8, v[64:65], s[94:95]
	global_store_dwordx2 v8, v[66:67], s[94:95] offset:512
	global_store_dwordx2 v8, v[68:69], s[94:95] offset:1024
	global_store_dwordx2 v8, v[70:71], s[94:95] offset:1536
	s_lshl_b32 s99, s98, 2
	v_mov_b32_e32 v9, s99
	v_mov_b32_e32 v10, 0
	v_cmp_eq_u32_e32 vcc, 0, v0
	s_and_saveexec_b64 s[98:99], vcc
	global_store_dword v9, v10, s[90:91]
	global_store_dword v9, v10, s[92:93]
	s_or_b64 exec, exec, s[98:99]
	s_add_u32 s98, s97, 2304
	s_lshl_b32 s98, s98, 12
	v_add_u32_e32 v3, s98, v1
	global_load_dwordx4 v[64:67], v3, s[88:89] nt
	global_load_dwordx4 v[68:71], v3, s[88:89] offset:1024 nt
	global_load_dwordx4 v[72:75], v3, s[88:89] offset:2048 nt
	global_load_dwordx4 v[76:79], v3, s[88:89] offset:3072 nt
	s_waitcnt vmcnt(44)
	v_mul_f32_e32 v4, v80, v80
	v_fma_f32 v4, v81, v81, v4
	v_fma_f32 v4, v82, v82, v4
	v_fma_f32 v4, v83, v83, v4
	v_fma_f32 v4, v84, v84, v4
	v_fma_f32 v4, v85, v85, v4
	v_fma_f32 v4, v86, v86, v4
	v_fma_f32 v4, v87, v87, v4
	v_fma_f32 v4, v88, v88, v4
	v_fma_f32 v4, v89, v89, v4
	v_fma_f32 v4, v90, v90, v4
	v_fma_f32 v4, v91, v91, v4
	v_fma_f32 v4, v92, v92, v4
	v_fma_f32 v4, v93, v93, v4
	v_fma_f32 v4, v94, v94, v4
	v_fma_f32 v4, v95, v95, v4
	s_nop 1
	v_add_f32_dpp v5, v4, v4 quad_perm:[1,0,3,2] row_mask:0xf bank_mask:0xf
	s_nop 1
	v_add_f32_dpp v4, v5, v5 quad_perm:[2,3,0,1] row_mask:0xf bank_mask:0xf
	s_nop 1
	v_add_f32_dpp v5, v4, v4 row_half_mirror row_mask:0xf bank_mask:0xf
	s_nop 1
	v_add_f32_dpp v4, v5, v5 row_mirror row_mask:0xf bank_mask:0xf
	s_nop 1
	v_readlane_b32 s98, v4, 0
	v_readlane_b32 s99, v4, 16
	s_nop 3
	v_mov_b32_e32 v5, s98
	v_add_f32_e32 v5, s99, v5
	v_readlane_b32 s98, v4, 32
	v_readlane_b32 s99, v4, 48
	s_nop 3
	v_add_f32_e32 v5, s98, v5
	v_add_f32_e32 v5, s99, v5
	v_mul_f32_e32 v5, 0x3a800000, v5
	v_add_f32_e32 v5, 0x358637bd, v5
	v_rsq_f32_e32 v6, v5
	s_nop 0
	s_add_u32 s98, s97, 1024
	v_pk_mul_f32 v[80:81], v[80:81], v[6:7] op_sel_hi:[1,0]
	v_pk_mul_f32 v[82:83], v[82:83], v[6:7] op_sel_hi:[1,0]
	v_pk_mul_f32 v[84:85], v[84:85], v[6:7] op_sel_hi:[1,0]
	v_pk_mul_f32 v[86:87], v[86:87], v[6:7] op_sel_hi:[1,0]
	v_pk_mul_f32 v[88:89], v[88:89], v[6:7] op_sel_hi:[1,0]
	v_pk_mul_f32 v[90:91], v[90:91], v[6:7] op_sel_hi:[1,0]
	v_pk_mul_f32 v[92:93], v[92:93], v[6:7] op_sel_hi:[1,0]
	v_pk_mul_f32 v[94:95], v[94:95], v[6:7] op_sel_hi:[1,0]
	v_pk_mul_f32 v[80:81], v[80:81], v[112:113]
	v_pk_mul_f32 v[82:83], v[82:83], v[114:115]
	v_pk_mul_f32 v[84:85], v[84:85], v[116:117]
	v_pk_mul_f32 v[86:87], v[86:87], v[118:119]
	v_pk_mul_f32 v[88:89], v[88:89], v[120:121]
	v_pk_mul_f32 v[90:91], v[90:91], v[122:123]
	v_pk_mul_f32 v[92:93], v[92:93], v[124:125]
	v_pk_mul_f32 v[94:95], v[94:95], v[126:127]
	v_pk_fma_f32 v[80:81], v[80:81], v[128:129], v[144:145]
	v_pk_fma_f32 v[82:83], v[82:83], v[130:131], v[146:147]
	v_pk_fma_f32 v[84:85], v[84:85], v[132:133], v[148:149]
	v_pk_fma_f32 v[86:87], v[86:87], v[134:135], v[150:151]
	v_pk_fma_f32 v[88:89], v[88:89], v[136:137], v[152:153]
	v_pk_fma_f32 v[90:91], v[90:91], v[138:139], v[154:155]
	v_pk_fma_f32 v[92:93], v[92:93], v[140:141], v[156:157]
	v_pk_fma_f32 v[94:95], v[94:95], v[142:143], v[158:159]
	v_cvt_pk_bf16_f32 v80, v80, v81
	v_cvt_pk_bf16_f32 v81, v82, v83
	v_cvt_pk_bf16_f32 v82, v84, v85
	v_cvt_pk_bf16_f32 v83, v86, v87
	v_cvt_pk_bf16_f32 v84, v88, v89
	v_cvt_pk_bf16_f32 v85, v90, v91
	v_cvt_pk_bf16_f32 v86, v92, v93
	v_cvt_pk_bf16_f32 v87, v94, v95
	s_lshl_b32 s99, s98, 11
	v_lshl_add_u32 v8, v0, 3, s99
	global_store_dwordx2 v8, v[80:81], s[94:95]
	global_store_dwordx2 v8, v[82:83], s[94:95] offset:512
	global_store_dwordx2 v8, v[84:85], s[94:95] offset:1024
	global_store_dwordx2 v8, v[86:87], s[94:95] offset:1536
	s_lshl_b32 s99, s98, 2
	v_mov_b32_e32 v9, s99
	v_mov_b32_e32 v10, 0
	v_cmp_eq_u32_e32 vcc, 0, v0
	s_and_saveexec_b64 s[98:99], vcc
	global_store_dword v9, v10, s[90:91]
	global_store_dword v9, v10, s[92:93]
	s_or_b64 exec, exec, s[98:99]
	s_add_u32 s98, s97, 2560
	s_lshl_b32 s98, s98, 12
	v_add_u32_e32 v3, s98, v1
	global_load_dwordx4 v[80:83], v3, s[88:89] nt
	global_load_dwordx4 v[84:87], v3, s[88:89] offset:1024 nt
	global_load_dwordx4 v[88:91], v3, s[88:89] offset:2048 nt
	global_load_dwordx4 v[92:95], v3, s[88:89] offset:3072 nt
	s_waitcnt vmcnt(50)
	v_mul_f32_e32 v4, v96, v96
	v_fma_f32 v4, v97, v97, v4
	v_fma_f32 v4, v98, v98, v4
	v_fma_f32 v4, v99, v99, v4
	v_fma_f32 v4, v100, v100, v4
	v_fma_f32 v4, v101, v101, v4
	v_fma_f32 v4, v102, v102, v4
	v_fma_f32 v4, v103, v103, v4
	v_fma_f32 v4, v104, v104, v4
	v_fma_f32 v4, v105, v105, v4
	v_fma_f32 v4, v106, v106, v4
	v_fma_f32 v4, v107, v107, v4
	v_fma_f32 v4, v108, v108, v4
	v_fma_f32 v4, v109, v109, v4
	v_fma_f32 v4, v110, v110, v4
	v_fma_f32 v4, v111, v111, v4
	s_nop 1
	v_add_f32_dpp v5, v4, v4 quad_perm:[1,0,3,2] row_mask:0xf bank_mask:0xf
	s_nop 1
	v_add_f32_dpp v4, v5, v5 quad_perm:[2,3,0,1] row_mask:0xf bank_mask:0xf
	s_nop 1
	v_add_f32_dpp v5, v4, v4 row_half_mirror row_mask:0xf bank_mask:0xf
	s_nop 1
	v_add_f32_dpp v4, v5, v5 row_mirror row_mask:0xf bank_mask:0xf
	s_nop 1
	v_readlane_b32 s98, v4, 0
	v_readlane_b32 s99, v4, 16
	s_nop 3
	v_mov_b32_e32 v5, s98
	v_add_f32_e32 v5, s99, v5
	v_readlane_b32 s98, v4, 32
	v_readlane_b32 s99, v4, 48
	s_nop 3
	v_add_f32_e32 v5, s98, v5
	v_add_f32_e32 v5, s99, v5
	v_mul_f32_e32 v5, 0x3a800000, v5
	v_add_f32_e32 v5, 0x358637bd, v5
	v_rsq_f32_e32 v6, v5
	s_nop 0
	s_add_u32 s98, s97, 1280
	v_pk_mul_f32 v[96:97], v[96:97], v[6:7] op_sel_hi:[1,0]
	v_pk_mul_f32 v[98:99], v[98:99], v[6:7] op_sel_hi:[1,0]
	v_pk_mul_f32 v[100:101], v[100:101], v[6:7] op_sel_hi:[1,0]
	v_pk_mul_f32 v[102:103], v[102:103], v[6:7] op_sel_hi:[1,0]
	v_pk_mul_f32 v[104:105], v[104:105], v[6:7] op_sel_hi:[1,0]
	v_pk_mul_f32 v[106:107], v[106:107], v[6:7] op_sel_hi:[1,0]
	v_pk_mul_f32 v[108:109], v[108:109], v[6:7] op_sel_hi:[1,0]
	v_pk_mul_f32 v[110:111], v[110:111], v[6:7] op_sel_hi:[1,0]
	v_pk_mul_f32 v[96:97], v[96:97], v[112:113]
	v_pk_mul_f32 v[98:99], v[98:99], v[114:115]
	v_pk_mul_f32 v[100:101], v[100:101], v[116:117]
	v_pk_mul_f32 v[102:103], v[102:103], v[118:119]
	v_pk_mul_f32 v[104:105], v[104:105], v[120:121]
	v_pk_mul_f32 v[106:107], v[106:107], v[122:123]
	v_pk_mul_f32 v[108:109], v[108:109], v[124:125]
	v_pk_mul_f32 v[110:111], v[110:111], v[126:127]
	v_pk_fma_f32 v[96:97], v[96:97], v[128:129], v[144:145]
	v_pk_fma_f32 v[98:99], v[98:99], v[130:131], v[146:147]
	v_pk_fma_f32 v[100:101], v[100:101], v[132:133], v[148:149]
	v_pk_fma_f32 v[102:103], v[102:103], v[134:135], v[150:151]
	v_pk_fma_f32 v[104:105], v[104:105], v[136:137], v[152:153]
	v_pk_fma_f32 v[106:107], v[106:107], v[138:139], v[154:155]
	v_pk_fma_f32 v[108:109], v[108:109], v[140:141], v[156:157]
	v_pk_fma_f32 v[110:111], v[110:111], v[142:143], v[158:159]
	v_cvt_pk_bf16_f32 v96, v96, v97
	v_cvt_pk_bf16_f32 v97, v98, v99
	v_cvt_pk_bf16_f32 v98, v100, v101
	v_cvt_pk_bf16_f32 v99, v102, v103
	v_cvt_pk_bf16_f32 v100, v104, v105
	v_cvt_pk_bf16_f32 v101, v106, v107
	v_cvt_pk_bf16_f32 v102, v108, v109
	v_cvt_pk_bf16_f32 v103, v110, v111
	s_lshl_b32 s99, s98, 11
	v_lshl_add_u32 v8, v0, 3, s99
	global_store_dwordx2 v8, v[96:97], s[94:95]
	global_store_dwordx2 v8, v[98:99], s[94:95] offset:512
	global_store_dwordx2 v8, v[100:101], s[94:95] offset:1024
	global_store_dwordx2 v8, v[102:103], s[94:95] offset:1536
	s_lshl_b32 s99, s98, 2
	v_mov_b32_e32 v9, s99
	v_mov_b32_e32 v10, 0
	v_cmp_eq_u32_e32 vcc, 0, v0
	s_and_saveexec_b64 s[98:99], vcc
	global_store_dword v9, v10, s[90:91]
	global_store_dword v9, v10, s[92:93]
	s_or_b64 exec, exec, s[98:99]
	s_add_u32 s98, s97, 2816
	s_lshl_b32 s98, s98, 12
	v_add_u32_e32 v3, s98, v1
	global_load_dwordx4 v[96:99], v3, s[88:89] nt
	global_load_dwordx4 v[100:103], v3, s[88:89] offset:1024 nt
	global_load_dwordx4 v[104:107], v3, s[88:89] offset:2048 nt
	global_load_dwordx4 v[108:111], v3, s[88:89] offset:3072 nt
	s_waitcnt vmcnt(50)
	v_mul_f32_e32 v4, v16, v16
	v_fma_f32 v4, v17, v17, v4
	v_fma_f32 v4, v18, v18, v4
	v_fma_f32 v4, v19, v19, v4
	v_fma_f32 v4, v20, v20, v4
	v_fma_f32 v4, v21, v21, v4
	v_fma_f32 v4, v22, v22, v4
	v_fma_f32 v4, v23, v23, v4
	v_fma_f32 v4, v24, v24, v4
	v_fma_f32 v4, v25, v25, v4
	v_fma_f32 v4, v26, v26, v4
	v_fma_f32 v4, v27, v27, v4
	v_fma_f32 v4, v28, v28, v4
	v_fma_f32 v4, v29, v29, v4
	v_fma_f32 v4, v30, v30, v4
	v_fma_f32 v4, v31, v31, v4
	s_nop 1
	v_add_f32_dpp v5, v4, v4 quad_perm:[1,0,3,2] row_mask:0xf bank_mask:0xf
	s_nop 1
	v_add_f32_dpp v4, v5, v5 quad_perm:[2,3,0,1] row_mask:0xf bank_mask:0xf
	s_nop 1
	v_add_f32_dpp v5, v4, v4 row_half_mirror row_mask:0xf bank_mask:0xf
	s_nop 1
	v_add_f32_dpp v4, v5, v5 row_mirror row_mask:0xf bank_mask:0xf
	s_nop 1
	v_readlane_b32 s98, v4, 0
	v_readlane_b32 s99, v4, 16
	s_nop 3
	v_mov_b32_e32 v5, s98
	v_add_f32_e32 v5, s99, v5
	v_readlane_b32 s98, v4, 32
	v_readlane_b32 s99, v4, 48
	s_nop 3
	v_add_f32_e32 v5, s98, v5
	v_add_f32_e32 v5, s99, v5
	v_mul_f32_e32 v5, 0x3a800000, v5
	v_add_f32_e32 v5, 0x358637bd, v5
	v_rsq_f32_e32 v6, v5
	s_nop 0
	s_add_u32 s98, s97, 1536
	v_pk_mul_f32 v[16:17], v[16:17], v[6:7] op_sel_hi:[1,0]
	v_pk_mul_f32 v[18:19], v[18:19], v[6:7] op_sel_hi:[1,0]
	v_pk_mul_f32 v[20:21], v[20:21], v[6:7] op_sel_hi:[1,0]
	v_pk_mul_f32 v[22:23], v[22:23], v[6:7] op_sel_hi:[1,0]
	v_pk_mul_f32 v[24:25], v[24:25], v[6:7] op_sel_hi:[1,0]
	v_pk_mul_f32 v[26:27], v[26:27], v[6:7] op_sel_hi:[1,0]
	v_pk_mul_f32 v[28:29], v[28:29], v[6:7] op_sel_hi:[1,0]
	v_pk_mul_f32 v[30:31], v[30:31], v[6:7] op_sel_hi:[1,0]
	v_pk_mul_f32 v[16:17], v[16:17], v[112:113]
	v_pk_mul_f32 v[18:19], v[18:19], v[114:115]
	v_pk_mul_f32 v[20:21], v[20:21], v[116:117]
	v_pk_mul_f32 v[22:23], v[22:23], v[118:119]
	v_pk_mul_f32 v[24:25], v[24:25], v[120:121]
	v_pk_mul_f32 v[26:27], v[26:27], v[122:123]
	v_pk_mul_f32 v[28:29], v[28:29], v[124:125]
	v_pk_mul_f32 v[30:31], v[30:31], v[126:127]
	v_pk_fma_f32 v[16:17], v[16:17], v[128:129], v[144:145]
	v_pk_fma_f32 v[18:19], v[18:19], v[130:131], v[146:147]
	v_pk_fma_f32 v[20:21], v[20:21], v[132:133], v[148:149]
	v_pk_fma_f32 v[22:23], v[22:23], v[134:135], v[150:151]
	v_pk_fma_f32 v[24:25], v[24:25], v[136:137], v[152:153]
	v_pk_fma_f32 v[26:27], v[26:27], v[138:139], v[154:155]
	v_pk_fma_f32 v[28:29], v[28:29], v[140:141], v[156:157]
	v_pk_fma_f32 v[30:31], v[30:31], v[142:143], v[158:159]
	v_cvt_pk_bf16_f32 v16, v16, v17
	v_cvt_pk_bf16_f32 v17, v18, v19
	v_cvt_pk_bf16_f32 v18, v20, v21
	v_cvt_pk_bf16_f32 v19, v22, v23
	v_cvt_pk_bf16_f32 v20, v24, v25
	v_cvt_pk_bf16_f32 v21, v26, v27
	v_cvt_pk_bf16_f32 v22, v28, v29
	v_cvt_pk_bf16_f32 v23, v30, v31
	s_lshl_b32 s99, s98, 11
	v_lshl_add_u32 v8, v0, 3, s99
	global_store_dwordx2 v8, v[16:17], s[94:95]
	global_store_dwordx2 v8, v[18:19], s[94:95] offset:512
	global_store_dwordx2 v8, v[20:21], s[94:95] offset:1024
	global_store_dwordx2 v8, v[22:23], s[94:95] offset:1536
	s_lshl_b32 s99, s98, 2
	v_mov_b32_e32 v9, s99
	v_mov_b32_e32 v10, 0
	v_cmp_eq_u32_e32 vcc, 0, v0
	s_and_saveexec_b64 s[98:99], vcc
	global_store_dword v9, v10, s[90:91]
	global_store_dword v9, v10, s[92:93]
	s_or_b64 exec, exec, s[98:99]
	s_add_u32 s98, s97, 3072
	s_lshl_b32 s98, s98, 12
	v_add_u32_e32 v3, s98, v1
	global_load_dwordx4 v[16:19], v3, s[88:89] nt
	global_load_dwordx4 v[20:23], v3, s[88:89] offset:1024 nt
	global_load_dwordx4 v[24:27], v3, s[88:89] offset:2048 nt
	global_load_dwordx4 v[28:31], v3, s[88:89] offset:3072 nt
	s_waitcnt vmcnt(50)
	v_mul_f32_e32 v4, v32, v32
	v_fma_f32 v4, v33, v33, v4
	v_fma_f32 v4, v34, v34, v4
	v_fma_f32 v4, v35, v35, v4
	v_fma_f32 v4, v36, v36, v4
	v_fma_f32 v4, v37, v37, v4
	v_fma_f32 v4, v38, v38, v4
	v_fma_f32 v4, v39, v39, v4
	v_fma_f32 v4, v40, v40, v4
	v_fma_f32 v4, v41, v41, v4
	v_fma_f32 v4, v42, v42, v4
	v_fma_f32 v4, v43, v43, v4
	v_fma_f32 v4, v44, v44, v4
	v_fma_f32 v4, v45, v45, v4
	v_fma_f32 v4, v46, v46, v4
	v_fma_f32 v4, v47, v47, v4
	s_nop 1
	v_add_f32_dpp v5, v4, v4 quad_perm:[1,0,3,2] row_mask:0xf bank_mask:0xf
	s_nop 1
	v_add_f32_dpp v4, v5, v5 quad_perm:[2,3,0,1] row_mask:0xf bank_mask:0xf
	s_nop 1
	v_add_f32_dpp v5, v4, v4 row_half_mirror row_mask:0xf bank_mask:0xf
	s_nop 1
	v_add_f32_dpp v4, v5, v5 row_mirror row_mask:0xf bank_mask:0xf
	s_nop 1
	v_readlane_b32 s98, v4, 0
	v_readlane_b32 s99, v4, 16
	s_nop 3
	v_mov_b32_e32 v5, s98
	v_add_f32_e32 v5, s99, v5
	v_readlane_b32 s98, v4, 32
	v_readlane_b32 s99, v4, 48
	s_nop 3
	v_add_f32_e32 v5, s98, v5
	v_add_f32_e32 v5, s99, v5
	v_mul_f32_e32 v5, 0x3a800000, v5
	v_add_f32_e32 v5, 0x358637bd, v5
	v_rsq_f32_e32 v6, v5
	s_nop 0
	s_add_u32 s98, s97, 1792
	v_pk_mul_f32 v[32:33], v[32:33], v[6:7] op_sel_hi:[1,0]
	v_pk_mul_f32 v[34:35], v[34:35], v[6:7] op_sel_hi:[1,0]
	v_pk_mul_f32 v[36:37], v[36:37], v[6:7] op_sel_hi:[1,0]
	v_pk_mul_f32 v[38:39], v[38:39], v[6:7] op_sel_hi:[1,0]
	v_pk_mul_f32 v[40:41], v[40:41], v[6:7] op_sel_hi:[1,0]
	v_pk_mul_f32 v[42:43], v[42:43], v[6:7] op_sel_hi:[1,0]
	v_pk_mul_f32 v[44:45], v[44:45], v[6:7] op_sel_hi:[1,0]
	v_pk_mul_f32 v[46:47], v[46:47], v[6:7] op_sel_hi:[1,0]
	v_pk_mul_f32 v[32:33], v[32:33], v[112:113]
	v_pk_mul_f32 v[34:35], v[34:35], v[114:115]
	v_pk_mul_f32 v[36:37], v[36:37], v[116:117]
	v_pk_mul_f32 v[38:39], v[38:39], v[118:119]
	v_pk_mul_f32 v[40:41], v[40:41], v[120:121]
	v_pk_mul_f32 v[42:43], v[42:43], v[122:123]
	v_pk_mul_f32 v[44:45], v[44:45], v[124:125]
	v_pk_mul_f32 v[46:47], v[46:47], v[126:127]
	v_pk_fma_f32 v[32:33], v[32:33], v[128:129], v[144:145]
	v_pk_fma_f32 v[34:35], v[34:35], v[130:131], v[146:147]
	v_pk_fma_f32 v[36:37], v[36:37], v[132:133], v[148:149]
	v_pk_fma_f32 v[38:39], v[38:39], v[134:135], v[150:151]
	v_pk_fma_f32 v[40:41], v[40:41], v[136:137], v[152:153]
	v_pk_fma_f32 v[42:43], v[42:43], v[138:139], v[154:155]
	v_pk_fma_f32 v[44:45], v[44:45], v[140:141], v[156:157]
	v_pk_fma_f32 v[46:47], v[46:47], v[142:143], v[158:159]
	v_cvt_pk_bf16_f32 v32, v32, v33
	v_cvt_pk_bf16_f32 v33, v34, v35
	v_cvt_pk_bf16_f32 v34, v36, v37
	v_cvt_pk_bf16_f32 v35, v38, v39
	v_cvt_pk_bf16_f32 v36, v40, v41
	v_cvt_pk_bf16_f32 v37, v42, v43
	v_cvt_pk_bf16_f32 v38, v44, v45
	v_cvt_pk_bf16_f32 v39, v46, v47
	s_lshl_b32 s99, s98, 11
	v_lshl_add_u32 v8, v0, 3, s99
	global_store_dwordx2 v8, v[32:33], s[94:95]
	global_store_dwordx2 v8, v[34:35], s[94:95] offset:512
	global_store_dwordx2 v8, v[36:37], s[94:95] offset:1024
	global_store_dwordx2 v8, v[38:39], s[94:95] offset:1536
	s_lshl_b32 s99, s98, 2
	v_mov_b32_e32 v9, s99
	v_mov_b32_e32 v10, 0
	v_cmp_eq_u32_e32 vcc, 0, v0
	s_and_saveexec_b64 s[98:99], vcc
	global_store_dword v9, v10, s[90:91]
	global_store_dword v9, v10, s[92:93]
	s_or_b64 exec, exec, s[98:99]
	s_add_u32 s98, s97, 3328
	s_lshl_b32 s98, s98, 12
	v_add_u32_e32 v3, s98, v1
	global_load_dwordx4 v[32:35], v3, s[88:89] nt
	global_load_dwordx4 v[36:39], v3, s[88:89] offset:1024 nt
	global_load_dwordx4 v[40:43], v3, s[88:89] offset:2048 nt
	global_load_dwordx4 v[44:47], v3, s[88:89] offset:3072 nt
	s_waitcnt vmcnt(50)
	v_mul_f32_e32 v4, v48, v48
	v_fma_f32 v4, v49, v49, v4
	v_fma_f32 v4, v50, v50, v4
	v_fma_f32 v4, v51, v51, v4
	v_fma_f32 v4, v52, v52, v4
	v_fma_f32 v4, v53, v53, v4
	v_fma_f32 v4, v54, v54, v4
	v_fma_f32 v4, v55, v55, v4
	v_fma_f32 v4, v56, v56, v4
	v_fma_f32 v4, v57, v57, v4
	v_fma_f32 v4, v58, v58, v4
	v_fma_f32 v4, v59, v59, v4
	v_fma_f32 v4, v60, v60, v4
	v_fma_f32 v4, v61, v61, v4
	v_fma_f32 v4, v62, v62, v4
	v_fma_f32 v4, v63, v63, v4
	s_nop 1
	v_add_f32_dpp v5, v4, v4 quad_perm:[1,0,3,2] row_mask:0xf bank_mask:0xf
	s_nop 1
	v_add_f32_dpp v4, v5, v5 quad_perm:[2,3,0,1] row_mask:0xf bank_mask:0xf
	s_nop 1
	v_add_f32_dpp v5, v4, v4 row_half_mirror row_mask:0xf bank_mask:0xf
	s_nop 1
	v_add_f32_dpp v4, v5, v5 row_mirror row_mask:0xf bank_mask:0xf
	s_nop 1
	v_readlane_b32 s98, v4, 0
	v_readlane_b32 s99, v4, 16
	s_nop 3
	v_mov_b32_e32 v5, s98
	v_add_f32_e32 v5, s99, v5
	v_readlane_b32 s98, v4, 32
	v_readlane_b32 s99, v4, 48
	s_nop 3
	v_add_f32_e32 v5, s98, v5
	v_add_f32_e32 v5, s99, v5
	v_mul_f32_e32 v5, 0x3a800000, v5
	v_add_f32_e32 v5, 0x358637bd, v5
	v_rsq_f32_e32 v6, v5
	s_nop 0
	s_add_u32 s98, s97, 2048
	v_pk_mul_f32 v[48:49], v[48:49], v[6:7] op_sel_hi:[1,0]
	v_pk_mul_f32 v[50:51], v[50:51], v[6:7] op_sel_hi:[1,0]
	v_pk_mul_f32 v[52:53], v[52:53], v[6:7] op_sel_hi:[1,0]
	v_pk_mul_f32 v[54:55], v[54:55], v[6:7] op_sel_hi:[1,0]
	v_pk_mul_f32 v[56:57], v[56:57], v[6:7] op_sel_hi:[1,0]
	v_pk_mul_f32 v[58:59], v[58:59], v[6:7] op_sel_hi:[1,0]
	v_pk_mul_f32 v[60:61], v[60:61], v[6:7] op_sel_hi:[1,0]
	v_pk_mul_f32 v[62:63], v[62:63], v[6:7] op_sel_hi:[1,0]
	v_pk_mul_f32 v[48:49], v[48:49], v[112:113]
	v_pk_mul_f32 v[50:51], v[50:51], v[114:115]
	v_pk_mul_f32 v[52:53], v[52:53], v[116:117]
	v_pk_mul_f32 v[54:55], v[54:55], v[118:119]
	v_pk_mul_f32 v[56:57], v[56:57], v[120:121]
	v_pk_mul_f32 v[58:59], v[58:59], v[122:123]
	v_pk_mul_f32 v[60:61], v[60:61], v[124:125]
	v_pk_mul_f32 v[62:63], v[62:63], v[126:127]
	v_pk_fma_f32 v[48:49], v[48:49], v[128:129], v[144:145]
	v_pk_fma_f32 v[50:51], v[50:51], v[130:131], v[146:147]
	v_pk_fma_f32 v[52:53], v[52:53], v[132:133], v[148:149]
	v_pk_fma_f32 v[54:55], v[54:55], v[134:135], v[150:151]
	v_pk_fma_f32 v[56:57], v[56:57], v[136:137], v[152:153]
	v_pk_fma_f32 v[58:59], v[58:59], v[138:139], v[154:155]
	v_pk_fma_f32 v[60:61], v[60:61], v[140:141], v[156:157]
	v_pk_fma_f32 v[62:63], v[62:63], v[142:143], v[158:159]
	v_cvt_pk_bf16_f32 v48, v48, v49
	v_cvt_pk_bf16_f32 v49, v50, v51
	v_cvt_pk_bf16_f32 v50, v52, v53
	v_cvt_pk_bf16_f32 v51, v54, v55
	v_cvt_pk_bf16_f32 v52, v56, v57
	v_cvt_pk_bf16_f32 v53, v58, v59
	v_cvt_pk_bf16_f32 v54, v60, v61
	v_cvt_pk_bf16_f32 v55, v62, v63
	s_lshl_b32 s99, s98, 11
	v_lshl_add_u32 v8, v0, 3, s99
	global_store_dwordx2 v8, v[48:49], s[94:95]
	global_store_dwordx2 v8, v[50:51], s[94:95] offset:512
	global_store_dwordx2 v8, v[52:53], s[94:95] offset:1024
	global_store_dwordx2 v8, v[54:55], s[94:95] offset:1536
	s_lshl_b32 s99, s98, 2
	v_mov_b32_e32 v9, s99
	v_mov_b32_e32 v10, 0
	v_cmp_eq_u32_e32 vcc, 0, v0
	s_and_saveexec_b64 s[98:99], vcc
	global_store_dword v9, v10, s[90:91]
	global_store_dword v9, v10, s[92:93]
	s_or_b64 exec, exec, s[98:99]
	s_add_u32 s98, s97, 3584
	s_lshl_b32 s98, s98, 12
	v_add_u32_e32 v3, s98, v1
	global_load_dwordx4 v[48:51], v3, s[88:89] nt
	global_load_dwordx4 v[52:55], v3, s[88:89] offset:1024 nt
	global_load_dwordx4 v[56:59], v3, s[88:89] offset:2048 nt
	global_load_dwordx4 v[60:63], v3, s[88:89] offset:3072 nt
	s_waitcnt vmcnt(50)
	v_mul_f32_e32 v4, v64, v64
	v_fma_f32 v4, v65, v65, v4
	v_fma_f32 v4, v66, v66, v4
	v_fma_f32 v4, v67, v67, v4
	v_fma_f32 v4, v68, v68, v4
	v_fma_f32 v4, v69, v69, v4
	v_fma_f32 v4, v70, v70, v4
	v_fma_f32 v4, v71, v71, v4
	v_fma_f32 v4, v72, v72, v4
	v_fma_f32 v4, v73, v73, v4
	v_fma_f32 v4, v74, v74, v4
	v_fma_f32 v4, v75, v75, v4
	v_fma_f32 v4, v76, v76, v4
	v_fma_f32 v4, v77, v77, v4
	v_fma_f32 v4, v78, v78, v4
	v_fma_f32 v4, v79, v79, v4
	s_nop 1
	v_add_f32_dpp v5, v4, v4 quad_perm:[1,0,3,2] row_mask:0xf bank_mask:0xf
	s_nop 1
	v_add_f32_dpp v4, v5, v5 quad_perm:[2,3,0,1] row_mask:0xf bank_mask:0xf
	s_nop 1
	v_add_f32_dpp v5, v4, v4 row_half_mirror row_mask:0xf bank_mask:0xf
	s_nop 1
	v_add_f32_dpp v4, v5, v5 row_mirror row_mask:0xf bank_mask:0xf
	s_nop 1
	v_readlane_b32 s98, v4, 0
	v_readlane_b32 s99, v4, 16
	s_nop 3
	v_mov_b32_e32 v5, s98
	v_add_f32_e32 v5, s99, v5
	v_readlane_b32 s98, v4, 32
	v_readlane_b32 s99, v4, 48
	s_nop 3
	v_add_f32_e32 v5, s98, v5
	v_add_f32_e32 v5, s99, v5
	v_mul_f32_e32 v5, 0x3a800000, v5
	v_add_f32_e32 v5, 0x358637bd, v5
	v_rsq_f32_e32 v6, v5
	s_nop 0
	s_add_u32 s98, s97, 2304
	v_pk_mul_f32 v[64:65], v[64:65], v[6:7] op_sel_hi:[1,0]
	v_pk_mul_f32 v[66:67], v[66:67], v[6:7] op_sel_hi:[1,0]
	v_pk_mul_f32 v[68:69], v[68:69], v[6:7] op_sel_hi:[1,0]
	v_pk_mul_f32 v[70:71], v[70:71], v[6:7] op_sel_hi:[1,0]
	v_pk_mul_f32 v[72:73], v[72:73], v[6:7] op_sel_hi:[1,0]
	v_pk_mul_f32 v[74:75], v[74:75], v[6:7] op_sel_hi:[1,0]
	v_pk_mul_f32 v[76:77], v[76:77], v[6:7] op_sel_hi:[1,0]
	v_pk_mul_f32 v[78:79], v[78:79], v[6:7] op_sel_hi:[1,0]
	v_pk_mul_f32 v[64:65], v[64:65], v[112:113]
	v_pk_mul_f32 v[66:67], v[66:67], v[114:115]
	v_pk_mul_f32 v[68:69], v[68:69], v[116:117]
	v_pk_mul_f32 v[70:71], v[70:71], v[118:119]
	v_pk_mul_f32 v[72:73], v[72:73], v[120:121]
	v_pk_mul_f32 v[74:75], v[74:75], v[122:123]
	v_pk_mul_f32 v[76:77], v[76:77], v[124:125]
	v_pk_mul_f32 v[78:79], v[78:79], v[126:127]
	v_pk_fma_f32 v[64:65], v[64:65], v[128:129], v[144:145]
	v_pk_fma_f32 v[66:67], v[66:67], v[130:131], v[146:147]
	v_pk_fma_f32 v[68:69], v[68:69], v[132:133], v[148:149]
	v_pk_fma_f32 v[70:71], v[70:71], v[134:135], v[150:151]
	v_pk_fma_f32 v[72:73], v[72:73], v[136:137], v[152:153]
	v_pk_fma_f32 v[74:75], v[74:75], v[138:139], v[154:155]
	v_pk_fma_f32 v[76:77], v[76:77], v[140:141], v[156:157]
	v_pk_fma_f32 v[78:79], v[78:79], v[142:143], v[158:159]
	v_cvt_pk_bf16_f32 v64, v64, v65
	v_cvt_pk_bf16_f32 v65, v66, v67
	v_cvt_pk_bf16_f32 v66, v68, v69
	v_cvt_pk_bf16_f32 v67, v70, v71
	v_cvt_pk_bf16_f32 v68, v72, v73
	v_cvt_pk_bf16_f32 v69, v74, v75
	v_cvt_pk_bf16_f32 v70, v76, v77
	v_cvt_pk_bf16_f32 v71, v78, v79
	s_lshl_b32 s99, s98, 11
	v_lshl_add_u32 v8, v0, 3, s99
	global_store_dwordx2 v8, v[64:65], s[94:95]
	global_store_dwordx2 v8, v[66:67], s[94:95] offset:512
	global_store_dwordx2 v8, v[68:69], s[94:95] offset:1024
	global_store_dwordx2 v8, v[70:71], s[94:95] offset:1536
	s_lshl_b32 s99, s98, 2
	v_mov_b32_e32 v9, s99
	v_mov_b32_e32 v10, 0
	v_cmp_eq_u32_e32 vcc, 0, v0
	s_and_saveexec_b64 s[98:99], vcc
	global_store_dword v9, v10, s[90:91]
	global_store_dword v9, v10, s[92:93]
	s_or_b64 exec, exec, s[98:99]
	s_add_u32 s98, s97, 3840
	s_lshl_b32 s98, s98, 12
	v_add_u32_e32 v3, s98, v1
	global_load_dwordx4 v[64:67], v3, s[88:89] nt
	global_load_dwordx4 v[68:71], v3, s[88:89] offset:1024 nt
	global_load_dwordx4 v[72:75], v3, s[88:89] offset:2048 nt
	global_load_dwordx4 v[76:79], v3, s[88:89] offset:3072 nt
	s_waitcnt vmcnt(50)
	v_mul_f32_e32 v4, v80, v80
	v_fma_f32 v4, v81, v81, v4
	v_fma_f32 v4, v82, v82, v4
	v_fma_f32 v4, v83, v83, v4
	v_fma_f32 v4, v84, v84, v4
	v_fma_f32 v4, v85, v85, v4
	v_fma_f32 v4, v86, v86, v4
	v_fma_f32 v4, v87, v87, v4
	v_fma_f32 v4, v88, v88, v4
	v_fma_f32 v4, v89, v89, v4
	v_fma_f32 v4, v90, v90, v4
	v_fma_f32 v4, v91, v91, v4
	v_fma_f32 v4, v92, v92, v4
	v_fma_f32 v4, v93, v93, v4
	v_fma_f32 v4, v94, v94, v4
	v_fma_f32 v4, v95, v95, v4
	s_nop 1
	v_add_f32_dpp v5, v4, v4 quad_perm:[1,0,3,2] row_mask:0xf bank_mask:0xf
	s_nop 1
	v_add_f32_dpp v4, v5, v5 quad_perm:[2,3,0,1] row_mask:0xf bank_mask:0xf
	s_nop 1
	v_add_f32_dpp v5, v4, v4 row_half_mirror row_mask:0xf bank_mask:0xf
	s_nop 1
	v_add_f32_dpp v4, v5, v5 row_mirror row_mask:0xf bank_mask:0xf
	s_nop 1
	v_readlane_b32 s98, v4, 0
	v_readlane_b32 s99, v4, 16
	s_nop 3
	v_mov_b32_e32 v5, s98
	v_add_f32_e32 v5, s99, v5
	v_readlane_b32 s98, v4, 32
	v_readlane_b32 s99, v4, 48
	s_nop 3
	v_add_f32_e32 v5, s98, v5
	v_add_f32_e32 v5, s99, v5
	v_mul_f32_e32 v5, 0x3a800000, v5
	v_add_f32_e32 v5, 0x358637bd, v5
	v_rsq_f32_e32 v6, v5
	s_nop 0
	s_add_u32 s98, s97, 2560
	v_pk_mul_f32 v[80:81], v[80:81], v[6:7] op_sel_hi:[1,0]
	v_pk_mul_f32 v[82:83], v[82:83], v[6:7] op_sel_hi:[1,0]
	v_pk_mul_f32 v[84:85], v[84:85], v[6:7] op_sel_hi:[1,0]
	v_pk_mul_f32 v[86:87], v[86:87], v[6:7] op_sel_hi:[1,0]
	v_pk_mul_f32 v[88:89], v[88:89], v[6:7] op_sel_hi:[1,0]
	v_pk_mul_f32 v[90:91], v[90:91], v[6:7] op_sel_hi:[1,0]
	v_pk_mul_f32 v[92:93], v[92:93], v[6:7] op_sel_hi:[1,0]
	v_pk_mul_f32 v[94:95], v[94:95], v[6:7] op_sel_hi:[1,0]
	v_pk_mul_f32 v[80:81], v[80:81], v[112:113]
	v_pk_mul_f32 v[82:83], v[82:83], v[114:115]
	v_pk_mul_f32 v[84:85], v[84:85], v[116:117]
	v_pk_mul_f32 v[86:87], v[86:87], v[118:119]
	v_pk_mul_f32 v[88:89], v[88:89], v[120:121]
	v_pk_mul_f32 v[90:91], v[90:91], v[122:123]
	v_pk_mul_f32 v[92:93], v[92:93], v[124:125]
	v_pk_mul_f32 v[94:95], v[94:95], v[126:127]
	v_pk_fma_f32 v[80:81], v[80:81], v[128:129], v[144:145]
	v_pk_fma_f32 v[82:83], v[82:83], v[130:131], v[146:147]
	v_pk_fma_f32 v[84:85], v[84:85], v[132:133], v[148:149]
	v_pk_fma_f32 v[86:87], v[86:87], v[134:135], v[150:151]
	v_pk_fma_f32 v[88:89], v[88:89], v[136:137], v[152:153]
	v_pk_fma_f32 v[90:91], v[90:91], v[138:139], v[154:155]
	v_pk_fma_f32 v[92:93], v[92:93], v[140:141], v[156:157]
	v_pk_fma_f32 v[94:95], v[94:95], v[142:143], v[158:159]
	v_cvt_pk_bf16_f32 v80, v80, v81
	v_cvt_pk_bf16_f32 v81, v82, v83
	v_cvt_pk_bf16_f32 v82, v84, v85
	v_cvt_pk_bf16_f32 v83, v86, v87
	v_cvt_pk_bf16_f32 v84, v88, v89
	v_cvt_pk_bf16_f32 v85, v90, v91
	v_cvt_pk_bf16_f32 v86, v92, v93
	v_cvt_pk_bf16_f32 v87, v94, v95
	s_lshl_b32 s99, s98, 11
	v_lshl_add_u32 v8, v0, 3, s99
	global_store_dwordx2 v8, v[80:81], s[94:95]
	global_store_dwordx2 v8, v[82:83], s[94:95] offset:512
	global_store_dwordx2 v8, v[84:85], s[94:95] offset:1024
	global_store_dwordx2 v8, v[86:87], s[94:95] offset:1536
	s_lshl_b32 s99, s98, 2
	v_mov_b32_e32 v9, s99
	v_mov_b32_e32 v10, 0
	v_cmp_eq_u32_e32 vcc, 0, v0
	s_and_saveexec_b64 s[98:99], vcc
	global_store_dword v9, v10, s[90:91]
	global_store_dword v9, v10, s[92:93]
	s_or_b64 exec, exec, s[98:99]
	s_waitcnt vmcnt(46)
	v_mul_f32_e32 v4, v96, v96
	v_fma_f32 v4, v97, v97, v4
	v_fma_f32 v4, v98, v98, v4
	v_fma_f32 v4, v99, v99, v4
	v_fma_f32 v4, v100, v100, v4
	v_fma_f32 v4, v101, v101, v4
	v_fma_f32 v4, v102, v102, v4
	v_fma_f32 v4, v103, v103, v4
	v_fma_f32 v4, v104, v104, v4
	v_fma_f32 v4, v105, v105, v4
	v_fma_f32 v4, v106, v106, v4
	v_fma_f32 v4, v107, v107, v4
	v_fma_f32 v4, v108, v108, v4
	v_fma_f32 v4, v109, v109, v4
	v_fma_f32 v4, v110, v110, v4
	v_fma_f32 v4, v111, v111, v4
	s_nop 1
	v_add_f32_dpp v5, v4, v4 quad_perm:[1,0,3,2] row_mask:0xf bank_mask:0xf
	s_nop 1
	v_add_f32_dpp v4, v5, v5 quad_perm:[2,3,0,1] row_mask:0xf bank_mask:0xf
	s_nop 1
	v_add_f32_dpp v5, v4, v4 row_half_mirror row_mask:0xf bank_mask:0xf
	s_nop 1
	v_add_f32_dpp v4, v5, v5 row_mirror row_mask:0xf bank_mask:0xf
	s_nop 1
	v_readlane_b32 s98, v4, 0
	v_readlane_b32 s99, v4, 16
	s_nop 3
	v_mov_b32_e32 v5, s98
	v_add_f32_e32 v5, s99, v5
	v_readlane_b32 s98, v4, 32
	v_readlane_b32 s99, v4, 48
	s_nop 3
	v_add_f32_e32 v5, s98, v5
	v_add_f32_e32 v5, s99, v5
	v_mul_f32_e32 v5, 0x3a800000, v5
	v_add_f32_e32 v5, 0x358637bd, v5
	v_rsq_f32_e32 v6, v5
	s_nop 0
	s_add_u32 s98, s97, 2816
	v_pk_mul_f32 v[96:97], v[96:97], v[6:7] op_sel_hi:[1,0]
	v_pk_mul_f32 v[98:99], v[98:99], v[6:7] op_sel_hi:[1,0]
	v_pk_mul_f32 v[100:101], v[100:101], v[6:7] op_sel_hi:[1,0]
	v_pk_mul_f32 v[102:103], v[102:103], v[6:7] op_sel_hi:[1,0]
	v_pk_mul_f32 v[104:105], v[104:105], v[6:7] op_sel_hi:[1,0]
	v_pk_mul_f32 v[106:107], v[106:107], v[6:7] op_sel_hi:[1,0]
	v_pk_mul_f32 v[108:109], v[108:109], v[6:7] op_sel_hi:[1,0]
	v_pk_mul_f32 v[110:111], v[110:111], v[6:7] op_sel_hi:[1,0]
	v_pk_mul_f32 v[96:97], v[96:97], v[112:113]
	v_pk_mul_f32 v[98:99], v[98:99], v[114:115]
	v_pk_mul_f32 v[100:101], v[100:101], v[116:117]
	v_pk_mul_f32 v[102:103], v[102:103], v[118:119]
	v_pk_mul_f32 v[104:105], v[104:105], v[120:121]
	v_pk_mul_f32 v[106:107], v[106:107], v[122:123]
	v_pk_mul_f32 v[108:109], v[108:109], v[124:125]
	v_pk_mul_f32 v[110:111], v[110:111], v[126:127]
	v_pk_fma_f32 v[96:97], v[96:97], v[128:129], v[144:145]
	v_pk_fma_f32 v[98:99], v[98:99], v[130:131], v[146:147]
	v_pk_fma_f32 v[100:101], v[100:101], v[132:133], v[148:149]
	v_pk_fma_f32 v[102:103], v[102:103], v[134:135], v[150:151]
	v_pk_fma_f32 v[104:105], v[104:105], v[136:137], v[152:153]
	v_pk_fma_f32 v[106:107], v[106:107], v[138:139], v[154:155]
	v_pk_fma_f32 v[108:109], v[108:109], v[140:141], v[156:157]
	v_pk_fma_f32 v[110:111], v[110:111], v[142:143], v[158:159]
	v_cvt_pk_bf16_f32 v96, v96, v97
	v_cvt_pk_bf16_f32 v97, v98, v99
	v_cvt_pk_bf16_f32 v98, v100, v101
	v_cvt_pk_bf16_f32 v99, v102, v103
	v_cvt_pk_bf16_f32 v100, v104, v105
	v_cvt_pk_bf16_f32 v101, v106, v107
	v_cvt_pk_bf16_f32 v102, v108, v109
	v_cvt_pk_bf16_f32 v103, v110, v111
	s_lshl_b32 s99, s98, 11
	v_lshl_add_u32 v8, v0, 3, s99
	global_store_dwordx2 v8, v[96:97], s[94:95]
	global_store_dwordx2 v8, v[98:99], s[94:95] offset:512
	global_store_dwordx2 v8, v[100:101], s[94:95] offset:1024
	global_store_dwordx2 v8, v[102:103], s[94:95] offset:1536
	s_lshl_b32 s99, s98, 2
	v_mov_b32_e32 v9, s99
	v_mov_b32_e32 v10, 0
	v_cmp_eq_u32_e32 vcc, 0, v0
	s_and_saveexec_b64 s[98:99], vcc
	global_store_dword v9, v10, s[90:91]
	global_store_dword v9, v10, s[92:93]
	s_or_b64 exec, exec, s[98:99]
	s_waitcnt vmcnt(42)
	v_mul_f32_e32 v4, v16, v16
	v_fma_f32 v4, v17, v17, v4
	v_fma_f32 v4, v18, v18, v4
	v_fma_f32 v4, v19, v19, v4
	v_fma_f32 v4, v20, v20, v4
	v_fma_f32 v4, v21, v21, v4
	v_fma_f32 v4, v22, v22, v4
	v_fma_f32 v4, v23, v23, v4
	v_fma_f32 v4, v24, v24, v4
	v_fma_f32 v4, v25, v25, v4
	v_fma_f32 v4, v26, v26, v4
	v_fma_f32 v4, v27, v27, v4
	v_fma_f32 v4, v28, v28, v4
	v_fma_f32 v4, v29, v29, v4
	v_fma_f32 v4, v30, v30, v4
	v_fma_f32 v4, v31, v31, v4
	s_nop 1
	v_add_f32_dpp v5, v4, v4 quad_perm:[1,0,3,2] row_mask:0xf bank_mask:0xf
	s_nop 1
	v_add_f32_dpp v4, v5, v5 quad_perm:[2,3,0,1] row_mask:0xf bank_mask:0xf
	s_nop 1
	v_add_f32_dpp v5, v4, v4 row_half_mirror row_mask:0xf bank_mask:0xf
	s_nop 1
	v_add_f32_dpp v4, v5, v5 row_mirror row_mask:0xf bank_mask:0xf
	s_nop 1
	v_readlane_b32 s98, v4, 0
	v_readlane_b32 s99, v4, 16
	s_nop 3
	v_mov_b32_e32 v5, s98
	v_add_f32_e32 v5, s99, v5
	v_readlane_b32 s98, v4, 32
	v_readlane_b32 s99, v4, 48
	s_nop 3
	v_add_f32_e32 v5, s98, v5
	v_add_f32_e32 v5, s99, v5
	v_mul_f32_e32 v5, 0x3a800000, v5
	v_add_f32_e32 v5, 0x358637bd, v5
	v_rsq_f32_e32 v6, v5
	s_nop 0
	s_add_u32 s98, s97, 3072
	v_pk_mul_f32 v[16:17], v[16:17], v[6:7] op_sel_hi:[1,0]
	v_pk_mul_f32 v[18:19], v[18:19], v[6:7] op_sel_hi:[1,0]
	v_pk_mul_f32 v[20:21], v[20:21], v[6:7] op_sel_hi:[1,0]
	v_pk_mul_f32 v[22:23], v[22:23], v[6:7] op_sel_hi:[1,0]
	v_pk_mul_f32 v[24:25], v[24:25], v[6:7] op_sel_hi:[1,0]
	v_pk_mul_f32 v[26:27], v[26:27], v[6:7] op_sel_hi:[1,0]
	v_pk_mul_f32 v[28:29], v[28:29], v[6:7] op_sel_hi:[1,0]
	v_pk_mul_f32 v[30:31], v[30:31], v[6:7] op_sel_hi:[1,0]
	v_pk_mul_f32 v[16:17], v[16:17], v[112:113]
	v_pk_mul_f32 v[18:19], v[18:19], v[114:115]
	v_pk_mul_f32 v[20:21], v[20:21], v[116:117]
	v_pk_mul_f32 v[22:23], v[22:23], v[118:119]
	v_pk_mul_f32 v[24:25], v[24:25], v[120:121]
	v_pk_mul_f32 v[26:27], v[26:27], v[122:123]
	v_pk_mul_f32 v[28:29], v[28:29], v[124:125]
	v_pk_mul_f32 v[30:31], v[30:31], v[126:127]
	v_pk_fma_f32 v[16:17], v[16:17], v[128:129], v[144:145]
	v_pk_fma_f32 v[18:19], v[18:19], v[130:131], v[146:147]
	v_pk_fma_f32 v[20:21], v[20:21], v[132:133], v[148:149]
	v_pk_fma_f32 v[22:23], v[22:23], v[134:135], v[150:151]
	v_pk_fma_f32 v[24:25], v[24:25], v[136:137], v[152:153]
	v_pk_fma_f32 v[26:27], v[26:27], v[138:139], v[154:155]
	v_pk_fma_f32 v[28:29], v[28:29], v[140:141], v[156:157]
	v_pk_fma_f32 v[30:31], v[30:31], v[142:143], v[158:159]
	v_cvt_pk_bf16_f32 v16, v16, v17
	v_cvt_pk_bf16_f32 v17, v18, v19
	v_cvt_pk_bf16_f32 v18, v20, v21
	v_cvt_pk_bf16_f32 v19, v22, v23
	v_cvt_pk_bf16_f32 v20, v24, v25
	v_cvt_pk_bf16_f32 v21, v26, v27
	v_cvt_pk_bf16_f32 v22, v28, v29
	v_cvt_pk_bf16_f32 v23, v30, v31
	s_lshl_b32 s99, s98, 11
	v_lshl_add_u32 v8, v0, 3, s99
	global_store_dwordx2 v8, v[16:17], s[94:95]
	global_store_dwordx2 v8, v[18:19], s[94:95] offset:512
	global_store_dwordx2 v8, v[20:21], s[94:95] offset:1024
	global_store_dwordx2 v8, v[22:23], s[94:95] offset:1536
	s_lshl_b32 s99, s98, 2
	v_mov_b32_e32 v9, s99
	v_mov_b32_e32 v10, 0
	v_cmp_eq_u32_e32 vcc, 0, v0
	s_and_saveexec_b64 s[98:99], vcc
	global_store_dword v9, v10, s[90:91]
	global_store_dword v9, v10, s[92:93]
	s_or_b64 exec, exec, s[98:99]
	s_waitcnt vmcnt(38)
	v_mul_f32_e32 v4, v32, v32
	v_fma_f32 v4, v33, v33, v4
	v_fma_f32 v4, v34, v34, v4
	v_fma_f32 v4, v35, v35, v4
	v_fma_f32 v4, v36, v36, v4
	v_fma_f32 v4, v37, v37, v4
	v_fma_f32 v4, v38, v38, v4
	v_fma_f32 v4, v39, v39, v4
	v_fma_f32 v4, v40, v40, v4
	v_fma_f32 v4, v41, v41, v4
	v_fma_f32 v4, v42, v42, v4
	v_fma_f32 v4, v43, v43, v4
	v_fma_f32 v4, v44, v44, v4
	v_fma_f32 v4, v45, v45, v4
	v_fma_f32 v4, v46, v46, v4
	v_fma_f32 v4, v47, v47, v4
	s_nop 1
	v_add_f32_dpp v5, v4, v4 quad_perm:[1,0,3,2] row_mask:0xf bank_mask:0xf
	s_nop 1
	v_add_f32_dpp v4, v5, v5 quad_perm:[2,3,0,1] row_mask:0xf bank_mask:0xf
	s_nop 1
	v_add_f32_dpp v5, v4, v4 row_half_mirror row_mask:0xf bank_mask:0xf
	s_nop 1
	v_add_f32_dpp v4, v5, v5 row_mirror row_mask:0xf bank_mask:0xf
	s_nop 1
	v_readlane_b32 s98, v4, 0
	v_readlane_b32 s99, v4, 16
	s_nop 3
	v_mov_b32_e32 v5, s98
	v_add_f32_e32 v5, s99, v5
	v_readlane_b32 s98, v4, 32
	v_readlane_b32 s99, v4, 48
	s_nop 3
	v_add_f32_e32 v5, s98, v5
	v_add_f32_e32 v5, s99, v5
	v_mul_f32_e32 v5, 0x3a800000, v5
	v_add_f32_e32 v5, 0x358637bd, v5
	v_rsq_f32_e32 v6, v5
	s_nop 0
	s_add_u32 s98, s97, 3328
	v_pk_mul_f32 v[32:33], v[32:33], v[6:7] op_sel_hi:[1,0]
	v_pk_mul_f32 v[34:35], v[34:35], v[6:7] op_sel_hi:[1,0]
	v_pk_mul_f32 v[36:37], v[36:37], v[6:7] op_sel_hi:[1,0]
	v_pk_mul_f32 v[38:39], v[38:39], v[6:7] op_sel_hi:[1,0]
	v_pk_mul_f32 v[40:41], v[40:41], v[6:7] op_sel_hi:[1,0]
	v_pk_mul_f32 v[42:43], v[42:43], v[6:7] op_sel_hi:[1,0]
	v_pk_mul_f32 v[44:45], v[44:45], v[6:7] op_sel_hi:[1,0]
	v_pk_mul_f32 v[46:47], v[46:47], v[6:7] op_sel_hi:[1,0]
	v_pk_mul_f32 v[32:33], v[32:33], v[112:113]
	v_pk_mul_f32 v[34:35], v[34:35], v[114:115]
	v_pk_mul_f32 v[36:37], v[36:37], v[116:117]
	v_pk_mul_f32 v[38:39], v[38:39], v[118:119]
	v_pk_mul_f32 v[40:41], v[40:41], v[120:121]
	v_pk_mul_f32 v[42:43], v[42:43], v[122:123]
	v_pk_mul_f32 v[44:45], v[44:45], v[124:125]
	v_pk_mul_f32 v[46:47], v[46:47], v[126:127]
	v_pk_fma_f32 v[32:33], v[32:33], v[128:129], v[144:145]
	v_pk_fma_f32 v[34:35], v[34:35], v[130:131], v[146:147]
	v_pk_fma_f32 v[36:37], v[36:37], v[132:133], v[148:149]
	v_pk_fma_f32 v[38:39], v[38:39], v[134:135], v[150:151]
	v_pk_fma_f32 v[40:41], v[40:41], v[136:137], v[152:153]
	v_pk_fma_f32 v[42:43], v[42:43], v[138:139], v[154:155]
	v_pk_fma_f32 v[44:45], v[44:45], v[140:141], v[156:157]
	v_pk_fma_f32 v[46:47], v[46:47], v[142:143], v[158:159]
	v_cvt_pk_bf16_f32 v32, v32, v33
	v_cvt_pk_bf16_f32 v33, v34, v35
	v_cvt_pk_bf16_f32 v34, v36, v37
	v_cvt_pk_bf16_f32 v35, v38, v39
	v_cvt_pk_bf16_f32 v36, v40, v41
	v_cvt_pk_bf16_f32 v37, v42, v43
	v_cvt_pk_bf16_f32 v38, v44, v45
	v_cvt_pk_bf16_f32 v39, v46, v47
	s_lshl_b32 s99, s98, 11
	v_lshl_add_u32 v8, v0, 3, s99
	global_store_dwordx2 v8, v[32:33], s[94:95]
	global_store_dwordx2 v8, v[34:35], s[94:95] offset:512
	global_store_dwordx2 v8, v[36:37], s[94:95] offset:1024
	global_store_dwordx2 v8, v[38:39], s[94:95] offset:1536
	s_lshl_b32 s99, s98, 2
	v_mov_b32_e32 v9, s99
	v_mov_b32_e32 v10, 0
	v_cmp_eq_u32_e32 vcc, 0, v0
	s_and_saveexec_b64 s[98:99], vcc
	global_store_dword v9, v10, s[90:91]
	global_store_dword v9, v10, s[92:93]
	s_or_b64 exec, exec, s[98:99]
	s_waitcnt vmcnt(34)
	v_mul_f32_e32 v4, v48, v48
	v_fma_f32 v4, v49, v49, v4
	v_fma_f32 v4, v50, v50, v4
	v_fma_f32 v4, v51, v51, v4
	v_fma_f32 v4, v52, v52, v4
	v_fma_f32 v4, v53, v53, v4
	v_fma_f32 v4, v54, v54, v4
	v_fma_f32 v4, v55, v55, v4
	v_fma_f32 v4, v56, v56, v4
	v_fma_f32 v4, v57, v57, v4
	v_fma_f32 v4, v58, v58, v4
	v_fma_f32 v4, v59, v59, v4
	v_fma_f32 v4, v60, v60, v4
	v_fma_f32 v4, v61, v61, v4
	v_fma_f32 v4, v62, v62, v4
	v_fma_f32 v4, v63, v63, v4
	s_nop 1
	v_add_f32_dpp v5, v4, v4 quad_perm:[1,0,3,2] row_mask:0xf bank_mask:0xf
	s_nop 1
	v_add_f32_dpp v4, v5, v5 quad_perm:[2,3,0,1] row_mask:0xf bank_mask:0xf
	s_nop 1
	v_add_f32_dpp v5, v4, v4 row_half_mirror row_mask:0xf bank_mask:0xf
	s_nop 1
	v_add_f32_dpp v4, v5, v5 row_mirror row_mask:0xf bank_mask:0xf
	s_nop 1
	v_readlane_b32 s98, v4, 0
	v_readlane_b32 s99, v4, 16
	s_nop 3
	v_mov_b32_e32 v5, s98
	v_add_f32_e32 v5, s99, v5
	v_readlane_b32 s98, v4, 32
	v_readlane_b32 s99, v4, 48
	s_nop 3
	v_add_f32_e32 v5, s98, v5
	v_add_f32_e32 v5, s99, v5
	v_mul_f32_e32 v5, 0x3a800000, v5
	v_add_f32_e32 v5, 0x358637bd, v5
	v_rsq_f32_e32 v6, v5
	s_nop 0
	s_add_u32 s98, s97, 3584
	v_pk_mul_f32 v[48:49], v[48:49], v[6:7] op_sel_hi:[1,0]
	v_pk_mul_f32 v[50:51], v[50:51], v[6:7] op_sel_hi:[1,0]
	v_pk_mul_f32 v[52:53], v[52:53], v[6:7] op_sel_hi:[1,0]
	v_pk_mul_f32 v[54:55], v[54:55], v[6:7] op_sel_hi:[1,0]
	v_pk_mul_f32 v[56:57], v[56:57], v[6:7] op_sel_hi:[1,0]
	v_pk_mul_f32 v[58:59], v[58:59], v[6:7] op_sel_hi:[1,0]
	v_pk_mul_f32 v[60:61], v[60:61], v[6:7] op_sel_hi:[1,0]
	v_pk_mul_f32 v[62:63], v[62:63], v[6:7] op_sel_hi:[1,0]
	v_pk_mul_f32 v[48:49], v[48:49], v[112:113]
	v_pk_mul_f32 v[50:51], v[50:51], v[114:115]
	v_pk_mul_f32 v[52:53], v[52:53], v[116:117]
	v_pk_mul_f32 v[54:55], v[54:55], v[118:119]
	v_pk_mul_f32 v[56:57], v[56:57], v[120:121]
	v_pk_mul_f32 v[58:59], v[58:59], v[122:123]
	v_pk_mul_f32 v[60:61], v[60:61], v[124:125]
	v_pk_mul_f32 v[62:63], v[62:63], v[126:127]
	v_pk_fma_f32 v[48:49], v[48:49], v[128:129], v[144:145]
	v_pk_fma_f32 v[50:51], v[50:51], v[130:131], v[146:147]
	v_pk_fma_f32 v[52:53], v[52:53], v[132:133], v[148:149]
	v_pk_fma_f32 v[54:55], v[54:55], v[134:135], v[150:151]
	v_pk_fma_f32 v[56:57], v[56:57], v[136:137], v[152:153]
	v_pk_fma_f32 v[58:59], v[58:59], v[138:139], v[154:155]
	v_pk_fma_f32 v[60:61], v[60:61], v[140:141], v[156:157]
	v_pk_fma_f32 v[62:63], v[62:63], v[142:143], v[158:159]
	v_cvt_pk_bf16_f32 v48, v48, v49
	v_cvt_pk_bf16_f32 v49, v50, v51
	v_cvt_pk_bf16_f32 v50, v52, v53
	v_cvt_pk_bf16_f32 v51, v54, v55
	v_cvt_pk_bf16_f32 v52, v56, v57
	v_cvt_pk_bf16_f32 v53, v58, v59
	v_cvt_pk_bf16_f32 v54, v60, v61
	v_cvt_pk_bf16_f32 v55, v62, v63
	s_lshl_b32 s99, s98, 11
	v_lshl_add_u32 v8, v0, 3, s99
	global_store_dwordx2 v8, v[48:49], s[94:95]
	global_store_dwordx2 v8, v[50:51], s[94:95] offset:512
	global_store_dwordx2 v8, v[52:53], s[94:95] offset:1024
	global_store_dwordx2 v8, v[54:55], s[94:95] offset:1536
	s_lshl_b32 s99, s98, 2
	v_mov_b32_e32 v9, s99
	v_mov_b32_e32 v10, 0
	v_cmp_eq_u32_e32 vcc, 0, v0
	s_and_saveexec_b64 s[98:99], vcc
	global_store_dword v9, v10, s[90:91]
	global_store_dword v9, v10, s[92:93]
	s_or_b64 exec, exec, s[98:99]
	s_waitcnt vmcnt(30)
	v_mul_f32_e32 v4, v64, v64
	v_fma_f32 v4, v65, v65, v4
	v_fma_f32 v4, v66, v66, v4
	v_fma_f32 v4, v67, v67, v4
	v_fma_f32 v4, v68, v68, v4
	v_fma_f32 v4, v69, v69, v4
	v_fma_f32 v4, v70, v70, v4
	v_fma_f32 v4, v71, v71, v4
	v_fma_f32 v4, v72, v72, v4
	v_fma_f32 v4, v73, v73, v4
	v_fma_f32 v4, v74, v74, v4
	v_fma_f32 v4, v75, v75, v4
	v_fma_f32 v4, v76, v76, v4
	v_fma_f32 v4, v77, v77, v4
	v_fma_f32 v4, v78, v78, v4
	v_fma_f32 v4, v79, v79, v4
	s_nop 1
	v_add_f32_dpp v5, v4, v4 quad_perm:[1,0,3,2] row_mask:0xf bank_mask:0xf
	s_nop 1
	v_add_f32_dpp v4, v5, v5 quad_perm:[2,3,0,1] row_mask:0xf bank_mask:0xf
	s_nop 1
	v_add_f32_dpp v5, v4, v4 row_half_mirror row_mask:0xf bank_mask:0xf
	s_nop 1
	v_add_f32_dpp v4, v5, v5 row_mirror row_mask:0xf bank_mask:0xf
	s_nop 1
	v_readlane_b32 s98, v4, 0
	v_readlane_b32 s99, v4, 16
	s_nop 3
	v_mov_b32_e32 v5, s98
	v_add_f32_e32 v5, s99, v5
	v_readlane_b32 s98, v4, 32
	v_readlane_b32 s99, v4, 48
	s_nop 3
	v_add_f32_e32 v5, s98, v5
	v_add_f32_e32 v5, s99, v5
	v_mul_f32_e32 v5, 0x3a800000, v5
	v_add_f32_e32 v5, 0x358637bd, v5
	v_rsq_f32_e32 v6, v5
	s_nop 0
	s_add_u32 s98, s97, 3840
	v_pk_mul_f32 v[64:65], v[64:65], v[6:7] op_sel_hi:[1,0]
	v_pk_mul_f32 v[66:67], v[66:67], v[6:7] op_sel_hi:[1,0]
	v_pk_mul_f32 v[68:69], v[68:69], v[6:7] op_sel_hi:[1,0]
	v_pk_mul_f32 v[70:71], v[70:71], v[6:7] op_sel_hi:[1,0]
	v_pk_mul_f32 v[72:73], v[72:73], v[6:7] op_sel_hi:[1,0]
	v_pk_mul_f32 v[74:75], v[74:75], v[6:7] op_sel_hi:[1,0]
	v_pk_mul_f32 v[76:77], v[76:77], v[6:7] op_sel_hi:[1,0]
	v_pk_mul_f32 v[78:79], v[78:79], v[6:7] op_sel_hi:[1,0]
	v_pk_mul_f32 v[64:65], v[64:65], v[112:113]
	v_pk_mul_f32 v[66:67], v[66:67], v[114:115]
	v_pk_mul_f32 v[68:69], v[68:69], v[116:117]
	v_pk_mul_f32 v[70:71], v[70:71], v[118:119]
	v_pk_mul_f32 v[72:73], v[72:73], v[120:121]
	v_pk_mul_f32 v[74:75], v[74:75], v[122:123]
	v_pk_mul_f32 v[76:77], v[76:77], v[124:125]
	v_pk_mul_f32 v[78:79], v[78:79], v[126:127]
	v_pk_fma_f32 v[64:65], v[64:65], v[128:129], v[144:145]
	v_pk_fma_f32 v[66:67], v[66:67], v[130:131], v[146:147]
	v_pk_fma_f32 v[68:69], v[68:69], v[132:133], v[148:149]
	v_pk_fma_f32 v[70:71], v[70:71], v[134:135], v[150:151]
	v_pk_fma_f32 v[72:73], v[72:73], v[136:137], v[152:153]
	v_pk_fma_f32 v[74:75], v[74:75], v[138:139], v[154:155]
	v_pk_fma_f32 v[76:77], v[76:77], v[140:141], v[156:157]
	v_pk_fma_f32 v[78:79], v[78:79], v[142:143], v[158:159]
	v_cvt_pk_bf16_f32 v64, v64, v65
	v_cvt_pk_bf16_f32 v65, v66, v67
	v_cvt_pk_bf16_f32 v66, v68, v69
	v_cvt_pk_bf16_f32 v67, v70, v71
	v_cvt_pk_bf16_f32 v68, v72, v73
	v_cvt_pk_bf16_f32 v69, v74, v75
	v_cvt_pk_bf16_f32 v70, v76, v77
	v_cvt_pk_bf16_f32 v71, v78, v79
	s_lshl_b32 s99, s98, 11
	v_lshl_add_u32 v8, v0, 3, s99
	global_store_dwordx2 v8, v[64:65], s[94:95]
	global_store_dwordx2 v8, v[66:67], s[94:95] offset:512
	global_store_dwordx2 v8, v[68:69], s[94:95] offset:1024
	global_store_dwordx2 v8, v[70:71], s[94:95] offset:1536
	s_lshl_b32 s99, s98, 2
	v_mov_b32_e32 v9, s99
	v_mov_b32_e32 v10, 0
	v_cmp_eq_u32_e32 vcc, 0, v0
	s_and_saveexec_b64 s[98:99], vcc
	global_store_dword v9, v10, s[90:91]
	global_store_dword v9, v10, s[92:93]
	s_or_b64 exec, exec, s[98:99]
	s_waitcnt vmcnt(0)

.LBB0_4600:
	s_cmp_gt_i32 s44, 17
	s_cselect_b64 s[2:3], -1, 0
	s_cmp_lt_i32 s45, 18
	s_cselect_b64 s[4:5], -1, 0
	s_or_b64 s[2:3], s[2:3], s[4:5]
	s_and_b64 vcc, exec, s[2:3]
	s_cbranch_vccnz .LBB0_4660
	s_lshl_b32 s96, s22, 3
	s_lshr_b32 s97, s70, 6
	s_add_u32 s96, s96, s97
	s_lshr_b32 s97, s96, 8
	s_lshl_b32 s97, s97, 12
	s_and_b32 s99, s96, 0xff
	s_or_b32 s97, s97, s99
	s_cmpk_ge_u32 s97, 0x8000
	s_cbranch_scc1 .Lnp17_done
	s_load_dwordx2 s[88:89], s[0:1], 0xb8
	s_load_dwordx2 s[90:91], s[0:1], 0x18
	s_load_dwordx2 s[92:93], s[0:1], 0x140
	s_load_dwordx2 s[94:95], s[0:1], 0x158
	v_mbcnt_hi_u32_b32 v0, -1, v210
	v_lshlrev_b32_e32 v1, 4, v0
	s_waitcnt lgkmcnt(0)
	s_add_u32 s90, s90, 12288
	s_addc_u32 s91, s91, 0
	global_load_dwordx4 v[112:115], v1, s[90:91] nt
	global_load_dwordx4 v[116:119], v1, s[90:91] offset:1024 nt
	global_load_dwordx4 v[120:123], v1, s[90:91] offset:2048 nt
	global_load_dwordx4 v[124:127], v1, s[90:91] offset:3072 nt
	s_lshr_b32 s98, s97, 12
	s_add_u32 s98, s98, 24
	s_mul_i32 s98, s98, 0x3000
	s_add_u32 s92, s92, s98
	s_addc_u32 s93, s93, 0
	global_load_dwordx4 v[144:147], v1, s[92:93] nt
	global_load_dwordx4 v[148:151], v1, s[92:93] offset:1024 nt
	global_load_dwordx4 v[152:155], v1, s[92:93] offset:2048 nt
	global_load_dwordx4 v[156:159], v1, s[92:93] offset:3072 nt
	s_add_u32 s92, s92, 0x1000
	s_addc_u32 s93, s93, 0
	global_load_dwordx4 v[128:131], v1, s[92:93] nt
	global_load_dwordx4 v[132:135], v1, s[92:93] offset:1024 nt
	global_load_dwordx4 v[136:139], v1, s[92:93] offset:2048 nt
	global_load_dwordx4 v[140:143], v1, s[92:93] offset:3072 nt
	s_load_dwordx2 s[90:91], s[0:1], 0x210
	s_load_dwordx2 s[92:93], s[0:1], 0x218
	s_waitcnt vmcnt(0) lgkmcnt(0)
	v_pk_add_f32 v[128:129], v[128:129], 1.0 op_sel_hi:[1,0]
	v_pk_add_f32 v[130:131], v[130:131], 1.0 op_sel_hi:[1,0]
	v_pk_add_f32 v[132:133], v[132:133], 1.0 op_sel_hi:[1,0]
	v_pk_add_f32 v[134:135], v[134:135], 1.0 op_sel_hi:[1,0]
	v_pk_add_f32 v[136:137], v[136:137], 1.0 op_sel_hi:[1,0]
	v_pk_add_f32 v[138:139], v[138:139], 1.0 op_sel_hi:[1,0]
	v_pk_add_f32 v[140:141], v[140:141], 1.0 op_sel_hi:[1,0]
	v_pk_add_f32 v[142:143], v[142:143], 1.0 op_sel_hi:[1,0]
	s_add_u32 s98, s97, 0
	s_lshl_b32 s98, s98, 12
	v_add_u32_e32 v3, s98, v1
	global_load_dwordx4 v[16:19], v3, s[88:89] nt
	global_load_dwordx4 v[20:23], v3, s[88:89] offset:1024 nt
	global_load_dwordx4 v[24:27], v3, s[88:89] offset:2048 nt
	global_load_dwordx4 v[28:31], v3, s[88:89] offset:3072 nt
	s_add_u32 s98, s97, 256
	s_lshl_b32 s98, s98, 12
	v_add_u32_e32 v3, s98, v1
	global_load_dwordx4 v[32:35], v3, s[88:89] nt
	global_load_dwordx4 v[36:39], v3, s[88:89] offset:1024 nt
	global_load_dwordx4 v[40:43], v3, s[88:89] offset:2048 nt
	global_load_dwordx4 v[44:47], v3, s[88:89] offset:3072 nt
	s_add_u32 s98, s97, 512
	s_lshl_b32 s98, s98, 12
	v_add_u32_e32 v3, s98, v1
	global_load_dwordx4 v[48:51], v3, s[88:89] nt
	global_load_dwordx4 v[52:55], v3, s[88:89] offset:1024 nt
	global_load_dwordx4 v[56:59], v3, s[88:89] offset:2048 nt
	global_load_dwordx4 v[60:63], v3, s[88:89] offset:3072 nt
	s_add_u32 s98, s97, 768
	s_lshl_b32 s98, s98, 12
	v_add_u32_e32 v3, s98, v1
	global_load_dwordx4 v[64:67], v3, s[88:89] nt
	global_load_dwordx4 v[68:71], v3, s[88:89] offset:1024 nt
	global_load_dwordx4 v[72:75], v3, s[88:89] offset:2048 nt
	global_load_dwordx4 v[76:79], v3, s[88:89] offset:3072 nt
	s_add_u32 s98, s97, 1024
	s_lshl_b32 s98, s98, 12
	v_add_u32_e32 v3, s98, v1
	global_load_dwordx4 v[80:83], v3, s[88:89] nt
	global_load_dwordx4 v[84:87], v3, s[88:89] offset:1024 nt
	global_load_dwordx4 v[88:91], v3, s[88:89] offset:2048 nt
	global_load_dwordx4 v[92:95], v3, s[88:89] offset:3072 nt
	s_add_u32 s98, s97, 1280
	s_lshl_b32 s98, s98, 12
	v_add_u32_e32 v3, s98, v1
	global_load_dwordx4 v[96:99], v3, s[88:89] nt
	global_load_dwordx4 v[100:103], v3, s[88:89] offset:1024 nt
	global_load_dwordx4 v[104:107], v3, s[88:89] offset:2048 nt
	global_load_dwordx4 v[108:111], v3, s[88:89] offset:3072 nt
	s_waitcnt vmcnt(20)
	v_mul_f32_e32 v4, v16, v16
	v_fma_f32 v4, v17, v17, v4
	v_fma_f32 v4, v18, v18, v4
	v_fma_f32 v4, v19, v19, v4
	v_fma_f32 v4, v20, v20, v4
	v_fma_f32 v4, v21, v21, v4
	v_fma_f32 v4, v22, v22, v4
	v_fma_f32 v4, v23, v23, v4
	v_fma_f32 v4, v24, v24, v4
	v_fma_f32 v4, v25, v25, v4
	v_fma_f32 v4, v26, v26, v4
	v_fma_f32 v4, v27, v27, v4
	v_fma_f32 v4, v28, v28, v4
	v_fma_f32 v4, v29, v29, v4
	v_fma_f32 v4, v30, v30, v4
	v_fma_f32 v4, v31, v31, v4
	s_nop 1
	v_add_f32_dpp v5, v4, v4 quad_perm:[1,0,3,2] row_mask:0xf bank_mask:0xf
	s_nop 1
	v_add_f32_dpp v4, v5, v5 quad_perm:[2,3,0,1] row_mask:0xf bank_mask:0xf
	s_nop 1
	v_add_f32_dpp v5, v4, v4 row_half_mirror row_mask:0xf bank_mask:0xf
	s_nop 1
	v_add_f32_dpp v4, v5, v5 row_mirror row_mask:0xf bank_mask:0xf
	s_nop 1
	v_readlane_b32 s98, v4, 0
	v_readlane_b32 s99, v4, 16
	s_nop 3
	v_mov_b32_e32 v5, s98
	v_add_f32_e32 v5, s99, v5
	v_readlane_b32 s98, v4, 32
	v_readlane_b32 s99, v4, 48
	s_nop 3
	v_add_f32_e32 v5, s98, v5
	v_add_f32_e32 v5, s99, v5
	v_mul_f32_e32 v5, 0x3a800000, v5
	v_add_f32_e32 v5, 0x358637bd, v5
	v_rsq_f32_e32 v6, v5
	s_nop 0
	s_add_u32 s98, s97, 0
	v_pk_mul_f32 v[16:17], v[16:17], v[6:7] op_sel_hi:[1,0]
	v_pk_mul_f32 v[18:19], v[18:19], v[6:7] op_sel_hi:[1,0]
	v_pk_mul_f32 v[20:21], v[20:21], v[6:7] op_sel_hi:[1,0]
	v_pk_mul_f32 v[22:23], v[22:23], v[6:7] op_sel_hi:[1,0]
	v_pk_mul_f32 v[24:25], v[24:25], v[6:7] op_sel_hi:[1,0]
	v_pk_mul_f32 v[26:27], v[26:27], v[6:7] op_sel_hi:[1,0]
	v_pk_mul_f32 v[28:29], v[28:29], v[6:7] op_sel_hi:[1,0]
	v_pk_mul_f32 v[30:31], v[30:31], v[6:7] op_sel_hi:[1,0]
	v_pk_mul_f32 v[16:17], v[16:17], v[112:113]
	v_pk_mul_f32 v[18:19], v[18:19], v[114:115]
	v_pk_mul_f32 v[20:21], v[20:21], v[116:117]
	v_pk_mul_f32 v[22:23], v[22:23], v[118:119]
	v_pk_mul_f32 v[24:25], v[24:25], v[120:121]
	v_pk_mul_f32 v[26:27], v[26:27], v[122:123]
	v_pk_mul_f32 v[28:29], v[28:29], v[124:125]
	v_pk_mul_f32 v[30:31], v[30:31], v[126:127]
	v_pk_fma_f32 v[16:17], v[16:17], v[128:129], v[144:145]
	v_pk_fma_f32 v[18:19], v[18:19], v[130:131], v[146:147]
	v_pk_fma_f32 v[20:21], v[20:21], v[132:133], v[148:149]
	v_pk_fma_f32 v[22:23], v[22:23], v[134:135], v[150:151]
	v_pk_fma_f32 v[24:25], v[24:25], v[136:137], v[152:153]
	v_pk_fma_f32 v[26:27], v[26:27], v[138:139], v[154:155]
	v_pk_fma_f32 v[28:29], v[28:29], v[140:141], v[156:157]
	v_pk_fma_f32 v[30:31], v[30:31], v[142:143], v[158:159]
	v_cvt_pk_bf16_f32 v16, v16, v17
	v_cvt_pk_bf16_f32 v17, v18, v19
	v_cvt_pk_bf16_f32 v18, v20, v21
	v_cvt_pk_bf16_f32 v19, v22, v23
	v_cvt_pk_bf16_f32 v20, v24, v25
	v_cvt_pk_bf16_f32 v21, v26, v27
	v_cvt_pk_bf16_f32 v22, v28, v29
	v_cvt_pk_bf16_f32 v23, v30, v31
	s_lshl_b32 s99, s98, 11
	v_lshl_add_u32 v8, v0, 3, s99
	global_store_dwordx2 v8, v[16:17], s[94:95]
	global_store_dwordx2 v8, v[18:19], s[94:95] offset:512
	global_store_dwordx2 v8, v[20:21], s[94:95] offset:1024
	global_store_dwordx2 v8, v[22:23], s[94:95] offset:1536
	s_lshl_b32 s99, s98, 2
	v_mov_b32_e32 v9, s99
	v_mov_b32_e32 v10, 0
	v_cmp_eq_u32_e32 vcc, 0, v0
	s_and_saveexec_b64 s[98:99], vcc
	global_store_dword v9, v10, s[90:91]
	global_store_dword v9, v10, s[92:93]
	s_or_b64 exec, exec, s[98:99]
	s_add_u32 s98, s97, 1536
	s_lshl_b32 s98, s98, 12
	v_add_u32_e32 v3, s98, v1
	global_load_dwordx4 v[16:19], v3, s[88:89] nt
	global_load_dwordx4 v[20:23], v3, s[88:89] offset:1024 nt
	global_load_dwordx4 v[24:27], v3, s[88:89] offset:2048 nt
	global_load_dwordx4 v[28:31], v3, s[88:89] offset:3072 nt
	s_waitcnt vmcnt(26)
	v_mul_f32_e32 v4, v32, v32
	v_fma_f32 v4, v33, v33, v4
	v_fma_f32 v4, v34, v34, v4
	v_fma_f32 v4, v35, v35, v4
	v_fma_f32 v4, v36, v36, v4
	v_fma_f32 v4, v37, v37, v4
	v_fma_f32 v4, v38, v38, v4
	v_fma_f32 v4, v39, v39, v4
	v_fma_f32 v4, v40, v40, v4
	v_fma_f32 v4, v41, v41, v4
	v_fma_f32 v4, v42, v42, v4
	v_fma_f32 v4, v43, v43, v4
	v_fma_f32 v4, v44, v44, v4
	v_fma_f32 v4, v45, v45, v4
	v_fma_f32 v4, v46, v46, v4
	v_fma_f32 v4, v47, v47, v4
	s_nop 1
	v_add_f32_dpp v5, v4, v4 quad_perm:[1,0,3,2] row_mask:0xf bank_mask:0xf
	s_nop 1
	v_add_f32_dpp v4, v5, v5 quad_perm:[2,3,0,1] row_mask:0xf bank_mask:0xf
	s_nop 1
	v_add_f32_dpp v5, v4, v4 row_half_mirror row_mask:0xf bank_mask:0xf
	s_nop 1
	v_add_f32_dpp v4, v5, v5 row_mirror row_mask:0xf bank_mask:0xf
	s_nop 1
	v_readlane_b32 s98, v4, 0
	v_readlane_b32 s99, v4, 16
	s_nop 3
	v_mov_b32_e32 v5, s98
	v_add_f32_e32 v5, s99, v5
	v_readlane_b32 s98, v4, 32
	v_readlane_b32 s99, v4, 48
	s_nop 3
	v_add_f32_e32 v5, s98, v5
	v_add_f32_e32 v5, s99, v5
	v_mul_f32_e32 v5, 0x3a800000, v5
	v_add_f32_e32 v5, 0x358637bd, v5
	v_rsq_f32_e32 v6, v5
	s_nop 0
	s_add_u32 s98, s97, 256
	v_pk_mul_f32 v[32:33], v[32:33], v[6:7] op_sel_hi:[1,0]
	v_pk_mul_f32 v[34:35], v[34:35], v[6:7] op_sel_hi:[1,0]
	v_pk_mul_f32 v[36:37], v[36:37], v[6:7] op_sel_hi:[1,0]
	v_pk_mul_f32 v[38:39], v[38:39], v[6:7] op_sel_hi:[1,0]
	v_pk_mul_f32 v[40:41], v[40:41], v[6:7] op_sel_hi:[1,0]
	v_pk_mul_f32 v[42:43], v[42:43], v[6:7] op_sel_hi:[1,0]
	v_pk_mul_f32 v[44:45], v[44:45], v[6:7] op_sel_hi:[1,0]
	v_pk_mul_f32 v[46:47], v[46:47], v[6:7] op_sel_hi:[1,0]
	v_pk_mul_f32 v[32:33], v[32:33], v[112:113]
	v_pk_mul_f32 v[34:35], v[34:35], v[114:115]
	v_pk_mul_f32 v[36:37], v[36:37], v[116:117]
	v_pk_mul_f32 v[38:39], v[38:39], v[118:119]
	v_pk_mul_f32 v[40:41], v[40:41], v[120:121]
	v_pk_mul_f32 v[42:43], v[42:43], v[122:123]
	v_pk_mul_f32 v[44:45], v[44:45], v[124:125]
	v_pk_mul_f32 v[46:47], v[46:47], v[126:127]
	v_pk_fma_f32 v[32:33], v[32:33], v[128:129], v[144:145]
	v_pk_fma_f32 v[34:35], v[34:35], v[130:131], v[146:147]
	v_pk_fma_f32 v[36:37], v[36:37], v[132:133], v[148:149]
	v_pk_fma_f32 v[38:39], v[38:39], v[134:135], v[150:151]
	v_pk_fma_f32 v[40:41], v[40:41], v[136:137], v[152:153]
	v_pk_fma_f32 v[42:43], v[42:43], v[138:139], v[154:155]
	v_pk_fma_f32 v[44:45], v[44:45], v[140:141], v[156:157]
	v_pk_fma_f32 v[46:47], v[46:47], v[142:143], v[158:159]
	v_cvt_pk_bf16_f32 v32, v32, v33
	v_cvt_pk_bf16_f32 v33, v34, v35
	v_cvt_pk_bf16_f32 v34, v36, v37
	v_cvt_pk_bf16_f32 v35, v38, v39
	v_cvt_pk_bf16_f32 v36, v40, v41
	v_cvt_pk_bf16_f32 v37, v42, v43
	v_cvt_pk_bf16_f32 v38, v44, v45
	v_cvt_pk_bf16_f32 v39, v46, v47
	s_lshl_b32 s99, s98, 11
	v_lshl_add_u32 v8, v0, 3, s99
	global_store_dwordx2 v8, v[32:33], s[94:95]
	global_store_dwordx2 v8, v[34:35], s[94:95] offset:512
	global_store_dwordx2 v8, v[36:37], s[94:95] offset:1024
	global_store_dwordx2 v8, v[38:39], s[94:95] offset:1536
	s_lshl_b32 s99, s98, 2
	v_mov_b32_e32 v9, s99
	v_mov_b32_e32 v10, 0
	v_cmp_eq_u32_e32 vcc, 0, v0
	s_and_saveexec_b64 s[98:99], vcc
	global_store_dword v9, v10, s[90:91]
	global_store_dword v9, v10, s[92:93]
	s_or_b64 exec, exec, s[98:99]
	s_add_u32 s98, s97, 1792
	s_lshl_b32 s98, s98, 12
	v_add_u32_e32 v3, s98, v1
	global_load_dwordx4 v[32:35], v3, s[88:89] nt
	global_load_dwordx4 v[36:39], v3, s[88:89] offset:1024 nt
	global_load_dwordx4 v[40:43], v3, s[88:89] offset:2048 nt
	global_load_dwordx4 v[44:47], v3, s[88:89] offset:3072 nt
	s_waitcnt vmcnt(32)
	v_mul_f32_e32 v4, v48, v48
	v_fma_f32 v4, v49, v49, v4
	v_fma_f32 v4, v50, v50, v4
	v_fma_f32 v4, v51, v51, v4
	v_fma_f32 v4, v52, v52, v4
	v_fma_f32 v4, v53, v53, v4
	v_fma_f32 v4, v54, v54, v4
	v_fma_f32 v4, v55, v55, v4
	v_fma_f32 v4, v56, v56, v4
	v_fma_f32 v4, v57, v57, v4
	v_fma_f32 v4, v58, v58, v4
	v_fma_f32 v4, v59, v59, v4
	v_fma_f32 v4, v60, v60, v4
	v_fma_f32 v4, v61, v61, v4
	v_fma_f32 v4, v62, v62, v4
	v_fma_f32 v4, v63, v63, v4
	s_nop 1
	v_add_f32_dpp v5, v4, v4 quad_perm:[1,0,3,2] row_mask:0xf bank_mask:0xf
	s_nop 1
	v_add_f32_dpp v4, v5, v5 quad_perm:[2,3,0,1] row_mask:0xf bank_mask:0xf
	s_nop 1
	v_add_f32_dpp v5, v4, v4 row_half_mirror row_mask:0xf bank_mask:0xf
	s_nop 1
	v_add_f32_dpp v4, v5, v5 row_mirror row_mask:0xf bank_mask:0xf
	s_nop 1
	v_readlane_b32 s98, v4, 0
	v_readlane_b32 s99, v4, 16
	s_nop 3
	v_mov_b32_e32 v5, s98
	v_add_f32_e32 v5, s99, v5
	v_readlane_b32 s98, v4, 32
	v_readlane_b32 s99, v4, 48
	s_nop 3
	v_add_f32_e32 v5, s98, v5
	v_add_f32_e32 v5, s99, v5
	v_mul_f32_e32 v5, 0x3a800000, v5
	v_add_f32_e32 v5, 0x358637bd, v5
	v_rsq_f32_e32 v6, v5
	s_nop 0
	s_add_u32 s98, s97, 512
	v_pk_mul_f32 v[48:49], v[48:49], v[6:7] op_sel_hi:[1,0]
	v_pk_mul_f32 v[50:51], v[50:51], v[6:7] op_sel_hi:[1,0]
	v_pk_mul_f32 v[52:53], v[52:53], v[6:7] op_sel_hi:[1,0]
	v_pk_mul_f32 v[54:55], v[54:55], v[6:7] op_sel_hi:[1,0]
	v_pk_mul_f32 v[56:57], v[56:57], v[6:7] op_sel_hi:[1,0]
	v_pk_mul_f32 v[58:59], v[58:59], v[6:7] op_sel_hi:[1,0]
	v_pk_mul_f32 v[60:61], v[60:61], v[6:7] op_sel_hi:[1,0]
	v_pk_mul_f32 v[62:63], v[62:63], v[6:7] op_sel_hi:[1,0]
	v_pk_mul_f32 v[48:49], v[48:49], v[112:113]
	v_pk_mul_f32 v[50:51], v[50:51], v[114:115]
	v_pk_mul_f32 v[52:53], v[52:53], v[116:117]
	v_pk_mul_f32 v[54:55], v[54:55], v[118:119]
	v_pk_mul_f32 v[56:57], v[56:57], v[120:121]
	v_pk_mul_f32 v[58:59], v[58:59], v[122:123]
	v_pk_mul_f32 v[60:61], v[60:61], v[124:125]
	v_pk_mul_f32 v[62:63], v[62:63], v[126:127]
	v_pk_fma_f32 v[48:49], v[48:49], v[128:129], v[144:145]
	v_pk_fma_f32 v[50:51], v[50:51], v[130:131], v[146:147]
	v_pk_fma_f32 v[52:53], v[52:53], v[132:133], v[148:149]
	v_pk_fma_f32 v[54:55], v[54:55], v[134:135], v[150:151]
	v_pk_fma_f32 v[56:57], v[56:57], v[136:137], v[152:153]
	v_pk_fma_f32 v[58:59], v[58:59], v[138:139], v[154:155]
	v_pk_fma_f32 v[60:61], v[60:61], v[140:141], v[156:157]
	v_pk_fma_f32 v[62:63], v[62:63], v[142:143], v[158:159]
	v_cvt_pk_bf16_f32 v48, v48, v49
	v_cvt_pk_bf16_f32 v49, v50, v51
	v_cvt_pk_bf16_f32 v50, v52, v53
	v_cvt_pk_bf16_f32 v51, v54, v55
	v_cvt_pk_bf16_f32 v52, v56, v57
	v_cvt_pk_bf16_f32 v53, v58, v59
	v_cvt_pk_bf16_f32 v54, v60, v61
	v_cvt_pk_bf16_f32 v55, v62, v63
	s_lshl_b32 s99, s98, 11
	v_lshl_add_u32 v8, v0, 3, s99
	global_store_dwordx2 v8, v[48:49], s[94:95]
	global_store_dwordx2 v8, v[50:51], s[94:95] offset:512
	global_store_dwordx2 v8, v[52:53], s[94:95] offset:1024
	global_store_dwordx2 v8, v[54:55], s[94:95] offset:1536
	s_lshl_b32 s99, s98, 2
	v_mov_b32_e32 v9, s99
	v_mov_b32_e32 v10, 0
	v_cmp_eq_u32_e32 vcc, 0, v0
	s_and_saveexec_b64 s[98:99], vcc
	global_store_dword v9, v10, s[90:91]
	global_store_dword v9, v10, s[92:93]
	s_or_b64 exec, exec, s[98:99]
	s_add_u32 s98, s97, 2048
	s_lshl_b32 s98, s98, 12
	v_add_u32_e32 v3, s98, v1
	global_load_dwordx4 v[48:51], v3, s[88:89] nt
	global_load_dwordx4 v[52:55], v3, s[88:89] offset:1024 nt
	global_load_dwordx4 v[56:59], v3, s[88:89] offset:2048 nt
	global_load_dwordx4 v[60:63], v3, s[88:89] offset:3072 nt
	s_waitcnt vmcnt(38)
	v_mul_f32_e32 v4, v64, v64
	v_fma_f32 v4, v65, v65, v4
	v_fma_f32 v4, v66, v66, v4
	v_fma_f32 v4, v67, v67, v4
	v_fma_f32 v4, v68, v68, v4
	v_fma_f32 v4, v69, v69, v4
	v_fma_f32 v4, v70, v70, v4
	v_fma_f32 v4, v71, v71, v4
	v_fma_f32 v4, v72, v72, v4
	v_fma_f32 v4, v73, v73, v4
	v_fma_f32 v4, v74, v74, v4
	v_fma_f32 v4, v75, v75, v4
	v_fma_f32 v4, v76, v76, v4
	v_fma_f32 v4, v77, v77, v4
	v_fma_f32 v4, v78, v78, v4
	v_fma_f32 v4, v79, v79, v4
	s_nop 1
	v_add_f32_dpp v5, v4, v4 quad_perm:[1,0,3,2] row_mask:0xf bank_mask:0xf
	s_nop 1
	v_add_f32_dpp v4, v5, v5 quad_perm:[2,3,0,1] row_mask:0xf bank_mask:0xf
	s_nop 1
	v_add_f32_dpp v5, v4, v4 row_half_mirror row_mask:0xf bank_mask:0xf
	s_nop 1
	v_add_f32_dpp v4, v5, v5 row_mirror row_mask:0xf bank_mask:0xf
	s_nop 1
	v_readlane_b32 s98, v4, 0
	v_readlane_b32 s99, v4, 16
	s_nop 3
	v_mov_b32_e32 v5, s98
	v_add_f32_e32 v5, s99, v5
	v_readlane_b32 s98, v4, 32
	v_readlane_b32 s99, v4, 48
	s_nop 3
	v_add_f32_e32 v5, s98, v5
	v_add_f32_e32 v5, s99, v5
	v_mul_f32_e32 v5, 0x3a800000, v5
	v_add_f32_e32 v5, 0x358637bd, v5
	v_rsq_f32_e32 v6, v5
	s_nop 0
	s_add_u32 s98, s97, 768
	v_pk_mul_f32 v[64:65], v[64:65], v[6:7] op_sel_hi:[1,0]
	v_pk_mul_f32 v[66:67], v[66:67], v[6:7] op_sel_hi:[1,0]
	v_pk_mul_f32 v[68:69], v[68:69], v[6:7] op_sel_hi:[1,0]
	v_pk_mul_f32 v[70:71], v[70:71], v[6:7] op_sel_hi:[1,0]
	v_pk_mul_f32 v[72:73], v[72:73], v[6:7] op_sel_hi:[1,0]
	v_pk_mul_f32 v[74:75], v[74:75], v[6:7] op_sel_hi:[1,0]
	v_pk_mul_f32 v[76:77], v[76:77], v[6:7] op_sel_hi:[1,0]
	v_pk_mul_f32 v[78:79], v[78:79], v[6:7] op_sel_hi:[1,0]
	v_pk_mul_f32 v[64:65], v[64:65], v[112:113]
	v_pk_mul_f32 v[66:67], v[66:67], v[114:115]
	v_pk_mul_f32 v[68:69], v[68:69], v[116:117]
	v_pk_mul_f32 v[70:71], v[70:71], v[118:119]
	v_pk_mul_f32 v[72:73], v[72:73], v[120:121]
	v_pk_mul_f32 v[74:75], v[74:75], v[122:123]
	v_pk_mul_f32 v[76:77], v[76:77], v[124:125]
	v_pk_mul_f32 v[78:79], v[78:79], v[126:127]
	v_pk_fma_f32 v[64:65], v[64:65], v[128:129], v[144:145]
	v_pk_fma_f32 v[66:67], v[66:67], v[130:131], v[146:147]
	v_pk_fma_f32 v[68:69], v[68:69], v[132:133], v[148:149]
	v_pk_fma_f32 v[70:71], v[70:71], v[134:135], v[150:151]
	v_pk_fma_f32 v[72:73], v[72:73], v[136:137], v[152:153]
	v_pk_fma_f32 v[74:75], v[74:75], v[138:139], v[154:155]
	v_pk_fma_f32 v[76:77], v[76:77], v[140:141], v[156:157]
	v_pk_fma_f32 v[78:79], v[78:79], v[142:143], v[158:159]
	v_cvt_pk_bf16_f32 v64, v64, v65
	v_cvt_pk_bf16_f32 v65, v66, v67
	v_cvt_pk_bf16_f32 v66, v68, v69
	v_cvt_pk_bf16_f32 v67, v70, v71
	v_cvt_pk_bf16_f32 v68, v72, v73
	v_cvt_pk_bf16_f32 v69, v74, v75
	v_cvt_pk_bf16_f32 v70, v76, v77
	v_cvt_pk_bf16_f32 v71, v78, v79
	s_lshl_b32 s99, s98, 11
	v_lshl_add_u32 v8, v0, 3, s99
	global_store_dwordx2 v8, v[64:65], s[94:95]
	global_store_dwordx2 v8, v[66:67], s[94:95] offset:512
	global_store_dwordx2 v8, v[68:69], s[94:95] offset:1024
	global_store_dwordx2 v8, v[70:71], s[94:95] offset:1536
	s_lshl_b32 s99, s98, 2
	v_mov_b32_e32 v9, s99
	v_mov_b32_e32 v10, 0
	v_cmp_eq_u32_e32 vcc, 0, v0
	s_and_saveexec_b64 s[98:99], vcc
	global_store_dword v9, v10, s[90:91]
	global_store_dword v9, v10, s[92:93]
	s_or_b64 exec, exec, s[98:99]
	s_add_u32 s98, s97, 2304
	s_lshl_b32 s98, s98, 12
	v_add_u32_e32 v3, s98, v1
	global_load_dwordx4 v[64:67], v3, s[88:89] nt
	global_load_dwordx4 v[68:71], v3, s[88:89] offset:1024 nt
	global_load_dwordx4 v[72:75], v3, s[88:89] offset:2048 nt
	global_load_dwordx4 v[76:79], v3, s[88:89] offset:3072 nt
	s_waitcnt vmcnt(44)
	v_mul_f32_e32 v4, v80, v80
	v_fma_f32 v4, v81, v81, v4
	v_fma_f32 v4, v82, v82, v4
	v_fma_f32 v4, v83, v83, v4
	v_fma_f32 v4, v84, v84, v4
	v_fma_f32 v4, v85, v85, v4
	v_fma_f32 v4, v86, v86, v4
	v_fma_f32 v4, v87, v87, v4
	v_fma_f32 v4, v88, v88, v4
	v_fma_f32 v4, v89, v89, v4
	v_fma_f32 v4, v90, v90, v4
	v_fma_f32 v4, v91, v91, v4
	v_fma_f32 v4, v92, v92, v4
	v_fma_f32 v4, v93, v93, v4
	v_fma_f32 v4, v94, v94, v4
	v_fma_f32 v4, v95, v95, v4
	s_nop 1
	v_add_f32_dpp v5, v4, v4 quad_perm:[1,0,3,2] row_mask:0xf bank_mask:0xf
	s_nop 1
	v_add_f32_dpp v4, v5, v5 quad_perm:[2,3,0,1] row_mask:0xf bank_mask:0xf
	s_nop 1
	v_add_f32_dpp v5, v4, v4 row_half_mirror row_mask:0xf bank_mask:0xf
	s_nop 1
	v_add_f32_dpp v4, v5, v5 row_mirror row_mask:0xf bank_mask:0xf
	s_nop 1
	v_readlane_b32 s98, v4, 0
	v_readlane_b32 s99, v4, 16
	s_nop 3
	v_mov_b32_e32 v5, s98
	v_add_f32_e32 v5, s99, v5
	v_readlane_b32 s98, v4, 32
	v_readlane_b32 s99, v4, 48
	s_nop 3
	v_add_f32_e32 v5, s98, v5
	v_add_f32_e32 v5, s99, v5
	v_mul_f32_e32 v5, 0x3a800000, v5
	v_add_f32_e32 v5, 0x358637bd, v5
	v_rsq_f32_e32 v6, v5
	s_nop 0
	s_add_u32 s98, s97, 1024
	v_pk_mul_f32 v[80:81], v[80:81], v[6:7] op_sel_hi:[1,0]
	v_pk_mul_f32 v[82:83], v[82:83], v[6:7] op_sel_hi:[1,0]
	v_pk_mul_f32 v[84:85], v[84:85], v[6:7] op_sel_hi:[1,0]
	v_pk_mul_f32 v[86:87], v[86:87], v[6:7] op_sel_hi:[1,0]
	v_pk_mul_f32 v[88:89], v[88:89], v[6:7] op_sel_hi:[1,0]
	v_pk_mul_f32 v[90:91], v[90:91], v[6:7] op_sel_hi:[1,0]
	v_pk_mul_f32 v[92:93], v[92:93], v[6:7] op_sel_hi:[1,0]
	v_pk_mul_f32 v[94:95], v[94:95], v[6:7] op_sel_hi:[1,0]
	v_pk_mul_f32 v[80:81], v[80:81], v[112:113]
	v_pk_mul_f32 v[82:83], v[82:83], v[114:115]
	v_pk_mul_f32 v[84:85], v[84:85], v[116:117]
	v_pk_mul_f32 v[86:87], v[86:87], v[118:119]
	v_pk_mul_f32 v[88:89], v[88:89], v[120:121]
	v_pk_mul_f32 v[90:91], v[90:91], v[122:123]
	v_pk_mul_f32 v[92:93], v[92:93], v[124:125]
	v_pk_mul_f32 v[94:95], v[94:95], v[126:127]
	v_pk_fma_f32 v[80:81], v[80:81], v[128:129], v[144:145]
	v_pk_fma_f32 v[82:83], v[82:83], v[130:131], v[146:147]
	v_pk_fma_f32 v[84:85], v[84:85], v[132:133], v[148:149]
	v_pk_fma_f32 v[86:87], v[86:87], v[134:135], v[150:151]
	v_pk_fma_f32 v[88:89], v[88:89], v[136:137], v[152:153]
	v_pk_fma_f32 v[90:91], v[90:91], v[138:139], v[154:155]
	v_pk_fma_f32 v[92:93], v[92:93], v[140:141], v[156:157]
	v_pk_fma_f32 v[94:95], v[94:95], v[142:143], v[158:159]
	v_cvt_pk_bf16_f32 v80, v80, v81
	v_cvt_pk_bf16_f32 v81, v82, v83
	v_cvt_pk_bf16_f32 v82, v84, v85
	v_cvt_pk_bf16_f32 v83, v86, v87
	v_cvt_pk_bf16_f32 v84, v88, v89
	v_cvt_pk_bf16_f32 v85, v90, v91
	v_cvt_pk_bf16_f32 v86, v92, v93
	v_cvt_pk_bf16_f32 v87, v94, v95
	s_lshl_b32 s99, s98, 11
	v_lshl_add_u32 v8, v0, 3, s99
	global_store_dwordx2 v8, v[80:81], s[94:95]
	global_store_dwordx2 v8, v[82:83], s[94:95] offset:512
	global_store_dwordx2 v8, v[84:85], s[94:95] offset:1024
	global_store_dwordx2 v8, v[86:87], s[94:95] offset:1536
	s_lshl_b32 s99, s98, 2
	v_mov_b32_e32 v9, s99
	v_mov_b32_e32 v10, 0
	v_cmp_eq_u32_e32 vcc, 0, v0
	s_and_saveexec_b64 s[98:99], vcc
	global_store_dword v9, v10, s[90:91]
	global_store_dword v9, v10, s[92:93]
	s_or_b64 exec, exec, s[98:99]
	s_add_u32 s98, s97, 2560
	s_lshl_b32 s98, s98, 12
	v_add_u32_e32 v3, s98, v1
	global_load_dwordx4 v[80:83], v3, s[88:89] nt
	global_load_dwordx4 v[84:87], v3, s[88:89] offset:1024 nt
	global_load_dwordx4 v[88:91], v3, s[88:89] offset:2048 nt
	global_load_dwordx4 v[92:95], v3, s[88:89] offset:3072 nt
	s_waitcnt vmcnt(50)
	v_mul_f32_e32 v4, v96, v96
	v_fma_f32 v4, v97, v97, v4
	v_fma_f32 v4, v98, v98, v4
	v_fma_f32 v4, v99, v99, v4
	v_fma_f32 v4, v100, v100, v4
	v_fma_f32 v4, v101, v101, v4
	v_fma_f32 v4, v102, v102, v4
	v_fma_f32 v4, v103, v103, v4
	v_fma_f32 v4, v104, v104, v4
	v_fma_f32 v4, v105, v105, v4
	v_fma_f32 v4, v106, v106, v4
	v_fma_f32 v4, v107, v107, v4
	v_fma_f32 v4, v108, v108, v4
	v_fma_f32 v4, v109, v109, v4
	v_fma_f32 v4, v110, v110, v4
	v_fma_f32 v4, v111, v111, v4
	s_nop 1
	v_add_f32_dpp v5, v4, v4 quad_perm:[1,0,3,2] row_mask:0xf bank_mask:0xf
	s_nop 1
	v_add_f32_dpp v4, v5, v5 quad_perm:[2,3,0,1] row_mask:0xf bank_mask:0xf
	s_nop 1
	v_add_f32_dpp v5, v4, v4 row_half_mirror row_mask:0xf bank_mask:0xf
	s_nop 1
	v_add_f32_dpp v4, v5, v5 row_mirror row_mask:0xf bank_mask:0xf
	s_nop 1
	v_readlane_b32 s98, v4, 0
	v_readlane_b32 s99, v4, 16
	s_nop 3
	v_mov_b32_e32 v5, s98
	v_add_f32_e32 v5, s99, v5
	v_readlane_b32 s98, v4, 32
	v_readlane_b32 s99, v4, 48
	s_nop 3
	v_add_f32_e32 v5, s98, v5
	v_add_f32_e32 v5, s99, v5
	v_mul_f32_e32 v5, 0x3a800000, v5
	v_add_f32_e32 v5, 0x358637bd, v5
	v_rsq_f32_e32 v6, v5
	s_nop 0
	s_add_u32 s98, s97, 1280
	v_pk_mul_f32 v[96:97], v[96:97], v[6:7] op_sel_hi:[1,0]
	v_pk_mul_f32 v[98:99], v[98:99], v[6:7] op_sel_hi:[1,0]
	v_pk_mul_f32 v[100:101], v[100:101], v[6:7] op_sel_hi:[1,0]
	v_pk_mul_f32 v[102:103], v[102:103], v[6:7] op_sel_hi:[1,0]
	v_pk_mul_f32 v[104:105], v[104:105], v[6:7] op_sel_hi:[1,0]
	v_pk_mul_f32 v[106:107], v[106:107], v[6:7] op_sel_hi:[1,0]
	v_pk_mul_f32 v[108:109], v[108:109], v[6:7] op_sel_hi:[1,0]
	v_pk_mul_f32 v[110:111], v[110:111], v[6:7] op_sel_hi:[1,0]
	v_pk_mul_f32 v[96:97], v[96:97], v[112:113]
	v_pk_mul_f32 v[98:99], v[98:99], v[114:115]
	v_pk_mul_f32 v[100:101], v[100:101], v[116:117]
	v_pk_mul_f32 v[102:103], v[102:103], v[118:119]
	v_pk_mul_f32 v[104:105], v[104:105], v[120:121]
	v_pk_mul_f32 v[106:107], v[106:107], v[122:123]
	v_pk_mul_f32 v[108:109], v[108:109], v[124:125]
	v_pk_mul_f32 v[110:111], v[110:111], v[126:127]
	v_pk_fma_f32 v[96:97], v[96:97], v[128:129], v[144:145]
	v_pk_fma_f32 v[98:99], v[98:99], v[130:131], v[146:147]
	v_pk_fma_f32 v[100:101], v[100:101], v[132:133], v[148:149]
	v_pk_fma_f32 v[102:103], v[102:103], v[134:135], v[150:151]
	v_pk_fma_f32 v[104:105], v[104:105], v[136:137], v[152:153]
	v_pk_fma_f32 v[106:107], v[106:107], v[138:139], v[154:155]
	v_pk_fma_f32 v[108:109], v[108:109], v[140:141], v[156:157]
	v_pk_fma_f32 v[110:111], v[110:111], v[142:143], v[158:159]
	v_cvt_pk_bf16_f32 v96, v96, v97
	v_cvt_pk_bf16_f32 v97, v98, v99
	v_cvt_pk_bf16_f32 v98, v100, v101
	v_cvt_pk_bf16_f32 v99, v102, v103
	v_cvt_pk_bf16_f32 v100, v104, v105
	v_cvt_pk_bf16_f32 v101, v106, v107
	v_cvt_pk_bf16_f32 v102, v108, v109
	v_cvt_pk_bf16_f32 v103, v110, v111
	s_lshl_b32 s99, s98, 11
	v_lshl_add_u32 v8, v0, 3, s99
	global_store_dwordx2 v8, v[96:97], s[94:95]
	global_store_dwordx2 v8, v[98:99], s[94:95] offset:512
	global_store_dwordx2 v8, v[100:101], s[94:95] offset:1024
	global_store_dwordx2 v8, v[102:103], s[94:95] offset:1536
	s_lshl_b32 s99, s98, 2
	v_mov_b32_e32 v9, s99
	v_mov_b32_e32 v10, 0
	v_cmp_eq_u32_e32 vcc, 0, v0
	s_and_saveexec_b64 s[98:99], vcc
	global_store_dword v9, v10, s[90:91]
	global_store_dword v9, v10, s[92:93]
	s_or_b64 exec, exec, s[98:99]
	s_add_u32 s98, s97, 2816
	s_lshl_b32 s98, s98, 12
	v_add_u32_e32 v3, s98, v1
	global_load_dwordx4 v[96:99], v3, s[88:89] nt
	global_load_dwordx4 v[100:103], v3, s[88:89] offset:1024 nt
	global_load_dwordx4 v[104:107], v3, s[88:89] offset:2048 nt
	global_load_dwordx4 v[108:111], v3, s[88:89] offset:3072 nt
	s_waitcnt vmcnt(50)
	v_mul_f32_e32 v4, v16, v16
	v_fma_f32 v4, v17, v17, v4
	v_fma_f32 v4, v18, v18, v4
	v_fma_f32 v4, v19, v19, v4
	v_fma_f32 v4, v20, v20, v4
	v_fma_f32 v4, v21, v21, v4
	v_fma_f32 v4, v22, v22, v4
	v_fma_f32 v4, v23, v23, v4
	v_fma_f32 v4, v24, v24, v4
	v_fma_f32 v4, v25, v25, v4
	v_fma_f32 v4, v26, v26, v4
	v_fma_f32 v4, v27, v27, v4
	v_fma_f32 v4, v28, v28, v4
	v_fma_f32 v4, v29, v29, v4
	v_fma_f32 v4, v30, v30, v4
	v_fma_f32 v4, v31, v31, v4
	s_nop 1
	v_add_f32_dpp v5, v4, v4 quad_perm:[1,0,3,2] row_mask:0xf bank_mask:0xf
	s_nop 1
	v_add_f32_dpp v4, v5, v5 quad_perm:[2,3,0,1] row_mask:0xf bank_mask:0xf
	s_nop 1
	v_add_f32_dpp v5, v4, v4 row_half_mirror row_mask:0xf bank_mask:0xf
	s_nop 1
	v_add_f32_dpp v4, v5, v5 row_mirror row_mask:0xf bank_mask:0xf
	s_nop 1
	v_readlane_b32 s98, v4, 0
	v_readlane_b32 s99, v4, 16
	s_nop 3
	v_mov_b32_e32 v5, s98
	v_add_f32_e32 v5, s99, v5
	v_readlane_b32 s98, v4, 32
	v_readlane_b32 s99, v4, 48
	s_nop 3
	v_add_f32_e32 v5, s98, v5
	v_add_f32_e32 v5, s99, v5
	v_mul_f32_e32 v5, 0x3a800000, v5
	v_add_f32_e32 v5, 0x358637bd, v5
	v_rsq_f32_e32 v6, v5
	s_nop 0
	s_add_u32 s98, s97, 1536
	v_pk_mul_f32 v[16:17], v[16:17], v[6:7] op_sel_hi:[1,0]
	v_pk_mul_f32 v[18:19], v[18:19], v[6:7] op_sel_hi:[1,0]
	v_pk_mul_f32 v[20:21], v[20:21], v[6:7] op_sel_hi:[1,0]
	v_pk_mul_f32 v[22:23], v[22:23], v[6:7] op_sel_hi:[1,0]
	v_pk_mul_f32 v[24:25], v[24:25], v[6:7] op_sel_hi:[1,0]
	v_pk_mul_f32 v[26:27], v[26:27], v[6:7] op_sel_hi:[1,0]
	v_pk_mul_f32 v[28:29], v[28:29], v[6:7] op_sel_hi:[1,0]
	v_pk_mul_f32 v[30:31], v[30:31], v[6:7] op_sel_hi:[1,0]
	v_pk_mul_f32 v[16:17], v[16:17], v[112:113]
	v_pk_mul_f32 v[18:19], v[18:19], v[114:115]
	v_pk_mul_f32 v[20:21], v[20:21], v[116:117]
	v_pk_mul_f32 v[22:23], v[22:23], v[118:119]
	v_pk_mul_f32 v[24:25], v[24:25], v[120:121]
	v_pk_mul_f32 v[26:27], v[26:27], v[122:123]
	v_pk_mul_f32 v[28:29], v[28:29], v[124:125]
	v_pk_mul_f32 v[30:31], v[30:31], v[126:127]
	v_pk_fma_f32 v[16:17], v[16:17], v[128:129], v[144:145]
	v_pk_fma_f32 v[18:19], v[18:19], v[130:131], v[146:147]
	v_pk_fma_f32 v[20:21], v[20:21], v[132:133], v[148:149]
	v_pk_fma_f32 v[22:23], v[22:23], v[134:135], v[150:151]
	v_pk_fma_f32 v[24:25], v[24:25], v[136:137], v[152:153]
	v_pk_fma_f32 v[26:27], v[26:27], v[138:139], v[154:155]
	v_pk_fma_f32 v[28:29], v[28:29], v[140:141], v[156:157]
	v_pk_fma_f32 v[30:31], v[30:31], v[142:143], v[158:159]
	v_cvt_pk_bf16_f32 v16, v16, v17
	v_cvt_pk_bf16_f32 v17, v18, v19
	v_cvt_pk_bf16_f32 v18, v20, v21
	v_cvt_pk_bf16_f32 v19, v22, v23
	v_cvt_pk_bf16_f32 v20, v24, v25
	v_cvt_pk_bf16_f32 v21, v26, v27
	v_cvt_pk_bf16_f32 v22, v28, v29
	v_cvt_pk_bf16_f32 v23, v30, v31
	s_lshl_b32 s99, s98, 11
	v_lshl_add_u32 v8, v0, 3, s99
	global_store_dwordx2 v8, v[16:17], s[94:95]
	global_store_dwordx2 v8, v[18:19], s[94:95] offset:512
	global_store_dwordx2 v8, v[20:21], s[94:95] offset:1024
	global_store_dwordx2 v8, v[22:23], s[94:95] offset:1536
	s_lshl_b32 s99, s98, 2
	v_mov_b32_e32 v9, s99
	v_mov_b32_e32 v10, 0
	v_cmp_eq_u32_e32 vcc, 0, v0
	s_and_saveexec_b64 s[98:99], vcc
	global_store_dword v9, v10, s[90:91]
	global_store_dword v9, v10, s[92:93]
	s_or_b64 exec, exec, s[98:99]
	s_add_u32 s98, s97, 3072
	s_lshl_b32 s98, s98, 12
	v_add_u32_e32 v3, s98, v1
	global_load_dwordx4 v[16:19], v3, s[88:89] nt
	global_load_dwordx4 v[20:23], v3, s[88:89] offset:1024 nt
	global_load_dwordx4 v[24:27], v3, s[88:89] offset:2048 nt
	global_load_dwordx4 v[28:31], v3, s[88:89] offset:3072 nt
	s_waitcnt vmcnt(50)
	v_mul_f32_e32 v4, v32, v32
	v_fma_f32 v4, v33, v33, v4
	v_fma_f32 v4, v34, v34, v4
	v_fma_f32 v4, v35, v35, v4
	v_fma_f32 v4, v36, v36, v4
	v_fma_f32 v4, v37, v37, v4
	v_fma_f32 v4, v38, v38, v4
	v_fma_f32 v4, v39, v39, v4
	v_fma_f32 v4, v40, v40, v4
	v_fma_f32 v4, v41, v41, v4
	v_fma_f32 v4, v42, v42, v4
	v_fma_f32 v4, v43, v43, v4
	v_fma_f32 v4, v44, v44, v4
	v_fma_f32 v4, v45, v45, v4
	v_fma_f32 v4, v46, v46, v4
	v_fma_f32 v4, v47, v47, v4
	s_nop 1
	v_add_f32_dpp v5, v4, v4 quad_perm:[1,0,3,2] row_mask:0xf bank_mask:0xf
	s_nop 1
	v_add_f32_dpp v4, v5, v5 quad_perm:[2,3,0,1] row_mask:0xf bank_mask:0xf
	s_nop 1
	v_add_f32_dpp v5, v4, v4 row_half_mirror row_mask:0xf bank_mask:0xf
	s_nop 1
	v_add_f32_dpp v4, v5, v5 row_mirror row_mask:0xf bank_mask:0xf
	s_nop 1
	v_readlane_b32 s98, v4, 0
	v_readlane_b32 s99, v4, 16
	s_nop 3
	v_mov_b32_e32 v5, s98
	v_add_f32_e32 v5, s99, v5
	v_readlane_b32 s98, v4, 32
	v_readlane_b32 s99, v4, 48
	s_nop 3
	v_add_f32_e32 v5, s98, v5
	v_add_f32_e32 v5, s99, v5
	v_mul_f32_e32 v5, 0x3a800000, v5
	v_add_f32_e32 v5, 0x358637bd, v5
	v_rsq_f32_e32 v6, v5
	s_nop 0
	s_add_u32 s98, s97, 1792
	v_pk_mul_f32 v[32:33], v[32:33], v[6:7] op_sel_hi:[1,0]
	v_pk_mul_f32 v[34:35], v[34:35], v[6:7] op_sel_hi:[1,0]
	v_pk_mul_f32 v[36:37], v[36:37], v[6:7] op_sel_hi:[1,0]
	v_pk_mul_f32 v[38:39], v[38:39], v[6:7] op_sel_hi:[1,0]
	v_pk_mul_f32 v[40:41], v[40:41], v[6:7] op_sel_hi:[1,0]
	v_pk_mul_f32 v[42:43], v[42:43], v[6:7] op_sel_hi:[1,0]
	v_pk_mul_f32 v[44:45], v[44:45], v[6:7] op_sel_hi:[1,0]
	v_pk_mul_f32 v[46:47], v[46:47], v[6:7] op_sel_hi:[1,0]
	v_pk_mul_f32 v[32:33], v[32:33], v[112:113]
	v_pk_mul_f32 v[34:35], v[34:35], v[114:115]
	v_pk_mul_f32 v[36:37], v[36:37], v[116:117]
	v_pk_mul_f32 v[38:39], v[38:39], v[118:119]
	v_pk_mul_f32 v[40:41], v[40:41], v[120:121]
	v_pk_mul_f32 v[42:43], v[42:43], v[122:123]
	v_pk_mul_f32 v[44:45], v[44:45], v[124:125]
	v_pk_mul_f32 v[46:47], v[46:47], v[126:127]
	v_pk_fma_f32 v[32:33], v[32:33], v[128:129], v[144:145]
	v_pk_fma_f32 v[34:35], v[34:35], v[130:131], v[146:147]
	v_pk_fma_f32 v[36:37], v[36:37], v[132:133], v[148:149]
	v_pk_fma_f32 v[38:39], v[38:39], v[134:135], v[150:151]
	v_pk_fma_f32 v[40:41], v[40:41], v[136:137], v[152:153]
	v_pk_fma_f32 v[42:43], v[42:43], v[138:139], v[154:155]
	v_pk_fma_f32 v[44:45], v[44:45], v[140:141], v[156:157]
	v_pk_fma_f32 v[46:47], v[46:47], v[142:143], v[158:159]
	v_cvt_pk_bf16_f32 v32, v32, v33
	v_cvt_pk_bf16_f32 v33, v34, v35
	v_cvt_pk_bf16_f32 v34, v36, v37
	v_cvt_pk_bf16_f32 v35, v38, v39
	v_cvt_pk_bf16_f32 v36, v40, v41
	v_cvt_pk_bf16_f32 v37, v42, v43
	v_cvt_pk_bf16_f32 v38, v44, v45
	v_cvt_pk_bf16_f32 v39, v46, v47
	s_lshl_b32 s99, s98, 11
	v_lshl_add_u32 v8, v0, 3, s99
	global_store_dwordx2 v8, v[32:33], s[94:95]
	global_store_dwordx2 v8, v[34:35], s[94:95] offset:512
	global_store_dwordx2 v8, v[36:37], s[94:95] offset:1024
	global_store_dwordx2 v8, v[38:39], s[94:95] offset:1536
	s_lshl_b32 s99, s98, 2
	v_mov_b32_e32 v9, s99
	v_mov_b32_e32 v10, 0
	v_cmp_eq_u32_e32 vcc, 0, v0
	s_and_saveexec_b64 s[98:99], vcc
	global_store_dword v9, v10, s[90:91]
	global_store_dword v9, v10, s[92:93]
	s_or_b64 exec, exec, s[98:99]
	s_add_u32 s98, s97, 3328
	s_lshl_b32 s98, s98, 12
	v_add_u32_e32 v3, s98, v1
	global_load_dwordx4 v[32:35], v3, s[88:89] nt
	global_load_dwordx4 v[36:39], v3, s[88:89] offset:1024 nt
	global_load_dwordx4 v[40:43], v3, s[88:89] offset:2048 nt
	global_load_dwordx4 v[44:47], v3, s[88:89] offset:3072 nt
	s_waitcnt vmcnt(50)
	v_mul_f32_e32 v4, v48, v48
	v_fma_f32 v4, v49, v49, v4
	v_fma_f32 v4, v50, v50, v4
	v_fma_f32 v4, v51, v51, v4
	v_fma_f32 v4, v52, v52, v4
	v_fma_f32 v4, v53, v53, v4
	v_fma_f32 v4, v54, v54, v4
	v_fma_f32 v4, v55, v55, v4
	v_fma_f32 v4, v56, v56, v4
	v_fma_f32 v4, v57, v57, v4
	v_fma_f32 v4, v58, v58, v4
	v_fma_f32 v4, v59, v59, v4
	v_fma_f32 v4, v60, v60, v4
	v_fma_f32 v4, v61, v61, v4
	v_fma_f32 v4, v62, v62, v4
	v_fma_f32 v4, v63, v63, v4
	s_nop 1
	v_add_f32_dpp v5, v4, v4 quad_perm:[1,0,3,2] row_mask:0xf bank_mask:0xf
	s_nop 1
	v_add_f32_dpp v4, v5, v5 quad_perm:[2,3,0,1] row_mask:0xf bank_mask:0xf
	s_nop 1
	v_add_f32_dpp v5, v4, v4 row_half_mirror row_mask:0xf bank_mask:0xf
	s_nop 1
	v_add_f32_dpp v4, v5, v5 row_mirror row_mask:0xf bank_mask:0xf
	s_nop 1
	v_readlane_b32 s98, v4, 0
	v_readlane_b32 s99, v4, 16
	s_nop 3
	v_mov_b32_e32 v5, s98
	v_add_f32_e32 v5, s99, v5
	v_readlane_b32 s98, v4, 32
	v_readlane_b32 s99, v4, 48
	s_nop 3
	v_add_f32_e32 v5, s98, v5
	v_add_f32_e32 v5, s99, v5
	v_mul_f32_e32 v5, 0x3a800000, v5
	v_add_f32_e32 v5, 0x358637bd, v5
	v_rsq_f32_e32 v6, v5
	s_nop 0
	s_add_u32 s98, s97, 2048
	v_pk_mul_f32 v[48:49], v[48:49], v[6:7] op_sel_hi:[1,0]
	v_pk_mul_f32 v[50:51], v[50:51], v[6:7] op_sel_hi:[1,0]
	v_pk_mul_f32 v[52:53], v[52:53], v[6:7] op_sel_hi:[1,0]
	v_pk_mul_f32 v[54:55], v[54:55], v[6:7] op_sel_hi:[1,0]
	v_pk_mul_f32 v[56:57], v[56:57], v[6:7] op_sel_hi:[1,0]
	v_pk_mul_f32 v[58:59], v[58:59], v[6:7] op_sel_hi:[1,0]
	v_pk_mul_f32 v[60:61], v[60:61], v[6:7] op_sel_hi:[1,0]
	v_pk_mul_f32 v[62:63], v[62:63], v[6:7] op_sel_hi:[1,0]
	v_pk_mul_f32 v[48:49], v[48:49], v[112:113]
	v_pk_mul_f32 v[50:51], v[50:51], v[114:115]
	v_pk_mul_f32 v[52:53], v[52:53], v[116:117]
	v_pk_mul_f32 v[54:55], v[54:55], v[118:119]
	v_pk_mul_f32 v[56:57], v[56:57], v[120:121]
	v_pk_mul_f32 v[58:59], v[58:59], v[122:123]
	v_pk_mul_f32 v[60:61], v[60:61], v[124:125]
	v_pk_mul_f32 v[62:63], v[62:63], v[126:127]
	v_pk_fma_f32 v[48:49], v[48:49], v[128:129], v[144:145]
	v_pk_fma_f32 v[50:51], v[50:51], v[130:131], v[146:147]
	v_pk_fma_f32 v[52:53], v[52:53], v[132:133], v[148:149]
	v_pk_fma_f32 v[54:55], v[54:55], v[134:135], v[150:151]
	v_pk_fma_f32 v[56:57], v[56:57], v[136:137], v[152:153]
	v_pk_fma_f32 v[58:59], v[58:59], v[138:139], v[154:155]
	v_pk_fma_f32 v[60:61], v[60:61], v[140:141], v[156:157]
	v_pk_fma_f32 v[62:63], v[62:63], v[142:143], v[158:159]
	v_cvt_pk_bf16_f32 v48, v48, v49
	v_cvt_pk_bf16_f32 v49, v50, v51
	v_cvt_pk_bf16_f32 v50, v52, v53
	v_cvt_pk_bf16_f32 v51, v54, v55
	v_cvt_pk_bf16_f32 v52, v56, v57
	v_cvt_pk_bf16_f32 v53, v58, v59
	v_cvt_pk_bf16_f32 v54, v60, v61
	v_cvt_pk_bf16_f32 v55, v62, v63
	s_lshl_b32 s99, s98, 11
	v_lshl_add_u32 v8, v0, 3, s99
	global_store_dwordx2 v8, v[48:49], s[94:95]
	global_store_dwordx2 v8, v[50:51], s[94:95] offset:512
	global_store_dwordx2 v8, v[52:53], s[94:95] offset:1024
	global_store_dwordx2 v8, v[54:55], s[94:95] offset:1536
	s_lshl_b32 s99, s98, 2
	v_mov_b32_e32 v9, s99
	v_mov_b32_e32 v10, 0
	v_cmp_eq_u32_e32 vcc, 0, v0
	s_and_saveexec_b64 s[98:99], vcc
	global_store_dword v9, v10, s[90:91]
	global_store_dword v9, v10, s[92:93]
	s_or_b64 exec, exec, s[98:99]
	s_add_u32 s98, s97, 3584
	s_lshl_b32 s98, s98, 12
	v_add_u32_e32 v3, s98, v1
	global_load_dwordx4 v[48:51], v3, s[88:89] nt
	global_load_dwordx4 v[52:55], v3, s[88:89] offset:1024 nt
	global_load_dwordx4 v[56:59], v3, s[88:89] offset:2048 nt
	global_load_dwordx4 v[60:63], v3, s[88:89] offset:3072 nt
	s_waitcnt vmcnt(50)
	v_mul_f32_e32 v4, v64, v64
	v_fma_f32 v4, v65, v65, v4
	v_fma_f32 v4, v66, v66, v4
	v_fma_f32 v4, v67, v67, v4
	v_fma_f32 v4, v68, v68, v4
	v_fma_f32 v4, v69, v69, v4
	v_fma_f32 v4, v70, v70, v4
	v_fma_f32 v4, v71, v71, v4
	v_fma_f32 v4, v72, v72, v4
	v_fma_f32 v4, v73, v73, v4
	v_fma_f32 v4, v74, v74, v4
	v_fma_f32 v4, v75, v75, v4
	v_fma_f32 v4, v76, v76, v4
	v_fma_f32 v4, v77, v77, v4
	v_fma_f32 v4, v78, v78, v4
	v_fma_f32 v4, v79, v79, v4
	s_nop 1
	v_add_f32_dpp v5, v4, v4 quad_perm:[1,0,3,2] row_mask:0xf bank_mask:0xf
	s_nop 1
	v_add_f32_dpp v4, v5, v5 quad_perm:[2,3,0,1] row_mask:0xf bank_mask:0xf
	s_nop 1
	v_add_f32_dpp v5, v4, v4 row_half_mirror row_mask:0xf bank_mask:0xf
	s_nop 1
	v_add_f32_dpp v4, v5, v5 row_mirror row_mask:0xf bank_mask:0xf
	s_nop 1
	v_readlane_b32 s98, v4, 0
	v_readlane_b32 s99, v4, 16
	s_nop 3
	v_mov_b32_e32 v5, s98
	v_add_f32_e32 v5, s99, v5
	v_readlane_b32 s98, v4, 32
	v_readlane_b32 s99, v4, 48
	s_nop 3
	v_add_f32_e32 v5, s98, v5
	v_add_f32_e32 v5, s99, v5
	v_mul_f32_e32 v5, 0x3a800000, v5
	v_add_f32_e32 v5, 0x358637bd, v5
	v_rsq_f32_e32 v6, v5
	s_nop 0
	s_add_u32 s98, s97, 2304
	v_pk_mul_f32 v[64:65], v[64:65], v[6:7] op_sel_hi:[1,0]
	v_pk_mul_f32 v[66:67], v[66:67], v[6:7] op_sel_hi:[1,0]
	v_pk_mul_f32 v[68:69], v[68:69], v[6:7] op_sel_hi:[1,0]
	v_pk_mul_f32 v[70:71], v[70:71], v[6:7] op_sel_hi:[1,0]
	v_pk_mul_f32 v[72:73], v[72:73], v[6:7] op_sel_hi:[1,0]
	v_pk_mul_f32 v[74:75], v[74:75], v[6:7] op_sel_hi:[1,0]
	v_pk_mul_f32 v[76:77], v[76:77], v[6:7] op_sel_hi:[1,0]
	v_pk_mul_f32 v[78:79], v[78:79], v[6:7] op_sel_hi:[1,0]
	v_pk_mul_f32 v[64:65], v[64:65], v[112:113]
	v_pk_mul_f32 v[66:67], v[66:67], v[114:115]
	v_pk_mul_f32 v[68:69], v[68:69], v[116:117]
	v_pk_mul_f32 v[70:71], v[70:71], v[118:119]
	v_pk_mul_f32 v[72:73], v[72:73], v[120:121]
	v_pk_mul_f32 v[74:75], v[74:75], v[122:123]
	v_pk_mul_f32 v[76:77], v[76:77], v[124:125]
	v_pk_mul_f32 v[78:79], v[78:79], v[126:127]
	v_pk_fma_f32 v[64:65], v[64:65], v[128:129], v[144:145]
	v_pk_fma_f32 v[66:67], v[66:67], v[130:131], v[146:147]
	v_pk_fma_f32 v[68:69], v[68:69], v[132:133], v[148:149]
	v_pk_fma_f32 v[70:71], v[70:71], v[134:135], v[150:151]
	v_pk_fma_f32 v[72:73], v[72:73], v[136:137], v[152:153]
	v_pk_fma_f32 v[74:75], v[74:75], v[138:139], v[154:155]
	v_pk_fma_f32 v[76:77], v[76:77], v[140:141], v[156:157]
	v_pk_fma_f32 v[78:79], v[78:79], v[142:143], v[158:159]
	v_cvt_pk_bf16_f32 v64, v64, v65
	v_cvt_pk_bf16_f32 v65, v66, v67
	v_cvt_pk_bf16_f32 v66, v68, v69
	v_cvt_pk_bf16_f32 v67, v70, v71
	v_cvt_pk_bf16_f32 v68, v72, v73
	v_cvt_pk_bf16_f32 v69, v74, v75
	v_cvt_pk_bf16_f32 v70, v76, v77
	v_cvt_pk_bf16_f32 v71, v78, v79
	s_lshl_b32 s99, s98, 11
	v_lshl_add_u32 v8, v0, 3, s99
	global_store_dwordx2 v8, v[64:65], s[94:95]
	global_store_dwordx2 v8, v[66:67], s[94:95] offset:512
	global_store_dwordx2 v8, v[68:69], s[94:95] offset:1024
	global_store_dwordx2 v8, v[70:71], s[94:95] offset:1536
	s_lshl_b32 s99, s98, 2
	v_mov_b32_e32 v9, s99
	v_mov_b32_e32 v10, 0
	v_cmp_eq_u32_e32 vcc, 0, v0
	s_and_saveexec_b64 s[98:99], vcc
	global_store_dword v9, v10, s[90:91]
	global_store_dword v9, v10, s[92:93]
	s_or_b64 exec, exec, s[98:99]
	s_add_u32 s98, s97, 3840
	s_lshl_b32 s98, s98, 12
	v_add_u32_e32 v3, s98, v1
	global_load_dwordx4 v[64:67], v3, s[88:89] nt
	global_load_dwordx4 v[68:71], v3, s[88:89] offset:1024 nt
	global_load_dwordx4 v[72:75], v3, s[88:89] offset:2048 nt
	global_load_dwordx4 v[76:79], v3, s[88:89] offset:3072 nt
	s_waitcnt vmcnt(50)
	v_mul_f32_e32 v4, v80, v80
	v_fma_f32 v4, v81, v81, v4
	v_fma_f32 v4, v82, v82, v4
	v_fma_f32 v4, v83, v83, v4
	v_fma_f32 v4, v84, v84, v4
	v_fma_f32 v4, v85, v85, v4
	v_fma_f32 v4, v86, v86, v4
	v_fma_f32 v4, v87, v87, v4
	v_fma_f32 v4, v88, v88, v4
	v_fma_f32 v4, v89, v89, v4
	v_fma_f32 v4, v90, v90, v4
	v_fma_f32 v4, v91, v91, v4
	v_fma_f32 v4, v92, v92, v4
	v_fma_f32 v4, v93, v93, v4
	v_fma_f32 v4, v94, v94, v4
	v_fma_f32 v4, v95, v95, v4
	s_nop 1
	v_add_f32_dpp v5, v4, v4 quad_perm:[1,0,3,2] row_mask:0xf bank_mask:0xf
	s_nop 1
	v_add_f32_dpp v4, v5, v5 quad_perm:[2,3,0,1] row_mask:0xf bank_mask:0xf
	s_nop 1
	v_add_f32_dpp v5, v4, v4 row_half_mirror row_mask:0xf bank_mask:0xf
	s_nop 1
	v_add_f32_dpp v4, v5, v5 row_mirror row_mask:0xf bank_mask:0xf
	s_nop 1
	v_readlane_b32 s98, v4, 0
	v_readlane_b32 s99, v4, 16
	s_nop 3
	v_mov_b32_e32 v5, s98
	v_add_f32_e32 v5, s99, v5
	v_readlane_b32 s98, v4, 32
	v_readlane_b32 s99, v4, 48
	s_nop 3
	v_add_f32_e32 v5, s98, v5
	v_add_f32_e32 v5, s99, v5
	v_mul_f32_e32 v5, 0x3a800000, v5
	v_add_f32_e32 v5, 0x358637bd, v5
	v_rsq_f32_e32 v6, v5
	s_nop 0
	s_add_u32 s98, s97, 2560
	v_pk_mul_f32 v[80:81], v[80:81], v[6:7] op_sel_hi:[1,0]
	v_pk_mul_f32 v[82:83], v[82:83], v[6:7] op_sel_hi:[1,0]
	v_pk_mul_f32 v[84:85], v[84:85], v[6:7] op_sel_hi:[1,0]
	v_pk_mul_f32 v[86:87], v[86:87], v[6:7] op_sel_hi:[1,0]
	v_pk_mul_f32 v[88:89], v[88:89], v[6:7] op_sel_hi:[1,0]
	v_pk_mul_f32 v[90:91], v[90:91], v[6:7] op_sel_hi:[1,0]
	v_pk_mul_f32 v[92:93], v[92:93], v[6:7] op_sel_hi:[1,0]
	v_pk_mul_f32 v[94:95], v[94:95], v[6:7] op_sel_hi:[1,0]
	v_pk_mul_f32 v[80:81], v[80:81], v[112:113]
	v_pk_mul_f32 v[82:83], v[82:83], v[114:115]
	v_pk_mul_f32 v[84:85], v[84:85], v[116:117]
	v_pk_mul_f32 v[86:87], v[86:87], v[118:119]
	v_pk_mul_f32 v[88:89], v[88:89], v[120:121]
	v_pk_mul_f32 v[90:91], v[90:91], v[122:123]
	v_pk_mul_f32 v[92:93], v[92:93], v[124:125]
	v_pk_mul_f32 v[94:95], v[94:95], v[126:127]
	v_pk_fma_f32 v[80:81], v[80:81], v[128:129], v[144:145]
	v_pk_fma_f32 v[82:83], v[82:83], v[130:131], v[146:147]
	v_pk_fma_f32 v[84:85], v[84:85], v[132:133], v[148:149]
	v_pk_fma_f32 v[86:87], v[86:87], v[134:135], v[150:151]
	v_pk_fma_f32 v[88:89], v[88:89], v[136:137], v[152:153]
	v_pk_fma_f32 v[90:91], v[90:91], v[138:139], v[154:155]
	v_pk_fma_f32 v[92:93], v[92:93], v[140:141], v[156:157]
	v_pk_fma_f32 v[94:95], v[94:95], v[142:143], v[158:159]
	v_cvt_pk_bf16_f32 v80, v80, v81
	v_cvt_pk_bf16_f32 v81, v82, v83
	v_cvt_pk_bf16_f32 v82, v84, v85
	v_cvt_pk_bf16_f32 v83, v86, v87
	v_cvt_pk_bf16_f32 v84, v88, v89
	v_cvt_pk_bf16_f32 v85, v90, v91
	v_cvt_pk_bf16_f32 v86, v92, v93
	v_cvt_pk_bf16_f32 v87, v94, v95
	s_lshl_b32 s99, s98, 11
	v_lshl_add_u32 v8, v0, 3, s99
	global_store_dwordx2 v8, v[80:81], s[94:95]
	global_store_dwordx2 v8, v[82:83], s[94:95] offset:512
	global_store_dwordx2 v8, v[84:85], s[94:95] offset:1024
	global_store_dwordx2 v8, v[86:87], s[94:95] offset:1536
	s_lshl_b32 s99, s98, 2
	v_mov_b32_e32 v9, s99
	v_mov_b32_e32 v10, 0
	v_cmp_eq_u32_e32 vcc, 0, v0
	s_and_saveexec_b64 s[98:99], vcc
	global_store_dword v9, v10, s[90:91]
	global_store_dword v9, v10, s[92:93]
	s_or_b64 exec, exec, s[98:99]
	s_waitcnt vmcnt(46)
	v_mul_f32_e32 v4, v96, v96
	v_fma_f32 v4, v97, v97, v4
	v_fma_f32 v4, v98, v98, v4
	v_fma_f32 v4, v99, v99, v4
	v_fma_f32 v4, v100, v100, v4
	v_fma_f32 v4, v101, v101, v4
	v_fma_f32 v4, v102, v102, v4
	v_fma_f32 v4, v103, v103, v4
	v_fma_f32 v4, v104, v104, v4
	v_fma_f32 v4, v105, v105, v4
	v_fma_f32 v4, v106, v106, v4
	v_fma_f32 v4, v107, v107, v4
	v_fma_f32 v4, v108, v108, v4
	v_fma_f32 v4, v109, v109, v4
	v_fma_f32 v4, v110, v110, v4
	v_fma_f32 v4, v111, v111, v4
	s_nop 1
	v_add_f32_dpp v5, v4, v4 quad_perm:[1,0,3,2] row_mask:0xf bank_mask:0xf
	s_nop 1
	v_add_f32_dpp v4, v5, v5 quad_perm:[2,3,0,1] row_mask:0xf bank_mask:0xf
	s_nop 1
	v_add_f32_dpp v5, v4, v4 row_half_mirror row_mask:0xf bank_mask:0xf
	s_nop 1
	v_add_f32_dpp v4, v5, v5 row_mirror row_mask:0xf bank_mask:0xf
	s_nop 1
	v_readlane_b32 s98, v4, 0
	v_readlane_b32 s99, v4, 16
	s_nop 3
	v_mov_b32_e32 v5, s98
	v_add_f32_e32 v5, s99, v5
	v_readlane_b32 s98, v4, 32
	v_readlane_b32 s99, v4, 48
	s_nop 3
	v_add_f32_e32 v5, s98, v5
	v_add_f32_e32 v5, s99, v5
	v_mul_f32_e32 v5, 0x3a800000, v5
	v_add_f32_e32 v5, 0x358637bd, v5
	v_rsq_f32_e32 v6, v5
	s_nop 0
	s_add_u32 s98, s97, 2816
	v_pk_mul_f32 v[96:97], v[96:97], v[6:7] op_sel_hi:[1,0]
	v_pk_mul_f32 v[98:99], v[98:99], v[6:7] op_sel_hi:[1,0]
	v_pk_mul_f32 v[100:101], v[100:101], v[6:7] op_sel_hi:[1,0]
	v_pk_mul_f32 v[102:103], v[102:103], v[6:7] op_sel_hi:[1,0]
	v_pk_mul_f32 v[104:105], v[104:105], v[6:7] op_sel_hi:[1,0]
	v_pk_mul_f32 v[106:107], v[106:107], v[6:7] op_sel_hi:[1,0]
	v_pk_mul_f32 v[108:109], v[108:109], v[6:7] op_sel_hi:[1,0]
	v_pk_mul_f32 v[110:111], v[110:111], v[6:7] op_sel_hi:[1,0]
	v_pk_mul_f32 v[96:97], v[96:97], v[112:113]
	v_pk_mul_f32 v[98:99], v[98:99], v[114:115]
	v_pk_mul_f32 v[100:101], v[100:101], v[116:117]
	v_pk_mul_f32 v[102:103], v[102:103], v[118:119]
	v_pk_mul_f32 v[104:105], v[104:105], v[120:121]
	v_pk_mul_f32 v[106:107], v[106:107], v[122:123]
	v_pk_mul_f32 v[108:109], v[108:109], v[124:125]
	v_pk_mul_f32 v[110:111], v[110:111], v[126:127]
	v_pk_fma_f32 v[96:97], v[96:97], v[128:129], v[144:145]
	v_pk_fma_f32 v[98:99], v[98:99], v[130:131], v[146:147]
	v_pk_fma_f32 v[100:101], v[100:101], v[132:133], v[148:149]
	v_pk_fma_f32 v[102:103], v[102:103], v[134:135], v[150:151]
	v_pk_fma_f32 v[104:105], v[104:105], v[136:137], v[152:153]
	v_pk_fma_f32 v[106:107], v[106:107], v[138:139], v[154:155]
	v_pk_fma_f32 v[108:109], v[108:109], v[140:141], v[156:157]
	v_pk_fma_f32 v[110:111], v[110:111], v[142:143], v[158:159]
	v_cvt_pk_bf16_f32 v96, v96, v97
	v_cvt_pk_bf16_f32 v97, v98, v99
	v_cvt_pk_bf16_f32 v98, v100, v101
	v_cvt_pk_bf16_f32 v99, v102, v103
	v_cvt_pk_bf16_f32 v100, v104, v105
	v_cvt_pk_bf16_f32 v101, v106, v107
	v_cvt_pk_bf16_f32 v102, v108, v109
	v_cvt_pk_bf16_f32 v103, v110, v111
	s_lshl_b32 s99, s98, 11
	v_lshl_add_u32 v8, v0, 3, s99
	global_store_dwordx2 v8, v[96:97], s[94:95]
	global_store_dwordx2 v8, v[98:99], s[94:95] offset:512
	global_store_dwordx2 v8, v[100:101], s[94:95] offset:1024
	global_store_dwordx2 v8, v[102:103], s[94:95] offset:1536
	s_lshl_b32 s99, s98, 2
	v_mov_b32_e32 v9, s99
	v_mov_b32_e32 v10, 0
	v_cmp_eq_u32_e32 vcc, 0, v0
	s_and_saveexec_b64 s[98:99], vcc
	global_store_dword v9, v10, s[90:91]
	global_store_dword v9, v10, s[92:93]
	s_or_b64 exec, exec, s[98:99]
	s_waitcnt vmcnt(42)
	v_mul_f32_e32 v4, v16, v16
	v_fma_f32 v4, v17, v17, v4
	v_fma_f32 v4, v18, v18, v4
	v_fma_f32 v4, v19, v19, v4
	v_fma_f32 v4, v20, v20, v4
	v_fma_f32 v4, v21, v21, v4
	v_fma_f32 v4, v22, v22, v4
	v_fma_f32 v4, v23, v23, v4
	v_fma_f32 v4, v24, v24, v4
	v_fma_f32 v4, v25, v25, v4
	v_fma_f32 v4, v26, v26, v4
	v_fma_f32 v4, v27, v27, v4
	v_fma_f32 v4, v28, v28, v4
	v_fma_f32 v4, v29, v29, v4
	v_fma_f32 v4, v30, v30, v4
	v_fma_f32 v4, v31, v31, v4
	s_nop 1
	v_add_f32_dpp v5, v4, v4 quad_perm:[1,0,3,2] row_mask:0xf bank_mask:0xf
	s_nop 1
	v_add_f32_dpp v4, v5, v5 quad_perm:[2,3,0,1] row_mask:0xf bank_mask:0xf
	s_nop 1
	v_add_f32_dpp v5, v4, v4 row_half_mirror row_mask:0xf bank_mask:0xf
	s_nop 1
	v_add_f32_dpp v4, v5, v5 row_mirror row_mask:0xf bank_mask:0xf
	s_nop 1
	v_readlane_b32 s98, v4, 0
	v_readlane_b32 s99, v4, 16
	s_nop 3
	v_mov_b32_e32 v5, s98
	v_add_f32_e32 v5, s99, v5
	v_readlane_b32 s98, v4, 32
	v_readlane_b32 s99, v4, 48
	s_nop 3
	v_add_f32_e32 v5, s98, v5
	v_add_f32_e32 v5, s99, v5
	v_mul_f32_e32 v5, 0x3a800000, v5
	v_add_f32_e32 v5, 0x358637bd, v5
	v_rsq_f32_e32 v6, v5
	s_nop 0
	s_add_u32 s98, s97, 3072
	v_pk_mul_f32 v[16:17], v[16:17], v[6:7] op_sel_hi:[1,0]
	v_pk_mul_f32 v[18:19], v[18:19], v[6:7] op_sel_hi:[1,0]
	v_pk_mul_f32 v[20:21], v[20:21], v[6:7] op_sel_hi:[1,0]
	v_pk_mul_f32 v[22:23], v[22:23], v[6:7] op_sel_hi:[1,0]
	v_pk_mul_f32 v[24:25], v[24:25], v[6:7] op_sel_hi:[1,0]
	v_pk_mul_f32 v[26:27], v[26:27], v[6:7] op_sel_hi:[1,0]
	v_pk_mul_f32 v[28:29], v[28:29], v[6:7] op_sel_hi:[1,0]
	v_pk_mul_f32 v[30:31], v[30:31], v[6:7] op_sel_hi:[1,0]
	v_pk_mul_f32 v[16:17], v[16:17], v[112:113]
	v_pk_mul_f32 v[18:19], v[18:19], v[114:115]
	v_pk_mul_f32 v[20:21], v[20:21], v[116:117]
	v_pk_mul_f32 v[22:23], v[22:23], v[118:119]
	v_pk_mul_f32 v[24:25], v[24:25], v[120:121]
	v_pk_mul_f32 v[26:27], v[26:27], v[122:123]
	v_pk_mul_f32 v[28:29], v[28:29], v[124:125]
	v_pk_mul_f32 v[30:31], v[30:31], v[126:127]
	v_pk_fma_f32 v[16:17], v[16:17], v[128:129], v[144:145]
	v_pk_fma_f32 v[18:19], v[18:19], v[130:131], v[146:147]
	v_pk_fma_f32 v[20:21], v[20:21], v[132:133], v[148:149]
	v_pk_fma_f32 v[22:23], v[22:23], v[134:135], v[150:151]
	v_pk_fma_f32 v[24:25], v[24:25], v[136:137], v[152:153]
	v_pk_fma_f32 v[26:27], v[26:27], v[138:139], v[154:155]
	v_pk_fma_f32 v[28:29], v[28:29], v[140:141], v[156:157]
	v_pk_fma_f32 v[30:31], v[30:31], v[142:143], v[158:159]
	v_cvt_pk_bf16_f32 v16, v16, v17
	v_cvt_pk_bf16_f32 v17, v18, v19
	v_cvt_pk_bf16_f32 v18, v20, v21
	v_cvt_pk_bf16_f32 v19, v22, v23
	v_cvt_pk_bf16_f32 v20, v24, v25
	v_cvt_pk_bf16_f32 v21, v26, v27
	v_cvt_pk_bf16_f32 v22, v28, v29
	v_cvt_pk_bf16_f32 v23, v30, v31
	s_lshl_b32 s99, s98, 11
	v_lshl_add_u32 v8, v0, 3, s99
	global_store_dwordx2 v8, v[16:17], s[94:95]
	global_store_dwordx2 v8, v[18:19], s[94:95] offset:512
	global_store_dwordx2 v8, v[20:21], s[94:95] offset:1024
	global_store_dwordx2 v8, v[22:23], s[94:95] offset:1536
	s_lshl_b32 s99, s98, 2
	v_mov_b32_e32 v9, s99
	v_mov_b32_e32 v10, 0
	v_cmp_eq_u32_e32 vcc, 0, v0
	s_and_saveexec_b64 s[98:99], vcc
	global_store_dword v9, v10, s[90:91]
	global_store_dword v9, v10, s[92:93]
	s_or_b64 exec, exec, s[98:99]
	s_waitcnt vmcnt(38)
	v_mul_f32_e32 v4, v32, v32
	v_fma_f32 v4, v33, v33, v4
	v_fma_f32 v4, v34, v34, v4
	v_fma_f32 v4, v35, v35, v4
	v_fma_f32 v4, v36, v36, v4
	v_fma_f32 v4, v37, v37, v4
	v_fma_f32 v4, v38, v38, v4
	v_fma_f32 v4, v39, v39, v4
	v_fma_f32 v4, v40, v40, v4
	v_fma_f32 v4, v41, v41, v4
	v_fma_f32 v4, v42, v42, v4
	v_fma_f32 v4, v43, v43, v4
	v_fma_f32 v4, v44, v44, v4
	v_fma_f32 v4, v45, v45, v4
	v_fma_f32 v4, v46, v46, v4
	v_fma_f32 v4, v47, v47, v4
	s_nop 1
	v_add_f32_dpp v5, v4, v4 quad_perm:[1,0,3,2] row_mask:0xf bank_mask:0xf
	s_nop 1
	v_add_f32_dpp v4, v5, v5 quad_perm:[2,3,0,1] row_mask:0xf bank_mask:0xf
	s_nop 1
	v_add_f32_dpp v5, v4, v4 row_half_mirror row_mask:0xf bank_mask:0xf
	s_nop 1
	v_add_f32_dpp v4, v5, v5 row_mirror row_mask:0xf bank_mask:0xf
	s_nop 1
	v_readlane_b32 s98, v4, 0
	v_readlane_b32 s99, v4, 16
	s_nop 3
	v_mov_b32_e32 v5, s98
	v_add_f32_e32 v5, s99, v5
	v_readlane_b32 s98, v4, 32
	v_readlane_b32 s99, v4, 48
	s_nop 3
	v_add_f32_e32 v5, s98, v5
	v_add_f32_e32 v5, s99, v5
	v_mul_f32_e32 v5, 0x3a800000, v5
	v_add_f32_e32 v5, 0x358637bd, v5
	v_rsq_f32_e32 v6, v5
	s_nop 0
	s_add_u32 s98, s97, 3328
	v_pk_mul_f32 v[32:33], v[32:33], v[6:7] op_sel_hi:[1,0]
	v_pk_mul_f32 v[34:35], v[34:35], v[6:7] op_sel_hi:[1,0]
	v_pk_mul_f32 v[36:37], v[36:37], v[6:7] op_sel_hi:[1,0]
	v_pk_mul_f32 v[38:39], v[38:39], v[6:7] op_sel_hi:[1,0]
	v_pk_mul_f32 v[40:41], v[40:41], v[6:7] op_sel_hi:[1,0]
	v_pk_mul_f32 v[42:43], v[42:43], v[6:7] op_sel_hi:[1,0]
	v_pk_mul_f32 v[44:45], v[44:45], v[6:7] op_sel_hi:[1,0]
	v_pk_mul_f32 v[46:47], v[46:47], v[6:7] op_sel_hi:[1,0]
	v_pk_mul_f32 v[32:33], v[32:33], v[112:113]
	v_pk_mul_f32 v[34:35], v[34:35], v[114:115]
	v_pk_mul_f32 v[36:37], v[36:37], v[116:117]
	v_pk_mul_f32 v[38:39], v[38:39], v[118:119]
	v_pk_mul_f32 v[40:41], v[40:41], v[120:121]
	v_pk_mul_f32 v[42:43], v[42:43], v[122:123]
	v_pk_mul_f32 v[44:45], v[44:45], v[124:125]
	v_pk_mul_f32 v[46:47], v[46:47], v[126:127]
	v_pk_fma_f32 v[32:33], v[32:33], v[128:129], v[144:145]
	v_pk_fma_f32 v[34:35], v[34:35], v[130:131], v[146:147]
	v_pk_fma_f32 v[36:37], v[36:37], v[132:133], v[148:149]
	v_pk_fma_f32 v[38:39], v[38:39], v[134:135], v[150:151]
	v_pk_fma_f32 v[40:41], v[40:41], v[136:137], v[152:153]
	v_pk_fma_f32 v[42:43], v[42:43], v[138:139], v[154:155]
	v_pk_fma_f32 v[44:45], v[44:45], v[140:141], v[156:157]
	v_pk_fma_f32 v[46:47], v[46:47], v[142:143], v[158:159]
	v_cvt_pk_bf16_f32 v32, v32, v33
	v_cvt_pk_bf16_f32 v33, v34, v35
	v_cvt_pk_bf16_f32 v34, v36, v37
	v_cvt_pk_bf16_f32 v35, v38, v39
	v_cvt_pk_bf16_f32 v36, v40, v41
	v_cvt_pk_bf16_f32 v37, v42, v43
	v_cvt_pk_bf16_f32 v38, v44, v45
	v_cvt_pk_bf16_f32 v39, v46, v47
	s_lshl_b32 s99, s98, 11
	v_lshl_add_u32 v8, v0, 3, s99
	global_store_dwordx2 v8, v[32:33], s[94:95]
	global_store_dwordx2 v8, v[34:35], s[94:95] offset:512
	global_store_dwordx2 v8, v[36:37], s[94:95] offset:1024
	global_store_dwordx2 v8, v[38:39], s[94:95] offset:1536
	s_lshl_b32 s99, s98, 2
	v_mov_b32_e32 v9, s99
	v_mov_b32_e32 v10, 0
	v_cmp_eq_u32_e32 vcc, 0, v0
	s_and_saveexec_b64 s[98:99], vcc
	global_store_dword v9, v10, s[90:91]
	global_store_dword v9, v10, s[92:93]
	s_or_b64 exec, exec, s[98:99]
	s_waitcnt vmcnt(34)
	v_mul_f32_e32 v4, v48, v48
	v_fma_f32 v4, v49, v49, v4
	v_fma_f32 v4, v50, v50, v4
	v_fma_f32 v4, v51, v51, v4
	v_fma_f32 v4, v52, v52, v4
	v_fma_f32 v4, v53, v53, v4
	v_fma_f32 v4, v54, v54, v4
	v_fma_f32 v4, v55, v55, v4
	v_fma_f32 v4, v56, v56, v4
	v_fma_f32 v4, v57, v57, v4
	v_fma_f32 v4, v58, v58, v4
	v_fma_f32 v4, v59, v59, v4
	v_fma_f32 v4, v60, v60, v4
	v_fma_f32 v4, v61, v61, v4
	v_fma_f32 v4, v62, v62, v4
	v_fma_f32 v4, v63, v63, v4
	s_nop 1
	v_add_f32_dpp v5, v4, v4 quad_perm:[1,0,3,2] row_mask:0xf bank_mask:0xf
	s_nop 1
	v_add_f32_dpp v4, v5, v5 quad_perm:[2,3,0,1] row_mask:0xf bank_mask:0xf
	s_nop 1
	v_add_f32_dpp v5, v4, v4 row_half_mirror row_mask:0xf bank_mask:0xf
	s_nop 1
	v_add_f32_dpp v4, v5, v5 row_mirror row_mask:0xf bank_mask:0xf
	s_nop 1
	v_readlane_b32 s98, v4, 0
	v_readlane_b32 s99, v4, 16
	s_nop 3
	v_mov_b32_e32 v5, s98
	v_add_f32_e32 v5, s99, v5
	v_readlane_b32 s98, v4, 32
	v_readlane_b32 s99, v4, 48
	s_nop 3
	v_add_f32_e32 v5, s98, v5
	v_add_f32_e32 v5, s99, v5
	v_mul_f32_e32 v5, 0x3a800000, v5
	v_add_f32_e32 v5, 0x358637bd, v5
	v_rsq_f32_e32 v6, v5
	s_nop 0
	s_add_u32 s98, s97, 3584
	v_pk_mul_f32 v[48:49], v[48:49], v[6:7] op_sel_hi:[1,0]
	v_pk_mul_f32 v[50:51], v[50:51], v[6:7] op_sel_hi:[1,0]
	v_pk_mul_f32 v[52:53], v[52:53], v[6:7] op_sel_hi:[1,0]
	v_pk_mul_f32 v[54:55], v[54:55], v[6:7] op_sel_hi:[1,0]
	v_pk_mul_f32 v[56:57], v[56:57], v[6:7] op_sel_hi:[1,0]
	v_pk_mul_f32 v[58:59], v[58:59], v[6:7] op_sel_hi:[1,0]
	v_pk_mul_f32 v[60:61], v[60:61], v[6:7] op_sel_hi:[1,0]
	v_pk_mul_f32 v[62:63], v[62:63], v[6:7] op_sel_hi:[1,0]
	v_pk_mul_f32 v[48:49], v[48:49], v[112:113]
	v_pk_mul_f32 v[50:51], v[50:51], v[114:115]
	v_pk_mul_f32 v[52:53], v[52:53], v[116:117]
	v_pk_mul_f32 v[54:55], v[54:55], v[118:119]
	v_pk_mul_f32 v[56:57], v[56:57], v[120:121]
	v_pk_mul_f32 v[58:59], v[58:59], v[122:123]
	v_pk_mul_f32 v[60:61], v[60:61], v[124:125]
	v_pk_mul_f32 v[62:63], v[62:63], v[126:127]
	v_pk_fma_f32 v[48:49], v[48:49], v[128:129], v[144:145]
	v_pk_fma_f32 v[50:51], v[50:51], v[130:131], v[146:147]
	v_pk_fma_f32 v[52:53], v[52:53], v[132:133], v[148:149]
	v_pk_fma_f32 v[54:55], v[54:55], v[134:135], v[150:151]
	v_pk_fma_f32 v[56:57], v[56:57], v[136:137], v[152:153]
	v_pk_fma_f32 v[58:59], v[58:59], v[138:139], v[154:155]
	v_pk_fma_f32 v[60:61], v[60:61], v[140:141], v[156:157]
	v_pk_fma_f32 v[62:63], v[62:63], v[142:143], v[158:159]
	v_cvt_pk_bf16_f32 v48, v48, v49
	v_cvt_pk_bf16_f32 v49, v50, v51
	v_cvt_pk_bf16_f32 v50, v52, v53
	v_cvt_pk_bf16_f32 v51, v54, v55
	v_cvt_pk_bf16_f32 v52, v56, v57
	v_cvt_pk_bf16_f32 v53, v58, v59
	v_cvt_pk_bf16_f32 v54, v60, v61
	v_cvt_pk_bf16_f32 v55, v62, v63
	s_lshl_b32 s99, s98, 11
	v_lshl_add_u32 v8, v0, 3, s99
	global_store_dwordx2 v8, v[48:49], s[94:95]
	global_store_dwordx2 v8, v[50:51], s[94:95] offset:512
	global_store_dwordx2 v8, v[52:53], s[94:95] offset:1024
	global_store_dwordx2 v8, v[54:55], s[94:95] offset:1536
	s_lshl_b32 s99, s98, 2
	v_mov_b32_e32 v9, s99
	v_mov_b32_e32 v10, 0
	v_cmp_eq_u32_e32 vcc, 0, v0
	s_and_saveexec_b64 s[98:99], vcc
	global_store_dword v9, v10, s[90:91]
	global_store_dword v9, v10, s[92:93]
	s_or_b64 exec, exec, s[98:99]
	s_waitcnt vmcnt(30)
	v_mul_f32_e32 v4, v64, v64
	v_fma_f32 v4, v65, v65, v4
	v_fma_f32 v4, v66, v66, v4
	v_fma_f32 v4, v67, v67, v4
	v_fma_f32 v4, v68, v68, v4
	v_fma_f32 v4, v69, v69, v4
	v_fma_f32 v4, v70, v70, v4
	v_fma_f32 v4, v71, v71, v4
	v_fma_f32 v4, v72, v72, v4
	v_fma_f32 v4, v73, v73, v4
	v_fma_f32 v4, v74, v74, v4
	v_fma_f32 v4, v75, v75, v4
	v_fma_f32 v4, v76, v76, v4
	v_fma_f32 v4, v77, v77, v4
	v_fma_f32 v4, v78, v78, v4
	v_fma_f32 v4, v79, v79, v4
	s_nop 1
	v_add_f32_dpp v5, v4, v4 quad_perm:[1,0,3,2] row_mask:0xf bank_mask:0xf
	s_nop 1
	v_add_f32_dpp v4, v5, v5 quad_perm:[2,3,0,1] row_mask:0xf bank_mask:0xf
	s_nop 1
	v_add_f32_dpp v5, v4, v4 row_half_mirror row_mask:0xf bank_mask:0xf
	s_nop 1
	v_add_f32_dpp v4, v5, v5 row_mirror row_mask:0xf bank_mask:0xf
	s_nop 1
	v_readlane_b32 s98, v4, 0
	v_readlane_b32 s99, v4, 16
	s_nop 3
	v_mov_b32_e32 v5, s98
	v_add_f32_e32 v5, s99, v5
	v_readlane_b32 s98, v4, 32
	v_readlane_b32 s99, v4, 48
	s_nop 3
	v_add_f32_e32 v5, s98, v5
	v_add_f32_e32 v5, s99, v5
	v_mul_f32_e32 v5, 0x3a800000, v5
	v_add_f32_e32 v5, 0x358637bd, v5
	v_rsq_f32_e32 v6, v5
	s_nop 0
	s_add_u32 s98, s97, 3840
	v_pk_mul_f32 v[64:65], v[64:65], v[6:7] op_sel_hi:[1,0]
	v_pk_mul_f32 v[66:67], v[66:67], v[6:7] op_sel_hi:[1,0]
	v_pk_mul_f32 v[68:69], v[68:69], v[6:7] op_sel_hi:[1,0]
	v_pk_mul_f32 v[70:71], v[70:71], v[6:7] op_sel_hi:[1,0]
	v_pk_mul_f32 v[72:73], v[72:73], v[6:7] op_sel_hi:[1,0]
	v_pk_mul_f32 v[74:75], v[74:75], v[6:7] op_sel_hi:[1,0]
	v_pk_mul_f32 v[76:77], v[76:77], v[6:7] op_sel_hi:[1,0]
	v_pk_mul_f32 v[78:79], v[78:79], v[6:7] op_sel_hi:[1,0]
	v_pk_mul_f32 v[64:65], v[64:65], v[112:113]
	v_pk_mul_f32 v[66:67], v[66:67], v[114:115]
	v_pk_mul_f32 v[68:69], v[68:69], v[116:117]
	v_pk_mul_f32 v[70:71], v[70:71], v[118:119]
	v_pk_mul_f32 v[72:73], v[72:73], v[120:121]
	v_pk_mul_f32 v[74:75], v[74:75], v[122:123]
	v_pk_mul_f32 v[76:77], v[76:77], v[124:125]
	v_pk_mul_f32 v[78:79], v[78:79], v[126:127]
	v_pk_fma_f32 v[64:65], v[64:65], v[128:129], v[144:145]
	v_pk_fma_f32 v[66:67], v[66:67], v[130:131], v[146:147]
	v_pk_fma_f32 v[68:69], v[68:69], v[132:133], v[148:149]
	v_pk_fma_f32 v[70:71], v[70:71], v[134:135], v[150:151]
	v_pk_fma_f32 v[72:73], v[72:73], v[136:137], v[152:153]
	v_pk_fma_f32 v[74:75], v[74:75], v[138:139], v[154:155]
	v_pk_fma_f32 v[76:77], v[76:77], v[140:141], v[156:157]
	v_pk_fma_f32 v[78:79], v[78:79], v[142:143], v[158:159]
	v_cvt_pk_bf16_f32 v64, v64, v65
	v_cvt_pk_bf16_f32 v65, v66, v67
	v_cvt_pk_bf16_f32 v66, v68, v69
	v_cvt_pk_bf16_f32 v67, v70, v71
	v_cvt_pk_bf16_f32 v68, v72, v73
	v_cvt_pk_bf16_f32 v69, v74, v75
	v_cvt_pk_bf16_f32 v70, v76, v77
	v_cvt_pk_bf16_f32 v71, v78, v79
	s_lshl_b32 s99, s98, 11
	v_lshl_add_u32 v8, v0, 3, s99
	global_store_dwordx2 v8, v[64:65], s[94:95]
	global_store_dwordx2 v8, v[66:67], s[94:95] offset:512
	global_store_dwordx2 v8, v[68:69], s[94:95] offset:1024
	global_store_dwordx2 v8, v[70:71], s[94:95] offset:1536
	s_lshl_b32 s99, s98, 2
	v_mov_b32_e32 v9, s99
	v_mov_b32_e32 v10, 0
	v_cmp_eq_u32_e32 vcc, 0, v0
	s_and_saveexec_b64 s[98:99], vcc
	global_store_dword v9, v10, s[90:91]
	global_store_dword v9, v10, s[92:93]
	s_or_b64 exec, exec, s[98:99]
	s_waitcnt vmcnt(0)

.LBB0_5762:
	s_cmp_gt_i32 s44, 22
	s_waitcnt lgkmcnt(0)
	s_cselect_b64 s[2:3], -1, 0
	s_cmp_lt_i32 s45, 23
	s_cselect_b64 s[4:5], -1, 0
	s_or_b64 s[2:3], s[2:3], s[4:5]
	s_and_b64 vcc, exec, s[2:3]
	s_cbranch_vccnz .LBB0_5820
	s_lshl_b32 s96, s22, 3
	s_lshr_b32 s97, s70, 6
	s_add_u32 s96, s96, s97
	s_lshr_b32 s97, s96, 8
	s_lshl_b32 s97, s97, 12
	s_and_b32 s99, s96, 0xff
	s_or_b32 s97, s97, s99
	s_cmpk_ge_u32 s97, 0x8000
	s_cbranch_scc1 .Lnp22_done
	s_load_dwordx2 s[88:89], s[0:1], 0xb8
	s_load_dwordx2 s[90:91], s[0:1], 0xb0
	v_mbcnt_hi_u32_b32 v0, -1, v210
	v_lshlrev_b32_e32 v1, 4, v0
	s_waitcnt lgkmcnt(0)
	global_load_dwordx4 v[112:115], v1, s[90:91] nt
	global_load_dwordx4 v[116:119], v1, s[90:91] offset:1024 nt
	global_load_dwordx4 v[120:123], v1, s[90:91] offset:2048 nt
	global_load_dwordx4 v[124:127], v1, s[90:91] offset:3072 nt
	s_waitcnt vmcnt(0) lgkmcnt(0)
	s_add_u32 s98, s97, 0
	s_lshl_b32 s98, s98, 12
	v_add_u32_e32 v3, s98, v1
	global_load_dwordx4 v[16:19], v3, s[88:89] nt
	global_load_dwordx4 v[20:23], v3, s[88:89] offset:1024 nt
	global_load_dwordx4 v[24:27], v3, s[88:89] offset:2048 nt
	global_load_dwordx4 v[28:31], v3, s[88:89] offset:3072 nt
	s_add_u32 s98, s97, 256
	s_lshl_b32 s98, s98, 12
	v_add_u32_e32 v3, s98, v1
	global_load_dwordx4 v[32:35], v3, s[88:89] nt
	global_load_dwordx4 v[36:39], v3, s[88:89] offset:1024 nt
	global_load_dwordx4 v[40:43], v3, s[88:89] offset:2048 nt
	global_load_dwordx4 v[44:47], v3, s[88:89] offset:3072 nt
	s_add_u32 s98, s97, 512
	s_lshl_b32 s98, s98, 12
	v_add_u32_e32 v3, s98, v1
	global_load_dwordx4 v[48:51], v3, s[88:89] nt
	global_load_dwordx4 v[52:55], v3, s[88:89] offset:1024 nt
	global_load_dwordx4 v[56:59], v3, s[88:89] offset:2048 nt
	global_load_dwordx4 v[60:63], v3, s[88:89] offset:3072 nt
	s_add_u32 s98, s97, 768
	s_lshl_b32 s98, s98, 12
	v_add_u32_e32 v3, s98, v1
	global_load_dwordx4 v[64:67], v3, s[88:89] nt
	global_load_dwordx4 v[68:71], v3, s[88:89] offset:1024 nt
	global_load_dwordx4 v[72:75], v3, s[88:89] offset:2048 nt
	global_load_dwordx4 v[76:79], v3, s[88:89] offset:3072 nt
	s_add_u32 s98, s97, 1024
	s_lshl_b32 s98, s98, 12
	v_add_u32_e32 v3, s98, v1
	global_load_dwordx4 v[80:83], v3, s[88:89] nt
	global_load_dwordx4 v[84:87], v3, s[88:89] offset:1024 nt
	global_load_dwordx4 v[88:91], v3, s[88:89] offset:2048 nt
	global_load_dwordx4 v[92:95], v3, s[88:89] offset:3072 nt
	s_add_u32 s98, s97, 1280
	s_lshl_b32 s98, s98, 12
	v_add_u32_e32 v3, s98, v1
	global_load_dwordx4 v[96:99], v3, s[88:89] nt
	global_load_dwordx4 v[100:103], v3, s[88:89] offset:1024 nt
	global_load_dwordx4 v[104:107], v3, s[88:89] offset:2048 nt
	global_load_dwordx4 v[108:111], v3, s[88:89] offset:3072 nt
	s_waitcnt vmcnt(20)
	v_mul_f32_e32 v4, v16, v16
	v_fma_f32 v4, v17, v17, v4
	v_fma_f32 v4, v18, v18, v4
	v_fma_f32 v4, v19, v19, v4
	v_fma_f32 v4, v20, v20, v4
	v_fma_f32 v4, v21, v21, v4
	v_fma_f32 v4, v22, v22, v4
	v_fma_f32 v4, v23, v23, v4
	v_fma_f32 v4, v24, v24, v4
	v_fma_f32 v4, v25, v25, v4
	v_fma_f32 v4, v26, v26, v4
	v_fma_f32 v4, v27, v27, v4
	v_fma_f32 v4, v28, v28, v4
	v_fma_f32 v4, v29, v29, v4
	v_fma_f32 v4, v30, v30, v4
	v_fma_f32 v4, v31, v31, v4
	s_nop 1
	v_add_f32_dpp v5, v4, v4 quad_perm:[1,0,3,2] row_mask:0xf bank_mask:0xf
	s_nop 1
	v_add_f32_dpp v4, v5, v5 quad_perm:[2,3,0,1] row_mask:0xf bank_mask:0xf
	s_nop 1
	v_add_f32_dpp v5, v4, v4 row_half_mirror row_mask:0xf bank_mask:0xf
	s_nop 1
	v_add_f32_dpp v4, v5, v5 row_mirror row_mask:0xf bank_mask:0xf
	s_nop 1
	v_readlane_b32 s98, v4, 0
	v_readlane_b32 s99, v4, 16
	s_nop 3
	v_mov_b32_e32 v5, s98
	v_add_f32_e32 v5, s99, v5
	v_readlane_b32 s98, v4, 32
	v_readlane_b32 s99, v4, 48
	s_nop 3
	v_add_f32_e32 v5, s98, v5
	v_add_f32_e32 v5, s99, v5
	v_mul_f32_e32 v5, 0x3a800000, v5
	v_add_f32_e32 v5, 0x358637bd, v5
	v_rsq_f32_e32 v6, v5
	s_nop 0
	s_add_u32 s98, s97, 0
	v_pk_mul_f32 v[16:17], v[16:17], v[6:7] op_sel_hi:[1,0]
	v_pk_mul_f32 v[18:19], v[18:19], v[6:7] op_sel_hi:[1,0]
	v_pk_mul_f32 v[20:21], v[20:21], v[6:7] op_sel_hi:[1,0]
	v_pk_mul_f32 v[22:23], v[22:23], v[6:7] op_sel_hi:[1,0]
	v_pk_mul_f32 v[24:25], v[24:25], v[6:7] op_sel_hi:[1,0]
	v_pk_mul_f32 v[26:27], v[26:27], v[6:7] op_sel_hi:[1,0]
	v_pk_mul_f32 v[28:29], v[28:29], v[6:7] op_sel_hi:[1,0]
	v_pk_mul_f32 v[30:31], v[30:31], v[6:7] op_sel_hi:[1,0]
	v_pk_mul_f32 v[16:17], v[16:17], v[112:113]
	v_pk_mul_f32 v[18:19], v[18:19], v[114:115]
	v_pk_mul_f32 v[20:21], v[20:21], v[116:117]
	v_pk_mul_f32 v[22:23], v[22:23], v[118:119]
	v_pk_mul_f32 v[24:25], v[24:25], v[120:121]
	v_pk_mul_f32 v[26:27], v[26:27], v[122:123]
	v_pk_mul_f32 v[28:29], v[28:29], v[124:125]
	v_pk_mul_f32 v[30:31], v[30:31], v[126:127]
	s_lshl_b32 s99, s98, 12
	v_add_u32_e32 v8, s99, v1
	global_store_dwordx4 v8, v[16:19], s[88:89] nt
	global_store_dwordx4 v8, v[20:23], s[88:89] offset:1024 nt
	global_store_dwordx4 v8, v[24:27], s[88:89] offset:2048 nt
	global_store_dwordx4 v8, v[28:31], s[88:89] offset:3072 nt
	s_add_u32 s98, s97, 1536
	s_lshl_b32 s98, s98, 12
	v_add_u32_e32 v3, s98, v1
	global_load_dwordx4 v[16:19], v3, s[88:89] nt
	global_load_dwordx4 v[20:23], v3, s[88:89] offset:1024 nt
	global_load_dwordx4 v[24:27], v3, s[88:89] offset:2048 nt
	global_load_dwordx4 v[28:31], v3, s[88:89] offset:3072 nt
	s_waitcnt vmcnt(24)
	v_mul_f32_e32 v4, v32, v32
	v_fma_f32 v4, v33, v33, v4
	v_fma_f32 v4, v34, v34, v4
	v_fma_f32 v4, v35, v35, v4
	v_fma_f32 v4, v36, v36, v4
	v_fma_f32 v4, v37, v37, v4
	v_fma_f32 v4, v38, v38, v4
	v_fma_f32 v4, v39, v39, v4
	v_fma_f32 v4, v40, v40, v4
	v_fma_f32 v4, v41, v41, v4
	v_fma_f32 v4, v42, v42, v4
	v_fma_f32 v4, v43, v43, v4
	v_fma_f32 v4, v44, v44, v4
	v_fma_f32 v4, v45, v45, v4
	v_fma_f32 v4, v46, v46, v4
	v_fma_f32 v4, v47, v47, v4
	s_nop 1
	v_add_f32_dpp v5, v4, v4 quad_perm:[1,0,3,2] row_mask:0xf bank_mask:0xf
	s_nop 1
	v_add_f32_dpp v4, v5, v5 quad_perm:[2,3,0,1] row_mask:0xf bank_mask:0xf
	s_nop 1
	v_add_f32_dpp v5, v4, v4 row_half_mirror row_mask:0xf bank_mask:0xf
	s_nop 1
	v_add_f32_dpp v4, v5, v5 row_mirror row_mask:0xf bank_mask:0xf
	s_nop 1
	v_readlane_b32 s98, v4, 0
	v_readlane_b32 s99, v4, 16
	s_nop 3
	v_mov_b32_e32 v5, s98
	v_add_f32_e32 v5, s99, v5
	v_readlane_b32 s98, v4, 32
	v_readlane_b32 s99, v4, 48
	s_nop 3
	v_add_f32_e32 v5, s98, v5
	v_add_f32_e32 v5, s99, v5
	v_mul_f32_e32 v5, 0x3a800000, v5
	v_add_f32_e32 v5, 0x358637bd, v5
	v_rsq_f32_e32 v6, v5
	s_nop 0
	s_add_u32 s98, s97, 256
	v_pk_mul_f32 v[32:33], v[32:33], v[6:7] op_sel_hi:[1,0]
	v_pk_mul_f32 v[34:35], v[34:35], v[6:7] op_sel_hi:[1,0]
	v_pk_mul_f32 v[36:37], v[36:37], v[6:7] op_sel_hi:[1,0]
	v_pk_mul_f32 v[38:39], v[38:39], v[6:7] op_sel_hi:[1,0]
	v_pk_mul_f32 v[40:41], v[40:41], v[6:7] op_sel_hi:[1,0]
	v_pk_mul_f32 v[42:43], v[42:43], v[6:7] op_sel_hi:[1,0]
	v_pk_mul_f32 v[44:45], v[44:45], v[6:7] op_sel_hi:[1,0]
	v_pk_mul_f32 v[46:47], v[46:47], v[6:7] op_sel_hi:[1,0]
	v_pk_mul_f32 v[32:33], v[32:33], v[112:113]
	v_pk_mul_f32 v[34:35], v[34:35], v[114:115]
	v_pk_mul_f32 v[36:37], v[36:37], v[116:117]
	v_pk_mul_f32 v[38:39], v[38:39], v[118:119]
	v_pk_mul_f32 v[40:41], v[40:41], v[120:121]
	v_pk_mul_f32 v[42:43], v[42:43], v[122:123]
	v_pk_mul_f32 v[44:45], v[44:45], v[124:125]
	v_pk_mul_f32 v[46:47], v[46:47], v[126:127]
	s_lshl_b32 s99, s98, 12
	v_add_u32_e32 v8, s99, v1
	global_store_dwordx4 v8, v[32:35], s[88:89] nt
	global_store_dwordx4 v8, v[36:39], s[88:89] offset:1024 nt
	global_store_dwordx4 v8, v[40:43], s[88:89] offset:2048 nt
	global_store_dwordx4 v8, v[44:47], s[88:89] offset:3072 nt
	s_add_u32 s98, s97, 1792
	s_lshl_b32 s98, s98, 12
	v_add_u32_e32 v3, s98, v1
	global_load_dwordx4 v[32:35], v3, s[88:89] nt
	global_load_dwordx4 v[36:39], v3, s[88:89] offset:1024 nt
	global_load_dwordx4 v[40:43], v3, s[88:89] offset:2048 nt
	global_load_dwordx4 v[44:47], v3, s[88:89] offset:3072 nt
	s_waitcnt vmcnt(28)
	v_mul_f32_e32 v4, v48, v48
	v_fma_f32 v4, v49, v49, v4
	v_fma_f32 v4, v50, v50, v4
	v_fma_f32 v4, v51, v51, v4
	v_fma_f32 v4, v52, v52, v4
	v_fma_f32 v4, v53, v53, v4
	v_fma_f32 v4, v54, v54, v4
	v_fma_f32 v4, v55, v55, v4
	v_fma_f32 v4, v56, v56, v4
	v_fma_f32 v4, v57, v57, v4
	v_fma_f32 v4, v58, v58, v4
	v_fma_f32 v4, v59, v59, v4
	v_fma_f32 v4, v60, v60, v4
	v_fma_f32 v4, v61, v61, v4
	v_fma_f32 v4, v62, v62, v4
	v_fma_f32 v4, v63, v63, v4
	s_nop 1
	v_add_f32_dpp v5, v4, v4 quad_perm:[1,0,3,2] row_mask:0xf bank_mask:0xf
	s_nop 1
	v_add_f32_dpp v4, v5, v5 quad_perm:[2,3,0,1] row_mask:0xf bank_mask:0xf
	s_nop 1
	v_add_f32_dpp v5, v4, v4 row_half_mirror row_mask:0xf bank_mask:0xf
	s_nop 1
	v_add_f32_dpp v4, v5, v5 row_mirror row_mask:0xf bank_mask:0xf
	s_nop 1
	v_readlane_b32 s98, v4, 0
	v_readlane_b32 s99, v4, 16
	s_nop 3
	v_mov_b32_e32 v5, s98
	v_add_f32_e32 v5, s99, v5
	v_readlane_b32 s98, v4, 32
	v_readlane_b32 s99, v4, 48
	s_nop 3
	v_add_f32_e32 v5, s98, v5
	v_add_f32_e32 v5, s99, v5
	v_mul_f32_e32 v5, 0x3a800000, v5
	v_add_f32_e32 v5, 0x358637bd, v5
	v_rsq_f32_e32 v6, v5
	s_nop 0
	s_add_u32 s98, s97, 512
	v_pk_mul_f32 v[48:49], v[48:49], v[6:7] op_sel_hi:[1,0]
	v_pk_mul_f32 v[50:51], v[50:51], v[6:7] op_sel_hi:[1,0]
	v_pk_mul_f32 v[52:53], v[52:53], v[6:7] op_sel_hi:[1,0]
	v_pk_mul_f32 v[54:55], v[54:55], v[6:7] op_sel_hi:[1,0]
	v_pk_mul_f32 v[56:57], v[56:57], v[6:7] op_sel_hi:[1,0]
	v_pk_mul_f32 v[58:59], v[58:59], v[6:7] op_sel_hi:[1,0]
	v_pk_mul_f32 v[60:61], v[60:61], v[6:7] op_sel_hi:[1,0]
	v_pk_mul_f32 v[62:63], v[62:63], v[6:7] op_sel_hi:[1,0]
	v_pk_mul_f32 v[48:49], v[48:49], v[112:113]
	v_pk_mul_f32 v[50:51], v[50:51], v[114:115]
	v_pk_mul_f32 v[52:53], v[52:53], v[116:117]
	v_pk_mul_f32 v[54:55], v[54:55], v[118:119]
	v_pk_mul_f32 v[56:57], v[56:57], v[120:121]
	v_pk_mul_f32 v[58:59], v[58:59], v[122:123]
	v_pk_mul_f32 v[60:61], v[60:61], v[124:125]
	v_pk_mul_f32 v[62:63], v[62:63], v[126:127]
	s_lshl_b32 s99, s98, 12
	v_add_u32_e32 v8, s99, v1
	global_store_dwordx4 v8, v[48:51], s[88:89] nt
	global_store_dwordx4 v8, v[52:55], s[88:89] offset:1024 nt
	global_store_dwordx4 v8, v[56:59], s[88:89] offset:2048 nt
	global_store_dwordx4 v8, v[60:63], s[88:89] offset:3072 nt
	s_add_u32 s98, s97, 2048
	s_lshl_b32 s98, s98, 12
	v_add_u32_e32 v3, s98, v1
	global_load_dwordx4 v[48:51], v3, s[88:89] nt
	global_load_dwordx4 v[52:55], v3, s[88:89] offset:1024 nt
	global_load_dwordx4 v[56:59], v3, s[88:89] offset:2048 nt
	global_load_dwordx4 v[60:63], v3, s[88:89] offset:3072 nt
	s_waitcnt vmcnt(32)
	v_mul_f32_e32 v4, v64, v64
	v_fma_f32 v4, v65, v65, v4
	v_fma_f32 v4, v66, v66, v4
	v_fma_f32 v4, v67, v67, v4
	v_fma_f32 v4, v68, v68, v4
	v_fma_f32 v4, v69, v69, v4
	v_fma_f32 v4, v70, v70, v4
	v_fma_f32 v4, v71, v71, v4
	v_fma_f32 v4, v72, v72, v4
	v_fma_f32 v4, v73, v73, v4
	v_fma_f32 v4, v74, v74, v4
	v_fma_f32 v4, v75, v75, v4
	v_fma_f32 v4, v76, v76, v4
	v_fma_f32 v4, v77, v77, v4
	v_fma_f32 v4, v78, v78, v4
	v_fma_f32 v4, v79, v79, v4
	s_nop 1
	v_add_f32_dpp v5, v4, v4 quad_perm:[1,0,3,2] row_mask:0xf bank_mask:0xf
	s_nop 1
	v_add_f32_dpp v4, v5, v5 quad_perm:[2,3,0,1] row_mask:0xf bank_mask:0xf
	s_nop 1
	v_add_f32_dpp v5, v4, v4 row_half_mirror row_mask:0xf bank_mask:0xf
	s_nop 1
	v_add_f32_dpp v4, v5, v5 row_mirror row_mask:0xf bank_mask:0xf
	s_nop 1
	v_readlane_b32 s98, v4, 0
	v_readlane_b32 s99, v4, 16
	s_nop 3
	v_mov_b32_e32 v5, s98
	v_add_f32_e32 v5, s99, v5
	v_readlane_b32 s98, v4, 32
	v_readlane_b32 s99, v4, 48
	s_nop 3
	v_add_f32_e32 v5, s98, v5
	v_add_f32_e32 v5, s99, v5
	v_mul_f32_e32 v5, 0x3a800000, v5
	v_add_f32_e32 v5, 0x358637bd, v5
	v_rsq_f32_e32 v6, v5
	s_nop 0
	s_add_u32 s98, s97, 768
	v_pk_mul_f32 v[64:65], v[64:65], v[6:7] op_sel_hi:[1,0]
	v_pk_mul_f32 v[66:67], v[66:67], v[6:7] op_sel_hi:[1,0]
	v_pk_mul_f32 v[68:69], v[68:69], v[6:7] op_sel_hi:[1,0]
	v_pk_mul_f32 v[70:71], v[70:71], v[6:7] op_sel_hi:[1,0]
	v_pk_mul_f32 v[72:73], v[72:73], v[6:7] op_sel_hi:[1,0]
	v_pk_mul_f32 v[74:75], v[74:75], v[6:7] op_sel_hi:[1,0]
	v_pk_mul_f32 v[76:77], v[76:77], v[6:7] op_sel_hi:[1,0]
	v_pk_mul_f32 v[78:79], v[78:79], v[6:7] op_sel_hi:[1,0]
	v_pk_mul_f32 v[64:65], v[64:65], v[112:113]
	v_pk_mul_f32 v[66:67], v[66:67], v[114:115]
	v_pk_mul_f32 v[68:69], v[68:69], v[116:117]
	v_pk_mul_f32 v[70:71], v[70:71], v[118:119]
	v_pk_mul_f32 v[72:73], v[72:73], v[120:121]
	v_pk_mul_f32 v[74:75], v[74:75], v[122:123]
	v_pk_mul_f32 v[76:77], v[76:77], v[124:125]
	v_pk_mul_f32 v[78:79], v[78:79], v[126:127]
	s_lshl_b32 s99, s98, 12
	v_add_u32_e32 v8, s99, v1
	global_store_dwordx4 v8, v[64:67], s[88:89] nt
	global_store_dwordx4 v8, v[68:71], s[88:89] offset:1024 nt
	global_store_dwordx4 v8, v[72:75], s[88:89] offset:2048 nt
	global_store_dwordx4 v8, v[76:79], s[88:89] offset:3072 nt
	s_add_u32 s98, s97, 2304
	s_lshl_b32 s98, s98, 12
	v_add_u32_e32 v3, s98, v1
	global_load_dwordx4 v[64:67], v3, s[88:89] nt
	global_load_dwordx4 v[68:71], v3, s[88:89] offset:1024 nt
	global_load_dwordx4 v[72:75], v3, s[88:89] offset:2048 nt
	global_load_dwordx4 v[76:79], v3, s[88:89] offset:3072 nt
	s_waitcnt vmcnt(36)
	v_mul_f32_e32 v4, v80, v80
	v_fma_f32 v4, v81, v81, v4
	v_fma_f32 v4, v82, v82, v4
	v_fma_f32 v4, v83, v83, v4
	v_fma_f32 v4, v84, v84, v4
	v_fma_f32 v4, v85, v85, v4
	v_fma_f32 v4, v86, v86, v4
	v_fma_f32 v4, v87, v87, v4
	v_fma_f32 v4, v88, v88, v4
	v_fma_f32 v4, v89, v89, v4
	v_fma_f32 v4, v90, v90, v4
	v_fma_f32 v4, v91, v91, v4
	v_fma_f32 v4, v92, v92, v4
	v_fma_f32 v4, v93, v93, v4
	v_fma_f32 v4, v94, v94, v4
	v_fma_f32 v4, v95, v95, v4
	s_nop 1
	v_add_f32_dpp v5, v4, v4 quad_perm:[1,0,3,2] row_mask:0xf bank_mask:0xf
	s_nop 1
	v_add_f32_dpp v4, v5, v5 quad_perm:[2,3,0,1] row_mask:0xf bank_mask:0xf
	s_nop 1
	v_add_f32_dpp v5, v4, v4 row_half_mirror row_mask:0xf bank_mask:0xf
	s_nop 1
	v_add_f32_dpp v4, v5, v5 row_mirror row_mask:0xf bank_mask:0xf
	s_nop 1
	v_readlane_b32 s98, v4, 0
	v_readlane_b32 s99, v4, 16
	s_nop 3
	v_mov_b32_e32 v5, s98
	v_add_f32_e32 v5, s99, v5
	v_readlane_b32 s98, v4, 32
	v_readlane_b32 s99, v4, 48
	s_nop 3
	v_add_f32_e32 v5, s98, v5
	v_add_f32_e32 v5, s99, v5
	v_mul_f32_e32 v5, 0x3a800000, v5
	v_add_f32_e32 v5, 0x358637bd, v5
	v_rsq_f32_e32 v6, v5
	s_nop 0
	s_add_u32 s98, s97, 1024
	v_pk_mul_f32 v[80:81], v[80:81], v[6:7] op_sel_hi:[1,0]
	v_pk_mul_f32 v[82:83], v[82:83], v[6:7] op_sel_hi:[1,0]
	v_pk_mul_f32 v[84:85], v[84:85], v[6:7] op_sel_hi:[1,0]
	v_pk_mul_f32 v[86:87], v[86:87], v[6:7] op_sel_hi:[1,0]
	v_pk_mul_f32 v[88:89], v[88:89], v[6:7] op_sel_hi:[1,0]
	v_pk_mul_f32 v[90:91], v[90:91], v[6:7] op_sel_hi:[1,0]
	v_pk_mul_f32 v[92:93], v[92:93], v[6:7] op_sel_hi:[1,0]
	v_pk_mul_f32 v[94:95], v[94:95], v[6:7] op_sel_hi:[1,0]
	v_pk_mul_f32 v[80:81], v[80:81], v[112:113]
	v_pk_mul_f32 v[82:83], v[82:83], v[114:115]
	v_pk_mul_f32 v[84:85], v[84:85], v[116:117]
	v_pk_mul_f32 v[86:87], v[86:87], v[118:119]
	v_pk_mul_f32 v[88:89], v[88:89], v[120:121]
	v_pk_mul_f32 v[90:91], v[90:91], v[122:123]
	v_pk_mul_f32 v[92:93], v[92:93], v[124:125]
	v_pk_mul_f32 v[94:95], v[94:95], v[126:127]
	s_lshl_b32 s99, s98, 12
	v_add_u32_e32 v8, s99, v1
	global_store_dwordx4 v8, v[80:83], s[88:89] nt
	global_store_dwordx4 v8, v[84:87], s[88:89] offset:1024 nt
	global_store_dwordx4 v8, v[88:91], s[88:89] offset:2048 nt
	global_store_dwordx4 v8, v[92:95], s[88:89] offset:3072 nt
	s_add_u32 s98, s97, 2560
	s_lshl_b32 s98, s98, 12
	v_add_u32_e32 v3, s98, v1
	global_load_dwordx4 v[80:83], v3, s[88:89] nt
	global_load_dwordx4 v[84:87], v3, s[88:89] offset:1024 nt
	global_load_dwordx4 v[88:91], v3, s[88:89] offset:2048 nt
	global_load_dwordx4 v[92:95], v3, s[88:89] offset:3072 nt
	s_waitcnt vmcnt(40)
	v_mul_f32_e32 v4, v96, v96
	v_fma_f32 v4, v97, v97, v4
	v_fma_f32 v4, v98, v98, v4
	v_fma_f32 v4, v99, v99, v4
	v_fma_f32 v4, v100, v100, v4
	v_fma_f32 v4, v101, v101, v4
	v_fma_f32 v4, v102, v102, v4
	v_fma_f32 v4, v103, v103, v4
	v_fma_f32 v4, v104, v104, v4
	v_fma_f32 v4, v105, v105, v4
	v_fma_f32 v4, v106, v106, v4
	v_fma_f32 v4, v107, v107, v4
	v_fma_f32 v4, v108, v108, v4
	v_fma_f32 v4, v109, v109, v4
	v_fma_f32 v4, v110, v110, v4
	v_fma_f32 v4, v111, v111, v4
	s_nop 1
	v_add_f32_dpp v5, v4, v4 quad_perm:[1,0,3,2] row_mask:0xf bank_mask:0xf
	s_nop 1
	v_add_f32_dpp v4, v5, v5 quad_perm:[2,3,0,1] row_mask:0xf bank_mask:0xf
	s_nop 1
	v_add_f32_dpp v5, v4, v4 row_half_mirror row_mask:0xf bank_mask:0xf
	s_nop 1
	v_add_f32_dpp v4, v5, v5 row_mirror row_mask:0xf bank_mask:0xf
	s_nop 1
	v_readlane_b32 s98, v4, 0
	v_readlane_b32 s99, v4, 16
	s_nop 3
	v_mov_b32_e32 v5, s98
	v_add_f32_e32 v5, s99, v5
	v_readlane_b32 s98, v4, 32
	v_readlane_b32 s99, v4, 48
	s_nop 3
	v_add_f32_e32 v5, s98, v5
	v_add_f32_e32 v5, s99, v5
	v_mul_f32_e32 v5, 0x3a800000, v5
	v_add_f32_e32 v5, 0x358637bd, v5
	v_rsq_f32_e32 v6, v5
	s_nop 0
	s_add_u32 s98, s97, 1280
	v_pk_mul_f32 v[96:97], v[96:97], v[6:7] op_sel_hi:[1,0]
	v_pk_mul_f32 v[98:99], v[98:99], v[6:7] op_sel_hi:[1,0]
	v_pk_mul_f32 v[100:101], v[100:101], v[6:7] op_sel_hi:[1,0]
	v_pk_mul_f32 v[102:103], v[102:103], v[6:7] op_sel_hi:[1,0]
	v_pk_mul_f32 v[104:105], v[104:105], v[6:7] op_sel_hi:[1,0]
	v_pk_mul_f32 v[106:107], v[106:107], v[6:7] op_sel_hi:[1,0]
	v_pk_mul_f32 v[108:109], v[108:109], v[6:7] op_sel_hi:[1,0]
	v_pk_mul_f32 v[110:111], v[110:111], v[6:7] op_sel_hi:[1,0]
	v_pk_mul_f32 v[96:97], v[96:97], v[112:113]
	v_pk_mul_f32 v[98:99], v[98:99], v[114:115]
	v_pk_mul_f32 v[100:101], v[100:101], v[116:117]
	v_pk_mul_f32 v[102:103], v[102:103], v[118:119]
	v_pk_mul_f32 v[104:105], v[104:105], v[120:121]
	v_pk_mul_f32 v[106:107], v[106:107], v[122:123]
	v_pk_mul_f32 v[108:109], v[108:109], v[124:125]
	v_pk_mul_f32 v[110:111], v[110:111], v[126:127]
	s_lshl_b32 s99, s98, 12
	v_add_u32_e32 v8, s99, v1
	global_store_dwordx4 v8, v[96:99], s[88:89] nt
	global_store_dwordx4 v8, v[100:103], s[88:89] offset:1024 nt
	global_store_dwordx4 v8, v[104:107], s[88:89] offset:2048 nt
	global_store_dwordx4 v8, v[108:111], s[88:89] offset:3072 nt
	s_add_u32 s98, s97, 2816
	s_lshl_b32 s98, s98, 12
	v_add_u32_e32 v3, s98, v1
	global_load_dwordx4 v[96:99], v3, s[88:89] nt
	global_load_dwordx4 v[100:103], v3, s[88:89] offset:1024 nt
	global_load_dwordx4 v[104:107], v3, s[88:89] offset:2048 nt
	global_load_dwordx4 v[108:111], v3, s[88:89] offset:3072 nt
	s_waitcnt vmcnt(40)
	v_mul_f32_e32 v4, v16, v16
	v_fma_f32 v4, v17, v17, v4
	v_fma_f32 v4, v18, v18, v4
	v_fma_f32 v4, v19, v19, v4
	v_fma_f32 v4, v20, v20, v4
	v_fma_f32 v4, v21, v21, v4
	v_fma_f32 v4, v22, v22, v4
	v_fma_f32 v4, v23, v23, v4
	v_fma_f32 v4, v24, v24, v4
	v_fma_f32 v4, v25, v25, v4
	v_fma_f32 v4, v26, v26, v4
	v_fma_f32 v4, v27, v27, v4
	v_fma_f32 v4, v28, v28, v4
	v_fma_f32 v4, v29, v29, v4
	v_fma_f32 v4, v30, v30, v4
	v_fma_f32 v4, v31, v31, v4
	s_nop 1
	v_add_f32_dpp v5, v4, v4 quad_perm:[1,0,3,2] row_mask:0xf bank_mask:0xf
	s_nop 1
	v_add_f32_dpp v4, v5, v5 quad_perm:[2,3,0,1] row_mask:0xf bank_mask:0xf
	s_nop 1
	v_add_f32_dpp v5, v4, v4 row_half_mirror row_mask:0xf bank_mask:0xf
	s_nop 1
	v_add_f32_dpp v4, v5, v5 row_mirror row_mask:0xf bank_mask:0xf
	s_nop 1
	v_readlane_b32 s98, v4, 0
	v_readlane_b32 s99, v4, 16
	s_nop 3
	v_mov_b32_e32 v5, s98
	v_add_f32_e32 v5, s99, v5
	v_readlane_b32 s98, v4, 32
	v_readlane_b32 s99, v4, 48
	s_nop 3
	v_add_f32_e32 v5, s98, v5
	v_add_f32_e32 v5, s99, v5
	v_mul_f32_e32 v5, 0x3a800000, v5
	v_add_f32_e32 v5, 0x358637bd, v5
	v_rsq_f32_e32 v6, v5
	s_nop 0
	s_add_u32 s98, s97, 1536
	v_pk_mul_f32 v[16:17], v[16:17], v[6:7] op_sel_hi:[1,0]
	v_pk_mul_f32 v[18:19], v[18:19], v[6:7] op_sel_hi:[1,0]
	v_pk_mul_f32 v[20:21], v[20:21], v[6:7] op_sel_hi:[1,0]
	v_pk_mul_f32 v[22:23], v[22:23], v[6:7] op_sel_hi:[1,0]
	v_pk_mul_f32 v[24:25], v[24:25], v[6:7] op_sel_hi:[1,0]
	v_pk_mul_f32 v[26:27], v[26:27], v[6:7] op_sel_hi:[1,0]
	v_pk_mul_f32 v[28:29], v[28:29], v[6:7] op_sel_hi:[1,0]
	v_pk_mul_f32 v[30:31], v[30:31], v[6:7] op_sel_hi:[1,0]
	v_pk_mul_f32 v[16:17], v[16:17], v[112:113]
	v_pk_mul_f32 v[18:19], v[18:19], v[114:115]
	v_pk_mul_f32 v[20:21], v[20:21], v[116:117]
	v_pk_mul_f32 v[22:23], v[22:23], v[118:119]
	v_pk_mul_f32 v[24:25], v[24:25], v[120:121]
	v_pk_mul_f32 v[26:27], v[26:27], v[122:123]
	v_pk_mul_f32 v[28:29], v[28:29], v[124:125]
	v_pk_mul_f32 v[30:31], v[30:31], v[126:127]
	s_lshl_b32 s99, s98, 12
	v_add_u32_e32 v8, s99, v1
	global_store_dwordx4 v8, v[16:19], s[88:89] nt
	global_store_dwordx4 v8, v[20:23], s[88:89] offset:1024 nt
	global_store_dwordx4 v8, v[24:27], s[88:89] offset:2048 nt
	global_store_dwordx4 v8, v[28:31], s[88:89] offset:3072 nt
	s_add_u32 s98, s97, 3072
	s_lshl_b32 s98, s98, 12
	v_add_u32_e32 v3, s98, v1
	global_load_dwordx4 v[16:19], v3, s[88:89] nt
	global_load_dwordx4 v[20:23], v3, s[88:89] offset:1024 nt
	global_load_dwordx4 v[24:27], v3, s[88:89] offset:2048 nt
	global_load_dwordx4 v[28:31], v3, s[88:89] offset:3072 nt
	s_waitcnt vmcnt(40)
	v_mul_f32_e32 v4, v32, v32
	v_fma_f32 v4, v33, v33, v4
	v_fma_f32 v4, v34, v34, v4
	v_fma_f32 v4, v35, v35, v4
	v_fma_f32 v4, v36, v36, v4
	v_fma_f32 v4, v37, v37, v4
	v_fma_f32 v4, v38, v38, v4
	v_fma_f32 v4, v39, v39, v4
	v_fma_f32 v4, v40, v40, v4
	v_fma_f32 v4, v41, v41, v4
	v_fma_f32 v4, v42, v42, v4
	v_fma_f32 v4, v43, v43, v4
	v_fma_f32 v4, v44, v44, v4
	v_fma_f32 v4, v45, v45, v4
	v_fma_f32 v4, v46, v46, v4
	v_fma_f32 v4, v47, v47, v4
	s_nop 1
	v_add_f32_dpp v5, v4, v4 quad_perm:[1,0,3,2] row_mask:0xf bank_mask:0xf
	s_nop 1
	v_add_f32_dpp v4, v5, v5 quad_perm:[2,3,0,1] row_mask:0xf bank_mask:0xf
	s_nop 1
	v_add_f32_dpp v5, v4, v4 row_half_mirror row_mask:0xf bank_mask:0xf
	s_nop 1
	v_add_f32_dpp v4, v5, v5 row_mirror row_mask:0xf bank_mask:0xf
	s_nop 1
	v_readlane_b32 s98, v4, 0
	v_readlane_b32 s99, v4, 16
	s_nop 3
	v_mov_b32_e32 v5, s98
	v_add_f32_e32 v5, s99, v5
	v_readlane_b32 s98, v4, 32
	v_readlane_b32 s99, v4, 48
	s_nop 3
	v_add_f32_e32 v5, s98, v5
	v_add_f32_e32 v5, s99, v5
	v_mul_f32_e32 v5, 0x3a800000, v5
	v_add_f32_e32 v5, 0x358637bd, v5
	v_rsq_f32_e32 v6, v5
	s_nop 0
	s_add_u32 s98, s97, 1792
	v_pk_mul_f32 v[32:33], v[32:33], v[6:7] op_sel_hi:[1,0]
	v_pk_mul_f32 v[34:35], v[34:35], v[6:7] op_sel_hi:[1,0]
	v_pk_mul_f32 v[36:37], v[36:37], v[6:7] op_sel_hi:[1,0]
	v_pk_mul_f32 v[38:39], v[38:39], v[6:7] op_sel_hi:[1,0]
	v_pk_mul_f32 v[40:41], v[40:41], v[6:7] op_sel_hi:[1,0]
	v_pk_mul_f32 v[42:43], v[42:43], v[6:7] op_sel_hi:[1,0]
	v_pk_mul_f32 v[44:45], v[44:45], v[6:7] op_sel_hi:[1,0]
	v_pk_mul_f32 v[46:47], v[46:47], v[6:7] op_sel_hi:[1,0]
	v_pk_mul_f32 v[32:33], v[32:33], v[112:113]
	v_pk_mul_f32 v[34:35], v[34:35], v[114:115]
	v_pk_mul_f32 v[36:37], v[36:37], v[116:117]
	v_pk_mul_f32 v[38:39], v[38:39], v[118:119]
	v_pk_mul_f32 v[40:41], v[40:41], v[120:121]
	v_pk_mul_f32 v[42:43], v[42:43], v[122:123]
	v_pk_mul_f32 v[44:45], v[44:45], v[124:125]
	v_pk_mul_f32 v[46:47], v[46:47], v[126:127]
	s_lshl_b32 s99, s98, 12
	v_add_u32_e32 v8, s99, v1
	global_store_dwordx4 v8, v[32:35], s[88:89] nt
	global_store_dwordx4 v8, v[36:39], s[88:89] offset:1024 nt
	global_store_dwordx4 v8, v[40:43], s[88:89] offset:2048 nt
	global_store_dwordx4 v8, v[44:47], s[88:89] offset:3072 nt
	s_add_u32 s98, s97, 3328
	s_lshl_b32 s98, s98, 12
	v_add_u32_e32 v3, s98, v1
	global_load_dwordx4 v[32:35], v3, s[88:89] nt
	global_load_dwordx4 v[36:39], v3, s[88:89] offset:1024 nt
	global_load_dwordx4 v[40:43], v3, s[88:89] offset:2048 nt
	global_load_dwordx4 v[44:47], v3, s[88:89] offset:3072 nt
	s_waitcnt vmcnt(40)
	v_mul_f32_e32 v4, v48, v48
	v_fma_f32 v4, v49, v49, v4
	v_fma_f32 v4, v50, v50, v4
	v_fma_f32 v4, v51, v51, v4
	v_fma_f32 v4, v52, v52, v4
	v_fma_f32 v4, v53, v53, v4
	v_fma_f32 v4, v54, v54, v4
	v_fma_f32 v4, v55, v55, v4
	v_fma_f32 v4, v56, v56, v4
	v_fma_f32 v4, v57, v57, v4
	v_fma_f32 v4, v58, v58, v4
	v_fma_f32 v4, v59, v59, v4
	v_fma_f32 v4, v60, v60, v4
	v_fma_f32 v4, v61, v61, v4
	v_fma_f32 v4, v62, v62, v4
	v_fma_f32 v4, v63, v63, v4
	s_nop 1
	v_add_f32_dpp v5, v4, v4 quad_perm:[1,0,3,2] row_mask:0xf bank_mask:0xf
	s_nop 1
	v_add_f32_dpp v4, v5, v5 quad_perm:[2,3,0,1] row_mask:0xf bank_mask:0xf
	s_nop 1
	v_add_f32_dpp v5, v4, v4 row_half_mirror row_mask:0xf bank_mask:0xf
	s_nop 1
	v_add_f32_dpp v4, v5, v5 row_mirror row_mask:0xf bank_mask:0xf
	s_nop 1
	v_readlane_b32 s98, v4, 0
	v_readlane_b32 s99, v4, 16
	s_nop 3
	v_mov_b32_e32 v5, s98
	v_add_f32_e32 v5, s99, v5
	v_readlane_b32 s98, v4, 32
	v_readlane_b32 s99, v4, 48
	s_nop 3
	v_add_f32_e32 v5, s98, v5
	v_add_f32_e32 v5, s99, v5
	v_mul_f32_e32 v5, 0x3a800000, v5
	v_add_f32_e32 v5, 0x358637bd, v5
	v_rsq_f32_e32 v6, v5
	s_nop 0
	s_add_u32 s98, s97, 2048
	v_pk_mul_f32 v[48:49], v[48:49], v[6:7] op_sel_hi:[1,0]
	v_pk_mul_f32 v[50:51], v[50:51], v[6:7] op_sel_hi:[1,0]
	v_pk_mul_f32 v[52:53], v[52:53], v[6:7] op_sel_hi:[1,0]
	v_pk_mul_f32 v[54:55], v[54:55], v[6:7] op_sel_hi:[1,0]
	v_pk_mul_f32 v[56:57], v[56:57], v[6:7] op_sel_hi:[1,0]
	v_pk_mul_f32 v[58:59], v[58:59], v[6:7] op_sel_hi:[1,0]
	v_pk_mul_f32 v[60:61], v[60:61], v[6:7] op_sel_hi:[1,0]
	v_pk_mul_f32 v[62:63], v[62:63], v[6:7] op_sel_hi:[1,0]
	v_pk_mul_f32 v[48:49], v[48:49], v[112:113]
	v_pk_mul_f32 v[50:51], v[50:51], v[114:115]
	v_pk_mul_f32 v[52:53], v[52:53], v[116:117]
	v_pk_mul_f32 v[54:55], v[54:55], v[118:119]
	v_pk_mul_f32 v[56:57], v[56:57], v[120:121]
	v_pk_mul_f32 v[58:59], v[58:59], v[122:123]
	v_pk_mul_f32 v[60:61], v[60:61], v[124:125]
	v_pk_mul_f32 v[62:63], v[62:63], v[126:127]
	s_lshl_b32 s99, s98, 12
	v_add_u32_e32 v8, s99, v1
	global_store_dwordx4 v8, v[48:51], s[88:89] nt
	global_store_dwordx4 v8, v[52:55], s[88:89] offset:1024 nt
	global_store_dwordx4 v8, v[56:59], s[88:89] offset:2048 nt
	global_store_dwordx4 v8, v[60:63], s[88:89] offset:3072 nt
	s_add_u32 s98, s97, 3584
	s_lshl_b32 s98, s98, 12
	v_add_u32_e32 v3, s98, v1
	global_load_dwordx4 v[48:51], v3, s[88:89] nt
	global_load_dwordx4 v[52:55], v3, s[88:89] offset:1024 nt
	global_load_dwordx4 v[56:59], v3, s[88:89] offset:2048 nt
	global_load_dwordx4 v[60:63], v3, s[88:89] offset:3072 nt
	s_waitcnt vmcnt(40)
	v_mul_f32_e32 v4, v64, v64
	v_fma_f32 v4, v65, v65, v4
	v_fma_f32 v4, v66, v66, v4
	v_fma_f32 v4, v67, v67, v4
	v_fma_f32 v4, v68, v68, v4
	v_fma_f32 v4, v69, v69, v4
	v_fma_f32 v4, v70, v70, v4
	v_fma_f32 v4, v71, v71, v4
	v_fma_f32 v4, v72, v72, v4
	v_fma_f32 v4, v73, v73, v4
	v_fma_f32 v4, v74, v74, v4
	v_fma_f32 v4, v75, v75, v4
	v_fma_f32 v4, v76, v76, v4
	v_fma_f32 v4, v77, v77, v4
	v_fma_f32 v4, v78, v78, v4
	v_fma_f32 v4, v79, v79, v4
	s_nop 1
	v_add_f32_dpp v5, v4, v4 quad_perm:[1,0,3,2] row_mask:0xf bank_mask:0xf
	s_nop 1
	v_add_f32_dpp v4, v5, v5 quad_perm:[2,3,0,1] row_mask:0xf bank_mask:0xf
	s_nop 1
	v_add_f32_dpp v5, v4, v4 row_half_mirror row_mask:0xf bank_mask:0xf
	s_nop 1
	v_add_f32_dpp v4, v5, v5 row_mirror row_mask:0xf bank_mask:0xf
	s_nop 1
	v_readlane_b32 s98, v4, 0
	v_readlane_b32 s99, v4, 16
	s_nop 3
	v_mov_b32_e32 v5, s98
	v_add_f32_e32 v5, s99, v5
	v_readlane_b32 s98, v4, 32
	v_readlane_b32 s99, v4, 48
	s_nop 3
	v_add_f32_e32 v5, s98, v5
	v_add_f32_e32 v5, s99, v5
	v_mul_f32_e32 v5, 0x3a800000, v5
	v_add_f32_e32 v5, 0x358637bd, v5
	v_rsq_f32_e32 v6, v5
	s_nop 0
	s_add_u32 s98, s97, 2304
	v_pk_mul_f32 v[64:65], v[64:65], v[6:7] op_sel_hi:[1,0]
	v_pk_mul_f32 v[66:67], v[66:67], v[6:7] op_sel_hi:[1,0]
	v_pk_mul_f32 v[68:69], v[68:69], v[6:7] op_sel_hi:[1,0]
	v_pk_mul_f32 v[70:71], v[70:71], v[6:7] op_sel_hi:[1,0]
	v_pk_mul_f32 v[72:73], v[72:73], v[6:7] op_sel_hi:[1,0]
	v_pk_mul_f32 v[74:75], v[74:75], v[6:7] op_sel_hi:[1,0]
	v_pk_mul_f32 v[76:77], v[76:77], v[6:7] op_sel_hi:[1,0]
	v_pk_mul_f32 v[78:79], v[78:79], v[6:7] op_sel_hi:[1,0]
	v_pk_mul_f32 v[64:65], v[64:65], v[112:113]
	v_pk_mul_f32 v[66:67], v[66:67], v[114:115]
	v_pk_mul_f32 v[68:69], v[68:69], v[116:117]
	v_pk_mul_f32 v[70:71], v[70:71], v[118:119]
	v_pk_mul_f32 v[72:73], v[72:73], v[120:121]
	v_pk_mul_f32 v[74:75], v[74:75], v[122:123]
	v_pk_mul_f32 v[76:77], v[76:77], v[124:125]
	v_pk_mul_f32 v[78:79], v[78:79], v[126:127]
	s_lshl_b32 s99, s98, 12
	v_add_u32_e32 v8, s99, v1
	global_store_dwordx4 v8, v[64:67], s[88:89] nt
	global_store_dwordx4 v8, v[68:71], s[88:89] offset:1024 nt
	global_store_dwordx4 v8, v[72:75], s[88:89] offset:2048 nt
	global_store_dwordx4 v8, v[76:79], s[88:89] offset:3072 nt
	s_add_u32 s98, s97, 3840
	s_lshl_b32 s98, s98, 12
	v_add_u32_e32 v3, s98, v1
	global_load_dwordx4 v[64:67], v3, s[88:89] nt
	global_load_dwordx4 v[68:71], v3, s[88:89] offset:1024 nt
	global_load_dwordx4 v[72:75], v3, s[88:89] offset:2048 nt
	global_load_dwordx4 v[76:79], v3, s[88:89] offset:3072 nt
	s_waitcnt vmcnt(40)
	v_mul_f32_e32 v4, v80, v80
	v_fma_f32 v4, v81, v81, v4
	v_fma_f32 v4, v82, v82, v4
	v_fma_f32 v4, v83, v83, v4
	v_fma_f32 v4, v84, v84, v4
	v_fma_f32 v4, v85, v85, v4
	v_fma_f32 v4, v86, v86, v4
	v_fma_f32 v4, v87, v87, v4
	v_fma_f32 v4, v88, v88, v4
	v_fma_f32 v4, v89, v89, v4
	v_fma_f32 v4, v90, v90, v4
	v_fma_f32 v4, v91, v91, v4
	v_fma_f32 v4, v92, v92, v4
	v_fma_f32 v4, v93, v93, v4
	v_fma_f32 v4, v94, v94, v4
	v_fma_f32 v4, v95, v95, v4
	s_nop 1
	v_add_f32_dpp v5, v4, v4 quad_perm:[1,0,3,2] row_mask:0xf bank_mask:0xf
	s_nop 1
	v_add_f32_dpp v4, v5, v5 quad_perm:[2,3,0,1] row_mask:0xf bank_mask:0xf
	s_nop 1
	v_add_f32_dpp v5, v4, v4 row_half_mirror row_mask:0xf bank_mask:0xf
	s_nop 1
	v_add_f32_dpp v4, v5, v5 row_mirror row_mask:0xf bank_mask:0xf
	s_nop 1
	v_readlane_b32 s98, v4, 0
	v_readlane_b32 s99, v4, 16
	s_nop 3
	v_mov_b32_e32 v5, s98
	v_add_f32_e32 v5, s99, v5
	v_readlane_b32 s98, v4, 32
	v_readlane_b32 s99, v4, 48
	s_nop 3
	v_add_f32_e32 v5, s98, v5
	v_add_f32_e32 v5, s99, v5
	v_mul_f32_e32 v5, 0x3a800000, v5
	v_add_f32_e32 v5, 0x358637bd, v5
	v_rsq_f32_e32 v6, v5
	s_nop 0
	s_add_u32 s98, s97, 2560
	v_pk_mul_f32 v[80:81], v[80:81], v[6:7] op_sel_hi:[1,0]
	v_pk_mul_f32 v[82:83], v[82:83], v[6:7] op_sel_hi:[1,0]
	v_pk_mul_f32 v[84:85], v[84:85], v[6:7] op_sel_hi:[1,0]
	v_pk_mul_f32 v[86:87], v[86:87], v[6:7] op_sel_hi:[1,0]
	v_pk_mul_f32 v[88:89], v[88:89], v[6:7] op_sel_hi:[1,0]
	v_pk_mul_f32 v[90:91], v[90:91], v[6:7] op_sel_hi:[1,0]
	v_pk_mul_f32 v[92:93], v[92:93], v[6:7] op_sel_hi:[1,0]
	v_pk_mul_f32 v[94:95], v[94:95], v[6:7] op_sel_hi:[1,0]
	v_pk_mul_f32 v[80:81], v[80:81], v[112:113]
	v_pk_mul_f32 v[82:83], v[82:83], v[114:115]
	v_pk_mul_f32 v[84:85], v[84:85], v[116:117]
	v_pk_mul_f32 v[86:87], v[86:87], v[118:119]
	v_pk_mul_f32 v[88:89], v[88:89], v[120:121]
	v_pk_mul_f32 v[90:91], v[90:91], v[122:123]
	v_pk_mul_f32 v[92:93], v[92:93], v[124:125]
	v_pk_mul_f32 v[94:95], v[94:95], v[126:127]
	s_lshl_b32 s99, s98, 12
	v_add_u32_e32 v8, s99, v1
	global_store_dwordx4 v8, v[80:83], s[88:89] nt
	global_store_dwordx4 v8, v[84:87], s[88:89] offset:1024 nt
	global_store_dwordx4 v8, v[88:91], s[88:89] offset:2048 nt
	global_store_dwordx4 v8, v[92:95], s[88:89] offset:3072 nt
	s_waitcnt vmcnt(36)
	v_mul_f32_e32 v4, v96, v96
	v_fma_f32 v4, v97, v97, v4
	v_fma_f32 v4, v98, v98, v4
	v_fma_f32 v4, v99, v99, v4
	v_fma_f32 v4, v100, v100, v4
	v_fma_f32 v4, v101, v101, v4
	v_fma_f32 v4, v102, v102, v4
	v_fma_f32 v4, v103, v103, v4
	v_fma_f32 v4, v104, v104, v4
	v_fma_f32 v4, v105, v105, v4
	v_fma_f32 v4, v106, v106, v4
	v_fma_f32 v4, v107, v107, v4
	v_fma_f32 v4, v108, v108, v4
	v_fma_f32 v4, v109, v109, v4
	v_fma_f32 v4, v110, v110, v4
	v_fma_f32 v4, v111, v111, v4
	s_nop 1
	v_add_f32_dpp v5, v4, v4 quad_perm:[1,0,3,2] row_mask:0xf bank_mask:0xf
	s_nop 1
	v_add_f32_dpp v4, v5, v5 quad_perm:[2,3,0,1] row_mask:0xf bank_mask:0xf
	s_nop 1
	v_add_f32_dpp v5, v4, v4 row_half_mirror row_mask:0xf bank_mask:0xf
	s_nop 1
	v_add_f32_dpp v4, v5, v5 row_mirror row_mask:0xf bank_mask:0xf
	s_nop 1
	v_readlane_b32 s98, v4, 0
	v_readlane_b32 s99, v4, 16
	s_nop 3
	v_mov_b32_e32 v5, s98
	v_add_f32_e32 v5, s99, v5
	v_readlane_b32 s98, v4, 32
	v_readlane_b32 s99, v4, 48
	s_nop 3
	v_add_f32_e32 v5, s98, v5
	v_add_f32_e32 v5, s99, v5
	v_mul_f32_e32 v5, 0x3a800000, v5
	v_add_f32_e32 v5, 0x358637bd, v5
	v_rsq_f32_e32 v6, v5
	s_nop 0
	s_add_u32 s98, s97, 2816
	v_pk_mul_f32 v[96:97], v[96:97], v[6:7] op_sel_hi:[1,0]
	v_pk_mul_f32 v[98:99], v[98:99], v[6:7] op_sel_hi:[1,0]
	v_pk_mul_f32 v[100:101], v[100:101], v[6:7] op_sel_hi:[1,0]
	v_pk_mul_f32 v[102:103], v[102:103], v[6:7] op_sel_hi:[1,0]
	v_pk_mul_f32 v[104:105], v[104:105], v[6:7] op_sel_hi:[1,0]
	v_pk_mul_f32 v[106:107], v[106:107], v[6:7] op_sel_hi:[1,0]
	v_pk_mul_f32 v[108:109], v[108:109], v[6:7] op_sel_hi:[1,0]
	v_pk_mul_f32 v[110:111], v[110:111], v[6:7] op_sel_hi:[1,0]
	v_pk_mul_f32 v[96:97], v[96:97], v[112:113]
	v_pk_mul_f32 v[98:99], v[98:99], v[114:115]
	v_pk_mul_f32 v[100:101], v[100:101], v[116:117]
	v_pk_mul_f32 v[102:103], v[102:103], v[118:119]
	v_pk_mul_f32 v[104:105], v[104:105], v[120:121]
	v_pk_mul_f32 v[106:107], v[106:107], v[122:123]
	v_pk_mul_f32 v[108:109], v[108:109], v[124:125]
	v_pk_mul_f32 v[110:111], v[110:111], v[126:127]
	s_lshl_b32 s99, s98, 12
	v_add_u32_e32 v8, s99, v1
	global_store_dwordx4 v8, v[96:99], s[88:89] nt
	global_store_dwordx4 v8, v[100:103], s[88:89] offset:1024 nt
	global_store_dwordx4 v8, v[104:107], s[88:89] offset:2048 nt
	global_store_dwordx4 v8, v[108:111], s[88:89] offset:3072 nt
	s_waitcnt vmcnt(32)
	v_mul_f32_e32 v4, v16, v16
	v_fma_f32 v4, v17, v17, v4
	v_fma_f32 v4, v18, v18, v4
	v_fma_f32 v4, v19, v19, v4
	v_fma_f32 v4, v20, v20, v4
	v_fma_f32 v4, v21, v21, v4
	v_fma_f32 v4, v22, v22, v4
	v_fma_f32 v4, v23, v23, v4
	v_fma_f32 v4, v24, v24, v4
	v_fma_f32 v4, v25, v25, v4
	v_fma_f32 v4, v26, v26, v4
	v_fma_f32 v4, v27, v27, v4
	v_fma_f32 v4, v28, v28, v4
	v_fma_f32 v4, v29, v29, v4
	v_fma_f32 v4, v30, v30, v4
	v_fma_f32 v4, v31, v31, v4
	s_nop 1
	v_add_f32_dpp v5, v4, v4 quad_perm:[1,0,3,2] row_mask:0xf bank_mask:0xf
	s_nop 1
	v_add_f32_dpp v4, v5, v5 quad_perm:[2,3,0,1] row_mask:0xf bank_mask:0xf
	s_nop 1
	v_add_f32_dpp v5, v4, v4 row_half_mirror row_mask:0xf bank_mask:0xf
	s_nop 1
	v_add_f32_dpp v4, v5, v5 row_mirror row_mask:0xf bank_mask:0xf
	s_nop 1
	v_readlane_b32 s98, v4, 0
	v_readlane_b32 s99, v4, 16
	s_nop 3
	v_mov_b32_e32 v5, s98
	v_add_f32_e32 v5, s99, v5
	v_readlane_b32 s98, v4, 32
	v_readlane_b32 s99, v4, 48
	s_nop 3
	v_add_f32_e32 v5, s98, v5
	v_add_f32_e32 v5, s99, v5
	v_mul_f32_e32 v5, 0x3a800000, v5
	v_add_f32_e32 v5, 0x358637bd, v5
	v_rsq_f32_e32 v6, v5
	s_nop 0
	s_add_u32 s98, s97, 3072
	v_pk_mul_f32 v[16:17], v[16:17], v[6:7] op_sel_hi:[1,0]
	v_pk_mul_f32 v[18:19], v[18:19], v[6:7] op_sel_hi:[1,0]
	v_pk_mul_f32 v[20:21], v[20:21], v[6:7] op_sel_hi:[1,0]
	v_pk_mul_f32 v[22:23], v[22:23], v[6:7] op_sel_hi:[1,0]
	v_pk_mul_f32 v[24:25], v[24:25], v[6:7] op_sel_hi:[1,0]
	v_pk_mul_f32 v[26:27], v[26:27], v[6:7] op_sel_hi:[1,0]
	v_pk_mul_f32 v[28:29], v[28:29], v[6:7] op_sel_hi:[1,0]
	v_pk_mul_f32 v[30:31], v[30:31], v[6:7] op_sel_hi:[1,0]
	v_pk_mul_f32 v[16:17], v[16:17], v[112:113]
	v_pk_mul_f32 v[18:19], v[18:19], v[114:115]
	v_pk_mul_f32 v[20:21], v[20:21], v[116:117]
	v_pk_mul_f32 v[22:23], v[22:23], v[118:119]
	v_pk_mul_f32 v[24:25], v[24:25], v[120:121]
	v_pk_mul_f32 v[26:27], v[26:27], v[122:123]
	v_pk_mul_f32 v[28:29], v[28:29], v[124:125]
	v_pk_mul_f32 v[30:31], v[30:31], v[126:127]
	s_lshl_b32 s99, s98, 12
	v_add_u32_e32 v8, s99, v1
	global_store_dwordx4 v8, v[16:19], s[88:89] nt
	global_store_dwordx4 v8, v[20:23], s[88:89] offset:1024 nt
	global_store_dwordx4 v8, v[24:27], s[88:89] offset:2048 nt
	global_store_dwordx4 v8, v[28:31], s[88:89] offset:3072 nt
	s_waitcnt vmcnt(28)
	v_mul_f32_e32 v4, v32, v32
	v_fma_f32 v4, v33, v33, v4
	v_fma_f32 v4, v34, v34, v4
	v_fma_f32 v4, v35, v35, v4
	v_fma_f32 v4, v36, v36, v4
	v_fma_f32 v4, v37, v37, v4
	v_fma_f32 v4, v38, v38, v4
	v_fma_f32 v4, v39, v39, v4
	v_fma_f32 v4, v40, v40, v4
	v_fma_f32 v4, v41, v41, v4
	v_fma_f32 v4, v42, v42, v4
	v_fma_f32 v4, v43, v43, v4
	v_fma_f32 v4, v44, v44, v4
	v_fma_f32 v4, v45, v45, v4
	v_fma_f32 v4, v46, v46, v4
	v_fma_f32 v4, v47, v47, v4
	s_nop 1
	v_add_f32_dpp v5, v4, v4 quad_perm:[1,0,3,2] row_mask:0xf bank_mask:0xf
	s_nop 1
	v_add_f32_dpp v4, v5, v5 quad_perm:[2,3,0,1] row_mask:0xf bank_mask:0xf
	s_nop 1
	v_add_f32_dpp v5, v4, v4 row_half_mirror row_mask:0xf bank_mask:0xf
	s_nop 1
	v_add_f32_dpp v4, v5, v5 row_mirror row_mask:0xf bank_mask:0xf
	s_nop 1
	v_readlane_b32 s98, v4, 0
	v_readlane_b32 s99, v4, 16
	s_nop 3
	v_mov_b32_e32 v5, s98
	v_add_f32_e32 v5, s99, v5
	v_readlane_b32 s98, v4, 32
	v_readlane_b32 s99, v4, 48
	s_nop 3
	v_add_f32_e32 v5, s98, v5
	v_add_f32_e32 v5, s99, v5
	v_mul_f32_e32 v5, 0x3a800000, v5
	v_add_f32_e32 v5, 0x358637bd, v5
	v_rsq_f32_e32 v6, v5
	s_nop 0
	s_add_u32 s98, s97, 3328
	v_pk_mul_f32 v[32:33], v[32:33], v[6:7] op_sel_hi:[1,0]
	v_pk_mul_f32 v[34:35], v[34:35], v[6:7] op_sel_hi:[1,0]
	v_pk_mul_f32 v[36:37], v[36:37], v[6:7] op_sel_hi:[1,0]
	v_pk_mul_f32 v[38:39], v[38:39], v[6:7] op_sel_hi:[1,0]
	v_pk_mul_f32 v[40:41], v[40:41], v[6:7] op_sel_hi:[1,0]
	v_pk_mul_f32 v[42:43], v[42:43], v[6:7] op_sel_hi:[1,0]
	v_pk_mul_f32 v[44:45], v[44:45], v[6:7] op_sel_hi:[1,0]
	v_pk_mul_f32 v[46:47], v[46:47], v[6:7] op_sel_hi:[1,0]
	v_pk_mul_f32 v[32:33], v[32:33], v[112:113]
	v_pk_mul_f32 v[34:35], v[34:35], v[114:115]
	v_pk_mul_f32 v[36:37], v[36:37], v[116:117]
	v_pk_mul_f32 v[38:39], v[38:39], v[118:119]
	v_pk_mul_f32 v[40:41], v[40:41], v[120:121]
	v_pk_mul_f32 v[42:43], v[42:43], v[122:123]
	v_pk_mul_f32 v[44:45], v[44:45], v[124:125]
	v_pk_mul_f32 v[46:47], v[46:47], v[126:127]
	s_lshl_b32 s99, s98, 12
	v_add_u32_e32 v8, s99, v1
	global_store_dwordx4 v8, v[32:35], s[88:89] nt
	global_store_dwordx4 v8, v[36:39], s[88:89] offset:1024 nt
	global_store_dwordx4 v8, v[40:43], s[88:89] offset:2048 nt
	global_store_dwordx4 v8, v[44:47], s[88:89] offset:3072 nt
	s_waitcnt vmcnt(24)
	v_mul_f32_e32 v4, v48, v48
	v_fma_f32 v4, v49, v49, v4
	v_fma_f32 v4, v50, v50, v4
	v_fma_f32 v4, v51, v51, v4
	v_fma_f32 v4, v52, v52, v4
	v_fma_f32 v4, v53, v53, v4
	v_fma_f32 v4, v54, v54, v4
	v_fma_f32 v4, v55, v55, v4
	v_fma_f32 v4, v56, v56, v4
	v_fma_f32 v4, v57, v57, v4
	v_fma_f32 v4, v58, v58, v4
	v_fma_f32 v4, v59, v59, v4
	v_fma_f32 v4, v60, v60, v4
	v_fma_f32 v4, v61, v61, v4
	v_fma_f32 v4, v62, v62, v4
	v_fma_f32 v4, v63, v63, v4
	s_nop 1
	v_add_f32_dpp v5, v4, v4 quad_perm:[1,0,3,2] row_mask:0xf bank_mask:0xf
	s_nop 1
	v_add_f32_dpp v4, v5, v5 quad_perm:[2,3,0,1] row_mask:0xf bank_mask:0xf
	s_nop 1
	v_add_f32_dpp v5, v4, v4 row_half_mirror row_mask:0xf bank_mask:0xf
	s_nop 1
	v_add_f32_dpp v4, v5, v5 row_mirror row_mask:0xf bank_mask:0xf
	s_nop 1
	v_readlane_b32 s98, v4, 0
	v_readlane_b32 s99, v4, 16
	s_nop 3
	v_mov_b32_e32 v5, s98
	v_add_f32_e32 v5, s99, v5
	v_readlane_b32 s98, v4, 32
	v_readlane_b32 s99, v4, 48
	s_nop 3
	v_add_f32_e32 v5, s98, v5
	v_add_f32_e32 v5, s99, v5
	v_mul_f32_e32 v5, 0x3a800000, v5
	v_add_f32_e32 v5, 0x358637bd, v5
	v_rsq_f32_e32 v6, v5
	s_nop 0
	s_add_u32 s98, s97, 3584
	v_pk_mul_f32 v[48:49], v[48:49], v[6:7] op_sel_hi:[1,0]
	v_pk_mul_f32 v[50:51], v[50:51], v[6:7] op_sel_hi:[1,0]
	v_pk_mul_f32 v[52:53], v[52:53], v[6:7] op_sel_hi:[1,0]
	v_pk_mul_f32 v[54:55], v[54:55], v[6:7] op_sel_hi:[1,0]
	v_pk_mul_f32 v[56:57], v[56:57], v[6:7] op_sel_hi:[1,0]
	v_pk_mul_f32 v[58:59], v[58:59], v[6:7] op_sel_hi:[1,0]
	v_pk_mul_f32 v[60:61], v[60:61], v[6:7] op_sel_hi:[1,0]
	v_pk_mul_f32 v[62:63], v[62:63], v[6:7] op_sel_hi:[1,0]
	v_pk_mul_f32 v[48:49], v[48:49], v[112:113]
	v_pk_mul_f32 v[50:51], v[50:51], v[114:115]
	v_pk_mul_f32 v[52:53], v[52:53], v[116:117]
	v_pk_mul_f32 v[54:55], v[54:55], v[118:119]
	v_pk_mul_f32 v[56:57], v[56:57], v[120:121]
	v_pk_mul_f32 v[58:59], v[58:59], v[122:123]
	v_pk_mul_f32 v[60:61], v[60:61], v[124:125]
	v_pk_mul_f32 v[62:63], v[62:63], v[126:127]
	s_lshl_b32 s99, s98, 12
	v_add_u32_e32 v8, s99, v1
	global_store_dwordx4 v8, v[48:51], s[88:89] nt
	global_store_dwordx4 v8, v[52:55], s[88:89] offset:1024 nt
	global_store_dwordx4 v8, v[56:59], s[88:89] offset:2048 nt
	global_store_dwordx4 v8, v[60:63], s[88:89] offset:3072 nt
	s_waitcnt vmcnt(20)
	v_mul_f32_e32 v4, v64, v64
	v_fma_f32 v4, v65, v65, v4
	v_fma_f32 v4, v66, v66, v4
	v_fma_f32 v4, v67, v67, v4
	v_fma_f32 v4, v68, v68, v4
	v_fma_f32 v4, v69, v69, v4
	v_fma_f32 v4, v70, v70, v4
	v_fma_f32 v4, v71, v71, v4
	v_fma_f32 v4, v72, v72, v4
	v_fma_f32 v4, v73, v73, v4
	v_fma_f32 v4, v74, v74, v4
	v_fma_f32 v4, v75, v75, v4
	v_fma_f32 v4, v76, v76, v4
	v_fma_f32 v4, v77, v77, v4
	v_fma_f32 v4, v78, v78, v4
	v_fma_f32 v4, v79, v79, v4
	s_nop 1
	v_add_f32_dpp v5, v4, v4 quad_perm:[1,0,3,2] row_mask:0xf bank_mask:0xf
	s_nop 1
	v_add_f32_dpp v4, v5, v5 quad_perm:[2,3,0,1] row_mask:0xf bank_mask:0xf
	s_nop 1
	v_add_f32_dpp v5, v4, v4 row_half_mirror row_mask:0xf bank_mask:0xf
	s_nop 1
	v_add_f32_dpp v4, v5, v5 row_mirror row_mask:0xf bank_mask:0xf
	s_nop 1
	v_readlane_b32 s98, v4, 0
	v_readlane_b32 s99, v4, 16
	s_nop 3
	v_mov_b32_e32 v5, s98
	v_add_f32_e32 v5, s99, v5
	v_readlane_b32 s98, v4, 32
	v_readlane_b32 s99, v4, 48
	s_nop 3
	v_add_f32_e32 v5, s98, v5
	v_add_f32_e32 v5, s99, v5
	v_mul_f32_e32 v5, 0x3a800000, v5
	v_add_f32_e32 v5, 0x358637bd, v5
	v_rsq_f32_e32 v6, v5
	s_nop 0
	s_add_u32 s98, s97, 3840
	v_pk_mul_f32 v[64:65], v[64:65], v[6:7] op_sel_hi:[1,0]
	v_pk_mul_f32 v[66:67], v[66:67], v[6:7] op_sel_hi:[1,0]
	v_pk_mul_f32 v[68:69], v[68:69], v[6:7] op_sel_hi:[1,0]
	v_pk_mul_f32 v[70:71], v[70:71], v[6:7] op_sel_hi:[1,0]
	v_pk_mul_f32 v[72:73], v[72:73], v[6:7] op_sel_hi:[1,0]
	v_pk_mul_f32 v[74:75], v[74:75], v[6:7] op_sel_hi:[1,0]
	v_pk_mul_f32 v[76:77], v[76:77], v[6:7] op_sel_hi:[1,0]
	v_pk_mul_f32 v[78:79], v[78:79], v[6:7] op_sel_hi:[1,0]
	v_pk_mul_f32 v[64:65], v[64:65], v[112:113]
	v_pk_mul_f32 v[66:67], v[66:67], v[114:115]
	v_pk_mul_f32 v[68:69], v[68:69], v[116:117]
	v_pk_mul_f32 v[70:71], v[70:71], v[118:119]
	v_pk_mul_f32 v[72:73], v[72:73], v[120:121]
	v_pk_mul_f32 v[74:75], v[74:75], v[122:123]
	v_pk_mul_f32 v[76:77], v[76:77], v[124:125]
	v_pk_mul_f32 v[78:79], v[78:79], v[126:127]
	s_lshl_b32 s99, s98, 12
	v_add_u32_e32 v8, s99, v1
	global_store_dwordx4 v8, v[64:67], s[88:89] nt
	global_store_dwordx4 v8, v[68:71], s[88:89] offset:1024 nt
	global_store_dwordx4 v8, v[72:75], s[88:89] offset:2048 nt
	global_store_dwordx4 v8, v[76:79], s[88:89] offset:3072 nt
	s_waitcnt vmcnt(0)
